# K-loops: the wave about to compute raises its priority before (not after) the barrier ending its load segment
# speedup vs baseline: 1.0071x; 1.0071x over previous
;     __device__ bool next(int i, Unit& u) const { if (i >= n) return false; const int q = first + i; u.pm = rowbase + q % rows; u.pn = q / rows; return true; }
; #define PG8_STAGE(bufoff, gbase, voff) do { _Pragma("unroll") for (int _i = 0; _i < 2; ++_i) \
;         __builtin_amdgcn_global_load_lds((const unsigned*)((const char*)(gbase) + (voff)[_i]), (PG8_LAS unsigned*)(lds + (bufoff) + ldsw + _i * 8192), 16, 0, 0); } while (0)
; #define PG8_LDA(dst, b, h) do { _Pragma("unroll") for (int m = 0; m < 4; ++m) _Pragma("unroll") for (int k = 0; k < 2; ++k) dst[m][k] = *(const PG8_LAS bf16x8*)(lds + PG8_SA(b, h) + aoff + m * 2048 + k * 1024); } while (0)
; #define PG8_WAIT_V(n) asm volatile("s_waitcnt vmcnt(" #n ")" ::: "memory")
; template <class Epi, class Sched, bool ALIGN_EPI = false, bool SP2 = false>
; __device__ __forceinline__ void gemm_phase(PG8_LAS unsigned char* lds, const Gemm g, const Sched& S, const Epi& E) {
;     ...
;         const bool has_next = S.next(ui + 1, nxt);
;         const char* nA = has_next ? (const char*)g.A + (size_t)nxt.pm * tstep : cA; const char* nB = has_next ? (const char*)g.Bt + (size_t)nxt.pn * tstep : cB;
;         constexpr int NSEG = Epi::HAS_MID ? 2 : 1; const int tseg = nt / NSEG;
; #pragma unroll
;         for (int seg = 0; seg < NSEG; ++seg) {
;         if constexpr (Epi::HAS_MID) { if (seg == 1) E.mid(acc, cur, wr, wc, fr, fq); }
;         for (int t = seg * tseg; t < (seg + 1) * tseg; t += 2) {
;             const bool last = (t == nt - 2);
;             const char* a1 = cA + (size_t)(t + 1) * kstep;
;             const char* a2 = last ? nA : cA + (size_t)(t + 2) * kstep; const char* b2 = last ? nB : cB + (size_t)(t + 2) * kstep;
;             const char* a3 = a2 + kstep; const char* b3 = b2 + kstep;
;             if (last && has_next) S.a_ready(nxt);
;             if constexpr (SP2) {
;             PG8_LDB(B0, 0, 0); PG8_LDB(B1, 0, 1); PG8_SCHED; PG8_LDA(At, 0, 0); PG8_STAGE(PG8_SA(1, 1), a1 + hstep, voffA);
;             PG8_WAIT_V(8); PG8_WAIT_L(0); PG8_BAR; PG8_MMA(0, 0, At, B0); PG8_MMA(0, 1, At, B1); PG8_BAR; PG8_SCHED;
;             PG8_LDA(At, 0, 1); PG8_STAGE(PG8_SB(0, 0), b2, voffB); PG8_STAGE(PG8_SB(0, 1), b2 + hstep, voffB); PG8_STAGE(PG8_SA(0, 0), a2, voffA);
;             PG8_WAIT_V(8); PG8_WAIT_L(0); PG8_BAR; PG8_MMA(1, 0, At, B0); PG8_MMA(1, 1, At, B1); PG8_BAR; PG8_SCHED;
.LBB0_275:
	s_ashr_i32 s15, s14, 31
	s_lshl_b64 s[0:1], s[14:15], 20
	s_add_u32 s64, s54, s0
	s_addc_u32 s65, s55, s1
	s_and_b64 s[0:1], s[20:21], exec
	s_cselect_b32 s0, s65, s75
	s_cselect_b32 s1, s64, s74
	s_ashr_i32 s13, s12, 31
	s_lshl_b64 s[28:29], s[12:13], 20
	s_add_u32 s68, s36, s28
	s_addc_u32 s69, s37, s29
	s_and_b64 s[28:29], s[20:21], exec
	s_cselect_b32 s3, s69, s85
	s_cselect_b32 s4, s68, s84
	s_add_u32 s74, s74, 0x80080
	s_addc_u32 s75, s75, 0
	s_add_u32 s13, s84, 0x100
	s_addc_u32 s15, s85, 0
	s_mov_b32 s28, -2
	ds_read_b128 v[150:153], v158
	ds_read_b128 v[162:165], v158 offset:1024
	ds_read_b128 v[166:169], v158 offset:2048
	ds_read_b128 v[170:173], v158 offset:3072
	ds_read_b128 v[174:177], v159
	ds_read_b128 v[178:181], v159 offset:1024
	ds_read_b128 v[182:185], v159 offset:2048
	ds_read_b128 v[190:193], v159 offset:3072
	s_add_u32 s29, s74, 0xfff80080
	s_addc_u32 s57, s75, -1
	s_cmp_eq_u32 s28, 28
	s_cselect_b32 s89, s0, s57
	s_cselect_b32 s88, s1, s29
	s_cselect_b32 s85, s3, s15
	s_cselect_b32 s84, s4, s13
	v_lshl_add_u64 v[154:155], s[74:75], 0, v[142:143]
	s_add_i32 m0, s30, 0xc000
	ds_read_b128 v[194:197], v160
	ds_read_b128 v[198:201], v160 offset:1024
	ds_read_b128 v[202:205], v160 offset:2048
	ds_read_b128 v[206:209], v160 offset:3072
	ds_read_b128 v[210:213], v160 offset:4096
	ds_read_b128 v[214:217], v160 offset:5120
	ds_read_b128 v[218:221], v160 offset:6144
	ds_read_b128 v[222:225], v160 offset:7168
	global_load_lds_dwordx4 v[154:155], off
	v_lshl_add_u64 v[154:155], s[74:75], 0, v[144:145]
	s_add_i32 m0, s30, 0xe000
	s_nop 0
	global_load_lds_dwordx4 v[154:155], off
	s_waitcnt vmcnt(8)
	s_waitcnt lgkmcnt(0)
	s_setprio 1
	s_barrier
	s_waitcnt lgkmcnt(0)
	v_mfma_f32_16x16x32_bf16 v[124:127], v[150:153], v[194:197], 0
	v_mfma_f32_16x16x32_bf16 v[116:119], v[166:169], v[194:197], 0
	v_mfma_f32_16x16x32_bf16 v[108:111], v[150:153], v[202:205], 0
	v_mfma_f32_16x16x32_bf16 v[100:103], v[166:169], v[202:205], 0
	v_mfma_f32_16x16x32_bf16 v[92:95], v[150:153], v[210:213], 0
	v_mfma_f32_16x16x32_bf16 v[84:87], v[166:169], v[210:213], 0
	v_mfma_f32_16x16x32_bf16 v[76:79], v[150:153], v[218:221], 0
	v_mfma_f32_16x16x32_bf16 v[68:71], v[166:169], v[218:221], 0
	v_mfma_f32_16x16x32_bf16 v[124:127], v[162:165], v[198:201], v[124:127]
	v_mfma_f32_16x16x32_bf16 v[116:119], v[170:173], v[198:201], v[116:119]
	v_mfma_f32_16x16x32_bf16 v[108:111], v[162:165], v[206:209], v[108:111]
	v_mfma_f32_16x16x32_bf16 v[100:103], v[170:173], v[206:209], v[100:103]
	v_mfma_f32_16x16x32_bf16 v[92:95], v[162:165], v[214:217], v[92:95]
	v_mfma_f32_16x16x32_bf16 v[84:87], v[170:173], v[214:217], v[84:87]
	v_mfma_f32_16x16x32_bf16 v[76:79], v[162:165], v[222:225], v[76:79]
	v_mfma_f32_16x16x32_bf16 v[68:71], v[170:173], v[222:225], v[68:71]
	s_setprio 0
	s_setprio 1
	v_mfma_f32_16x16x32_bf16 v[120:123], v[174:177], v[194:197], 0
	v_mfma_f32_16x16x32_bf16 v[112:115], v[182:185], v[194:197], 0
	v_mfma_f32_16x16x32_bf16 v[104:107], v[174:177], v[202:205], 0
	v_mfma_f32_16x16x32_bf16 v[96:99], v[182:185], v[202:205], 0
	v_mfma_f32_16x16x32_bf16 v[88:91], v[174:177], v[210:213], 0
	v_mfma_f32_16x16x32_bf16 v[80:83], v[182:185], v[210:213], 0
	v_mfma_f32_16x16x32_bf16 v[72:75], v[174:177], v[218:221], 0
	v_mfma_f32_16x16x32_bf16 v[64:67], v[182:185], v[218:221], 0
	v_mfma_f32_16x16x32_bf16 v[120:123], v[178:181], v[198:201], v[120:123]
	v_mfma_f32_16x16x32_bf16 v[112:115], v[190:193], v[198:201], v[112:115]
	v_mfma_f32_16x16x32_bf16 v[104:107], v[178:181], v[206:209], v[104:107]
	v_mfma_f32_16x16x32_bf16 v[96:99], v[190:193], v[206:209], v[96:99]
	v_mfma_f32_16x16x32_bf16 v[88:91], v[178:181], v[214:217], v[88:91]
	v_mfma_f32_16x16x32_bf16 v[80:83], v[190:193], v[214:217], v[80:83]
	v_mfma_f32_16x16x32_bf16 v[72:75], v[178:181], v[222:225], v[72:75]
	v_mfma_f32_16x16x32_bf16 v[64:67], v[190:193], v[222:225], v[64:67]
	s_setprio 0
	s_barrier
	s_add_i32 s29, s94, s23
	v_lshl_add_u64 v[154:155], s[84:85], 0, v[130:131]
	s_mov_b32 m0, s29
	ds_read_b128 v[194:197], v160 offset:16384
	ds_read_b128 v[198:201], v160 offset:17408
	ds_read_b128 v[202:205], v160 offset:18432
	ds_read_b128 v[206:209], v160 offset:19456
	ds_read_b128 v[210:213], v160 offset:20480
	ds_read_b128 v[214:217], v160 offset:21504
	ds_read_b128 v[218:221], v160 offset:22528
	ds_read_b128 v[222:225], v160 offset:23552
	global_load_lds_dwordx4 v[154:155], off
	s_add_i32 m0, s29, 0x2000
	s_add_u32 s96, s84, 0x80000
	v_lshl_add_u64 v[186:187], s[84:85], 0, v[134:135]
	s_addc_u32 s97, s85, 0
	s_add_i32 s29, s95, s23
	global_load_lds_dwordx4 v[186:187], off
	v_lshl_add_u64 v[226:227], s[96:97], 0, v[130:131]
	s_mov_b32 m0, s29
	v_lshl_add_u64 v[228:229], s[88:89], 0, v[132:133]
	global_load_lds_dwordx4 v[226:227], off
	v_lshl_add_u64 v[226:227], s[96:97], 0, v[134:135]
	s_add_i32 m0, s29, 0x2000
	s_nop 0
	global_load_lds_dwordx4 v[226:227], off
	v_lshl_add_u64 v[226:227], s[88:89], 0, v[128:129]
	s_mov_b32 m0, s30
	s_nop 0
	global_load_lds_dwordx4 v[226:227], off
	s_mov_b32 m0, s31
	s_nop 0
	global_load_lds_dwordx4 v[228:229], off
	s_waitcnt vmcnt(8)
	s_waitcnt lgkmcnt(0)
	s_setprio 1
	s_barrier
; #define PG8_STAGE(bufoff, gbase, voff) do { _Pragma("unroll") for (int _i = 0; _i < 2; ++_i) \
;         __builtin_amdgcn_global_load_lds((const unsigned*)((const char*)(gbase) + (voff)[_i]), (PG8_LAS unsigned*)(lds + (bufoff) + ldsw + _i * 8192), 16, 0, 0); } while (0)
; #define PG8_LDA(dst, b, h) do { _Pragma("unroll") for (int m = 0; m < 4; ++m) _Pragma("unroll") for (int k = 0; k < 2; ++k) dst[m][k] = *(const PG8_LAS bf16x8*)(lds + PG8_SA(b, h) + aoff + m * 2048 + k * 1024); } while (0)
; #define PG8_LDB(dst, b, h) do { _Pragma("unroll") for (int n = 0; n < 2; ++n) _Pragma("unroll") for (int k = 0; k < 2; ++k) dst[n][k] = *(const PG8_LAS bf16x8*)(lds + PG8_SB(b, h) + boff + n * 2048 + k * 1024); } while (0)
; #define PG8_MMA(ai, bj, At, Bt) do { __builtin_amdgcn_s_setprio(1); _Pragma("unroll") for (int m = 0; m < 4; ++m) _Pragma("unroll") for (int n = 0; n < 2; ++n) _Pragma("unroll") for (int k = 0; k < 2; ++k) \
;         acc[ai][bj][m][n] = __builtin_amdgcn_mfma_f32_16x16x32_bf16(Bt[n][k], At[m][k], acc[ai][bj][m][n], 0, 0, 0); __builtin_amdgcn_s_setprio(0); } while (0)
; #define PG8_BAR __builtin_amdgcn_s_barrier()
; template <class Epi, class Sched, bool ALIGN_EPI = false, bool SP2 = false>
; __device__ __forceinline__ void gemm_phase(PG8_LAS unsigned char* lds, const Gemm g, const Sched& S, const Epi& E) {
;     ...
;             if constexpr (SP2) {
;             PG8_LDB(B0, 0, 0); PG8_LDB(B1, 0, 1); PG8_SCHED; PG8_LDA(At, 0, 0); PG8_STAGE(PG8_SA(1, 1), a1 + hstep, voffA);
;             PG8_WAIT_V(8); PG8_WAIT_L(0); PG8_BAR; PG8_MMA(0, 0, At, B0); PG8_MMA(0, 1, At, B1); PG8_BAR; PG8_SCHED;
;             PG8_LDA(At, 0, 1); PG8_STAGE(PG8_SB(0, 0), b2, voffB); PG8_STAGE(PG8_SB(0, 1), b2 + hstep, voffB); PG8_STAGE(PG8_SA(0, 0), a2, voffA);
;             PG8_WAIT_V(8); PG8_WAIT_L(0); PG8_BAR; PG8_MMA(1, 0, At, B0); PG8_MMA(1, 1, At, B1); PG8_BAR; PG8_SCHED;
;             PG8_LDB(B0, 1, 0); PG8_LDB(B1, 1, 1); PG8_SCHED; PG8_LDA(At, 1, 0); PG8_STAGE(PG8_SA(0, 1), a2 + hstep, voffA);
;             PG8_WAIT_V(8); PG8_WAIT_L(0); PG8_BAR; PG8_MMA(0, 0, At, B0); PG8_MMA(0, 1, At, B1); PG8_BAR; PG8_SCHED;
;             PG8_LDA(At, 1, 1); PG8_STAGE(PG8_SB(1, 0), b3, voffB); PG8_STAGE(PG8_SB(1, 1), b3 + hstep, voffB); PG8_STAGE(PG8_SA(1, 0), a3, voffA);
;             PG8_WAIT_V(8); PG8_WAIT_L(0); PG8_BAR; PG8_MMA(1, 0, At, B0); PG8_MMA(1, 1, At, B1); PG8_BAR; PG8_SCHED;
	s_waitcnt lgkmcnt(0)
	v_mfma_f32_16x16x32_bf16 v[60:63], v[150:153], v[194:197], 0
	v_mfma_f32_16x16x32_bf16 v[52:55], v[166:169], v[194:197], 0
	v_mfma_f32_16x16x32_bf16 v[44:47], v[150:153], v[202:205], 0
	v_mfma_f32_16x16x32_bf16 v[36:39], v[166:169], v[202:205], 0
	v_mfma_f32_16x16x32_bf16 v[28:31], v[150:153], v[210:213], 0
	v_mfma_f32_16x16x32_bf16 v[20:23], v[166:169], v[210:213], 0
	v_mfma_f32_16x16x32_bf16 v[12:15], v[150:153], v[218:221], 0
	v_mfma_f32_16x16x32_bf16 v[4:7], v[166:169], v[218:221], 0
	v_mfma_f32_16x16x32_bf16 v[60:63], v[162:165], v[198:201], v[60:63]
	v_mfma_f32_16x16x32_bf16 v[52:55], v[170:173], v[198:201], v[52:55]
	v_mfma_f32_16x16x32_bf16 v[44:47], v[162:165], v[206:209], v[44:47]
	v_mfma_f32_16x16x32_bf16 v[36:39], v[170:173], v[206:209], v[36:39]
	v_mfma_f32_16x16x32_bf16 v[28:31], v[162:165], v[214:217], v[28:31]
	v_mfma_f32_16x16x32_bf16 v[20:23], v[170:173], v[214:217], v[20:23]
	v_mfma_f32_16x16x32_bf16 v[12:15], v[162:165], v[222:225], v[12:15]
	v_mfma_f32_16x16x32_bf16 v[4:7], v[170:173], v[222:225], v[4:7]
	s_setprio 0
	s_setprio 1
	v_mfma_f32_16x16x32_bf16 v[56:59], v[174:177], v[194:197], 0
	v_mfma_f32_16x16x32_bf16 v[48:51], v[182:185], v[194:197], 0
	v_mfma_f32_16x16x32_bf16 v[40:43], v[174:177], v[202:205], 0
	v_mfma_f32_16x16x32_bf16 v[32:35], v[182:185], v[202:205], 0
	v_mfma_f32_16x16x32_bf16 v[24:27], v[174:177], v[210:213], 0
	v_mfma_f32_16x16x32_bf16 v[16:19], v[182:185], v[210:213], 0
	v_mfma_f32_16x16x32_bf16 v[8:11], v[174:177], v[218:221], 0
	v_mfma_f32_16x16x32_bf16 v[0:3], v[182:185], v[218:221], 0
	v_mfma_f32_16x16x32_bf16 v[56:59], v[178:181], v[198:201], v[56:59]
	v_mfma_f32_16x16x32_bf16 v[48:51], v[190:193], v[198:201], v[48:51]
	v_mfma_f32_16x16x32_bf16 v[40:43], v[178:181], v[206:209], v[40:43]
	v_mfma_f32_16x16x32_bf16 v[32:35], v[190:193], v[206:209], v[32:35]
	v_mfma_f32_16x16x32_bf16 v[24:27], v[178:181], v[214:217], v[24:27]
	v_mfma_f32_16x16x32_bf16 v[16:19], v[190:193], v[214:217], v[16:19]
	v_mfma_f32_16x16x32_bf16 v[8:11], v[178:181], v[222:225], v[8:11]
	v_mfma_f32_16x16x32_bf16 v[0:3], v[190:193], v[222:225], v[0:3]
	s_setprio 0
	s_barrier
	s_add_i32 s29, 0, 0x18000
	v_add_u32_e32 v136, s29, v156
	s_add_i32 s57, 0, 0x1c000
	ds_read_b128 v[150:153], v136
	ds_read_b128 v[162:165], v136 offset:1024
	ds_read_b128 v[166:169], v136 offset:2048
	ds_read_b128 v[170:173], v136 offset:3072
	v_add_u32_e32 v136, s57, v156
	ds_read_b128 v[174:177], v136
	ds_read_b128 v[178:181], v136 offset:1024
	ds_read_b128 v[182:185], v136 offset:2048
	ds_read_b128 v[190:193], v136 offset:3072
	s_add_u32 s88, s88, 0x80000
	s_addc_u32 s89, s89, 0
	s_mov_b32 m0, s33
	v_lshl_add_u64 v[230:231], s[88:89], 0, v[128:129]
	ds_read_b128 v[194:197], v160 offset:32768
	ds_read_b128 v[198:201], v160 offset:33792
	ds_read_b128 v[202:205], v160 offset:34816
	ds_read_b128 v[206:209], v160 offset:35840
	ds_read_b128 v[210:213], v160 offset:36864
	ds_read_b128 v[214:217], v160 offset:37888
	ds_read_b128 v[218:221], v160 offset:38912
	ds_read_b128 v[222:225], v160 offset:39936
	global_load_lds_dwordx4 v[230:231], off
	v_lshl_add_u64 v[230:231], s[88:89], 0, v[132:133]
	s_mov_b32 m0, s71
	s_nop 0
	global_load_lds_dwordx4 v[230:231], off
	s_waitcnt vmcnt(8)
	s_waitcnt lgkmcnt(0)
	s_setprio 1
	s_barrier
	s_waitcnt lgkmcnt(0)
	v_mfma_f32_16x16x32_bf16 v[124:127], v[150:153], v[194:197], v[124:127]
	v_mfma_f32_16x16x32_bf16 v[116:119], v[166:169], v[194:197], v[116:119]
	v_mfma_f32_16x16x32_bf16 v[108:111], v[150:153], v[202:205], v[108:111]
	v_mfma_f32_16x16x32_bf16 v[100:103], v[166:169], v[202:205], v[100:103]
	v_mfma_f32_16x16x32_bf16 v[92:95], v[150:153], v[210:213], v[92:95]
	v_mfma_f32_16x16x32_bf16 v[84:87], v[166:169], v[210:213], v[84:87]
	v_mfma_f32_16x16x32_bf16 v[76:79], v[150:153], v[218:221], v[76:79]
	v_mfma_f32_16x16x32_bf16 v[68:71], v[166:169], v[218:221], v[68:71]
	v_mfma_f32_16x16x32_bf16 v[124:127], v[162:165], v[198:201], v[124:127]
	v_mfma_f32_16x16x32_bf16 v[116:119], v[170:173], v[198:201], v[116:119]
	v_mfma_f32_16x16x32_bf16 v[108:111], v[162:165], v[206:209], v[108:111]
	v_mfma_f32_16x16x32_bf16 v[100:103], v[170:173], v[206:209], v[100:103]
	v_mfma_f32_16x16x32_bf16 v[92:95], v[162:165], v[214:217], v[92:95]
	v_mfma_f32_16x16x32_bf16 v[84:87], v[170:173], v[214:217], v[84:87]
	v_mfma_f32_16x16x32_bf16 v[76:79], v[162:165], v[222:225], v[76:79]
	v_mfma_f32_16x16x32_bf16 v[68:71], v[170:173], v[222:225], v[68:71]
	s_setprio 0
	s_setprio 1
	v_mfma_f32_16x16x32_bf16 v[120:123], v[174:177], v[194:197], v[120:123]
	v_mfma_f32_16x16x32_bf16 v[112:115], v[182:185], v[194:197], v[112:115]
	v_mfma_f32_16x16x32_bf16 v[104:107], v[174:177], v[202:205], v[104:107]
	v_mfma_f32_16x16x32_bf16 v[96:99], v[182:185], v[202:205], v[96:99]
	v_mfma_f32_16x16x32_bf16 v[88:91], v[174:177], v[210:213], v[88:91]
	v_mfma_f32_16x16x32_bf16 v[80:83], v[182:185], v[210:213], v[80:83]
	v_mfma_f32_16x16x32_bf16 v[72:75], v[174:177], v[218:221], v[72:75]
	v_mfma_f32_16x16x32_bf16 v[64:67], v[182:185], v[218:221], v[64:67]
	v_mfma_f32_16x16x32_bf16 v[120:123], v[178:181], v[198:201], v[120:123]
	v_mfma_f32_16x16x32_bf16 v[112:115], v[190:193], v[198:201], v[112:115]
	v_mfma_f32_16x16x32_bf16 v[104:107], v[178:181], v[206:209], v[104:107]
	v_mfma_f32_16x16x32_bf16 v[96:99], v[190:193], v[206:209], v[96:99]
	v_mfma_f32_16x16x32_bf16 v[88:91], v[178:181], v[214:217], v[88:91]
	v_mfma_f32_16x16x32_bf16 v[80:83], v[190:193], v[214:217], v[80:83]
	v_mfma_f32_16x16x32_bf16 v[72:75], v[178:181], v[222:225], v[72:75]
	v_mfma_f32_16x16x32_bf16 v[64:67], v[190:193], v[222:225], v[64:67]
	s_setprio 0
	s_barrier
; #define PG8_STAGE(bufoff, gbase, voff) do { _Pragma("unroll") for (int _i = 0; _i < 2; ++_i) \
;         __builtin_amdgcn_global_load_lds((const unsigned*)((const char*)(gbase) + (voff)[_i]), (PG8_LAS unsigned*)(lds + (bufoff) + ldsw + _i * 8192), 16, 0, 0); } while (0)
; #define PG8_LDA(dst, b, h) do { _Pragma("unroll") for (int m = 0; m < 4; ++m) _Pragma("unroll") for (int k = 0; k < 2; ++k) dst[m][k] = *(const PG8_LAS bf16x8*)(lds + PG8_SA(b, h) + aoff + m * 2048 + k * 1024); } while (0)
; #define PG8_LDB(dst, b, h) do { _Pragma("unroll") for (int n = 0; n < 2; ++n) _Pragma("unroll") for (int k = 0; k < 2; ++k) dst[n][k] = *(const PG8_LAS bf16x8*)(lds + PG8_SB(b, h) + boff + n * 2048 + k * 1024); } while (0)
; #define PG8_WAIT_V(n) asm volatile("s_waitcnt vmcnt(" #n ")" ::: "memory")
; #define PG8_WAIT_L(n) asm volatile("s_waitcnt lgkmcnt(" #n ")" ::: "memory")
; #define PG8_BAR __builtin_amdgcn_s_barrier()
; #define PG8_SCHED __builtin_amdgcn_sched_barrier(0)
; template <class Epi, class Sched, bool ALIGN_EPI = false, bool SP2 = false>
; __device__ __forceinline__ void gemm_phase(PG8_LAS unsigned char* lds, const Gemm g, const Sched& S, const Epi& E) {
;     ...
;         for (int t = seg * tseg; t < (seg + 1) * tseg; t += 2) {
;     ...
;             if constexpr (SP2) {
;             PG8_LDB(B0, 0, 0); PG8_LDB(B1, 0, 1); PG8_SCHED; PG8_LDA(At, 0, 0); PG8_STAGE(PG8_SA(1, 1), a1 + hstep, voffA);
;             PG8_WAIT_V(8); PG8_WAIT_L(0); PG8_BAR; PG8_MMA(0, 0, At, B0); PG8_MMA(0, 1, At, B1); PG8_BAR; PG8_SCHED;
;             PG8_LDA(At, 0, 1); PG8_STAGE(PG8_SB(0, 0), b2, voffB); PG8_STAGE(PG8_SB(0, 1), b2 + hstep, voffB); PG8_STAGE(PG8_SA(0, 0), a2, voffA);
;             PG8_WAIT_V(8); PG8_WAIT_L(0); PG8_BAR; PG8_MMA(1, 0, At, B0); PG8_MMA(1, 1, At, B1); PG8_BAR; PG8_SCHED;
;             PG8_LDB(B0, 1, 0); PG8_LDB(B1, 1, 1); PG8_SCHED; PG8_LDA(At, 1, 0); PG8_STAGE(PG8_SA(0, 1), a2 + hstep, voffA);
;             PG8_WAIT_V(8); PG8_WAIT_L(0); PG8_BAR; PG8_MMA(0, 0, At, B0); PG8_MMA(0, 1, At, B1); PG8_BAR; PG8_SCHED;
;             PG8_LDA(At, 1, 1); PG8_STAGE(PG8_SB(1, 0), b3, voffB); PG8_STAGE(PG8_SB(1, 1), b3 + hstep, voffB); PG8_STAGE(PG8_SA(1, 0), a3, voffA);
;             PG8_WAIT_V(8); PG8_WAIT_L(0); PG8_BAR; PG8_MMA(1, 0, At, B0); PG8_MMA(1, 1, At, B1); PG8_BAR; PG8_SCHED;
	s_add_i32 s29, s29, s23
	v_lshl_add_u64 v[154:155], v[154:155], 0, s[8:9]
	s_mov_b32 m0, s29
	ds_read_b128 v[194:197], v160 offset:49152
	ds_read_b128 v[198:201], v160 offset:50176
	ds_read_b128 v[202:205], v160 offset:51200
	ds_read_b128 v[206:209], v160 offset:52224
	ds_read_b128 v[210:213], v160 offset:53248
	ds_read_b128 v[214:217], v160 offset:54272
	ds_read_b128 v[218:221], v160 offset:55296
	ds_read_b128 v[222:225], v160 offset:56320
	global_load_lds_dwordx4 v[154:155], off
	s_add_i32 m0, s29, 0x2000
	s_add_u32 s84, s84, 0x80080
	v_lshl_add_u64 v[154:155], v[186:187], 0, s[8:9]
	s_addc_u32 s85, s85, 0
	s_add_i32 s29, s57, s23
	global_load_lds_dwordx4 v[154:155], off
	v_lshl_add_u64 v[154:155], s[84:85], 0, v[130:131]
	s_mov_b32 m0, s29
	s_nop 0
	global_load_lds_dwordx4 v[154:155], off
	v_lshl_add_u64 v[154:155], s[84:85], 0, v[134:135]
	s_add_i32 m0, s29, 0x2000
	s_nop 0
	global_load_lds_dwordx4 v[154:155], off
	v_lshl_add_u64 v[154:155], v[226:227], 0, s[8:9]
	s_mov_b32 m0, s92
	s_nop 0
	global_load_lds_dwordx4 v[154:155], off
	v_lshl_add_u64 v[154:155], v[228:229], 0, s[8:9]
	s_mov_b32 m0, s93
	s_nop 0
	global_load_lds_dwordx4 v[154:155], off
	s_waitcnt vmcnt(8)
	s_waitcnt lgkmcnt(0)
	s_setprio 1
	s_barrier
	s_waitcnt lgkmcnt(0)
	v_mfma_f32_16x16x32_bf16 v[60:63], v[150:153], v[194:197], v[60:63]
	v_mfma_f32_16x16x32_bf16 v[52:55], v[166:169], v[194:197], v[52:55]
	v_mfma_f32_16x16x32_bf16 v[44:47], v[150:153], v[202:205], v[44:47]
	v_mfma_f32_16x16x32_bf16 v[36:39], v[166:169], v[202:205], v[36:39]
	v_mfma_f32_16x16x32_bf16 v[28:31], v[150:153], v[210:213], v[28:31]
	v_mfma_f32_16x16x32_bf16 v[20:23], v[166:169], v[210:213], v[20:23]
	v_mfma_f32_16x16x32_bf16 v[12:15], v[150:153], v[218:221], v[12:15]
	v_mfma_f32_16x16x32_bf16 v[4:7], v[166:169], v[218:221], v[4:7]
	v_mfma_f32_16x16x32_bf16 v[60:63], v[162:165], v[198:201], v[60:63]
	v_mfma_f32_16x16x32_bf16 v[52:55], v[170:173], v[198:201], v[52:55]
	v_mfma_f32_16x16x32_bf16 v[44:47], v[162:165], v[206:209], v[44:47]
	v_mfma_f32_16x16x32_bf16 v[36:39], v[170:173], v[206:209], v[36:39]
	v_mfma_f32_16x16x32_bf16 v[28:31], v[162:165], v[214:217], v[28:31]
	v_mfma_f32_16x16x32_bf16 v[20:23], v[170:173], v[214:217], v[20:23]
	v_mfma_f32_16x16x32_bf16 v[12:15], v[162:165], v[222:225], v[12:15]
	v_mfma_f32_16x16x32_bf16 v[4:7], v[170:173], v[222:225], v[4:7]
	s_setprio 0
	s_setprio 1
	v_mfma_f32_16x16x32_bf16 v[56:59], v[174:177], v[194:197], v[56:59]
	v_mfma_f32_16x16x32_bf16 v[48:51], v[182:185], v[194:197], v[48:51]
	v_mfma_f32_16x16x32_bf16 v[40:43], v[174:177], v[202:205], v[40:43]
	v_mfma_f32_16x16x32_bf16 v[32:35], v[182:185], v[202:205], v[32:35]
	v_mfma_f32_16x16x32_bf16 v[24:27], v[174:177], v[210:213], v[24:27]
	v_mfma_f32_16x16x32_bf16 v[16:19], v[182:185], v[210:213], v[16:19]
	v_mfma_f32_16x16x32_bf16 v[8:11], v[174:177], v[218:221], v[8:11]
	v_mfma_f32_16x16x32_bf16 v[0:3], v[182:185], v[218:221], v[0:3]
	v_mfma_f32_16x16x32_bf16 v[56:59], v[178:181], v[198:201], v[56:59]
	v_mfma_f32_16x16x32_bf16 v[48:51], v[190:193], v[198:201], v[48:51]
	v_mfma_f32_16x16x32_bf16 v[40:43], v[178:181], v[206:209], v[40:43]
	v_mfma_f32_16x16x32_bf16 v[32:35], v[190:193], v[206:209], v[32:35]
	v_mfma_f32_16x16x32_bf16 v[24:27], v[178:181], v[214:217], v[24:27]
	v_mfma_f32_16x16x32_bf16 v[16:19], v[190:193], v[214:217], v[16:19]
	v_mfma_f32_16x16x32_bf16 v[8:11], v[178:181], v[222:225], v[8:11]
	v_mfma_f32_16x16x32_bf16 v[0:3], v[190:193], v[222:225], v[0:3]
	s_setprio 0
	s_barrier
	s_add_i32 s28, s28, 2
	s_add_u32 s74, s74, 0x100
	s_addc_u32 s75, s75, 0
	s_add_u32 s13, s13, 0x100
	s_addc_u32 s15, s15, 0
	s_cmp_gt_u32 s28, 29
.LBB0_276:
	ds_read_b128 v[150:153], v158
	ds_read_b128 v[162:165], v158 offset:1024
	ds_read_b128 v[166:169], v158 offset:2048
	ds_read_b128 v[170:173], v158 offset:3072
	ds_read_b128 v[174:177], v159
	ds_read_b128 v[178:181], v159 offset:1024
	ds_read_b128 v[182:185], v159 offset:2048
	ds_read_b128 v[190:193], v159 offset:3072
	s_add_u32 s29, s74, 0xfff80080
	s_addc_u32 s57, s75, -1
	s_cmp_eq_u32 s28, 28
	s_cselect_b32 s89, s0, s57
	s_cselect_b32 s88, s1, s29
	s_cselect_b32 s85, s3, s15
	s_cselect_b32 s84, s4, s13
	v_lshl_add_u64 v[154:155], s[74:75], 0, v[142:143]
	s_add_i32 m0, s30, 0xc000
	ds_read_b128 v[194:197], v160
	ds_read_b128 v[198:201], v160 offset:1024
	ds_read_b128 v[202:205], v160 offset:2048
	ds_read_b128 v[206:209], v160 offset:3072
	ds_read_b128 v[210:213], v160 offset:4096
	ds_read_b128 v[214:217], v160 offset:5120
	ds_read_b128 v[218:221], v160 offset:6144
	ds_read_b128 v[222:225], v160 offset:7168
	global_load_lds_dwordx4 v[154:155], off
	v_lshl_add_u64 v[154:155], s[74:75], 0, v[144:145]
	s_add_i32 m0, s30, 0xe000
	s_nop 0
	global_load_lds_dwordx4 v[154:155], off
	s_waitcnt vmcnt(8)
	s_waitcnt lgkmcnt(0)
	s_setprio 1
	s_barrier
; #define PG8_STAGE(bufoff, gbase, voff) do { _Pragma("unroll") for (int _i = 0; _i < 2; ++_i) \
;         __builtin_amdgcn_global_load_lds((const unsigned*)((const char*)(gbase) + (voff)[_i]), (PG8_LAS unsigned*)(lds + (bufoff) + ldsw + _i * 8192), 16, 0, 0); } while (0)
; #define PG8_LDA(dst, b, h) do { _Pragma("unroll") for (int m = 0; m < 4; ++m) _Pragma("unroll") for (int k = 0; k < 2; ++k) dst[m][k] = *(const PG8_LAS bf16x8*)(lds + PG8_SA(b, h) + aoff + m * 2048 + k * 1024); } while (0)
; #define PG8_LDB(dst, b, h) do { _Pragma("unroll") for (int n = 0; n < 2; ++n) _Pragma("unroll") for (int k = 0; k < 2; ++k) dst[n][k] = *(const PG8_LAS bf16x8*)(lds + PG8_SB(b, h) + boff + n * 2048 + k * 1024); } while (0)
; #define PG8_MMA(ai, bj, At, Bt) do { __builtin_amdgcn_s_setprio(1); _Pragma("unroll") for (int m = 0; m < 4; ++m) _Pragma("unroll") for (int n = 0; n < 2; ++n) _Pragma("unroll") for (int k = 0; k < 2; ++k) \
;         acc[ai][bj][m][n] = __builtin_amdgcn_mfma_f32_16x16x32_bf16(Bt[n][k], At[m][k], acc[ai][bj][m][n], 0, 0, 0); __builtin_amdgcn_s_setprio(0); } while (0)
; #define PG8_WAIT_V(n) asm volatile("s_waitcnt vmcnt(" #n ")" ::: "memory")
; #define PG8_WAIT_L(n) asm volatile("s_waitcnt lgkmcnt(" #n ")" ::: "memory")
; #define PG8_BAR __builtin_amdgcn_s_barrier()
; #define PG8_SCHED __builtin_amdgcn_sched_barrier(0)
; template <class Epi, class Sched, bool ALIGN_EPI = false, bool SP2 = false>
; __device__ __forceinline__ void gemm_phase(PG8_LAS unsigned char* lds, const Gemm g, const Sched& S, const Epi& E) {
;     ...
;             if constexpr (SP2) {
;             PG8_LDB(B0, 0, 0); PG8_LDB(B1, 0, 1); PG8_SCHED; PG8_LDA(At, 0, 0); PG8_STAGE(PG8_SA(1, 1), a1 + hstep, voffA);
;             PG8_WAIT_V(8); PG8_WAIT_L(0); PG8_BAR; PG8_MMA(0, 0, At, B0); PG8_MMA(0, 1, At, B1); PG8_BAR; PG8_SCHED;
;             PG8_LDA(At, 0, 1); PG8_STAGE(PG8_SB(0, 0), b2, voffB); PG8_STAGE(PG8_SB(0, 1), b2 + hstep, voffB); PG8_STAGE(PG8_SA(0, 0), a2, voffA);
;             PG8_WAIT_V(8); PG8_WAIT_L(0); PG8_BAR; PG8_MMA(1, 0, At, B0); PG8_MMA(1, 1, At, B1); PG8_BAR; PG8_SCHED;
	s_waitcnt lgkmcnt(0)
	v_mfma_f32_16x16x32_bf16 v[124:127], v[150:153], v[194:197], v[124:127]
	v_mfma_f32_16x16x32_bf16 v[116:119], v[166:169], v[194:197], v[116:119]
	v_mfma_f32_16x16x32_bf16 v[108:111], v[150:153], v[202:205], v[108:111]
	v_mfma_f32_16x16x32_bf16 v[100:103], v[166:169], v[202:205], v[100:103]
	v_mfma_f32_16x16x32_bf16 v[92:95], v[150:153], v[210:213], v[92:95]
	v_mfma_f32_16x16x32_bf16 v[84:87], v[166:169], v[210:213], v[84:87]
	v_mfma_f32_16x16x32_bf16 v[76:79], v[150:153], v[218:221], v[76:79]
	v_mfma_f32_16x16x32_bf16 v[68:71], v[166:169], v[218:221], v[68:71]
	v_mfma_f32_16x16x32_bf16 v[124:127], v[162:165], v[198:201], v[124:127]
	v_mfma_f32_16x16x32_bf16 v[116:119], v[170:173], v[198:201], v[116:119]
	v_mfma_f32_16x16x32_bf16 v[108:111], v[162:165], v[206:209], v[108:111]
	v_mfma_f32_16x16x32_bf16 v[100:103], v[170:173], v[206:209], v[100:103]
	v_mfma_f32_16x16x32_bf16 v[92:95], v[162:165], v[214:217], v[92:95]
	v_mfma_f32_16x16x32_bf16 v[84:87], v[170:173], v[214:217], v[84:87]
	v_mfma_f32_16x16x32_bf16 v[76:79], v[162:165], v[222:225], v[76:79]
	v_mfma_f32_16x16x32_bf16 v[68:71], v[170:173], v[222:225], v[68:71]
	s_setprio 0
	s_setprio 1
	v_mfma_f32_16x16x32_bf16 v[120:123], v[174:177], v[194:197], v[120:123]
	v_mfma_f32_16x16x32_bf16 v[112:115], v[182:185], v[194:197], v[112:115]
	v_mfma_f32_16x16x32_bf16 v[104:107], v[174:177], v[202:205], v[104:107]
	v_mfma_f32_16x16x32_bf16 v[96:99], v[182:185], v[202:205], v[96:99]
	v_mfma_f32_16x16x32_bf16 v[88:91], v[174:177], v[210:213], v[88:91]
	v_mfma_f32_16x16x32_bf16 v[80:83], v[182:185], v[210:213], v[80:83]
	v_mfma_f32_16x16x32_bf16 v[72:75], v[174:177], v[218:221], v[72:75]
	v_mfma_f32_16x16x32_bf16 v[64:67], v[182:185], v[218:221], v[64:67]
	v_mfma_f32_16x16x32_bf16 v[120:123], v[178:181], v[198:201], v[120:123]
	v_mfma_f32_16x16x32_bf16 v[112:115], v[190:193], v[198:201], v[112:115]
	v_mfma_f32_16x16x32_bf16 v[104:107], v[178:181], v[206:209], v[104:107]
	v_mfma_f32_16x16x32_bf16 v[96:99], v[190:193], v[206:209], v[96:99]
	v_mfma_f32_16x16x32_bf16 v[88:91], v[178:181], v[214:217], v[88:91]
	v_mfma_f32_16x16x32_bf16 v[80:83], v[190:193], v[214:217], v[80:83]
	v_mfma_f32_16x16x32_bf16 v[72:75], v[178:181], v[222:225], v[72:75]
	v_mfma_f32_16x16x32_bf16 v[64:67], v[190:193], v[222:225], v[64:67]
	s_setprio 0
	s_barrier
	s_add_i32 s29, s94, s23
	v_lshl_add_u64 v[154:155], s[84:85], 0, v[130:131]
	s_mov_b32 m0, s29
	ds_read_b128 v[194:197], v160 offset:16384
	ds_read_b128 v[198:201], v160 offset:17408
	ds_read_b128 v[202:205], v160 offset:18432
	ds_read_b128 v[206:209], v160 offset:19456
	ds_read_b128 v[210:213], v160 offset:20480
	ds_read_b128 v[214:217], v160 offset:21504
	ds_read_b128 v[218:221], v160 offset:22528
	ds_read_b128 v[222:225], v160 offset:23552
	global_load_lds_dwordx4 v[154:155], off
	s_add_i32 m0, s29, 0x2000
	s_add_u32 s96, s84, 0x80000
	v_lshl_add_u64 v[186:187], s[84:85], 0, v[134:135]
	s_addc_u32 s97, s85, 0
	s_add_i32 s29, s95, s23
	global_load_lds_dwordx4 v[186:187], off
	v_lshl_add_u64 v[226:227], s[96:97], 0, v[130:131]
	s_mov_b32 m0, s29
	v_lshl_add_u64 v[228:229], s[88:89], 0, v[132:133]
	global_load_lds_dwordx4 v[226:227], off
	v_lshl_add_u64 v[226:227], s[96:97], 0, v[134:135]
	s_add_i32 m0, s29, 0x2000
	s_nop 0
	global_load_lds_dwordx4 v[226:227], off
	v_lshl_add_u64 v[226:227], s[88:89], 0, v[128:129]
	s_mov_b32 m0, s30
	s_nop 0
	global_load_lds_dwordx4 v[226:227], off
	s_mov_b32 m0, s31
	s_nop 0
	global_load_lds_dwordx4 v[228:229], off
	s_waitcnt vmcnt(8)
	s_waitcnt lgkmcnt(0)
	s_setprio 1
	s_barrier
	s_waitcnt lgkmcnt(0)
	v_mfma_f32_16x16x32_bf16 v[60:63], v[150:153], v[194:197], v[60:63]
	v_mfma_f32_16x16x32_bf16 v[52:55], v[166:169], v[194:197], v[52:55]
	v_mfma_f32_16x16x32_bf16 v[44:47], v[150:153], v[202:205], v[44:47]
	v_mfma_f32_16x16x32_bf16 v[36:39], v[166:169], v[202:205], v[36:39]
	v_mfma_f32_16x16x32_bf16 v[28:31], v[150:153], v[210:213], v[28:31]
	v_mfma_f32_16x16x32_bf16 v[20:23], v[166:169], v[210:213], v[20:23]
	v_mfma_f32_16x16x32_bf16 v[12:15], v[150:153], v[218:221], v[12:15]
	v_mfma_f32_16x16x32_bf16 v[4:7], v[166:169], v[218:221], v[4:7]
	v_mfma_f32_16x16x32_bf16 v[60:63], v[162:165], v[198:201], v[60:63]
	v_mfma_f32_16x16x32_bf16 v[52:55], v[170:173], v[198:201], v[52:55]
	v_mfma_f32_16x16x32_bf16 v[44:47], v[162:165], v[206:209], v[44:47]
	v_mfma_f32_16x16x32_bf16 v[36:39], v[170:173], v[206:209], v[36:39]
	v_mfma_f32_16x16x32_bf16 v[28:31], v[162:165], v[214:217], v[28:31]
	v_mfma_f32_16x16x32_bf16 v[20:23], v[170:173], v[214:217], v[20:23]
	v_mfma_f32_16x16x32_bf16 v[12:15], v[162:165], v[222:225], v[12:15]
	v_mfma_f32_16x16x32_bf16 v[4:7], v[170:173], v[222:225], v[4:7]
	s_setprio 0
	s_setprio 1
	v_mfma_f32_16x16x32_bf16 v[56:59], v[174:177], v[194:197], v[56:59]
	v_mfma_f32_16x16x32_bf16 v[48:51], v[182:185], v[194:197], v[48:51]
	v_mfma_f32_16x16x32_bf16 v[40:43], v[174:177], v[202:205], v[40:43]
	v_mfma_f32_16x16x32_bf16 v[32:35], v[182:185], v[202:205], v[32:35]
	v_mfma_f32_16x16x32_bf16 v[24:27], v[174:177], v[210:213], v[24:27]
	v_mfma_f32_16x16x32_bf16 v[16:19], v[182:185], v[210:213], v[16:19]
	v_mfma_f32_16x16x32_bf16 v[8:11], v[174:177], v[218:221], v[8:11]
	v_mfma_f32_16x16x32_bf16 v[0:3], v[182:185], v[218:221], v[0:3]
	v_mfma_f32_16x16x32_bf16 v[56:59], v[178:181], v[198:201], v[56:59]
	v_mfma_f32_16x16x32_bf16 v[48:51], v[190:193], v[198:201], v[48:51]
	v_mfma_f32_16x16x32_bf16 v[40:43], v[178:181], v[206:209], v[40:43]
	v_mfma_f32_16x16x32_bf16 v[32:35], v[190:193], v[206:209], v[32:35]
	v_mfma_f32_16x16x32_bf16 v[24:27], v[178:181], v[214:217], v[24:27]
	v_mfma_f32_16x16x32_bf16 v[16:19], v[190:193], v[214:217], v[16:19]
	v_mfma_f32_16x16x32_bf16 v[8:11], v[178:181], v[222:225], v[8:11]
	v_mfma_f32_16x16x32_bf16 v[0:3], v[190:193], v[222:225], v[0:3]
	s_setprio 0
	s_barrier
; #define PG8_STAGE(bufoff, gbase, voff) do { _Pragma("unroll") for (int _i = 0; _i < 2; ++_i) \
;         __builtin_amdgcn_global_load_lds((const unsigned*)((const char*)(gbase) + (voff)[_i]), (PG8_LAS unsigned*)(lds + (bufoff) + ldsw + _i * 8192), 16, 0, 0); } while (0)
; #define PG8_LDA(dst, b, h) do { _Pragma("unroll") for (int m = 0; m < 4; ++m) _Pragma("unroll") for (int k = 0; k < 2; ++k) dst[m][k] = *(const PG8_LAS bf16x8*)(lds + PG8_SA(b, h) + aoff + m * 2048 + k * 1024); } while (0)
; #define PG8_LDB(dst, b, h) do { _Pragma("unroll") for (int n = 0; n < 2; ++n) _Pragma("unroll") for (int k = 0; k < 2; ++k) dst[n][k] = *(const PG8_LAS bf16x8*)(lds + PG8_SB(b, h) + boff + n * 2048 + k * 1024); } while (0)
; #define PG8_MMA(ai, bj, At, Bt) do { __builtin_amdgcn_s_setprio(1); _Pragma("unroll") for (int m = 0; m < 4; ++m) _Pragma("unroll") for (int n = 0; n < 2; ++n) _Pragma("unroll") for (int k = 0; k < 2; ++k) \
;         acc[ai][bj][m][n] = __builtin_amdgcn_mfma_f32_16x16x32_bf16(Bt[n][k], At[m][k], acc[ai][bj][m][n], 0, 0, 0); __builtin_amdgcn_s_setprio(0); } while (0)
; #define PG8_WAIT_V(n) asm volatile("s_waitcnt vmcnt(" #n ")" ::: "memory")
; #define PG8_WAIT_L(n) asm volatile("s_waitcnt lgkmcnt(" #n ")" ::: "memory")
; #define PG8_BAR __builtin_amdgcn_s_barrier()
; #define PG8_SCHED __builtin_amdgcn_sched_barrier(0)
; template <class Epi, class Sched, bool ALIGN_EPI = false, bool SP2 = false>
; __device__ __forceinline__ void gemm_phase(PG8_LAS unsigned char* lds, const Gemm g, const Sched& S, const Epi& E) {
;     ...
;             PG8_LDB(B0, 1, 0); PG8_LDB(B1, 1, 1); PG8_SCHED; PG8_LDA(At, 1, 0); PG8_STAGE(PG8_SA(0, 1), a2 + hstep, voffA);
;             PG8_WAIT_V(8); PG8_WAIT_L(0); PG8_BAR; PG8_MMA(0, 0, At, B0); PG8_MMA(0, 1, At, B1); PG8_BAR; PG8_SCHED;
	s_add_i32 s29, 0, 0x18000
	v_add_u32_e32 v136, s29, v156
	s_add_i32 s57, 0, 0x1c000
	ds_read_b128 v[150:153], v136
	ds_read_b128 v[162:165], v136 offset:1024
	ds_read_b128 v[166:169], v136 offset:2048
	ds_read_b128 v[170:173], v136 offset:3072
	v_add_u32_e32 v136, s57, v156
	ds_read_b128 v[174:177], v136
	ds_read_b128 v[178:181], v136 offset:1024
	ds_read_b128 v[182:185], v136 offset:2048
	ds_read_b128 v[190:193], v136 offset:3072
	s_add_u32 s88, s88, 0x80000
	s_addc_u32 s89, s89, 0
	s_mov_b32 m0, s33
	v_lshl_add_u64 v[230:231], s[88:89], 0, v[128:129]
	ds_read_b128 v[194:197], v160 offset:32768
	ds_read_b128 v[198:201], v160 offset:33792
	ds_read_b128 v[202:205], v160 offset:34816
	ds_read_b128 v[206:209], v160 offset:35840
	ds_read_b128 v[210:213], v160 offset:36864
	ds_read_b128 v[214:217], v160 offset:37888
	ds_read_b128 v[218:221], v160 offset:38912
	ds_read_b128 v[222:225], v160 offset:39936
	global_load_lds_dwordx4 v[230:231], off
	v_lshl_add_u64 v[230:231], s[88:89], 0, v[132:133]
	s_mov_b32 m0, s71
	s_nop 0
	global_load_lds_dwordx4 v[230:231], off
	s_waitcnt vmcnt(8)
	s_waitcnt lgkmcnt(0)
	s_setprio 1
	s_barrier
	s_waitcnt lgkmcnt(0)
	v_mfma_f32_16x16x32_bf16 v[124:127], v[150:153], v[194:197], v[124:127]
	v_mfma_f32_16x16x32_bf16 v[116:119], v[166:169], v[194:197], v[116:119]
	v_mfma_f32_16x16x32_bf16 v[108:111], v[150:153], v[202:205], v[108:111]
	v_mfma_f32_16x16x32_bf16 v[100:103], v[166:169], v[202:205], v[100:103]
	v_mfma_f32_16x16x32_bf16 v[92:95], v[150:153], v[210:213], v[92:95]
	v_mfma_f32_16x16x32_bf16 v[84:87], v[166:169], v[210:213], v[84:87]
	v_mfma_f32_16x16x32_bf16 v[76:79], v[150:153], v[218:221], v[76:79]
	v_mfma_f32_16x16x32_bf16 v[68:71], v[166:169], v[218:221], v[68:71]
	v_mfma_f32_16x16x32_bf16 v[124:127], v[162:165], v[198:201], v[124:127]
	v_mfma_f32_16x16x32_bf16 v[116:119], v[170:173], v[198:201], v[116:119]
	v_mfma_f32_16x16x32_bf16 v[108:111], v[162:165], v[206:209], v[108:111]
	v_mfma_f32_16x16x32_bf16 v[100:103], v[170:173], v[206:209], v[100:103]
	v_mfma_f32_16x16x32_bf16 v[92:95], v[162:165], v[214:217], v[92:95]
	v_mfma_f32_16x16x32_bf16 v[84:87], v[170:173], v[214:217], v[84:87]
	v_mfma_f32_16x16x32_bf16 v[76:79], v[162:165], v[222:225], v[76:79]
	v_mfma_f32_16x16x32_bf16 v[68:71], v[170:173], v[222:225], v[68:71]
	s_setprio 0
	s_setprio 1
	v_mfma_f32_16x16x32_bf16 v[120:123], v[174:177], v[194:197], v[120:123]
	v_mfma_f32_16x16x32_bf16 v[112:115], v[182:185], v[194:197], v[112:115]
	v_mfma_f32_16x16x32_bf16 v[104:107], v[174:177], v[202:205], v[104:107]
	v_mfma_f32_16x16x32_bf16 v[96:99], v[182:185], v[202:205], v[96:99]
	v_mfma_f32_16x16x32_bf16 v[88:91], v[174:177], v[210:213], v[88:91]
	v_mfma_f32_16x16x32_bf16 v[80:83], v[182:185], v[210:213], v[80:83]
	v_mfma_f32_16x16x32_bf16 v[72:75], v[174:177], v[218:221], v[72:75]
	v_mfma_f32_16x16x32_bf16 v[64:67], v[182:185], v[218:221], v[64:67]
	v_mfma_f32_16x16x32_bf16 v[120:123], v[178:181], v[198:201], v[120:123]
	v_mfma_f32_16x16x32_bf16 v[112:115], v[190:193], v[198:201], v[112:115]
	v_mfma_f32_16x16x32_bf16 v[104:107], v[178:181], v[206:209], v[104:107]
	v_mfma_f32_16x16x32_bf16 v[96:99], v[190:193], v[206:209], v[96:99]
	v_mfma_f32_16x16x32_bf16 v[88:91], v[178:181], v[214:217], v[88:91]
	v_mfma_f32_16x16x32_bf16 v[80:83], v[190:193], v[214:217], v[80:83]
	v_mfma_f32_16x16x32_bf16 v[72:75], v[178:181], v[222:225], v[72:75]
	v_mfma_f32_16x16x32_bf16 v[64:67], v[190:193], v[222:225], v[64:67]
	s_setprio 0
	s_barrier
; #define PG8_STAGE(bufoff, gbase, voff) do { _Pragma("unroll") for (int _i = 0; _i < 2; ++_i) \
;         __builtin_amdgcn_global_load_lds((const unsigned*)((const char*)(gbase) + (voff)[_i]), (PG8_LAS unsigned*)(lds + (bufoff) + ldsw + _i * 8192), 16, 0, 0); } while (0)
; #define PG8_LDA(dst, b, h) do { _Pragma("unroll") for (int m = 0; m < 4; ++m) _Pragma("unroll") for (int k = 0; k < 2; ++k) dst[m][k] = *(const PG8_LAS bf16x8*)(lds + PG8_SA(b, h) + aoff + m * 2048 + k * 1024); } while (0)
; #define PG8_MMA(ai, bj, At, Bt) do { __builtin_amdgcn_s_setprio(1); _Pragma("unroll") for (int m = 0; m < 4; ++m) _Pragma("unroll") for (int n = 0; n < 2; ++n) _Pragma("unroll") for (int k = 0; k < 2; ++k) \
;         acc[ai][bj][m][n] = __builtin_amdgcn_mfma_f32_16x16x32_bf16(Bt[n][k], At[m][k], acc[ai][bj][m][n], 0, 0, 0); __builtin_amdgcn_s_setprio(0); } while (0)
; #define PG8_WAIT_V(n) asm volatile("s_waitcnt vmcnt(" #n ")" ::: "memory")
; #define PG8_WAIT_L(n) asm volatile("s_waitcnt lgkmcnt(" #n ")" ::: "memory")
; #define PG8_BAR __builtin_amdgcn_s_barrier()
; #define PG8_SCHED __builtin_amdgcn_sched_barrier(0)
; template <class Epi, class Sched, bool ALIGN_EPI = false, bool SP2 = false>
; __device__ __forceinline__ void gemm_phase(PG8_LAS unsigned char* lds, const Gemm g, const Sched& S, const Epi& E) {
;     ...
;         for (int t = seg * tseg; t < (seg + 1) * tseg; t += 2) {
;             const bool last = (t == nt - 2);
;             const char* a1 = cA + (size_t)(t + 1) * kstep;
;             const char* a2 = last ? nA : cA + (size_t)(t + 2) * kstep; const char* b2 = last ? nB : cB + (size_t)(t + 2) * kstep;
;     ...
;             PG8_LDA(At, 1, 1); PG8_STAGE(PG8_SB(1, 0), b3, voffB); PG8_STAGE(PG8_SB(1, 1), b3 + hstep, voffB); PG8_STAGE(PG8_SA(1, 0), a3, voffA);
;             PG8_WAIT_V(8); PG8_WAIT_L(0); PG8_BAR; PG8_MMA(1, 0, At, B0); PG8_MMA(1, 1, At, B1); PG8_BAR; PG8_SCHED;
	s_add_i32 s29, s29, s23
	v_lshl_add_u64 v[154:155], v[154:155], 0, s[8:9]
	s_mov_b32 m0, s29
	ds_read_b128 v[194:197], v160 offset:49152
	ds_read_b128 v[198:201], v160 offset:50176
	ds_read_b128 v[202:205], v160 offset:51200
	ds_read_b128 v[206:209], v160 offset:52224
	ds_read_b128 v[210:213], v160 offset:53248
	ds_read_b128 v[214:217], v160 offset:54272
	ds_read_b128 v[218:221], v160 offset:55296
	ds_read_b128 v[222:225], v160 offset:56320
	global_load_lds_dwordx4 v[154:155], off
	s_add_i32 m0, s29, 0x2000
	s_add_u32 s84, s84, 0x80080
	v_lshl_add_u64 v[154:155], v[186:187], 0, s[8:9]
	s_addc_u32 s85, s85, 0
	s_add_i32 s29, s57, s23
	global_load_lds_dwordx4 v[154:155], off
	v_lshl_add_u64 v[154:155], s[84:85], 0, v[130:131]
	s_mov_b32 m0, s29
	s_nop 0
	global_load_lds_dwordx4 v[154:155], off
	v_lshl_add_u64 v[154:155], s[84:85], 0, v[134:135]
	s_add_i32 m0, s29, 0x2000
	s_nop 0
	global_load_lds_dwordx4 v[154:155], off
	v_lshl_add_u64 v[154:155], v[226:227], 0, s[8:9]
	s_mov_b32 m0, s92
	s_nop 0
	global_load_lds_dwordx4 v[154:155], off
	v_lshl_add_u64 v[154:155], v[228:229], 0, s[8:9]
	s_mov_b32 m0, s93
	s_nop 0
	global_load_lds_dwordx4 v[154:155], off
	s_waitcnt vmcnt(8)
	s_waitcnt lgkmcnt(0)
	s_setprio 1
	s_barrier
	s_waitcnt lgkmcnt(0)
	v_mfma_f32_16x16x32_bf16 v[60:63], v[150:153], v[194:197], v[60:63]
	v_mfma_f32_16x16x32_bf16 v[52:55], v[166:169], v[194:197], v[52:55]
	v_mfma_f32_16x16x32_bf16 v[44:47], v[150:153], v[202:205], v[44:47]
	v_mfma_f32_16x16x32_bf16 v[36:39], v[166:169], v[202:205], v[36:39]
	v_mfma_f32_16x16x32_bf16 v[28:31], v[150:153], v[210:213], v[28:31]
	v_mfma_f32_16x16x32_bf16 v[20:23], v[166:169], v[210:213], v[20:23]
	v_mfma_f32_16x16x32_bf16 v[12:15], v[150:153], v[218:221], v[12:15]
	v_mfma_f32_16x16x32_bf16 v[4:7], v[166:169], v[218:221], v[4:7]
	v_mfma_f32_16x16x32_bf16 v[60:63], v[162:165], v[198:201], v[60:63]
	v_mfma_f32_16x16x32_bf16 v[52:55], v[170:173], v[198:201], v[52:55]
	v_mfma_f32_16x16x32_bf16 v[44:47], v[162:165], v[206:209], v[44:47]
	v_mfma_f32_16x16x32_bf16 v[36:39], v[170:173], v[206:209], v[36:39]
	v_mfma_f32_16x16x32_bf16 v[28:31], v[162:165], v[214:217], v[28:31]
	v_mfma_f32_16x16x32_bf16 v[20:23], v[170:173], v[214:217], v[20:23]
	v_mfma_f32_16x16x32_bf16 v[12:15], v[162:165], v[222:225], v[12:15]
	v_mfma_f32_16x16x32_bf16 v[4:7], v[170:173], v[222:225], v[4:7]
	s_setprio 0
	s_setprio 1
	v_mfma_f32_16x16x32_bf16 v[56:59], v[174:177], v[194:197], v[56:59]
	v_mfma_f32_16x16x32_bf16 v[48:51], v[182:185], v[194:197], v[48:51]
	v_mfma_f32_16x16x32_bf16 v[40:43], v[174:177], v[202:205], v[40:43]
	v_mfma_f32_16x16x32_bf16 v[32:35], v[182:185], v[202:205], v[32:35]
	v_mfma_f32_16x16x32_bf16 v[24:27], v[174:177], v[210:213], v[24:27]
	v_mfma_f32_16x16x32_bf16 v[16:19], v[182:185], v[210:213], v[16:19]
	v_mfma_f32_16x16x32_bf16 v[8:11], v[174:177], v[218:221], v[8:11]
	v_mfma_f32_16x16x32_bf16 v[0:3], v[182:185], v[218:221], v[0:3]
	v_mfma_f32_16x16x32_bf16 v[56:59], v[178:181], v[198:201], v[56:59]
	v_mfma_f32_16x16x32_bf16 v[48:51], v[190:193], v[198:201], v[48:51]
	v_mfma_f32_16x16x32_bf16 v[40:43], v[178:181], v[206:209], v[40:43]
	v_mfma_f32_16x16x32_bf16 v[32:35], v[190:193], v[206:209], v[32:35]
	v_mfma_f32_16x16x32_bf16 v[24:27], v[178:181], v[214:217], v[24:27]
	v_mfma_f32_16x16x32_bf16 v[16:19], v[190:193], v[214:217], v[16:19]
	v_mfma_f32_16x16x32_bf16 v[8:11], v[178:181], v[222:225], v[8:11]
	v_mfma_f32_16x16x32_bf16 v[0:3], v[190:193], v[222:225], v[0:3]
	s_setprio 0
	s_barrier
	s_add_i32 s28, s28, 2
	s_add_u32 s74, s74, 0x100
	s_addc_u32 s75, s75, 0
	s_add_u32 s13, s13, 0x100
	s_addc_u32 s15, s15, 0
	s_cmp_gt_u32 s28, 29
	s_cbranch_scc0 .LBB0_276
	s_and_b64 vcc, exec, s[10:11]
	s_cbranch_vccz .LBB0_279
	s_barrier

; #define PG8_STAGE(bufoff, gbase, voff) do { _Pragma("unroll") for (int _i = 0; _i < 2; ++_i) \
;         __builtin_amdgcn_global_load_lds((const unsigned*)((const char*)(gbase) + (voff)[_i]), (PG8_LAS unsigned*)(lds + (bufoff) + ldsw + _i * 8192), 16, 0, 0); } while (0)
; #define PG8_LDA(dst, b, h) do { _Pragma("unroll") for (int m = 0; m < 4; ++m) _Pragma("unroll") for (int k = 0; k < 2; ++k) dst[m][k] = *(const PG8_LAS bf16x8*)(lds + PG8_SA(b, h) + aoff + m * 2048 + k * 1024); } while (0)
; #define PG8_LDB(dst, b, h) do { _Pragma("unroll") for (int n = 0; n < 2; ++n) _Pragma("unroll") for (int k = 0; k < 2; ++k) dst[n][k] = *(const PG8_LAS bf16x8*)(lds + PG8_SB(b, h) + boff + n * 2048 + k * 1024); } while (0)
; #define PG8_MMA(ai, bj, At, Bt) do { __builtin_amdgcn_s_setprio(1); _Pragma("unroll") for (int m = 0; m < 4; ++m) _Pragma("unroll") for (int n = 0; n < 2; ++n) _Pragma("unroll") for (int k = 0; k < 2; ++k) \
;         acc[ai][bj][m][n] = __builtin_amdgcn_mfma_f32_16x16x32_bf16(Bt[n][k], At[m][k], acc[ai][bj][m][n], 0, 0, 0); __builtin_amdgcn_s_setprio(0); } while (0)
; #define PG8_WAIT_V(n) asm volatile("s_waitcnt vmcnt(" #n ")" ::: "memory")
; #define PG8_WAIT_L(n) asm volatile("s_waitcnt lgkmcnt(" #n ")" ::: "memory")
; template <class Epi, class Sched, bool ALIGN_EPI = false, bool SP2 = false>
; __device__ __forceinline__ void gemm_phase(PG8_LAS unsigned char* lds, const Gemm g, const Sched& S, const Epi& E) {
;     ...
;             const bool last = (t == nt - 2);
;             const char* a1 = cA + (size_t)(t + 1) * kstep;
;             const char* a2 = last ? nA : cA + (size_t)(t + 2) * kstep; const char* b2 = last ? nB : cB + (size_t)(t + 2) * kstep;
;             const char* a3 = a2 + kstep; const char* b3 = b2 + kstep;
;             if (last && has_next) S.a_ready(nxt);
;             if constexpr (SP2) {
;             PG8_LDB(B0, 0, 0); PG8_LDB(B1, 0, 1); PG8_SCHED; PG8_LDA(At, 0, 0); PG8_STAGE(PG8_SA(1, 1), a1 + hstep, voffA);
;             PG8_WAIT_V(8); PG8_WAIT_L(0); PG8_BAR; PG8_MMA(0, 0, At, B0); PG8_MMA(0, 1, At, B1); PG8_BAR; PG8_SCHED;
;             PG8_LDA(At, 0, 1); PG8_STAGE(PG8_SB(0, 0), b2, voffB); PG8_STAGE(PG8_SB(0, 1), b2 + hstep, voffB); PG8_STAGE(PG8_SA(0, 0), a2, voffA);
;             PG8_WAIT_V(8); PG8_WAIT_L(0); PG8_BAR; PG8_MMA(1, 0, At, B0); PG8_MMA(1, 1, At, B1); PG8_BAR; PG8_SCHED;
.LBB0_519:
	s_add_u32 s0, s40, 0x100
	s_addc_u32 s1, s41, 0
	s_mov_b32 s97, -2
	ds_read_b128 v[140:143], v150
	ds_read_b128 v[144:147], v150 offset:1024
	ds_read_b128 v[156:159], v150 offset:2048
	ds_read_b128 v[160:163], v150 offset:3072
	ds_read_b128 v[164:167], v151
	ds_read_b128 v[168:171], v151 offset:1024
	ds_read_b128 v[172:175], v151 offset:2048
	ds_read_b128 v[176:179], v151 offset:3072
	s_add_u32 s40, s14, 0x100
	s_addc_u32 s41, s15, 0
	s_cmp_eq_u32 s97, 8
	s_cselect_b32 s65, s13, s41
	s_cselect_b32 s64, s12, s40
	s_cselect_b32 s47, s3, s1
	s_cselect_b32 s46, s2, s0
	s_mov_b32 m0, s77
	v_lshl_add_u64 v[210:211], s[14:15], 0, v[136:137]
	ds_read_b128 v[180:183], v152
	ds_read_b128 v[184:187], v152 offset:1024
	ds_read_b128 v[190:193], v152 offset:2048
	ds_read_b128 v[194:197], v152 offset:3072
	ds_read_b128 v[198:201], v152 offset:4096
	ds_read_b128 v[202:205], v152 offset:5120
	ds_read_b128 v[206:209], v152 offset:6144
	ds_read_b128 v[214:217], v152 offset:7168
	global_load_lds_dwordx4 v[210:211], off
	v_lshl_add_u64 v[210:211], s[14:15], 0, v[138:139]
	s_mov_b32 m0, s78
	s_nop 0
	global_load_lds_dwordx4 v[210:211], off
	s_waitcnt vmcnt(8)
	s_waitcnt lgkmcnt(0)
	s_setprio 1
	s_barrier
	s_waitcnt lgkmcnt(0)
	v_mfma_f32_16x16x32_bf16 v[124:127], v[140:143], v[180:183], 0
	v_mfma_f32_16x16x32_bf16 v[120:123], v[156:159], v[180:183], 0
	v_mfma_f32_16x16x32_bf16 v[108:111], v[140:143], v[190:193], 0
	v_mfma_f32_16x16x32_bf16 v[104:107], v[156:159], v[190:193], 0
	v_mfma_f32_16x16x32_bf16 v[92:95], v[140:143], v[198:201], 0
	v_mfma_f32_16x16x32_bf16 v[88:91], v[156:159], v[198:201], 0
	v_mfma_f32_16x16x32_bf16 v[76:79], v[140:143], v[206:209], 0
	v_mfma_f32_16x16x32_bf16 v[72:75], v[156:159], v[206:209], 0
	v_mfma_f32_16x16x32_bf16 v[124:127], v[144:147], v[184:187], v[124:127]
	v_mfma_f32_16x16x32_bf16 v[120:123], v[160:163], v[184:187], v[120:123]
	v_mfma_f32_16x16x32_bf16 v[108:111], v[144:147], v[194:197], v[108:111]
	v_mfma_f32_16x16x32_bf16 v[104:107], v[160:163], v[194:197], v[104:107]
	v_mfma_f32_16x16x32_bf16 v[92:95], v[144:147], v[202:205], v[92:95]
	v_mfma_f32_16x16x32_bf16 v[88:91], v[160:163], v[202:205], v[88:91]
	v_mfma_f32_16x16x32_bf16 v[76:79], v[144:147], v[214:217], v[76:79]
	v_mfma_f32_16x16x32_bf16 v[72:75], v[160:163], v[214:217], v[72:75]
	s_setprio 0
	s_setprio 1
	v_mfma_f32_16x16x32_bf16 v[116:119], v[164:167], v[180:183], 0
	v_mfma_f32_16x16x32_bf16 v[112:115], v[172:175], v[180:183], 0
	v_mfma_f32_16x16x32_bf16 v[100:103], v[164:167], v[190:193], 0
	v_mfma_f32_16x16x32_bf16 v[96:99], v[172:175], v[190:193], 0
	v_mfma_f32_16x16x32_bf16 v[84:87], v[164:167], v[198:201], 0
	v_mfma_f32_16x16x32_bf16 v[80:83], v[172:175], v[198:201], 0
	v_mfma_f32_16x16x32_bf16 v[68:71], v[164:167], v[206:209], 0
	v_mfma_f32_16x16x32_bf16 v[64:67], v[172:175], v[206:209], 0
	v_mfma_f32_16x16x32_bf16 v[116:119], v[168:171], v[184:187], v[116:119]
	v_mfma_f32_16x16x32_bf16 v[112:115], v[176:179], v[184:187], v[112:115]
	v_mfma_f32_16x16x32_bf16 v[100:103], v[168:171], v[194:197], v[100:103]
	v_mfma_f32_16x16x32_bf16 v[96:99], v[176:179], v[194:197], v[96:99]
	v_mfma_f32_16x16x32_bf16 v[84:87], v[168:171], v[202:205], v[84:87]
	v_mfma_f32_16x16x32_bf16 v[80:83], v[176:179], v[202:205], v[80:83]
	v_mfma_f32_16x16x32_bf16 v[68:71], v[168:171], v[214:217], v[68:71]
	v_mfma_f32_16x16x32_bf16 v[64:67], v[176:179], v[214:217], v[64:67]
	s_setprio 0
	s_barrier
	s_mov_b32 m0, s79
	v_lshl_add_u64 v[210:211], s[46:47], 0, v[132:133]
	s_add_u32 s14, s46, 0x30000
	ds_read_b128 v[180:183], v152 offset:16384
	ds_read_b128 v[184:187], v152 offset:17408
	ds_read_b128 v[190:193], v152 offset:18432
	ds_read_b128 v[194:197], v152 offset:19456
	ds_read_b128 v[198:201], v152 offset:20480
	ds_read_b128 v[202:205], v152 offset:21504
	ds_read_b128 v[206:209], v152 offset:22528
	ds_read_b128 v[214:217], v152 offset:23552
	global_load_lds_dwordx4 v[210:211], off
	v_lshl_add_u64 v[218:219], s[46:47], 0, v[128:129]
	s_mov_b32 m0, s80
	s_addc_u32 s15, s47, 0
	global_load_lds_dwordx4 v[218:219], off
	v_lshl_add_u64 v[220:221], s[14:15], 0, v[132:133]
	s_mov_b32 m0, s81
	v_lshl_add_u64 v[222:223], s[64:65], 0, v[130:131]
	global_load_lds_dwordx4 v[220:221], off
	v_lshl_add_u64 v[220:221], s[14:15], 0, v[128:129]
	s_mov_b32 m0, s82
	s_nop 0
	global_load_lds_dwordx4 v[220:221], off
	v_lshl_add_u64 v[220:221], s[64:65], 0, v[134:135]
	s_mov_b32 m0, s56
	s_nop 0
	global_load_lds_dwordx4 v[220:221], off
	s_mov_b32 m0, s57
	s_nop 0
	global_load_lds_dwordx4 v[222:223], off
	s_waitcnt vmcnt(8)
	s_waitcnt lgkmcnt(0)
	s_setprio 1
	s_barrier
; #define PG8_STAGE(bufoff, gbase, voff) do { _Pragma("unroll") for (int _i = 0; _i < 2; ++_i) \
;         __builtin_amdgcn_global_load_lds((const unsigned*)((const char*)(gbase) + (voff)[_i]), (PG8_LAS unsigned*)(lds + (bufoff) + ldsw + _i * 8192), 16, 0, 0); } while (0)
; #define PG8_LDA(dst, b, h) do { _Pragma("unroll") for (int m = 0; m < 4; ++m) _Pragma("unroll") for (int k = 0; k < 2; ++k) dst[m][k] = *(const PG8_LAS bf16x8*)(lds + PG8_SA(b, h) + aoff + m * 2048 + k * 1024); } while (0)
; #define PG8_LDB(dst, b, h) do { _Pragma("unroll") for (int n = 0; n < 2; ++n) _Pragma("unroll") for (int k = 0; k < 2; ++k) dst[n][k] = *(const PG8_LAS bf16x8*)(lds + PG8_SB(b, h) + boff + n * 2048 + k * 1024); } while (0)
; #define PG8_MMA(ai, bj, At, Bt) do { __builtin_amdgcn_s_setprio(1); _Pragma("unroll") for (int m = 0; m < 4; ++m) _Pragma("unroll") for (int n = 0; n < 2; ++n) _Pragma("unroll") for (int k = 0; k < 2; ++k) \
;         acc[ai][bj][m][n] = __builtin_amdgcn_mfma_f32_16x16x32_bf16(Bt[n][k], At[m][k], acc[ai][bj][m][n], 0, 0, 0); __builtin_amdgcn_s_setprio(0); } while (0)
; #define PG8_WAIT_V(n) asm volatile("s_waitcnt vmcnt(" #n ")" ::: "memory")
; #define PG8_WAIT_L(n) asm volatile("s_waitcnt lgkmcnt(" #n ")" ::: "memory")
; #define PG8_BAR __builtin_amdgcn_s_barrier()
; #define PG8_SCHED __builtin_amdgcn_sched_barrier(0)
; template <class Epi, class Sched, bool ALIGN_EPI = false, bool SP2 = false>
; __device__ __forceinline__ void gemm_phase(PG8_LAS unsigned char* lds, const Gemm g, const Sched& S, const Epi& E) {
;     ...
;             PG8_WAIT_V(8); PG8_WAIT_L(0); PG8_BAR; PG8_MMA(1, 0, At, B0); PG8_MMA(1, 1, At, B1); PG8_BAR; PG8_SCHED;
;             PG8_LDB(B0, 1, 0); PG8_LDB(B1, 1, 1); PG8_SCHED; PG8_LDA(At, 1, 0); PG8_STAGE(PG8_SA(0, 1), a2 + hstep, voffA);
;             PG8_WAIT_V(8); PG8_WAIT_L(0); PG8_BAR; PG8_MMA(0, 0, At, B0); PG8_MMA(0, 1, At, B1); PG8_BAR; PG8_SCHED;
;             PG8_LDA(At, 1, 1); PG8_STAGE(PG8_SB(1, 0), b3, voffB); PG8_STAGE(PG8_SB(1, 1), b3 + hstep, voffB); PG8_STAGE(PG8_SA(1, 0), a3, voffA);
;             PG8_WAIT_V(8); PG8_WAIT_L(0); PG8_BAR; PG8_MMA(1, 0, At, B0); PG8_MMA(1, 1, At, B1); PG8_BAR; PG8_SCHED;
	s_waitcnt lgkmcnt(0)
	v_mfma_f32_16x16x32_bf16 v[60:63], v[140:143], v[180:183], 0
	v_mfma_f32_16x16x32_bf16 v[56:59], v[156:159], v[180:183], 0
	v_mfma_f32_16x16x32_bf16 v[44:47], v[140:143], v[190:193], 0
	v_mfma_f32_16x16x32_bf16 v[40:43], v[156:159], v[190:193], 0
	v_mfma_f32_16x16x32_bf16 v[28:31], v[140:143], v[198:201], 0
	v_mfma_f32_16x16x32_bf16 v[24:27], v[156:159], v[198:201], 0
	v_mfma_f32_16x16x32_bf16 v[12:15], v[140:143], v[206:209], 0
	v_mfma_f32_16x16x32_bf16 v[8:11], v[156:159], v[206:209], 0
	v_mfma_f32_16x16x32_bf16 v[60:63], v[144:147], v[184:187], v[60:63]
	v_mfma_f32_16x16x32_bf16 v[56:59], v[160:163], v[184:187], v[56:59]
	v_mfma_f32_16x16x32_bf16 v[44:47], v[144:147], v[194:197], v[44:47]
	v_mfma_f32_16x16x32_bf16 v[40:43], v[160:163], v[194:197], v[40:43]
	v_mfma_f32_16x16x32_bf16 v[28:31], v[144:147], v[202:205], v[28:31]
	v_mfma_f32_16x16x32_bf16 v[24:27], v[160:163], v[202:205], v[24:27]
	v_mfma_f32_16x16x32_bf16 v[12:15], v[144:147], v[214:217], v[12:15]
	v_mfma_f32_16x16x32_bf16 v[8:11], v[160:163], v[214:217], v[8:11]
	s_setprio 0
	s_setprio 1
	v_mfma_f32_16x16x32_bf16 v[52:55], v[164:167], v[180:183], 0
	v_mfma_f32_16x16x32_bf16 v[48:51], v[172:175], v[180:183], 0
	v_mfma_f32_16x16x32_bf16 v[36:39], v[164:167], v[190:193], 0
	v_mfma_f32_16x16x32_bf16 v[32:35], v[172:175], v[190:193], 0
	v_mfma_f32_16x16x32_bf16 v[20:23], v[164:167], v[198:201], 0
	v_mfma_f32_16x16x32_bf16 v[16:19], v[172:175], v[198:201], 0
	v_mfma_f32_16x16x32_bf16 v[4:7], v[164:167], v[206:209], 0
	v_mfma_f32_16x16x32_bf16 v[0:3], v[172:175], v[206:209], 0
	v_mfma_f32_16x16x32_bf16 v[52:55], v[168:171], v[184:187], v[52:55]
	v_mfma_f32_16x16x32_bf16 v[48:51], v[176:179], v[184:187], v[48:51]
	v_mfma_f32_16x16x32_bf16 v[36:39], v[168:171], v[194:197], v[36:39]
	v_mfma_f32_16x16x32_bf16 v[32:35], v[176:179], v[194:197], v[32:35]
	v_mfma_f32_16x16x32_bf16 v[20:23], v[168:171], v[202:205], v[20:23]
	v_mfma_f32_16x16x32_bf16 v[16:19], v[176:179], v[202:205], v[16:19]
	v_mfma_f32_16x16x32_bf16 v[4:7], v[168:171], v[214:217], v[4:7]
	v_mfma_f32_16x16x32_bf16 v[0:3], v[176:179], v[214:217], v[0:3]
	s_setprio 0
	s_barrier
	ds_read_b128 v[140:143], v153
	ds_read_b128 v[144:147], v153 offset:1024
	ds_read_b128 v[156:159], v153 offset:2048
	ds_read_b128 v[160:163], v153 offset:3072
	ds_read_b128 v[164:167], v154
	ds_read_b128 v[168:171], v154 offset:1024
	ds_read_b128 v[172:175], v154 offset:2048
	ds_read_b128 v[176:179], v154 offset:3072
	s_add_u32 s14, s64, 0x30000
	s_addc_u32 s15, s65, 0
	s_mov_b32 m0, s66
	v_lshl_add_u64 v[224:225], s[14:15], 0, v[134:135]
	ds_read_b128 v[180:183], v152 offset:32768
	ds_read_b128 v[184:187], v152 offset:33792
	ds_read_b128 v[190:193], v152 offset:34816
	ds_read_b128 v[194:197], v152 offset:35840
	ds_read_b128 v[198:201], v152 offset:36864
	ds_read_b128 v[202:205], v152 offset:37888
	ds_read_b128 v[206:209], v152 offset:38912
	ds_read_b128 v[214:217], v152 offset:39936
	global_load_lds_dwordx4 v[224:225], off
	v_lshl_add_u64 v[224:225], s[14:15], 0, v[130:131]
	s_mov_b32 m0, s67
	s_nop 0
	global_load_lds_dwordx4 v[224:225], off
	s_waitcnt vmcnt(8)
	s_waitcnt lgkmcnt(0)
	s_setprio 1
	s_barrier
	s_waitcnt lgkmcnt(0)
	v_mfma_f32_16x16x32_bf16 v[124:127], v[140:143], v[180:183], v[124:127]
	v_mfma_f32_16x16x32_bf16 v[120:123], v[156:159], v[180:183], v[120:123]
	v_mfma_f32_16x16x32_bf16 v[108:111], v[140:143], v[190:193], v[108:111]
	v_mfma_f32_16x16x32_bf16 v[104:107], v[156:159], v[190:193], v[104:107]
	v_mfma_f32_16x16x32_bf16 v[92:95], v[140:143], v[198:201], v[92:95]
	v_mfma_f32_16x16x32_bf16 v[88:91], v[156:159], v[198:201], v[88:91]
	v_mfma_f32_16x16x32_bf16 v[76:79], v[140:143], v[206:209], v[76:79]
	v_mfma_f32_16x16x32_bf16 v[72:75], v[156:159], v[206:209], v[72:75]
	v_mfma_f32_16x16x32_bf16 v[124:127], v[144:147], v[184:187], v[124:127]
	v_mfma_f32_16x16x32_bf16 v[120:123], v[160:163], v[184:187], v[120:123]
	v_mfma_f32_16x16x32_bf16 v[108:111], v[144:147], v[194:197], v[108:111]
	v_mfma_f32_16x16x32_bf16 v[104:107], v[160:163], v[194:197], v[104:107]
	v_mfma_f32_16x16x32_bf16 v[92:95], v[144:147], v[202:205], v[92:95]
	v_mfma_f32_16x16x32_bf16 v[88:91], v[160:163], v[202:205], v[88:91]
	v_mfma_f32_16x16x32_bf16 v[76:79], v[144:147], v[214:217], v[76:79]
	v_mfma_f32_16x16x32_bf16 v[72:75], v[160:163], v[214:217], v[72:75]
	s_setprio 0
	s_setprio 1
	v_mfma_f32_16x16x32_bf16 v[116:119], v[164:167], v[180:183], v[116:119]
	v_mfma_f32_16x16x32_bf16 v[112:115], v[172:175], v[180:183], v[112:115]
	v_mfma_f32_16x16x32_bf16 v[100:103], v[164:167], v[190:193], v[100:103]
	v_mfma_f32_16x16x32_bf16 v[96:99], v[172:175], v[190:193], v[96:99]
	v_mfma_f32_16x16x32_bf16 v[84:87], v[164:167], v[198:201], v[84:87]
	v_mfma_f32_16x16x32_bf16 v[80:83], v[172:175], v[198:201], v[80:83]
	v_mfma_f32_16x16x32_bf16 v[68:71], v[164:167], v[206:209], v[68:71]
	v_mfma_f32_16x16x32_bf16 v[64:67], v[172:175], v[206:209], v[64:67]
	v_mfma_f32_16x16x32_bf16 v[116:119], v[168:171], v[184:187], v[116:119]
	v_mfma_f32_16x16x32_bf16 v[112:115], v[176:179], v[184:187], v[112:115]
	v_mfma_f32_16x16x32_bf16 v[100:103], v[168:171], v[194:197], v[100:103]
	v_mfma_f32_16x16x32_bf16 v[96:99], v[176:179], v[194:197], v[96:99]
	v_mfma_f32_16x16x32_bf16 v[84:87], v[168:171], v[202:205], v[84:87]
	v_mfma_f32_16x16x32_bf16 v[80:83], v[176:179], v[202:205], v[80:83]
	v_mfma_f32_16x16x32_bf16 v[68:71], v[168:171], v[214:217], v[68:71]
	v_mfma_f32_16x16x32_bf16 v[64:67], v[176:179], v[214:217], v[64:67]
	s_setprio 0
	s_barrier
; #define PG8_STAGE(bufoff, gbase, voff) do { _Pragma("unroll") for (int _i = 0; _i < 2; ++_i) \
;         __builtin_amdgcn_global_load_lds((const unsigned*)((const char*)(gbase) + (voff)[_i]), (PG8_LAS unsigned*)(lds + (bufoff) + ldsw + _i * 8192), 16, 0, 0); } while (0)
; #define PG8_LDA(dst, b, h) do { _Pragma("unroll") for (int m = 0; m < 4; ++m) _Pragma("unroll") for (int k = 0; k < 2; ++k) dst[m][k] = *(const PG8_LAS bf16x8*)(lds + PG8_SA(b, h) + aoff + m * 2048 + k * 1024); } while (0)
; #define PG8_LDB(dst, b, h) do { _Pragma("unroll") for (int n = 0; n < 2; ++n) _Pragma("unroll") for (int k = 0; k < 2; ++k) dst[n][k] = *(const PG8_LAS bf16x8*)(lds + PG8_SB(b, h) + boff + n * 2048 + k * 1024); } while (0)
; #define PG8_MMA(ai, bj, At, Bt) do { __builtin_amdgcn_s_setprio(1); _Pragma("unroll") for (int m = 0; m < 4; ++m) _Pragma("unroll") for (int n = 0; n < 2; ++n) _Pragma("unroll") for (int k = 0; k < 2; ++k) \
;         acc[ai][bj][m][n] = __builtin_amdgcn_mfma_f32_16x16x32_bf16(Bt[n][k], At[m][k], acc[ai][bj][m][n], 0, 0, 0); __builtin_amdgcn_s_setprio(0); } while (0)
; #define PG8_WAIT_V(n) asm volatile("s_waitcnt vmcnt(" #n ")" ::: "memory")
; #define PG8_WAIT_L(n) asm volatile("s_waitcnt lgkmcnt(" #n ")" ::: "memory")
; template <class Epi, class Sched, bool ALIGN_EPI = false, bool SP2 = false>
; __device__ __forceinline__ void gemm_phase(PG8_LAS unsigned char* lds, const Gemm g, const Sched& S, const Epi& E) {
;     ...
;             const bool last = (t == nt - 2);
;             const char* a1 = cA + (size_t)(t + 1) * kstep;
;             const char* a2 = last ? nA : cA + (size_t)(t + 2) * kstep; const char* b2 = last ? nB : cB + (size_t)(t + 2) * kstep;
;             const char* a3 = a2 + kstep; const char* b3 = b2 + kstep;
;             if (last && has_next) S.a_ready(nxt);
;             if constexpr (SP2) {
;             PG8_LDB(B0, 0, 0); PG8_LDB(B1, 0, 1); PG8_SCHED; PG8_LDA(At, 0, 0); PG8_STAGE(PG8_SA(1, 1), a1 + hstep, voffA);
;             PG8_WAIT_V(8); PG8_WAIT_L(0); PG8_BAR; PG8_MMA(0, 0, At, B0); PG8_MMA(0, 1, At, B1); PG8_BAR; PG8_SCHED;
;     ...
;             PG8_LDA(At, 1, 1); PG8_STAGE(PG8_SB(1, 0), b3, voffB); PG8_STAGE(PG8_SB(1, 1), b3 + hstep, voffB); PG8_STAGE(PG8_SA(1, 0), a3, voffA);
;             PG8_WAIT_V(8); PG8_WAIT_L(0); PG8_BAR; PG8_MMA(1, 0, At, B0); PG8_MMA(1, 1, At, B1); PG8_BAR; PG8_SCHED;
	s_add_i32 s14, s75, s33
	v_lshl_add_u64 v[210:211], v[210:211], 0, s[8:9]
	s_mov_b32 m0, s14
	ds_read_b128 v[180:183], v152 offset:49152
	ds_read_b128 v[184:187], v152 offset:50176
	ds_read_b128 v[190:193], v152 offset:51200
	ds_read_b128 v[194:197], v152 offset:52224
	ds_read_b128 v[198:201], v152 offset:53248
	ds_read_b128 v[202:205], v152 offset:54272
	ds_read_b128 v[206:209], v152 offset:55296
	ds_read_b128 v[214:217], v152 offset:56320
	global_load_lds_dwordx4 v[210:211], off
	s_add_i32 m0, s14, 0x2000
	s_add_u32 s14, s46, 0x30080
	v_lshl_add_u64 v[210:211], v[218:219], 0, s[8:9]
	s_addc_u32 s15, s47, 0
	s_add_i32 s46, s84, s33
	global_load_lds_dwordx4 v[210:211], off
	v_lshl_add_u64 v[210:211], s[14:15], 0, v[132:133]
	s_mov_b32 m0, s46
	s_nop 0
	global_load_lds_dwordx4 v[210:211], off
	v_lshl_add_u64 v[210:211], s[14:15], 0, v[128:129]
	s_add_i32 m0, s46, 0x2000
	s_nop 0
	global_load_lds_dwordx4 v[210:211], off
	v_lshl_add_u64 v[210:211], v[220:221], 0, s[8:9]
	s_mov_b32 m0, s68
	s_nop 0
	global_load_lds_dwordx4 v[210:211], off
	v_lshl_add_u64 v[210:211], v[222:223], 0, s[8:9]
	s_mov_b32 m0, s69
	s_nop 0
	global_load_lds_dwordx4 v[210:211], off
	s_waitcnt vmcnt(8)
	s_waitcnt lgkmcnt(0)
	s_setprio 1
	s_barrier
	s_waitcnt lgkmcnt(0)
	v_mfma_f32_16x16x32_bf16 v[60:63], v[140:143], v[180:183], v[60:63]
	v_mfma_f32_16x16x32_bf16 v[56:59], v[156:159], v[180:183], v[56:59]
	v_mfma_f32_16x16x32_bf16 v[44:47], v[140:143], v[190:193], v[44:47]
	v_mfma_f32_16x16x32_bf16 v[40:43], v[156:159], v[190:193], v[40:43]
	v_mfma_f32_16x16x32_bf16 v[28:31], v[140:143], v[198:201], v[28:31]
	v_mfma_f32_16x16x32_bf16 v[24:27], v[156:159], v[198:201], v[24:27]
	v_mfma_f32_16x16x32_bf16 v[12:15], v[140:143], v[206:209], v[12:15]
	v_mfma_f32_16x16x32_bf16 v[8:11], v[156:159], v[206:209], v[8:11]
	v_mfma_f32_16x16x32_bf16 v[60:63], v[144:147], v[184:187], v[60:63]
	v_mfma_f32_16x16x32_bf16 v[56:59], v[160:163], v[184:187], v[56:59]
	v_mfma_f32_16x16x32_bf16 v[44:47], v[144:147], v[194:197], v[44:47]
	v_mfma_f32_16x16x32_bf16 v[40:43], v[160:163], v[194:197], v[40:43]
	v_mfma_f32_16x16x32_bf16 v[28:31], v[144:147], v[202:205], v[28:31]
	v_mfma_f32_16x16x32_bf16 v[24:27], v[160:163], v[202:205], v[24:27]
	v_mfma_f32_16x16x32_bf16 v[12:15], v[144:147], v[214:217], v[12:15]
	v_mfma_f32_16x16x32_bf16 v[8:11], v[160:163], v[214:217], v[8:11]
	s_setprio 0
	s_setprio 1
	v_mfma_f32_16x16x32_bf16 v[52:55], v[164:167], v[180:183], v[52:55]
	v_mfma_f32_16x16x32_bf16 v[48:51], v[172:175], v[180:183], v[48:51]
	v_mfma_f32_16x16x32_bf16 v[36:39], v[164:167], v[190:193], v[36:39]
	v_mfma_f32_16x16x32_bf16 v[32:35], v[172:175], v[190:193], v[32:35]
	v_mfma_f32_16x16x32_bf16 v[20:23], v[164:167], v[198:201], v[20:23]
	v_mfma_f32_16x16x32_bf16 v[16:19], v[172:175], v[198:201], v[16:19]
	v_mfma_f32_16x16x32_bf16 v[4:7], v[164:167], v[206:209], v[4:7]
	v_mfma_f32_16x16x32_bf16 v[0:3], v[172:175], v[206:209], v[0:3]
	v_mfma_f32_16x16x32_bf16 v[52:55], v[168:171], v[184:187], v[52:55]
	v_mfma_f32_16x16x32_bf16 v[48:51], v[176:179], v[184:187], v[48:51]
	v_mfma_f32_16x16x32_bf16 v[36:39], v[168:171], v[194:197], v[36:39]
	v_mfma_f32_16x16x32_bf16 v[32:35], v[176:179], v[194:197], v[32:35]
	v_mfma_f32_16x16x32_bf16 v[20:23], v[168:171], v[202:205], v[20:23]
	v_mfma_f32_16x16x32_bf16 v[16:19], v[176:179], v[202:205], v[16:19]
	v_mfma_f32_16x16x32_bf16 v[4:7], v[168:171], v[214:217], v[4:7]
	v_mfma_f32_16x16x32_bf16 v[0:3], v[176:179], v[214:217], v[0:3]
	s_setprio 0
	s_barrier
	s_add_i32 s97, s97, 2
	s_add_u32 s0, s0, 0x100
	s_addc_u32 s1, s1, 0
	s_cmp_gt_u32 s97, 9
	s_mov_b64 s[14:15], s[40:41]
.LBB0_520:
	ds_read_b128 v[140:143], v150
	ds_read_b128 v[144:147], v150 offset:1024
	ds_read_b128 v[156:159], v150 offset:2048
	ds_read_b128 v[160:163], v150 offset:3072
	ds_read_b128 v[164:167], v151
	ds_read_b128 v[168:171], v151 offset:1024
	ds_read_b128 v[172:175], v151 offset:2048
	ds_read_b128 v[176:179], v151 offset:3072
	s_add_u32 s40, s14, 0x100
	s_addc_u32 s41, s15, 0
	s_cmp_eq_u32 s97, 8
	s_cselect_b32 s65, s13, s41
	s_cselect_b32 s64, s12, s40
	s_cselect_b32 s47, s3, s1
	s_cselect_b32 s46, s2, s0
	s_mov_b32 m0, s77
	v_lshl_add_u64 v[210:211], s[14:15], 0, v[136:137]
	ds_read_b128 v[180:183], v152
	ds_read_b128 v[184:187], v152 offset:1024
	ds_read_b128 v[190:193], v152 offset:2048
	ds_read_b128 v[194:197], v152 offset:3072
	ds_read_b128 v[198:201], v152 offset:4096
	ds_read_b128 v[202:205], v152 offset:5120
	ds_read_b128 v[206:209], v152 offset:6144
	ds_read_b128 v[214:217], v152 offset:7168
	global_load_lds_dwordx4 v[210:211], off
	v_lshl_add_u64 v[210:211], s[14:15], 0, v[138:139]
	s_mov_b32 m0, s78
	s_nop 0
	global_load_lds_dwordx4 v[210:211], off
	s_waitcnt vmcnt(8)
	s_waitcnt lgkmcnt(0)
	s_setprio 1
	s_barrier
; #define PG8_STAGE(bufoff, gbase, voff) do { _Pragma("unroll") for (int _i = 0; _i < 2; ++_i) \
;         __builtin_amdgcn_global_load_lds((const unsigned*)((const char*)(gbase) + (voff)[_i]), (PG8_LAS unsigned*)(lds + (bufoff) + ldsw + _i * 8192), 16, 0, 0); } while (0)
; #define PG8_LDA(dst, b, h) do { _Pragma("unroll") for (int m = 0; m < 4; ++m) _Pragma("unroll") for (int k = 0; k < 2; ++k) dst[m][k] = *(const PG8_LAS bf16x8*)(lds + PG8_SA(b, h) + aoff + m * 2048 + k * 1024); } while (0)
; #define PG8_LDB(dst, b, h) do { _Pragma("unroll") for (int n = 0; n < 2; ++n) _Pragma("unroll") for (int k = 0; k < 2; ++k) dst[n][k] = *(const PG8_LAS bf16x8*)(lds + PG8_SB(b, h) + boff + n * 2048 + k * 1024); } while (0)
; #define PG8_MMA(ai, bj, At, Bt) do { __builtin_amdgcn_s_setprio(1); _Pragma("unroll") for (int m = 0; m < 4; ++m) _Pragma("unroll") for (int n = 0; n < 2; ++n) _Pragma("unroll") for (int k = 0; k < 2; ++k) \
;         acc[ai][bj][m][n] = __builtin_amdgcn_mfma_f32_16x16x32_bf16(Bt[n][k], At[m][k], acc[ai][bj][m][n], 0, 0, 0); __builtin_amdgcn_s_setprio(0); } while (0)
; #define PG8_WAIT_V(n) asm volatile("s_waitcnt vmcnt(" #n ")" ::: "memory")
; #define PG8_WAIT_L(n) asm volatile("s_waitcnt lgkmcnt(" #n ")" ::: "memory")
; #define PG8_BAR __builtin_amdgcn_s_barrier()
; #define PG8_SCHED __builtin_amdgcn_sched_barrier(0)
; template <class Epi, class Sched, bool ALIGN_EPI = false, bool SP2 = false>
; __device__ __forceinline__ void gemm_phase(PG8_LAS unsigned char* lds, const Gemm g, const Sched& S, const Epi& E) {
;     ...
;             PG8_LDB(B0, 0, 0); PG8_LDB(B1, 0, 1); PG8_SCHED; PG8_LDA(At, 0, 0); PG8_STAGE(PG8_SA(1, 1), a1 + hstep, voffA);
;             PG8_WAIT_V(8); PG8_WAIT_L(0); PG8_BAR; PG8_MMA(0, 0, At, B0); PG8_MMA(0, 1, At, B1); PG8_BAR; PG8_SCHED;
;             PG8_LDA(At, 0, 1); PG8_STAGE(PG8_SB(0, 0), b2, voffB); PG8_STAGE(PG8_SB(0, 1), b2 + hstep, voffB); PG8_STAGE(PG8_SA(0, 0), a2, voffA);
;             PG8_WAIT_V(8); PG8_WAIT_L(0); PG8_BAR; PG8_MMA(1, 0, At, B0); PG8_MMA(1, 1, At, B1); PG8_BAR; PG8_SCHED;
;             PG8_LDB(B0, 1, 0); PG8_LDB(B1, 1, 1); PG8_SCHED; PG8_LDA(At, 1, 0); PG8_STAGE(PG8_SA(0, 1), a2 + hstep, voffA);
;             PG8_WAIT_V(8); PG8_WAIT_L(0); PG8_BAR; PG8_MMA(0, 0, At, B0); PG8_MMA(0, 1, At, B1); PG8_BAR; PG8_SCHED;
	s_waitcnt lgkmcnt(0)
	v_mfma_f32_16x16x32_bf16 v[124:127], v[140:143], v[180:183], v[124:127]
	v_mfma_f32_16x16x32_bf16 v[120:123], v[156:159], v[180:183], v[120:123]
	v_mfma_f32_16x16x32_bf16 v[108:111], v[140:143], v[190:193], v[108:111]
	v_mfma_f32_16x16x32_bf16 v[104:107], v[156:159], v[190:193], v[104:107]
	v_mfma_f32_16x16x32_bf16 v[92:95], v[140:143], v[198:201], v[92:95]
	v_mfma_f32_16x16x32_bf16 v[88:91], v[156:159], v[198:201], v[88:91]
	v_mfma_f32_16x16x32_bf16 v[76:79], v[140:143], v[206:209], v[76:79]
	v_mfma_f32_16x16x32_bf16 v[72:75], v[156:159], v[206:209], v[72:75]
	v_mfma_f32_16x16x32_bf16 v[124:127], v[144:147], v[184:187], v[124:127]
	v_mfma_f32_16x16x32_bf16 v[120:123], v[160:163], v[184:187], v[120:123]
	v_mfma_f32_16x16x32_bf16 v[108:111], v[144:147], v[194:197], v[108:111]
	v_mfma_f32_16x16x32_bf16 v[104:107], v[160:163], v[194:197], v[104:107]
	v_mfma_f32_16x16x32_bf16 v[92:95], v[144:147], v[202:205], v[92:95]
	v_mfma_f32_16x16x32_bf16 v[88:91], v[160:163], v[202:205], v[88:91]
	v_mfma_f32_16x16x32_bf16 v[76:79], v[144:147], v[214:217], v[76:79]
	v_mfma_f32_16x16x32_bf16 v[72:75], v[160:163], v[214:217], v[72:75]
	s_setprio 0
	s_setprio 1
	v_mfma_f32_16x16x32_bf16 v[116:119], v[164:167], v[180:183], v[116:119]
	v_mfma_f32_16x16x32_bf16 v[112:115], v[172:175], v[180:183], v[112:115]
	v_mfma_f32_16x16x32_bf16 v[100:103], v[164:167], v[190:193], v[100:103]
	v_mfma_f32_16x16x32_bf16 v[96:99], v[172:175], v[190:193], v[96:99]
	v_mfma_f32_16x16x32_bf16 v[84:87], v[164:167], v[198:201], v[84:87]
	v_mfma_f32_16x16x32_bf16 v[80:83], v[172:175], v[198:201], v[80:83]
	v_mfma_f32_16x16x32_bf16 v[68:71], v[164:167], v[206:209], v[68:71]
	v_mfma_f32_16x16x32_bf16 v[64:67], v[172:175], v[206:209], v[64:67]
	v_mfma_f32_16x16x32_bf16 v[116:119], v[168:171], v[184:187], v[116:119]
	v_mfma_f32_16x16x32_bf16 v[112:115], v[176:179], v[184:187], v[112:115]
	v_mfma_f32_16x16x32_bf16 v[100:103], v[168:171], v[194:197], v[100:103]
	v_mfma_f32_16x16x32_bf16 v[96:99], v[176:179], v[194:197], v[96:99]
	v_mfma_f32_16x16x32_bf16 v[84:87], v[168:171], v[202:205], v[84:87]
	v_mfma_f32_16x16x32_bf16 v[80:83], v[176:179], v[202:205], v[80:83]
	v_mfma_f32_16x16x32_bf16 v[68:71], v[168:171], v[214:217], v[68:71]
	v_mfma_f32_16x16x32_bf16 v[64:67], v[176:179], v[214:217], v[64:67]
	s_setprio 0
	s_barrier
	s_mov_b32 m0, s79
	v_lshl_add_u64 v[210:211], s[46:47], 0, v[132:133]
	s_add_u32 s14, s46, 0x30000
	ds_read_b128 v[180:183], v152 offset:16384
	ds_read_b128 v[184:187], v152 offset:17408
	ds_read_b128 v[190:193], v152 offset:18432
	ds_read_b128 v[194:197], v152 offset:19456
	ds_read_b128 v[198:201], v152 offset:20480
	ds_read_b128 v[202:205], v152 offset:21504
	ds_read_b128 v[206:209], v152 offset:22528
	ds_read_b128 v[214:217], v152 offset:23552
	global_load_lds_dwordx4 v[210:211], off
	v_lshl_add_u64 v[218:219], s[46:47], 0, v[128:129]
	s_mov_b32 m0, s80
	s_addc_u32 s15, s47, 0
	global_load_lds_dwordx4 v[218:219], off
	v_lshl_add_u64 v[220:221], s[14:15], 0, v[132:133]
	s_mov_b32 m0, s81
	v_lshl_add_u64 v[222:223], s[64:65], 0, v[130:131]
	global_load_lds_dwordx4 v[220:221], off
	v_lshl_add_u64 v[220:221], s[14:15], 0, v[128:129]
	s_mov_b32 m0, s82
	s_nop 0
	global_load_lds_dwordx4 v[220:221], off
	v_lshl_add_u64 v[220:221], s[64:65], 0, v[134:135]
	s_mov_b32 m0, s56
	s_nop 0
	global_load_lds_dwordx4 v[220:221], off
	s_mov_b32 m0, s57
	s_nop 0
	global_load_lds_dwordx4 v[222:223], off
	s_waitcnt vmcnt(8)
	s_waitcnt lgkmcnt(0)
	s_setprio 1
	s_barrier
	s_waitcnt lgkmcnt(0)
	v_mfma_f32_16x16x32_bf16 v[60:63], v[140:143], v[180:183], v[60:63]
	v_mfma_f32_16x16x32_bf16 v[56:59], v[156:159], v[180:183], v[56:59]
	v_mfma_f32_16x16x32_bf16 v[44:47], v[140:143], v[190:193], v[44:47]
	v_mfma_f32_16x16x32_bf16 v[40:43], v[156:159], v[190:193], v[40:43]
	v_mfma_f32_16x16x32_bf16 v[28:31], v[140:143], v[198:201], v[28:31]
	v_mfma_f32_16x16x32_bf16 v[24:27], v[156:159], v[198:201], v[24:27]
	v_mfma_f32_16x16x32_bf16 v[12:15], v[140:143], v[206:209], v[12:15]
	v_mfma_f32_16x16x32_bf16 v[8:11], v[156:159], v[206:209], v[8:11]
	v_mfma_f32_16x16x32_bf16 v[60:63], v[144:147], v[184:187], v[60:63]
	v_mfma_f32_16x16x32_bf16 v[56:59], v[160:163], v[184:187], v[56:59]
	v_mfma_f32_16x16x32_bf16 v[44:47], v[144:147], v[194:197], v[44:47]
	v_mfma_f32_16x16x32_bf16 v[40:43], v[160:163], v[194:197], v[40:43]
	v_mfma_f32_16x16x32_bf16 v[28:31], v[144:147], v[202:205], v[28:31]
	v_mfma_f32_16x16x32_bf16 v[24:27], v[160:163], v[202:205], v[24:27]
	v_mfma_f32_16x16x32_bf16 v[12:15], v[144:147], v[214:217], v[12:15]
	v_mfma_f32_16x16x32_bf16 v[8:11], v[160:163], v[214:217], v[8:11]
	s_setprio 0
	s_setprio 1
	v_mfma_f32_16x16x32_bf16 v[52:55], v[164:167], v[180:183], v[52:55]
	v_mfma_f32_16x16x32_bf16 v[48:51], v[172:175], v[180:183], v[48:51]
	v_mfma_f32_16x16x32_bf16 v[36:39], v[164:167], v[190:193], v[36:39]
	v_mfma_f32_16x16x32_bf16 v[32:35], v[172:175], v[190:193], v[32:35]
	v_mfma_f32_16x16x32_bf16 v[20:23], v[164:167], v[198:201], v[20:23]
	v_mfma_f32_16x16x32_bf16 v[16:19], v[172:175], v[198:201], v[16:19]
	v_mfma_f32_16x16x32_bf16 v[4:7], v[164:167], v[206:209], v[4:7]
	v_mfma_f32_16x16x32_bf16 v[0:3], v[172:175], v[206:209], v[0:3]
	v_mfma_f32_16x16x32_bf16 v[52:55], v[168:171], v[184:187], v[52:55]
	v_mfma_f32_16x16x32_bf16 v[48:51], v[176:179], v[184:187], v[48:51]
	v_mfma_f32_16x16x32_bf16 v[36:39], v[168:171], v[194:197], v[36:39]
	v_mfma_f32_16x16x32_bf16 v[32:35], v[176:179], v[194:197], v[32:35]
	v_mfma_f32_16x16x32_bf16 v[20:23], v[168:171], v[202:205], v[20:23]
	v_mfma_f32_16x16x32_bf16 v[16:19], v[176:179], v[202:205], v[16:19]
	v_mfma_f32_16x16x32_bf16 v[4:7], v[168:171], v[214:217], v[4:7]
	v_mfma_f32_16x16x32_bf16 v[0:3], v[176:179], v[214:217], v[0:3]
	s_setprio 0
	s_barrier
; #define PG8_STAGE(bufoff, gbase, voff) do { _Pragma("unroll") for (int _i = 0; _i < 2; ++_i) \
;         __builtin_amdgcn_global_load_lds((const unsigned*)((const char*)(gbase) + (voff)[_i]), (PG8_LAS unsigned*)(lds + (bufoff) + ldsw + _i * 8192), 16, 0, 0); } while (0)
; #define PG8_LDA(dst, b, h) do { _Pragma("unroll") for (int m = 0; m < 4; ++m) _Pragma("unroll") for (int k = 0; k < 2; ++k) dst[m][k] = *(const PG8_LAS bf16x8*)(lds + PG8_SA(b, h) + aoff + m * 2048 + k * 1024); } while (0)
; #define PG8_LDB(dst, b, h) do { _Pragma("unroll") for (int n = 0; n < 2; ++n) _Pragma("unroll") for (int k = 0; k < 2; ++k) dst[n][k] = *(const PG8_LAS bf16x8*)(lds + PG8_SB(b, h) + boff + n * 2048 + k * 1024); } while (0)
; #define PG8_MMA(ai, bj, At, Bt) do { __builtin_amdgcn_s_setprio(1); _Pragma("unroll") for (int m = 0; m < 4; ++m) _Pragma("unroll") for (int n = 0; n < 2; ++n) _Pragma("unroll") for (int k = 0; k < 2; ++k) \
;         acc[ai][bj][m][n] = __builtin_amdgcn_mfma_f32_16x16x32_bf16(Bt[n][k], At[m][k], acc[ai][bj][m][n], 0, 0, 0); __builtin_amdgcn_s_setprio(0); } while (0)
; #define PG8_WAIT_V(n) asm volatile("s_waitcnt vmcnt(" #n ")" ::: "memory")
; #define PG8_WAIT_L(n) asm volatile("s_waitcnt lgkmcnt(" #n ")" ::: "memory")
; #define PG8_BAR __builtin_amdgcn_s_barrier()
; #define PG8_SCHED __builtin_amdgcn_sched_barrier(0)
; template <class Epi, class Sched, bool ALIGN_EPI = false, bool SP2 = false>
; __device__ __forceinline__ void gemm_phase(PG8_LAS unsigned char* lds, const Gemm g, const Sched& S, const Epi& E) {
;     ...
;             PG8_LDB(B0, 1, 0); PG8_LDB(B1, 1, 1); PG8_SCHED; PG8_LDA(At, 1, 0); PG8_STAGE(PG8_SA(0, 1), a2 + hstep, voffA);
;             PG8_WAIT_V(8); PG8_WAIT_L(0); PG8_BAR; PG8_MMA(0, 0, At, B0); PG8_MMA(0, 1, At, B1); PG8_BAR; PG8_SCHED;
	ds_read_b128 v[140:143], v153
	ds_read_b128 v[144:147], v153 offset:1024
	ds_read_b128 v[156:159], v153 offset:2048
	ds_read_b128 v[160:163], v153 offset:3072
	ds_read_b128 v[164:167], v154
	ds_read_b128 v[168:171], v154 offset:1024
	ds_read_b128 v[172:175], v154 offset:2048
	ds_read_b128 v[176:179], v154 offset:3072
	s_add_u32 s14, s64, 0x30000
	s_addc_u32 s15, s65, 0
	s_mov_b32 m0, s66
	v_lshl_add_u64 v[224:225], s[14:15], 0, v[134:135]
	ds_read_b128 v[180:183], v152 offset:32768
	ds_read_b128 v[184:187], v152 offset:33792
	ds_read_b128 v[190:193], v152 offset:34816
	ds_read_b128 v[194:197], v152 offset:35840
	ds_read_b128 v[198:201], v152 offset:36864
	ds_read_b128 v[202:205], v152 offset:37888
	ds_read_b128 v[206:209], v152 offset:38912
	ds_read_b128 v[214:217], v152 offset:39936
	global_load_lds_dwordx4 v[224:225], off
	v_lshl_add_u64 v[224:225], s[14:15], 0, v[130:131]
	s_mov_b32 m0, s67
	s_nop 0
	global_load_lds_dwordx4 v[224:225], off
	s_waitcnt vmcnt(8)
	s_waitcnt lgkmcnt(0)
	s_setprio 1
	s_barrier
	s_waitcnt lgkmcnt(0)
	v_mfma_f32_16x16x32_bf16 v[124:127], v[140:143], v[180:183], v[124:127]
	v_mfma_f32_16x16x32_bf16 v[120:123], v[156:159], v[180:183], v[120:123]
	v_mfma_f32_16x16x32_bf16 v[108:111], v[140:143], v[190:193], v[108:111]
	v_mfma_f32_16x16x32_bf16 v[104:107], v[156:159], v[190:193], v[104:107]
	v_mfma_f32_16x16x32_bf16 v[92:95], v[140:143], v[198:201], v[92:95]
	v_mfma_f32_16x16x32_bf16 v[88:91], v[156:159], v[198:201], v[88:91]
	v_mfma_f32_16x16x32_bf16 v[76:79], v[140:143], v[206:209], v[76:79]
	v_mfma_f32_16x16x32_bf16 v[72:75], v[156:159], v[206:209], v[72:75]
	v_mfma_f32_16x16x32_bf16 v[124:127], v[144:147], v[184:187], v[124:127]
	v_mfma_f32_16x16x32_bf16 v[120:123], v[160:163], v[184:187], v[120:123]
	v_mfma_f32_16x16x32_bf16 v[108:111], v[144:147], v[194:197], v[108:111]
	v_mfma_f32_16x16x32_bf16 v[104:107], v[160:163], v[194:197], v[104:107]
	v_mfma_f32_16x16x32_bf16 v[92:95], v[144:147], v[202:205], v[92:95]
	v_mfma_f32_16x16x32_bf16 v[88:91], v[160:163], v[202:205], v[88:91]
	v_mfma_f32_16x16x32_bf16 v[76:79], v[144:147], v[214:217], v[76:79]
	v_mfma_f32_16x16x32_bf16 v[72:75], v[160:163], v[214:217], v[72:75]
	s_setprio 0
	s_setprio 1
	v_mfma_f32_16x16x32_bf16 v[116:119], v[164:167], v[180:183], v[116:119]
	v_mfma_f32_16x16x32_bf16 v[112:115], v[172:175], v[180:183], v[112:115]
	v_mfma_f32_16x16x32_bf16 v[100:103], v[164:167], v[190:193], v[100:103]
	v_mfma_f32_16x16x32_bf16 v[96:99], v[172:175], v[190:193], v[96:99]
	v_mfma_f32_16x16x32_bf16 v[84:87], v[164:167], v[198:201], v[84:87]
	v_mfma_f32_16x16x32_bf16 v[80:83], v[172:175], v[198:201], v[80:83]
	v_mfma_f32_16x16x32_bf16 v[68:71], v[164:167], v[206:209], v[68:71]
	v_mfma_f32_16x16x32_bf16 v[64:67], v[172:175], v[206:209], v[64:67]
	v_mfma_f32_16x16x32_bf16 v[116:119], v[168:171], v[184:187], v[116:119]
	v_mfma_f32_16x16x32_bf16 v[112:115], v[176:179], v[184:187], v[112:115]
	v_mfma_f32_16x16x32_bf16 v[100:103], v[168:171], v[194:197], v[100:103]
	v_mfma_f32_16x16x32_bf16 v[96:99], v[176:179], v[194:197], v[96:99]
	v_mfma_f32_16x16x32_bf16 v[84:87], v[168:171], v[202:205], v[84:87]
	v_mfma_f32_16x16x32_bf16 v[80:83], v[176:179], v[202:205], v[80:83]
	v_mfma_f32_16x16x32_bf16 v[68:71], v[168:171], v[214:217], v[68:71]
	v_mfma_f32_16x16x32_bf16 v[64:67], v[176:179], v[214:217], v[64:67]
	s_setprio 0
	s_barrier
; #define PG8_STAGE(bufoff, gbase, voff) do { _Pragma("unroll") for (int _i = 0; _i < 2; ++_i) \
;         __builtin_amdgcn_global_load_lds((const unsigned*)((const char*)(gbase) + (voff)[_i]), (PG8_LAS unsigned*)(lds + (bufoff) + ldsw + _i * 8192), 16, 0, 0); } while (0)
; #define PG8_LDA(dst, b, h) do { _Pragma("unroll") for (int m = 0; m < 4; ++m) _Pragma("unroll") for (int k = 0; k < 2; ++k) dst[m][k] = *(const PG8_LAS bf16x8*)(lds + PG8_SA(b, h) + aoff + m * 2048 + k * 1024); } while (0)
; #define PG8_MMA(ai, bj, At, Bt) do { __builtin_amdgcn_s_setprio(1); _Pragma("unroll") for (int m = 0; m < 4; ++m) _Pragma("unroll") for (int n = 0; n < 2; ++n) _Pragma("unroll") for (int k = 0; k < 2; ++k) \
;         acc[ai][bj][m][n] = __builtin_amdgcn_mfma_f32_16x16x32_bf16(Bt[n][k], At[m][k], acc[ai][bj][m][n], 0, 0, 0); __builtin_amdgcn_s_setprio(0); } while (0)
; #define PG8_WAIT_V(n) asm volatile("s_waitcnt vmcnt(" #n ")" ::: "memory")
; #define PG8_WAIT_L(n) asm volatile("s_waitcnt lgkmcnt(" #n ")" ::: "memory")
; #define PG8_BAR __builtin_amdgcn_s_barrier()
; #define PG8_SCHED __builtin_amdgcn_sched_barrier(0)
; template <class Epi, class Sched, bool ALIGN_EPI = false, bool SP2 = false>
; __device__ __forceinline__ void gemm_phase(PG8_LAS unsigned char* lds, const Gemm g, const Sched& S, const Epi& E) {
;     ...
;         for (int t = seg * tseg; t < (seg + 1) * tseg; t += 2) {
;     ...
;             PG8_LDA(At, 1, 1); PG8_STAGE(PG8_SB(1, 0), b3, voffB); PG8_STAGE(PG8_SB(1, 1), b3 + hstep, voffB); PG8_STAGE(PG8_SA(1, 0), a3, voffA);
;             PG8_WAIT_V(8); PG8_WAIT_L(0); PG8_BAR; PG8_MMA(1, 0, At, B0); PG8_MMA(1, 1, At, B1); PG8_BAR; PG8_SCHED;
	s_add_i32 s14, s75, s33
	v_lshl_add_u64 v[210:211], v[210:211], 0, s[8:9]
	s_mov_b32 m0, s14
	ds_read_b128 v[180:183], v152 offset:49152
	ds_read_b128 v[184:187], v152 offset:50176
	ds_read_b128 v[190:193], v152 offset:51200
	ds_read_b128 v[194:197], v152 offset:52224
	ds_read_b128 v[198:201], v152 offset:53248
	ds_read_b128 v[202:205], v152 offset:54272
	ds_read_b128 v[206:209], v152 offset:55296
	ds_read_b128 v[214:217], v152 offset:56320
	global_load_lds_dwordx4 v[210:211], off
	s_add_i32 m0, s14, 0x2000
	s_add_u32 s14, s46, 0x30080
	v_lshl_add_u64 v[210:211], v[218:219], 0, s[8:9]
	s_addc_u32 s15, s47, 0
	s_add_i32 s46, s84, s33
	global_load_lds_dwordx4 v[210:211], off
	v_lshl_add_u64 v[210:211], s[14:15], 0, v[132:133]
	s_mov_b32 m0, s46
	s_nop 0
	global_load_lds_dwordx4 v[210:211], off
	v_lshl_add_u64 v[210:211], s[14:15], 0, v[128:129]
	s_add_i32 m0, s46, 0x2000
	s_nop 0
	global_load_lds_dwordx4 v[210:211], off
	v_lshl_add_u64 v[210:211], v[220:221], 0, s[8:9]
	s_mov_b32 m0, s68
	s_nop 0
	global_load_lds_dwordx4 v[210:211], off
	v_lshl_add_u64 v[210:211], v[222:223], 0, s[8:9]
	s_mov_b32 m0, s69
	s_nop 0
	global_load_lds_dwordx4 v[210:211], off
	s_waitcnt vmcnt(8)
	s_waitcnt lgkmcnt(0)
	s_setprio 1
	s_barrier
	s_waitcnt lgkmcnt(0)
	v_mfma_f32_16x16x32_bf16 v[60:63], v[140:143], v[180:183], v[60:63]
	v_mfma_f32_16x16x32_bf16 v[56:59], v[156:159], v[180:183], v[56:59]
	v_mfma_f32_16x16x32_bf16 v[44:47], v[140:143], v[190:193], v[44:47]
	v_mfma_f32_16x16x32_bf16 v[40:43], v[156:159], v[190:193], v[40:43]
	v_mfma_f32_16x16x32_bf16 v[28:31], v[140:143], v[198:201], v[28:31]
	v_mfma_f32_16x16x32_bf16 v[24:27], v[156:159], v[198:201], v[24:27]
	v_mfma_f32_16x16x32_bf16 v[12:15], v[140:143], v[206:209], v[12:15]
	v_mfma_f32_16x16x32_bf16 v[8:11], v[156:159], v[206:209], v[8:11]
	v_mfma_f32_16x16x32_bf16 v[60:63], v[144:147], v[184:187], v[60:63]
	v_mfma_f32_16x16x32_bf16 v[56:59], v[160:163], v[184:187], v[56:59]
	v_mfma_f32_16x16x32_bf16 v[44:47], v[144:147], v[194:197], v[44:47]
	v_mfma_f32_16x16x32_bf16 v[40:43], v[160:163], v[194:197], v[40:43]
	v_mfma_f32_16x16x32_bf16 v[28:31], v[144:147], v[202:205], v[28:31]
	v_mfma_f32_16x16x32_bf16 v[24:27], v[160:163], v[202:205], v[24:27]
	v_mfma_f32_16x16x32_bf16 v[12:15], v[144:147], v[214:217], v[12:15]
	v_mfma_f32_16x16x32_bf16 v[8:11], v[160:163], v[214:217], v[8:11]
	s_setprio 0
	s_setprio 1
	v_mfma_f32_16x16x32_bf16 v[52:55], v[164:167], v[180:183], v[52:55]
	v_mfma_f32_16x16x32_bf16 v[48:51], v[172:175], v[180:183], v[48:51]
	v_mfma_f32_16x16x32_bf16 v[36:39], v[164:167], v[190:193], v[36:39]
	v_mfma_f32_16x16x32_bf16 v[32:35], v[172:175], v[190:193], v[32:35]
	v_mfma_f32_16x16x32_bf16 v[20:23], v[164:167], v[198:201], v[20:23]
	v_mfma_f32_16x16x32_bf16 v[16:19], v[172:175], v[198:201], v[16:19]
	v_mfma_f32_16x16x32_bf16 v[4:7], v[164:167], v[206:209], v[4:7]
	v_mfma_f32_16x16x32_bf16 v[0:3], v[172:175], v[206:209], v[0:3]
	v_mfma_f32_16x16x32_bf16 v[52:55], v[168:171], v[184:187], v[52:55]
	v_mfma_f32_16x16x32_bf16 v[48:51], v[176:179], v[184:187], v[48:51]
	v_mfma_f32_16x16x32_bf16 v[36:39], v[168:171], v[194:197], v[36:39]
	v_mfma_f32_16x16x32_bf16 v[32:35], v[176:179], v[194:197], v[32:35]
	v_mfma_f32_16x16x32_bf16 v[20:23], v[168:171], v[202:205], v[20:23]
	v_mfma_f32_16x16x32_bf16 v[16:19], v[176:179], v[202:205], v[16:19]
	v_mfma_f32_16x16x32_bf16 v[4:7], v[168:171], v[214:217], v[4:7]
	v_mfma_f32_16x16x32_bf16 v[0:3], v[176:179], v[214:217], v[0:3]
	s_setprio 0
	s_barrier
	s_add_i32 s97, s97, 2
	s_add_u32 s0, s0, 0x100
	s_addc_u32 s1, s1, 0
	s_cmp_gt_u32 s97, 9
	s_mov_b64 s[14:15], s[40:41]
	s_cbranch_scc0 .LBB0_520
	s_and_b64 vcc, exec, s[10:11]
	s_cbranch_vccz .LBB0_523
	s_barrier

;     __device__ bool next(int i, Unit& u) const { if (i >= n) return false; const int q = first + i; u.pm = rowbase + q % rows; u.pn = q / rows; return true; }
; #define PG8_STAGE(bufoff, gbase, voff) do { _Pragma("unroll") for (int _i = 0; _i < 2; ++_i) \
;         __builtin_amdgcn_global_load_lds((const unsigned*)((const char*)(gbase) + (voff)[_i]), (PG8_LAS unsigned*)(lds + (bufoff) + ldsw + _i * 8192), 16, 0, 0); } while (0)
; #define PG8_LDA(dst, b, h) do { _Pragma("unroll") for (int m = 0; m < 4; ++m) _Pragma("unroll") for (int k = 0; k < 2; ++k) dst[m][k] = *(const PG8_LAS bf16x8*)(lds + PG8_SA(b, h) + aoff + m * 2048 + k * 1024); } while (0)
; #define PG8_WAIT_V(n) asm volatile("s_waitcnt vmcnt(" #n ")" ::: "memory")
; template <class Epi, class Sched, bool ALIGN_EPI = false, bool SP2 = false>
; __device__ __forceinline__ void gemm_phase(PG8_LAS unsigned char* lds, const Gemm g, const Sched& S, const Epi& E) {
;     ...
;         const bool has_next = S.next(ui + 1, nxt);
;         const char* nA = has_next ? (const char*)g.A + (size_t)nxt.pm * tstep : cA; const char* nB = has_next ? (const char*)g.Bt + (size_t)nxt.pn * tstep : cB;
;         constexpr int NSEG = Epi::HAS_MID ? 2 : 1; const int tseg = nt / NSEG;
; #pragma unroll
;         for (int seg = 0; seg < NSEG; ++seg) {
;         if constexpr (Epi::HAS_MID) { if (seg == 1) E.mid(acc, cur, wr, wc, fr, fq); }
;         for (int t = seg * tseg; t < (seg + 1) * tseg; t += 2) {
;             const bool last = (t == nt - 2);
;             const char* a1 = cA + (size_t)(t + 1) * kstep;
;             const char* a2 = last ? nA : cA + (size_t)(t + 2) * kstep; const char* b2 = last ? nB : cB + (size_t)(t + 2) * kstep;
;             const char* a3 = a2 + kstep; const char* b3 = b2 + kstep;
;             if (last && has_next) S.a_ready(nxt);
;             if constexpr (SP2) {
;             PG8_LDB(B0, 0, 0); PG8_LDB(B1, 0, 1); PG8_SCHED; PG8_LDA(At, 0, 0); PG8_STAGE(PG8_SA(1, 1), a1 + hstep, voffA);
;             PG8_WAIT_V(8); PG8_WAIT_L(0); PG8_BAR; PG8_MMA(0, 0, At, B0); PG8_MMA(0, 1, At, B1); PG8_BAR; PG8_SCHED;
;             PG8_LDA(At, 0, 1); PG8_STAGE(PG8_SB(0, 0), b2, voffB); PG8_STAGE(PG8_SB(0, 1), b2 + hstep, voffB); PG8_STAGE(PG8_SA(0, 0), a2, voffA);
;             PG8_WAIT_V(8); PG8_WAIT_L(0); PG8_BAR; PG8_MMA(1, 0, At, B0); PG8_MMA(1, 1, At, B1); PG8_BAR; PG8_SCHED;
.LBB0_534:
	s_ashr_i32 s41, s40, 31
	s_lshl_b64 s[46:47], s[40:41], 18
	s_add_u32 s46, s72, s46
	s_addc_u32 s47, s73, s47
	s_and_b64 s[60:61], s[0:1], exec
	s_cselect_b32 s41, s47, s63
	s_cselect_b32 s76, s46, s62
	s_ashr_i32 s37, s36, 31
	s_lshl_b64 s[60:61], s[36:37], 18
	s_add_u32 s60, s58, s60
	s_addc_u32 s61, s59, s61
	s_and_b64 s[0:1], s[0:1], exec
	s_cselect_b32 s0, s61, s65
	s_cselect_b32 s1, s60, s64
	s_add_u32 s62, s62, 0x20080
	s_addc_u32 s63, s63, 0
	s_add_u32 s37, s64, 0x100
	s_addc_u32 s77, s65, 0
	s_mov_b32 s78, -2
	ds_read_b128 v[140:143], v149
	ds_read_b128 v[152:155], v149 offset:1024
	ds_read_b128 v[156:159], v149 offset:2048
	ds_read_b128 v[160:163], v149 offset:3072
	ds_read_b128 v[164:167], v150
	ds_read_b128 v[168:171], v150 offset:1024
	ds_read_b128 v[172:175], v150 offset:2048
	ds_read_b128 v[176:179], v150 offset:3072
	s_add_u32 s64, s62, 0xfffe0080
	s_addc_u32 s65, s63, -1
	s_cmp_eq_u32 s78, 4
	s_cselect_b32 s67, s41, s65
	s_cselect_b32 s66, s76, s64
	s_cselect_b32 s65, s0, s77
	s_cselect_b32 s64, s1, s37
	v_lshl_add_u64 v[144:145], s[62:63], 0, v[136:137]
	s_add_i32 m0, s30, 0xc000
	ds_read_b128 v[180:183], v151
	ds_read_b128 v[184:187], v151 offset:1024
	ds_read_b128 v[190:193], v151 offset:2048
	ds_read_b128 v[194:197], v151 offset:3072
	ds_read_b128 v[198:201], v151 offset:4096
	ds_read_b128 v[202:205], v151 offset:5120
	ds_read_b128 v[206:209], v151 offset:6144
	ds_read_b128 v[214:217], v151 offset:7168
	global_load_lds_dwordx4 v[144:145], off
	v_lshl_add_u64 v[144:145], s[62:63], 0, v[138:139]
	s_add_i32 m0, s30, 0xe000
	s_nop 0
	global_load_lds_dwordx4 v[144:145], off
	s_waitcnt vmcnt(8)
	s_waitcnt lgkmcnt(0)
	s_setprio 1
	s_barrier
	s_waitcnt lgkmcnt(0)
	v_mfma_f32_16x16x32_bf16 v[124:127], v[140:143], v[180:183], 0
	v_mfma_f32_16x16x32_bf16 v[120:123], v[156:159], v[180:183], 0
	v_mfma_f32_16x16x32_bf16 v[108:111], v[140:143], v[190:193], 0
	v_mfma_f32_16x16x32_bf16 v[104:107], v[156:159], v[190:193], 0
	v_mfma_f32_16x16x32_bf16 v[92:95], v[140:143], v[198:201], 0
	v_mfma_f32_16x16x32_bf16 v[88:91], v[156:159], v[198:201], 0
	v_mfma_f32_16x16x32_bf16 v[76:79], v[140:143], v[206:209], 0
	v_mfma_f32_16x16x32_bf16 v[72:75], v[156:159], v[206:209], 0
	v_mfma_f32_16x16x32_bf16 v[124:127], v[152:155], v[184:187], v[124:127]
	v_mfma_f32_16x16x32_bf16 v[120:123], v[160:163], v[184:187], v[120:123]
	v_mfma_f32_16x16x32_bf16 v[108:111], v[152:155], v[194:197], v[108:111]
	v_mfma_f32_16x16x32_bf16 v[104:107], v[160:163], v[194:197], v[104:107]
	v_mfma_f32_16x16x32_bf16 v[92:95], v[152:155], v[202:205], v[92:95]
	v_mfma_f32_16x16x32_bf16 v[88:91], v[160:163], v[202:205], v[88:91]
	v_mfma_f32_16x16x32_bf16 v[76:79], v[152:155], v[214:217], v[76:79]
	v_mfma_f32_16x16x32_bf16 v[72:75], v[160:163], v[214:217], v[72:75]
	s_setprio 0
	s_setprio 1
	v_mfma_f32_16x16x32_bf16 v[116:119], v[164:167], v[180:183], 0
	v_mfma_f32_16x16x32_bf16 v[112:115], v[172:175], v[180:183], 0
	v_mfma_f32_16x16x32_bf16 v[100:103], v[164:167], v[190:193], 0
	v_mfma_f32_16x16x32_bf16 v[96:99], v[172:175], v[190:193], 0
	v_mfma_f32_16x16x32_bf16 v[84:87], v[164:167], v[198:201], 0
	v_mfma_f32_16x16x32_bf16 v[80:83], v[172:175], v[198:201], 0
	v_mfma_f32_16x16x32_bf16 v[68:71], v[164:167], v[206:209], 0
	v_mfma_f32_16x16x32_bf16 v[64:67], v[172:175], v[206:209], 0
	v_mfma_f32_16x16x32_bf16 v[116:119], v[168:171], v[184:187], v[116:119]
	v_mfma_f32_16x16x32_bf16 v[112:115], v[176:179], v[184:187], v[112:115]
	v_mfma_f32_16x16x32_bf16 v[100:103], v[168:171], v[194:197], v[100:103]
	v_mfma_f32_16x16x32_bf16 v[96:99], v[176:179], v[194:197], v[96:99]
	v_mfma_f32_16x16x32_bf16 v[84:87], v[168:171], v[202:205], v[84:87]
	v_mfma_f32_16x16x32_bf16 v[80:83], v[176:179], v[202:205], v[80:83]
	v_mfma_f32_16x16x32_bf16 v[68:71], v[168:171], v[214:217], v[68:71]
	v_mfma_f32_16x16x32_bf16 v[64:67], v[176:179], v[214:217], v[64:67]
	s_setprio 0
	s_barrier
	s_add_i32 s79, s31, s29
	v_lshl_add_u64 v[144:145], s[64:65], 0, v[132:133]
	s_mov_b32 m0, s79
	ds_read_b128 v[180:183], v151 offset:16384
	ds_read_b128 v[184:187], v151 offset:17408
	ds_read_b128 v[190:193], v151 offset:18432
	ds_read_b128 v[194:197], v151 offset:19456
	ds_read_b128 v[198:201], v151 offset:20480
	ds_read_b128 v[202:205], v151 offset:21504
	ds_read_b128 v[206:209], v151 offset:22528
	ds_read_b128 v[214:217], v151 offset:23552
	global_load_lds_dwordx4 v[144:145], off
	s_add_i32 m0, s79, 0x2000
	s_add_u32 s80, s64, 0x20000
	v_lshl_add_u64 v[210:211], s[64:65], 0, v[128:129]
	s_addc_u32 s81, s65, 0
	s_add_i32 s79, s74, s29
	global_load_lds_dwordx4 v[210:211], off
	v_lshl_add_u64 v[218:219], s[80:81], 0, v[132:133]
	s_mov_b32 m0, s79
	v_lshl_add_u64 v[220:221], s[66:67], 0, v[130:131]
	global_load_lds_dwordx4 v[218:219], off
	v_lshl_add_u64 v[218:219], s[80:81], 0, v[128:129]
	s_add_i32 m0, s79, 0x2000
	s_nop 0
	global_load_lds_dwordx4 v[218:219], off
	v_lshl_add_u64 v[218:219], s[66:67], 0, v[134:135]
	s_mov_b32 m0, s30
	s_nop 0
	global_load_lds_dwordx4 v[218:219], off
	s_mov_b32 m0, s33
	s_nop 0
	global_load_lds_dwordx4 v[220:221], off
	s_waitcnt vmcnt(8)
	s_waitcnt lgkmcnt(0)
	s_setprio 1
	s_barrier
; #define PG8_STAGE(bufoff, gbase, voff) do { _Pragma("unroll") for (int _i = 0; _i < 2; ++_i) \
;         __builtin_amdgcn_global_load_lds((const unsigned*)((const char*)(gbase) + (voff)[_i]), (PG8_LAS unsigned*)(lds + (bufoff) + ldsw + _i * 8192), 16, 0, 0); } while (0)
; #define PG8_LDA(dst, b, h) do { _Pragma("unroll") for (int m = 0; m < 4; ++m) _Pragma("unroll") for (int k = 0; k < 2; ++k) dst[m][k] = *(const PG8_LAS bf16x8*)(lds + PG8_SA(b, h) + aoff + m * 2048 + k * 1024); } while (0)
; #define PG8_LDB(dst, b, h) do { _Pragma("unroll") for (int n = 0; n < 2; ++n) _Pragma("unroll") for (int k = 0; k < 2; ++k) dst[n][k] = *(const PG8_LAS bf16x8*)(lds + PG8_SB(b, h) + boff + n * 2048 + k * 1024); } while (0)
; #define PG8_MMA(ai, bj, At, Bt) do { __builtin_amdgcn_s_setprio(1); _Pragma("unroll") for (int m = 0; m < 4; ++m) _Pragma("unroll") for (int n = 0; n < 2; ++n) _Pragma("unroll") for (int k = 0; k < 2; ++k) \
;         acc[ai][bj][m][n] = __builtin_amdgcn_mfma_f32_16x16x32_bf16(Bt[n][k], At[m][k], acc[ai][bj][m][n], 0, 0, 0); __builtin_amdgcn_s_setprio(0); } while (0)
; #define PG8_WAIT_V(n) asm volatile("s_waitcnt vmcnt(" #n ")" ::: "memory")
; #define PG8_WAIT_L(n) asm volatile("s_waitcnt lgkmcnt(" #n ")" ::: "memory")
; #define PG8_BAR __builtin_amdgcn_s_barrier()
; #define PG8_SCHED __builtin_amdgcn_sched_barrier(0)
; template <class Epi, class Sched, bool ALIGN_EPI = false, bool SP2 = false>
; __device__ __forceinline__ void gemm_phase(PG8_LAS unsigned char* lds, const Gemm g, const Sched& S, const Epi& E) {
;     ...
;             PG8_WAIT_V(8); PG8_WAIT_L(0); PG8_BAR; PG8_MMA(1, 0, At, B0); PG8_MMA(1, 1, At, B1); PG8_BAR; PG8_SCHED;
;             PG8_LDB(B0, 1, 0); PG8_LDB(B1, 1, 1); PG8_SCHED; PG8_LDA(At, 1, 0); PG8_STAGE(PG8_SA(0, 1), a2 + hstep, voffA);
;             PG8_WAIT_V(8); PG8_WAIT_L(0); PG8_BAR; PG8_MMA(0, 0, At, B0); PG8_MMA(0, 1, At, B1); PG8_BAR; PG8_SCHED;
;             PG8_LDA(At, 1, 1); PG8_STAGE(PG8_SB(1, 0), b3, voffB); PG8_STAGE(PG8_SB(1, 1), b3 + hstep, voffB); PG8_STAGE(PG8_SA(1, 0), a3, voffA);
;             PG8_WAIT_V(8); PG8_WAIT_L(0); PG8_BAR; PG8_MMA(1, 0, At, B0); PG8_MMA(1, 1, At, B1); PG8_BAR; PG8_SCHED;
	s_waitcnt lgkmcnt(0)
	v_mfma_f32_16x16x32_bf16 v[60:63], v[140:143], v[180:183], 0
	v_mfma_f32_16x16x32_bf16 v[56:59], v[156:159], v[180:183], 0
	v_mfma_f32_16x16x32_bf16 v[44:47], v[140:143], v[190:193], 0
	v_mfma_f32_16x16x32_bf16 v[40:43], v[156:159], v[190:193], 0
	v_mfma_f32_16x16x32_bf16 v[28:31], v[140:143], v[198:201], 0
	v_mfma_f32_16x16x32_bf16 v[24:27], v[156:159], v[198:201], 0
	v_mfma_f32_16x16x32_bf16 v[12:15], v[140:143], v[206:209], 0
	v_mfma_f32_16x16x32_bf16 v[8:11], v[156:159], v[206:209], 0
	v_mfma_f32_16x16x32_bf16 v[60:63], v[152:155], v[184:187], v[60:63]
	v_mfma_f32_16x16x32_bf16 v[56:59], v[160:163], v[184:187], v[56:59]
	v_mfma_f32_16x16x32_bf16 v[44:47], v[152:155], v[194:197], v[44:47]
	v_mfma_f32_16x16x32_bf16 v[40:43], v[160:163], v[194:197], v[40:43]
	v_mfma_f32_16x16x32_bf16 v[28:31], v[152:155], v[202:205], v[28:31]
	v_mfma_f32_16x16x32_bf16 v[24:27], v[160:163], v[202:205], v[24:27]
	v_mfma_f32_16x16x32_bf16 v[12:15], v[152:155], v[214:217], v[12:15]
	v_mfma_f32_16x16x32_bf16 v[8:11], v[160:163], v[214:217], v[8:11]
	s_setprio 0
	s_setprio 1
	v_mfma_f32_16x16x32_bf16 v[52:55], v[164:167], v[180:183], 0
	v_mfma_f32_16x16x32_bf16 v[48:51], v[172:175], v[180:183], 0
	v_mfma_f32_16x16x32_bf16 v[36:39], v[164:167], v[190:193], 0
	v_mfma_f32_16x16x32_bf16 v[32:35], v[172:175], v[190:193], 0
	v_mfma_f32_16x16x32_bf16 v[20:23], v[164:167], v[198:201], 0
	v_mfma_f32_16x16x32_bf16 v[16:19], v[172:175], v[198:201], 0
	v_mfma_f32_16x16x32_bf16 v[4:7], v[164:167], v[206:209], 0
	v_mfma_f32_16x16x32_bf16 v[0:3], v[172:175], v[206:209], 0
	v_mfma_f32_16x16x32_bf16 v[52:55], v[168:171], v[184:187], v[52:55]
	v_mfma_f32_16x16x32_bf16 v[48:51], v[176:179], v[184:187], v[48:51]
	v_mfma_f32_16x16x32_bf16 v[36:39], v[168:171], v[194:197], v[36:39]
	v_mfma_f32_16x16x32_bf16 v[32:35], v[176:179], v[194:197], v[32:35]
	v_mfma_f32_16x16x32_bf16 v[20:23], v[168:171], v[202:205], v[20:23]
	v_mfma_f32_16x16x32_bf16 v[16:19], v[176:179], v[202:205], v[16:19]
	v_mfma_f32_16x16x32_bf16 v[4:7], v[168:171], v[214:217], v[4:7]
	v_mfma_f32_16x16x32_bf16 v[0:3], v[176:179], v[214:217], v[0:3]
	s_setprio 0
	s_barrier
	v_add_u32_e32 v160, s75, v147
	v_add_u32_e32 v176, s84, v147
	ds_read_b128 v[140:143], v160
	ds_read_b128 v[152:155], v160 offset:1024
	ds_read_b128 v[156:159], v160 offset:2048
	ds_read_b128 v[160:163], v160 offset:3072
	ds_read_b128 v[164:167], v176
	ds_read_b128 v[168:171], v176 offset:1024
	ds_read_b128 v[172:175], v176 offset:2048
	ds_read_b128 v[176:179], v176 offset:3072
	s_add_u32 s66, s66, 0x20000
	s_addc_u32 s67, s67, 0
	s_mov_b32 m0, s56
	v_lshl_add_u64 v[222:223], s[66:67], 0, v[134:135]
	ds_read_b128 v[180:183], v151 offset:32768
	ds_read_b128 v[184:187], v151 offset:33792
	ds_read_b128 v[190:193], v151 offset:34816
	ds_read_b128 v[194:197], v151 offset:35840
	ds_read_b128 v[198:201], v151 offset:36864
	ds_read_b128 v[202:205], v151 offset:37888
	ds_read_b128 v[206:209], v151 offset:38912
	ds_read_b128 v[214:217], v151 offset:39936
	global_load_lds_dwordx4 v[222:223], off
	v_lshl_add_u64 v[222:223], s[66:67], 0, v[130:131]
	s_mov_b32 m0, s57
	s_nop 0
	global_load_lds_dwordx4 v[222:223], off
	s_waitcnt vmcnt(8)
	s_waitcnt lgkmcnt(0)
	s_setprio 1
	s_barrier
	s_waitcnt lgkmcnt(0)
	v_mfma_f32_16x16x32_bf16 v[124:127], v[140:143], v[180:183], v[124:127]
	v_mfma_f32_16x16x32_bf16 v[120:123], v[156:159], v[180:183], v[120:123]
	v_mfma_f32_16x16x32_bf16 v[108:111], v[140:143], v[190:193], v[108:111]
	v_mfma_f32_16x16x32_bf16 v[104:107], v[156:159], v[190:193], v[104:107]
	v_mfma_f32_16x16x32_bf16 v[92:95], v[140:143], v[198:201], v[92:95]
	v_mfma_f32_16x16x32_bf16 v[88:91], v[156:159], v[198:201], v[88:91]
	v_mfma_f32_16x16x32_bf16 v[76:79], v[140:143], v[206:209], v[76:79]
	v_mfma_f32_16x16x32_bf16 v[72:75], v[156:159], v[206:209], v[72:75]
	v_mfma_f32_16x16x32_bf16 v[124:127], v[152:155], v[184:187], v[124:127]
	v_mfma_f32_16x16x32_bf16 v[120:123], v[160:163], v[184:187], v[120:123]
	v_mfma_f32_16x16x32_bf16 v[108:111], v[152:155], v[194:197], v[108:111]
	v_mfma_f32_16x16x32_bf16 v[104:107], v[160:163], v[194:197], v[104:107]
	v_mfma_f32_16x16x32_bf16 v[92:95], v[152:155], v[202:205], v[92:95]
	v_mfma_f32_16x16x32_bf16 v[88:91], v[160:163], v[202:205], v[88:91]
	v_mfma_f32_16x16x32_bf16 v[76:79], v[152:155], v[214:217], v[76:79]
	v_mfma_f32_16x16x32_bf16 v[72:75], v[160:163], v[214:217], v[72:75]
	s_setprio 0
	s_setprio 1
	v_mfma_f32_16x16x32_bf16 v[116:119], v[164:167], v[180:183], v[116:119]
	v_mfma_f32_16x16x32_bf16 v[112:115], v[172:175], v[180:183], v[112:115]
	v_mfma_f32_16x16x32_bf16 v[100:103], v[164:167], v[190:193], v[100:103]
	v_mfma_f32_16x16x32_bf16 v[96:99], v[172:175], v[190:193], v[96:99]
	v_mfma_f32_16x16x32_bf16 v[84:87], v[164:167], v[198:201], v[84:87]
	v_mfma_f32_16x16x32_bf16 v[80:83], v[172:175], v[198:201], v[80:83]
	v_mfma_f32_16x16x32_bf16 v[68:71], v[164:167], v[206:209], v[68:71]
	v_mfma_f32_16x16x32_bf16 v[64:67], v[172:175], v[206:209], v[64:67]
	v_mfma_f32_16x16x32_bf16 v[116:119], v[168:171], v[184:187], v[116:119]
	v_mfma_f32_16x16x32_bf16 v[112:115], v[176:179], v[184:187], v[112:115]
	v_mfma_f32_16x16x32_bf16 v[100:103], v[168:171], v[194:197], v[100:103]
	v_mfma_f32_16x16x32_bf16 v[96:99], v[176:179], v[194:197], v[96:99]
	v_mfma_f32_16x16x32_bf16 v[84:87], v[168:171], v[202:205], v[84:87]
	v_mfma_f32_16x16x32_bf16 v[80:83], v[176:179], v[202:205], v[80:83]
	v_mfma_f32_16x16x32_bf16 v[68:71], v[168:171], v[214:217], v[68:71]
	v_mfma_f32_16x16x32_bf16 v[64:67], v[176:179], v[214:217], v[64:67]
	s_setprio 0
	s_barrier
; #define PG8_STAGE(bufoff, gbase, voff) do { _Pragma("unroll") for (int _i = 0; _i < 2; ++_i) \
;         __builtin_amdgcn_global_load_lds((const unsigned*)((const char*)(gbase) + (voff)[_i]), (PG8_LAS unsigned*)(lds + (bufoff) + ldsw + _i * 8192), 16, 0, 0); } while (0)
; #define PG8_LDA(dst, b, h) do { _Pragma("unroll") for (int m = 0; m < 4; ++m) _Pragma("unroll") for (int k = 0; k < 2; ++k) dst[m][k] = *(const PG8_LAS bf16x8*)(lds + PG8_SA(b, h) + aoff + m * 2048 + k * 1024); } while (0)
; #define PG8_LDB(dst, b, h) do { _Pragma("unroll") for (int n = 0; n < 2; ++n) _Pragma("unroll") for (int k = 0; k < 2; ++k) dst[n][k] = *(const PG8_LAS bf16x8*)(lds + PG8_SB(b, h) + boff + n * 2048 + k * 1024); } while (0)
; #define PG8_MMA(ai, bj, At, Bt) do { __builtin_amdgcn_s_setprio(1); _Pragma("unroll") for (int m = 0; m < 4; ++m) _Pragma("unroll") for (int n = 0; n < 2; ++n) _Pragma("unroll") for (int k = 0; k < 2; ++k) \
;         acc[ai][bj][m][n] = __builtin_amdgcn_mfma_f32_16x16x32_bf16(Bt[n][k], At[m][k], acc[ai][bj][m][n], 0, 0, 0); __builtin_amdgcn_s_setprio(0); } while (0)
; #define PG8_WAIT_V(n) asm volatile("s_waitcnt vmcnt(" #n ")" ::: "memory")
; #define PG8_WAIT_L(n) asm volatile("s_waitcnt lgkmcnt(" #n ")" ::: "memory")
; template <class Epi, class Sched, bool ALIGN_EPI = false, bool SP2 = false>
; __device__ __forceinline__ void gemm_phase(PG8_LAS unsigned char* lds, const Gemm g, const Sched& S, const Epi& E) {
;     ...
;             const bool last = (t == nt - 2);
;             const char* a1 = cA + (size_t)(t + 1) * kstep;
;             const char* a2 = last ? nA : cA + (size_t)(t + 2) * kstep; const char* b2 = last ? nB : cB + (size_t)(t + 2) * kstep;
;             const char* a3 = a2 + kstep; const char* b3 = b2 + kstep;
;             if (last && has_next) S.a_ready(nxt);
;             if constexpr (SP2) {
;             PG8_LDB(B0, 0, 0); PG8_LDB(B1, 0, 1); PG8_SCHED; PG8_LDA(At, 0, 0); PG8_STAGE(PG8_SA(1, 1), a1 + hstep, voffA);
;             PG8_WAIT_V(8); PG8_WAIT_L(0); PG8_BAR; PG8_MMA(0, 0, At, B0); PG8_MMA(0, 1, At, B1); PG8_BAR; PG8_SCHED;
;     ...
;             PG8_LDA(At, 1, 1); PG8_STAGE(PG8_SB(1, 0), b3, voffB); PG8_STAGE(PG8_SB(1, 1), b3 + hstep, voffB); PG8_STAGE(PG8_SA(1, 0), a3, voffA);
;             PG8_WAIT_V(8); PG8_WAIT_L(0); PG8_BAR; PG8_MMA(1, 0, At, B0); PG8_MMA(1, 1, At, B1); PG8_BAR; PG8_SCHED;
	s_add_i32 s66, s75, s29
	v_lshl_add_u64 v[144:145], v[144:145], 0, s[12:13]
	s_mov_b32 m0, s66
	ds_read_b128 v[180:183], v151 offset:49152
	ds_read_b128 v[184:187], v151 offset:50176
	ds_read_b128 v[190:193], v151 offset:51200
	ds_read_b128 v[194:197], v151 offset:52224
	ds_read_b128 v[198:201], v151 offset:53248
	ds_read_b128 v[202:205], v151 offset:54272
	ds_read_b128 v[206:209], v151 offset:55296
	ds_read_b128 v[214:217], v151 offset:56320
	global_load_lds_dwordx4 v[144:145], off
	s_add_i32 m0, s66, 0x2000
	s_add_u32 s64, s64, 0x20080
	v_lshl_add_u64 v[144:145], v[210:211], 0, s[12:13]
	s_addc_u32 s65, s65, 0
	s_add_i32 s66, s84, s29
	global_load_lds_dwordx4 v[144:145], off
	v_lshl_add_u64 v[144:145], s[64:65], 0, v[132:133]
	s_mov_b32 m0, s66
	s_nop 0
	global_load_lds_dwordx4 v[144:145], off
	v_lshl_add_u64 v[144:145], s[64:65], 0, v[128:129]
	s_add_i32 m0, s66, 0x2000
	s_nop 0
	global_load_lds_dwordx4 v[144:145], off
	v_lshl_add_u64 v[144:145], v[218:219], 0, s[12:13]
	s_mov_b32 m0, s68
	s_nop 0
	global_load_lds_dwordx4 v[144:145], off
	v_lshl_add_u64 v[144:145], v[220:221], 0, s[12:13]
	s_mov_b32 m0, s69
	s_nop 0
	global_load_lds_dwordx4 v[144:145], off
	s_waitcnt vmcnt(8)
	s_waitcnt lgkmcnt(0)
	s_setprio 1
	s_barrier
	s_waitcnt lgkmcnt(0)
	v_mfma_f32_16x16x32_bf16 v[60:63], v[140:143], v[180:183], v[60:63]
	v_mfma_f32_16x16x32_bf16 v[56:59], v[156:159], v[180:183], v[56:59]
	v_mfma_f32_16x16x32_bf16 v[44:47], v[140:143], v[190:193], v[44:47]
	v_mfma_f32_16x16x32_bf16 v[40:43], v[156:159], v[190:193], v[40:43]
	v_mfma_f32_16x16x32_bf16 v[28:31], v[140:143], v[198:201], v[28:31]
	v_mfma_f32_16x16x32_bf16 v[24:27], v[156:159], v[198:201], v[24:27]
	v_mfma_f32_16x16x32_bf16 v[12:15], v[140:143], v[206:209], v[12:15]
	v_mfma_f32_16x16x32_bf16 v[8:11], v[156:159], v[206:209], v[8:11]
	v_mfma_f32_16x16x32_bf16 v[60:63], v[152:155], v[184:187], v[60:63]
	v_mfma_f32_16x16x32_bf16 v[56:59], v[160:163], v[184:187], v[56:59]
	v_mfma_f32_16x16x32_bf16 v[44:47], v[152:155], v[194:197], v[44:47]
	v_mfma_f32_16x16x32_bf16 v[40:43], v[160:163], v[194:197], v[40:43]
	v_mfma_f32_16x16x32_bf16 v[28:31], v[152:155], v[202:205], v[28:31]
	v_mfma_f32_16x16x32_bf16 v[24:27], v[160:163], v[202:205], v[24:27]
	v_mfma_f32_16x16x32_bf16 v[12:15], v[152:155], v[214:217], v[12:15]
	v_mfma_f32_16x16x32_bf16 v[8:11], v[160:163], v[214:217], v[8:11]
	s_setprio 0
	s_setprio 1
	v_mfma_f32_16x16x32_bf16 v[52:55], v[164:167], v[180:183], v[52:55]
	v_mfma_f32_16x16x32_bf16 v[48:51], v[172:175], v[180:183], v[48:51]
	v_mfma_f32_16x16x32_bf16 v[36:39], v[164:167], v[190:193], v[36:39]
	v_mfma_f32_16x16x32_bf16 v[32:35], v[172:175], v[190:193], v[32:35]
	v_mfma_f32_16x16x32_bf16 v[20:23], v[164:167], v[198:201], v[20:23]
	v_mfma_f32_16x16x32_bf16 v[16:19], v[172:175], v[198:201], v[16:19]
	v_mfma_f32_16x16x32_bf16 v[4:7], v[164:167], v[206:209], v[4:7]
	v_mfma_f32_16x16x32_bf16 v[0:3], v[172:175], v[206:209], v[0:3]
	v_mfma_f32_16x16x32_bf16 v[52:55], v[168:171], v[184:187], v[52:55]
	v_mfma_f32_16x16x32_bf16 v[48:51], v[176:179], v[184:187], v[48:51]
	v_mfma_f32_16x16x32_bf16 v[36:39], v[168:171], v[194:197], v[36:39]
	v_mfma_f32_16x16x32_bf16 v[32:35], v[176:179], v[194:197], v[32:35]
	v_mfma_f32_16x16x32_bf16 v[20:23], v[168:171], v[202:205], v[20:23]
	v_mfma_f32_16x16x32_bf16 v[16:19], v[176:179], v[202:205], v[16:19]
	v_mfma_f32_16x16x32_bf16 v[4:7], v[168:171], v[214:217], v[4:7]
	v_mfma_f32_16x16x32_bf16 v[0:3], v[176:179], v[214:217], v[0:3]
	s_setprio 0
	s_barrier
	s_add_i32 s78, s78, 2
	s_add_u32 s62, s62, 0x100
	s_addc_u32 s63, s63, 0
	s_add_u32 s37, s37, 0x100
	s_addc_u32 s77, s77, 0
	s_cmp_gt_u32 s78, 5
.LBB0_535:
	ds_read_b128 v[140:143], v149
	ds_read_b128 v[152:155], v149 offset:1024
	ds_read_b128 v[156:159], v149 offset:2048
	ds_read_b128 v[160:163], v149 offset:3072
	ds_read_b128 v[164:167], v150
	ds_read_b128 v[168:171], v150 offset:1024
	ds_read_b128 v[172:175], v150 offset:2048
	ds_read_b128 v[176:179], v150 offset:3072
	s_add_u32 s64, s62, 0xfffe0080
	s_addc_u32 s65, s63, -1
	s_cmp_eq_u32 s78, 4
	s_cselect_b32 s67, s41, s65
	s_cselect_b32 s66, s76, s64
	s_cselect_b32 s65, s0, s77
	s_cselect_b32 s64, s1, s37
	v_lshl_add_u64 v[144:145], s[62:63], 0, v[136:137]
	s_add_i32 m0, s30, 0xc000
	ds_read_b128 v[180:183], v151
	ds_read_b128 v[184:187], v151 offset:1024
	ds_read_b128 v[190:193], v151 offset:2048
	ds_read_b128 v[194:197], v151 offset:3072
	ds_read_b128 v[198:201], v151 offset:4096
	ds_read_b128 v[202:205], v151 offset:5120
	ds_read_b128 v[206:209], v151 offset:6144
	ds_read_b128 v[214:217], v151 offset:7168
	global_load_lds_dwordx4 v[144:145], off
	v_lshl_add_u64 v[144:145], s[62:63], 0, v[138:139]
	s_add_i32 m0, s30, 0xe000
	s_nop 0
	global_load_lds_dwordx4 v[144:145], off
	s_waitcnt vmcnt(8)
	s_waitcnt lgkmcnt(0)
	s_setprio 1
	s_barrier
; #define PG8_STAGE(bufoff, gbase, voff) do { _Pragma("unroll") for (int _i = 0; _i < 2; ++_i) \
;         __builtin_amdgcn_global_load_lds((const unsigned*)((const char*)(gbase) + (voff)[_i]), (PG8_LAS unsigned*)(lds + (bufoff) + ldsw + _i * 8192), 16, 0, 0); } while (0)
; #define PG8_LDA(dst, b, h) do { _Pragma("unroll") for (int m = 0; m < 4; ++m) _Pragma("unroll") for (int k = 0; k < 2; ++k) dst[m][k] = *(const PG8_LAS bf16x8*)(lds + PG8_SA(b, h) + aoff + m * 2048 + k * 1024); } while (0)
; #define PG8_LDB(dst, b, h) do { _Pragma("unroll") for (int n = 0; n < 2; ++n) _Pragma("unroll") for (int k = 0; k < 2; ++k) dst[n][k] = *(const PG8_LAS bf16x8*)(lds + PG8_SB(b, h) + boff + n * 2048 + k * 1024); } while (0)
; #define PG8_MMA(ai, bj, At, Bt) do { __builtin_amdgcn_s_setprio(1); _Pragma("unroll") for (int m = 0; m < 4; ++m) _Pragma("unroll") for (int n = 0; n < 2; ++n) _Pragma("unroll") for (int k = 0; k < 2; ++k) \
;         acc[ai][bj][m][n] = __builtin_amdgcn_mfma_f32_16x16x32_bf16(Bt[n][k], At[m][k], acc[ai][bj][m][n], 0, 0, 0); __builtin_amdgcn_s_setprio(0); } while (0)
; #define PG8_WAIT_V(n) asm volatile("s_waitcnt vmcnt(" #n ")" ::: "memory")
; #define PG8_WAIT_L(n) asm volatile("s_waitcnt lgkmcnt(" #n ")" ::: "memory")
; #define PG8_BAR __builtin_amdgcn_s_barrier()
; #define PG8_SCHED __builtin_amdgcn_sched_barrier(0)
; template <class Epi, class Sched, bool ALIGN_EPI = false, bool SP2 = false>
; __device__ __forceinline__ void gemm_phase(PG8_LAS unsigned char* lds, const Gemm g, const Sched& S, const Epi& E) {
;     ...
;             PG8_LDB(B0, 0, 0); PG8_LDB(B1, 0, 1); PG8_SCHED; PG8_LDA(At, 0, 0); PG8_STAGE(PG8_SA(1, 1), a1 + hstep, voffA);
;             PG8_WAIT_V(8); PG8_WAIT_L(0); PG8_BAR; PG8_MMA(0, 0, At, B0); PG8_MMA(0, 1, At, B1); PG8_BAR; PG8_SCHED;
;             PG8_LDA(At, 0, 1); PG8_STAGE(PG8_SB(0, 0), b2, voffB); PG8_STAGE(PG8_SB(0, 1), b2 + hstep, voffB); PG8_STAGE(PG8_SA(0, 0), a2, voffA);
;             PG8_WAIT_V(8); PG8_WAIT_L(0); PG8_BAR; PG8_MMA(1, 0, At, B0); PG8_MMA(1, 1, At, B1); PG8_BAR; PG8_SCHED;
;             PG8_LDB(B0, 1, 0); PG8_LDB(B1, 1, 1); PG8_SCHED; PG8_LDA(At, 1, 0); PG8_STAGE(PG8_SA(0, 1), a2 + hstep, voffA);
;             PG8_WAIT_V(8); PG8_WAIT_L(0); PG8_BAR; PG8_MMA(0, 0, At, B0); PG8_MMA(0, 1, At, B1); PG8_BAR; PG8_SCHED;
	s_waitcnt lgkmcnt(0)
	v_mfma_f32_16x16x32_bf16 v[124:127], v[140:143], v[180:183], v[124:127]
	v_mfma_f32_16x16x32_bf16 v[120:123], v[156:159], v[180:183], v[120:123]
	v_mfma_f32_16x16x32_bf16 v[108:111], v[140:143], v[190:193], v[108:111]
	v_mfma_f32_16x16x32_bf16 v[104:107], v[156:159], v[190:193], v[104:107]
	v_mfma_f32_16x16x32_bf16 v[92:95], v[140:143], v[198:201], v[92:95]
	v_mfma_f32_16x16x32_bf16 v[88:91], v[156:159], v[198:201], v[88:91]
	v_mfma_f32_16x16x32_bf16 v[76:79], v[140:143], v[206:209], v[76:79]
	v_mfma_f32_16x16x32_bf16 v[72:75], v[156:159], v[206:209], v[72:75]
	v_mfma_f32_16x16x32_bf16 v[124:127], v[152:155], v[184:187], v[124:127]
	v_mfma_f32_16x16x32_bf16 v[120:123], v[160:163], v[184:187], v[120:123]
	v_mfma_f32_16x16x32_bf16 v[108:111], v[152:155], v[194:197], v[108:111]
	v_mfma_f32_16x16x32_bf16 v[104:107], v[160:163], v[194:197], v[104:107]
	v_mfma_f32_16x16x32_bf16 v[92:95], v[152:155], v[202:205], v[92:95]
	v_mfma_f32_16x16x32_bf16 v[88:91], v[160:163], v[202:205], v[88:91]
	v_mfma_f32_16x16x32_bf16 v[76:79], v[152:155], v[214:217], v[76:79]
	v_mfma_f32_16x16x32_bf16 v[72:75], v[160:163], v[214:217], v[72:75]
	s_setprio 0
	s_setprio 1
	v_mfma_f32_16x16x32_bf16 v[116:119], v[164:167], v[180:183], v[116:119]
	v_mfma_f32_16x16x32_bf16 v[112:115], v[172:175], v[180:183], v[112:115]
	v_mfma_f32_16x16x32_bf16 v[100:103], v[164:167], v[190:193], v[100:103]
	v_mfma_f32_16x16x32_bf16 v[96:99], v[172:175], v[190:193], v[96:99]
	v_mfma_f32_16x16x32_bf16 v[84:87], v[164:167], v[198:201], v[84:87]
	v_mfma_f32_16x16x32_bf16 v[80:83], v[172:175], v[198:201], v[80:83]
	v_mfma_f32_16x16x32_bf16 v[68:71], v[164:167], v[206:209], v[68:71]
	v_mfma_f32_16x16x32_bf16 v[64:67], v[172:175], v[206:209], v[64:67]
	v_mfma_f32_16x16x32_bf16 v[116:119], v[168:171], v[184:187], v[116:119]
	v_mfma_f32_16x16x32_bf16 v[112:115], v[176:179], v[184:187], v[112:115]
	v_mfma_f32_16x16x32_bf16 v[100:103], v[168:171], v[194:197], v[100:103]
	v_mfma_f32_16x16x32_bf16 v[96:99], v[176:179], v[194:197], v[96:99]
	v_mfma_f32_16x16x32_bf16 v[84:87], v[168:171], v[202:205], v[84:87]
	v_mfma_f32_16x16x32_bf16 v[80:83], v[176:179], v[202:205], v[80:83]
	v_mfma_f32_16x16x32_bf16 v[68:71], v[168:171], v[214:217], v[68:71]
	v_mfma_f32_16x16x32_bf16 v[64:67], v[176:179], v[214:217], v[64:67]
	s_setprio 0
	s_barrier
	s_add_i32 s79, s31, s29
	v_lshl_add_u64 v[144:145], s[64:65], 0, v[132:133]
	s_mov_b32 m0, s79
	ds_read_b128 v[180:183], v151 offset:16384
	ds_read_b128 v[184:187], v151 offset:17408
	ds_read_b128 v[190:193], v151 offset:18432
	ds_read_b128 v[194:197], v151 offset:19456
	ds_read_b128 v[198:201], v151 offset:20480
	ds_read_b128 v[202:205], v151 offset:21504
	ds_read_b128 v[206:209], v151 offset:22528
	ds_read_b128 v[214:217], v151 offset:23552
	global_load_lds_dwordx4 v[144:145], off
	s_add_i32 m0, s79, 0x2000
	s_add_u32 s80, s64, 0x20000
	v_lshl_add_u64 v[210:211], s[64:65], 0, v[128:129]
	s_addc_u32 s81, s65, 0
	s_add_i32 s79, s74, s29
	global_load_lds_dwordx4 v[210:211], off
	v_lshl_add_u64 v[218:219], s[80:81], 0, v[132:133]
	s_mov_b32 m0, s79
	v_lshl_add_u64 v[220:221], s[66:67], 0, v[130:131]
	global_load_lds_dwordx4 v[218:219], off
	v_lshl_add_u64 v[218:219], s[80:81], 0, v[128:129]
	s_add_i32 m0, s79, 0x2000
	s_nop 0
	global_load_lds_dwordx4 v[218:219], off
	v_lshl_add_u64 v[218:219], s[66:67], 0, v[134:135]
	s_mov_b32 m0, s30
	s_nop 0
	global_load_lds_dwordx4 v[218:219], off
	s_mov_b32 m0, s33
	s_nop 0
	global_load_lds_dwordx4 v[220:221], off
	s_waitcnt vmcnt(8)
	s_waitcnt lgkmcnt(0)
	s_setprio 1
	s_barrier
	s_waitcnt lgkmcnt(0)
	v_mfma_f32_16x16x32_bf16 v[60:63], v[140:143], v[180:183], v[60:63]
	v_mfma_f32_16x16x32_bf16 v[56:59], v[156:159], v[180:183], v[56:59]
	v_mfma_f32_16x16x32_bf16 v[44:47], v[140:143], v[190:193], v[44:47]
	v_mfma_f32_16x16x32_bf16 v[40:43], v[156:159], v[190:193], v[40:43]
	v_mfma_f32_16x16x32_bf16 v[28:31], v[140:143], v[198:201], v[28:31]
	v_mfma_f32_16x16x32_bf16 v[24:27], v[156:159], v[198:201], v[24:27]
	v_mfma_f32_16x16x32_bf16 v[12:15], v[140:143], v[206:209], v[12:15]
	v_mfma_f32_16x16x32_bf16 v[8:11], v[156:159], v[206:209], v[8:11]
	v_mfma_f32_16x16x32_bf16 v[60:63], v[152:155], v[184:187], v[60:63]
	v_mfma_f32_16x16x32_bf16 v[56:59], v[160:163], v[184:187], v[56:59]
	v_mfma_f32_16x16x32_bf16 v[44:47], v[152:155], v[194:197], v[44:47]
	v_mfma_f32_16x16x32_bf16 v[40:43], v[160:163], v[194:197], v[40:43]
	v_mfma_f32_16x16x32_bf16 v[28:31], v[152:155], v[202:205], v[28:31]
	v_mfma_f32_16x16x32_bf16 v[24:27], v[160:163], v[202:205], v[24:27]
	v_mfma_f32_16x16x32_bf16 v[12:15], v[152:155], v[214:217], v[12:15]
	v_mfma_f32_16x16x32_bf16 v[8:11], v[160:163], v[214:217], v[8:11]
	s_setprio 0
	s_setprio 1
	v_mfma_f32_16x16x32_bf16 v[52:55], v[164:167], v[180:183], v[52:55]
	v_mfma_f32_16x16x32_bf16 v[48:51], v[172:175], v[180:183], v[48:51]
	v_mfma_f32_16x16x32_bf16 v[36:39], v[164:167], v[190:193], v[36:39]
	v_mfma_f32_16x16x32_bf16 v[32:35], v[172:175], v[190:193], v[32:35]
	v_mfma_f32_16x16x32_bf16 v[20:23], v[164:167], v[198:201], v[20:23]
	v_mfma_f32_16x16x32_bf16 v[16:19], v[172:175], v[198:201], v[16:19]
	v_mfma_f32_16x16x32_bf16 v[4:7], v[164:167], v[206:209], v[4:7]
	v_mfma_f32_16x16x32_bf16 v[0:3], v[172:175], v[206:209], v[0:3]
	v_mfma_f32_16x16x32_bf16 v[52:55], v[168:171], v[184:187], v[52:55]
	v_mfma_f32_16x16x32_bf16 v[48:51], v[176:179], v[184:187], v[48:51]
	v_mfma_f32_16x16x32_bf16 v[36:39], v[168:171], v[194:197], v[36:39]
	v_mfma_f32_16x16x32_bf16 v[32:35], v[176:179], v[194:197], v[32:35]
	v_mfma_f32_16x16x32_bf16 v[20:23], v[168:171], v[202:205], v[20:23]
	v_mfma_f32_16x16x32_bf16 v[16:19], v[176:179], v[202:205], v[16:19]
	v_mfma_f32_16x16x32_bf16 v[4:7], v[168:171], v[214:217], v[4:7]
	v_mfma_f32_16x16x32_bf16 v[0:3], v[176:179], v[214:217], v[0:3]
	s_setprio 0
	s_barrier
; #define PG8_STAGE(bufoff, gbase, voff) do { _Pragma("unroll") for (int _i = 0; _i < 2; ++_i) \
;         __builtin_amdgcn_global_load_lds((const unsigned*)((const char*)(gbase) + (voff)[_i]), (PG8_LAS unsigned*)(lds + (bufoff) + ldsw + _i * 8192), 16, 0, 0); } while (0)
; #define PG8_LDA(dst, b, h) do { _Pragma("unroll") for (int m = 0; m < 4; ++m) _Pragma("unroll") for (int k = 0; k < 2; ++k) dst[m][k] = *(const PG8_LAS bf16x8*)(lds + PG8_SA(b, h) + aoff + m * 2048 + k * 1024); } while (0)
; #define PG8_LDB(dst, b, h) do { _Pragma("unroll") for (int n = 0; n < 2; ++n) _Pragma("unroll") for (int k = 0; k < 2; ++k) dst[n][k] = *(const PG8_LAS bf16x8*)(lds + PG8_SB(b, h) + boff + n * 2048 + k * 1024); } while (0)
; #define PG8_MMA(ai, bj, At, Bt) do { __builtin_amdgcn_s_setprio(1); _Pragma("unroll") for (int m = 0; m < 4; ++m) _Pragma("unroll") for (int n = 0; n < 2; ++n) _Pragma("unroll") for (int k = 0; k < 2; ++k) \
;         acc[ai][bj][m][n] = __builtin_amdgcn_mfma_f32_16x16x32_bf16(Bt[n][k], At[m][k], acc[ai][bj][m][n], 0, 0, 0); __builtin_amdgcn_s_setprio(0); } while (0)
; #define PG8_WAIT_V(n) asm volatile("s_waitcnt vmcnt(" #n ")" ::: "memory")
; #define PG8_WAIT_L(n) asm volatile("s_waitcnt lgkmcnt(" #n ")" ::: "memory")
; #define PG8_BAR __builtin_amdgcn_s_barrier()
; #define PG8_SCHED __builtin_amdgcn_sched_barrier(0)
; template <class Epi, class Sched, bool ALIGN_EPI = false, bool SP2 = false>
; __device__ __forceinline__ void gemm_phase(PG8_LAS unsigned char* lds, const Gemm g, const Sched& S, const Epi& E) {
;     ...
;             PG8_LDB(B0, 1, 0); PG8_LDB(B1, 1, 1); PG8_SCHED; PG8_LDA(At, 1, 0); PG8_STAGE(PG8_SA(0, 1), a2 + hstep, voffA);
;             PG8_WAIT_V(8); PG8_WAIT_L(0); PG8_BAR; PG8_MMA(0, 0, At, B0); PG8_MMA(0, 1, At, B1); PG8_BAR; PG8_SCHED;
	v_add_u32_e32 v160, s75, v147
	v_add_u32_e32 v176, s84, v147
	ds_read_b128 v[140:143], v160
	ds_read_b128 v[152:155], v160 offset:1024
	ds_read_b128 v[156:159], v160 offset:2048
	ds_read_b128 v[160:163], v160 offset:3072
	ds_read_b128 v[164:167], v176
	ds_read_b128 v[168:171], v176 offset:1024
	ds_read_b128 v[172:175], v176 offset:2048
	ds_read_b128 v[176:179], v176 offset:3072
	s_add_u32 s66, s66, 0x20000
	s_addc_u32 s67, s67, 0
	s_mov_b32 m0, s56
	v_lshl_add_u64 v[222:223], s[66:67], 0, v[134:135]
	ds_read_b128 v[180:183], v151 offset:32768
	ds_read_b128 v[184:187], v151 offset:33792
	ds_read_b128 v[190:193], v151 offset:34816
	ds_read_b128 v[194:197], v151 offset:35840
	ds_read_b128 v[198:201], v151 offset:36864
	ds_read_b128 v[202:205], v151 offset:37888
	ds_read_b128 v[206:209], v151 offset:38912
	ds_read_b128 v[214:217], v151 offset:39936
	global_load_lds_dwordx4 v[222:223], off
	v_lshl_add_u64 v[222:223], s[66:67], 0, v[130:131]
	s_mov_b32 m0, s57
	s_nop 0
	global_load_lds_dwordx4 v[222:223], off
	s_waitcnt vmcnt(8)
	s_waitcnt lgkmcnt(0)
	s_setprio 1
	s_barrier
	s_waitcnt lgkmcnt(0)
	v_mfma_f32_16x16x32_bf16 v[124:127], v[140:143], v[180:183], v[124:127]
	v_mfma_f32_16x16x32_bf16 v[120:123], v[156:159], v[180:183], v[120:123]
	v_mfma_f32_16x16x32_bf16 v[108:111], v[140:143], v[190:193], v[108:111]
	v_mfma_f32_16x16x32_bf16 v[104:107], v[156:159], v[190:193], v[104:107]
	v_mfma_f32_16x16x32_bf16 v[92:95], v[140:143], v[198:201], v[92:95]
	v_mfma_f32_16x16x32_bf16 v[88:91], v[156:159], v[198:201], v[88:91]
	v_mfma_f32_16x16x32_bf16 v[76:79], v[140:143], v[206:209], v[76:79]
	v_mfma_f32_16x16x32_bf16 v[72:75], v[156:159], v[206:209], v[72:75]
	v_mfma_f32_16x16x32_bf16 v[124:127], v[152:155], v[184:187], v[124:127]
	v_mfma_f32_16x16x32_bf16 v[120:123], v[160:163], v[184:187], v[120:123]
	v_mfma_f32_16x16x32_bf16 v[108:111], v[152:155], v[194:197], v[108:111]
	v_mfma_f32_16x16x32_bf16 v[104:107], v[160:163], v[194:197], v[104:107]
	v_mfma_f32_16x16x32_bf16 v[92:95], v[152:155], v[202:205], v[92:95]
	v_mfma_f32_16x16x32_bf16 v[88:91], v[160:163], v[202:205], v[88:91]
	v_mfma_f32_16x16x32_bf16 v[76:79], v[152:155], v[214:217], v[76:79]
	v_mfma_f32_16x16x32_bf16 v[72:75], v[160:163], v[214:217], v[72:75]
	s_setprio 0
	s_setprio 1
	v_mfma_f32_16x16x32_bf16 v[116:119], v[164:167], v[180:183], v[116:119]
	v_mfma_f32_16x16x32_bf16 v[112:115], v[172:175], v[180:183], v[112:115]
	v_mfma_f32_16x16x32_bf16 v[100:103], v[164:167], v[190:193], v[100:103]
	v_mfma_f32_16x16x32_bf16 v[96:99], v[172:175], v[190:193], v[96:99]
	v_mfma_f32_16x16x32_bf16 v[84:87], v[164:167], v[198:201], v[84:87]
	v_mfma_f32_16x16x32_bf16 v[80:83], v[172:175], v[198:201], v[80:83]
	v_mfma_f32_16x16x32_bf16 v[68:71], v[164:167], v[206:209], v[68:71]
	v_mfma_f32_16x16x32_bf16 v[64:67], v[172:175], v[206:209], v[64:67]
	v_mfma_f32_16x16x32_bf16 v[116:119], v[168:171], v[184:187], v[116:119]
	v_mfma_f32_16x16x32_bf16 v[112:115], v[176:179], v[184:187], v[112:115]
	v_mfma_f32_16x16x32_bf16 v[100:103], v[168:171], v[194:197], v[100:103]
	v_mfma_f32_16x16x32_bf16 v[96:99], v[176:179], v[194:197], v[96:99]
	v_mfma_f32_16x16x32_bf16 v[84:87], v[168:171], v[202:205], v[84:87]
	v_mfma_f32_16x16x32_bf16 v[80:83], v[176:179], v[202:205], v[80:83]
	v_mfma_f32_16x16x32_bf16 v[68:71], v[168:171], v[214:217], v[68:71]
	v_mfma_f32_16x16x32_bf16 v[64:67], v[176:179], v[214:217], v[64:67]
	s_setprio 0
	s_barrier
; #define PG8_STAGE(bufoff, gbase, voff) do { _Pragma("unroll") for (int _i = 0; _i < 2; ++_i) \
;         __builtin_amdgcn_global_load_lds((const unsigned*)((const char*)(gbase) + (voff)[_i]), (PG8_LAS unsigned*)(lds + (bufoff) + ldsw + _i * 8192), 16, 0, 0); } while (0)
; #define PG8_LDA(dst, b, h) do { _Pragma("unroll") for (int m = 0; m < 4; ++m) _Pragma("unroll") for (int k = 0; k < 2; ++k) dst[m][k] = *(const PG8_LAS bf16x8*)(lds + PG8_SA(b, h) + aoff + m * 2048 + k * 1024); } while (0)
; #define PG8_MMA(ai, bj, At, Bt) do { __builtin_amdgcn_s_setprio(1); _Pragma("unroll") for (int m = 0; m < 4; ++m) _Pragma("unroll") for (int n = 0; n < 2; ++n) _Pragma("unroll") for (int k = 0; k < 2; ++k) \
;         acc[ai][bj][m][n] = __builtin_amdgcn_mfma_f32_16x16x32_bf16(Bt[n][k], At[m][k], acc[ai][bj][m][n], 0, 0, 0); __builtin_amdgcn_s_setprio(0); } while (0)
; #define PG8_WAIT_V(n) asm volatile("s_waitcnt vmcnt(" #n ")" ::: "memory")
; #define PG8_WAIT_L(n) asm volatile("s_waitcnt lgkmcnt(" #n ")" ::: "memory")
; #define PG8_BAR __builtin_amdgcn_s_barrier()
; #define PG8_SCHED __builtin_amdgcn_sched_barrier(0)
; template <class Epi, class Sched, bool ALIGN_EPI = false, bool SP2 = false>
; __device__ __forceinline__ void gemm_phase(PG8_LAS unsigned char* lds, const Gemm g, const Sched& S, const Epi& E) {
;     ...
;         for (int t = seg * tseg; t < (seg + 1) * tseg; t += 2) {
;     ...
;             PG8_LDA(At, 1, 1); PG8_STAGE(PG8_SB(1, 0), b3, voffB); PG8_STAGE(PG8_SB(1, 1), b3 + hstep, voffB); PG8_STAGE(PG8_SA(1, 0), a3, voffA);
;             PG8_WAIT_V(8); PG8_WAIT_L(0); PG8_BAR; PG8_MMA(1, 0, At, B0); PG8_MMA(1, 1, At, B1); PG8_BAR; PG8_SCHED;
	s_add_i32 s66, s75, s29
	v_lshl_add_u64 v[144:145], v[144:145], 0, s[12:13]
	s_mov_b32 m0, s66
	ds_read_b128 v[180:183], v151 offset:49152
	ds_read_b128 v[184:187], v151 offset:50176
	ds_read_b128 v[190:193], v151 offset:51200
	ds_read_b128 v[194:197], v151 offset:52224
	ds_read_b128 v[198:201], v151 offset:53248
	ds_read_b128 v[202:205], v151 offset:54272
	ds_read_b128 v[206:209], v151 offset:55296
	ds_read_b128 v[214:217], v151 offset:56320
	global_load_lds_dwordx4 v[144:145], off
	s_add_i32 m0, s66, 0x2000
	s_add_u32 s64, s64, 0x20080
	v_lshl_add_u64 v[144:145], v[210:211], 0, s[12:13]
	s_addc_u32 s65, s65, 0
	s_add_i32 s66, s84, s29
	global_load_lds_dwordx4 v[144:145], off
	v_lshl_add_u64 v[144:145], s[64:65], 0, v[132:133]
	s_mov_b32 m0, s66
	s_nop 0
	global_load_lds_dwordx4 v[144:145], off
	v_lshl_add_u64 v[144:145], s[64:65], 0, v[128:129]
	s_add_i32 m0, s66, 0x2000
	s_nop 0
	global_load_lds_dwordx4 v[144:145], off
	v_lshl_add_u64 v[144:145], v[218:219], 0, s[12:13]
	s_mov_b32 m0, s68
	s_nop 0
	global_load_lds_dwordx4 v[144:145], off
	v_lshl_add_u64 v[144:145], v[220:221], 0, s[12:13]
	s_mov_b32 m0, s69
	s_nop 0
	global_load_lds_dwordx4 v[144:145], off
	s_waitcnt vmcnt(8)
	s_waitcnt lgkmcnt(0)
	s_setprio 1
	s_barrier
	s_waitcnt lgkmcnt(0)
	v_mfma_f32_16x16x32_bf16 v[60:63], v[140:143], v[180:183], v[60:63]
	v_mfma_f32_16x16x32_bf16 v[56:59], v[156:159], v[180:183], v[56:59]
	v_mfma_f32_16x16x32_bf16 v[44:47], v[140:143], v[190:193], v[44:47]
	v_mfma_f32_16x16x32_bf16 v[40:43], v[156:159], v[190:193], v[40:43]
	v_mfma_f32_16x16x32_bf16 v[28:31], v[140:143], v[198:201], v[28:31]
	v_mfma_f32_16x16x32_bf16 v[24:27], v[156:159], v[198:201], v[24:27]
	v_mfma_f32_16x16x32_bf16 v[12:15], v[140:143], v[206:209], v[12:15]
	v_mfma_f32_16x16x32_bf16 v[8:11], v[156:159], v[206:209], v[8:11]
	v_mfma_f32_16x16x32_bf16 v[60:63], v[152:155], v[184:187], v[60:63]
	v_mfma_f32_16x16x32_bf16 v[56:59], v[160:163], v[184:187], v[56:59]
	v_mfma_f32_16x16x32_bf16 v[44:47], v[152:155], v[194:197], v[44:47]
	v_mfma_f32_16x16x32_bf16 v[40:43], v[160:163], v[194:197], v[40:43]
	v_mfma_f32_16x16x32_bf16 v[28:31], v[152:155], v[202:205], v[28:31]
	v_mfma_f32_16x16x32_bf16 v[24:27], v[160:163], v[202:205], v[24:27]
	v_mfma_f32_16x16x32_bf16 v[12:15], v[152:155], v[214:217], v[12:15]
	v_mfma_f32_16x16x32_bf16 v[8:11], v[160:163], v[214:217], v[8:11]
	s_setprio 0
	s_setprio 1
	v_mfma_f32_16x16x32_bf16 v[52:55], v[164:167], v[180:183], v[52:55]
	v_mfma_f32_16x16x32_bf16 v[48:51], v[172:175], v[180:183], v[48:51]
	v_mfma_f32_16x16x32_bf16 v[36:39], v[164:167], v[190:193], v[36:39]
	v_mfma_f32_16x16x32_bf16 v[32:35], v[172:175], v[190:193], v[32:35]
	v_mfma_f32_16x16x32_bf16 v[20:23], v[164:167], v[198:201], v[20:23]
	v_mfma_f32_16x16x32_bf16 v[16:19], v[172:175], v[198:201], v[16:19]
	v_mfma_f32_16x16x32_bf16 v[4:7], v[164:167], v[206:209], v[4:7]
	v_mfma_f32_16x16x32_bf16 v[0:3], v[172:175], v[206:209], v[0:3]
	v_mfma_f32_16x16x32_bf16 v[52:55], v[168:171], v[184:187], v[52:55]
	v_mfma_f32_16x16x32_bf16 v[48:51], v[176:179], v[184:187], v[48:51]
	v_mfma_f32_16x16x32_bf16 v[36:39], v[168:171], v[194:197], v[36:39]
	v_mfma_f32_16x16x32_bf16 v[32:35], v[176:179], v[194:197], v[32:35]
	v_mfma_f32_16x16x32_bf16 v[20:23], v[168:171], v[202:205], v[20:23]
	v_mfma_f32_16x16x32_bf16 v[16:19], v[176:179], v[202:205], v[16:19]
	v_mfma_f32_16x16x32_bf16 v[4:7], v[168:171], v[214:217], v[4:7]
	v_mfma_f32_16x16x32_bf16 v[0:3], v[176:179], v[214:217], v[0:3]
	s_setprio 0
	s_barrier
	s_add_i32 s78, s78, 2
	s_add_u32 s62, s62, 0x100
	s_addc_u32 s63, s63, 0
	s_add_u32 s37, s37, 0x100
	s_addc_u32 s77, s77, 0
	s_cmp_gt_u32 s78, 5
	s_cbranch_scc0 .LBB0_535
	s_and_b64 vcc, exec, s[14:15]
	s_cbranch_vccz .LBB0_538
	s_barrier

; #define PG8_STAGE(bufoff, gbase, voff) do { _Pragma("unroll") for (int _i = 0; _i < 2; ++_i) \
;         __builtin_amdgcn_global_load_lds((const unsigned*)((const char*)(gbase) + (voff)[_i]), (PG8_LAS unsigned*)(lds + (bufoff) + ldsw + _i * 8192), 16, 0, 0); } while (0)
; #define PG8_LDA(dst, b, h) do { _Pragma("unroll") for (int m = 0; m < 4; ++m) _Pragma("unroll") for (int k = 0; k < 2; ++k) dst[m][k] = *(const PG8_LAS bf16x8*)(lds + PG8_SA(b, h) + aoff + m * 2048 + k * 1024); } while (0)
; #define PG8_LDB(dst, b, h) do { _Pragma("unroll") for (int n = 0; n < 2; ++n) _Pragma("unroll") for (int k = 0; k < 2; ++k) dst[n][k] = *(const PG8_LAS bf16x8*)(lds + PG8_SB(b, h) + boff + n * 2048 + k * 1024); } while (0)
; #define PG8_MMA(ai, bj, At, Bt) do { __builtin_amdgcn_s_setprio(1); _Pragma("unroll") for (int m = 0; m < 4; ++m) _Pragma("unroll") for (int n = 0; n < 2; ++n) _Pragma("unroll") for (int k = 0; k < 2; ++k) \
;         acc[ai][bj][m][n] = __builtin_amdgcn_mfma_f32_16x16x32_bf16(Bt[n][k], At[m][k], acc[ai][bj][m][n], 0, 0, 0); __builtin_amdgcn_s_setprio(0); } while (0)
; #define PG8_WAIT_V(n) asm volatile("s_waitcnt vmcnt(" #n ")" ::: "memory")
; #define PG8_WAIT_L(n) asm volatile("s_waitcnt lgkmcnt(" #n ")" ::: "memory")
; #define PG8_BAR __builtin_amdgcn_s_barrier()
; #define PG8_SCHED __builtin_amdgcn_sched_barrier(0)
; template <class Epi, class Sched, bool ALIGN_EPI = false, bool SP2 = false>
; __device__ __forceinline__ void gemm_phase(PG8_LAS unsigned char* lds, const Gemm g, const Sched& S, const Epi& E) {
;     ...
;             PG8_LDB(B0, 0, 0); PG8_LDB(B1, 0, 1); PG8_SCHED; PG8_LDA(At, 0, 0); PG8_STAGE(PG8_SA(1, 1), a1 + hstep, voffA);
;             PG8_WAIT_V(8); PG8_WAIT_L(0); PG8_BAR; PG8_MMA(0, 0, At, B0); PG8_MMA(0, 1, At, B1); PG8_BAR; PG8_SCHED;
;             PG8_LDA(At, 0, 1); PG8_STAGE(PG8_SB(0, 0), b2, voffB); PG8_STAGE(PG8_SB(0, 1), b2 + hstep, voffB); PG8_STAGE(PG8_SA(0, 0), a2, voffA);
;             PG8_WAIT_V(8); PG8_WAIT_L(0); PG8_BAR; PG8_MMA(1, 0, At, B0); PG8_MMA(1, 1, At, B1); PG8_BAR; PG8_SCHED;
.LBB0_702:
	v_lshl_add_u64 v[148:149], s[62:63], 0, v[136:137]
	v_lshl_add_u64 v[150:151], s[62:63], 0, v[138:139]
	v_lshl_add_u64 v[152:153], s[60:61], 0, v[140:141]
	v_lshl_add_u64 v[154:155], s[60:61], 0, v[142:143]
	s_mov_b32 s59, -2
	s_mov_b64 s[64:65], 0
	ds_read_b128 v[162:165], v159
	ds_read_b128 v[166:169], v159 offset:1024
	ds_read_b128 v[170:173], v159 offset:2048
	ds_read_b128 v[174:177], v159 offset:3072
	ds_read_b128 v[178:181], v160
	ds_read_b128 v[182:185], v160 offset:1024
	ds_read_b128 v[190:193], v160 offset:2048
	ds_read_b128 v[194:197], v160 offset:3072
	v_lshl_add_u64 v[210:211], v[148:149], 0, s[64:65]
	s_mov_b32 m0, s77
	v_lshl_add_u64 v[186:187], v[210:211], 0, s[10:11]
	v_lshl_add_u64 v[234:235], v[150:151], 0, s[64:65]
	ds_read_b128 v[198:201], v161
	ds_read_b128 v[202:205], v161 offset:1024
	ds_read_b128 v[206:209], v161 offset:2048
	ds_read_b128 v[214:217], v161 offset:3072
	ds_read_b128 v[218:221], v161 offset:4096
	ds_read_b128 v[222:225], v161 offset:5120
	ds_read_b128 v[226:229], v161 offset:6144
	ds_read_b128 v[230:233], v161 offset:7168
	global_load_lds_dwordx4 v[186:187], off
	v_lshl_add_u64 v[186:187], v[234:235], 0, s[10:11]
	s_mov_b32 m0, s78
	s_nop 0
	global_load_lds_dwordx4 v[186:187], off
	s_waitcnt vmcnt(8)
	s_waitcnt lgkmcnt(0)
	s_setprio 1
	s_barrier
	s_waitcnt lgkmcnt(0)
	v_mfma_f32_16x16x32_bf16 v[124:127], v[162:165], v[198:201], 0
	v_mfma_f32_16x16x32_bf16 v[120:123], v[170:173], v[198:201], 0
	v_mfma_f32_16x16x32_bf16 v[116:119], v[162:165], v[206:209], 0
	v_mfma_f32_16x16x32_bf16 v[112:115], v[170:173], v[206:209], 0
	v_mfma_f32_16x16x32_bf16 v[108:111], v[162:165], v[218:221], 0
	v_mfma_f32_16x16x32_bf16 v[104:107], v[170:173], v[218:221], 0
	v_mfma_f32_16x16x32_bf16 v[100:103], v[162:165], v[226:229], 0
	v_mfma_f32_16x16x32_bf16 v[96:99], v[170:173], v[226:229], 0
	v_mfma_f32_16x16x32_bf16 v[124:127], v[166:169], v[202:205], v[124:127]
	v_mfma_f32_16x16x32_bf16 v[120:123], v[174:177], v[202:205], v[120:123]
	v_mfma_f32_16x16x32_bf16 v[116:119], v[166:169], v[214:217], v[116:119]
	v_mfma_f32_16x16x32_bf16 v[112:115], v[174:177], v[214:217], v[112:115]
	v_mfma_f32_16x16x32_bf16 v[108:111], v[166:169], v[222:225], v[108:111]
	v_mfma_f32_16x16x32_bf16 v[104:107], v[174:177], v[222:225], v[104:107]
	v_mfma_f32_16x16x32_bf16 v[100:103], v[166:169], v[230:233], v[100:103]
	v_mfma_f32_16x16x32_bf16 v[96:99], v[174:177], v[230:233], v[96:99]
	s_setprio 0
	s_setprio 1
	v_mfma_f32_16x16x32_bf16 v[88:91], v[178:181], v[198:201], 0
	v_mfma_f32_16x16x32_bf16 v[92:95], v[190:193], v[198:201], 0
	v_mfma_f32_16x16x32_bf16 v[80:83], v[178:181], v[206:209], 0
	v_mfma_f32_16x16x32_bf16 v[84:87], v[190:193], v[206:209], 0
	v_mfma_f32_16x16x32_bf16 v[72:75], v[178:181], v[218:221], 0
	v_mfma_f32_16x16x32_bf16 v[76:79], v[190:193], v[218:221], 0
	v_mfma_f32_16x16x32_bf16 v[64:67], v[178:181], v[226:229], 0
	v_mfma_f32_16x16x32_bf16 v[68:71], v[190:193], v[226:229], 0
	v_mfma_f32_16x16x32_bf16 v[88:91], v[182:185], v[202:205], v[88:91]
	v_mfma_f32_16x16x32_bf16 v[92:95], v[194:197], v[202:205], v[92:95]
	v_mfma_f32_16x16x32_bf16 v[80:83], v[182:185], v[214:217], v[80:83]
	v_mfma_f32_16x16x32_bf16 v[84:87], v[194:197], v[214:217], v[84:87]
	v_mfma_f32_16x16x32_bf16 v[72:75], v[182:185], v[222:225], v[72:75]
	v_mfma_f32_16x16x32_bf16 v[76:79], v[194:197], v[222:225], v[76:79]
	v_mfma_f32_16x16x32_bf16 v[64:67], v[182:185], v[230:233], v[64:67]
	v_mfma_f32_16x16x32_bf16 v[68:71], v[194:197], v[230:233], v[68:71]
	s_setprio 0
	s_barrier
	v_lshl_add_u64 v[236:237], v[152:153], 0, s[64:65]
	s_mov_b32 m0, s79
	v_lshl_add_u64 v[186:187], v[236:237], 0, s[14:15]
	v_lshl_add_u64 v[238:239], v[154:155], 0, s[64:65]
	ds_read_b128 v[198:201], v161 offset:16384
	ds_read_b128 v[202:205], v161 offset:17408
	ds_read_b128 v[206:209], v161 offset:18432
	ds_read_b128 v[214:217], v161 offset:19456
	ds_read_b128 v[218:221], v161 offset:20480
	ds_read_b128 v[222:225], v161 offset:21504
	ds_read_b128 v[226:229], v161 offset:22528
	ds_read_b128 v[230:233], v161 offset:23552
	global_load_lds_dwordx4 v[186:187], off
	v_lshl_add_u64 v[186:187], v[238:239], 0, s[14:15]
	s_mov_b32 m0, s80
	s_add_i32 s0, s74, s23
	global_load_lds_dwordx4 v[186:187], off
	v_lshl_add_u64 v[186:187], v[236:237], 0, s[36:37]
	s_mov_b32 m0, s0
	s_add_i32 s1, s0, 0x2000
	global_load_lds_dwordx4 v[186:187], off
	v_lshl_add_u64 v[186:187], v[238:239], 0, s[36:37]
	s_mov_b32 m0, s1
	s_nop 0
	global_load_lds_dwordx4 v[186:187], off
	v_lshl_add_u64 v[186:187], v[210:211], 0, s[14:15]
	s_mov_b32 m0, s28
	s_nop 0
	global_load_lds_dwordx4 v[186:187], off
	v_lshl_add_u64 v[186:187], v[234:235], 0, s[14:15]
	s_mov_b32 m0, s29
	s_nop 0
	global_load_lds_dwordx4 v[186:187], off
	s_waitcnt vmcnt(8)
	s_waitcnt lgkmcnt(0)
	s_setprio 1
	s_barrier
; #define PG8_STAGE(bufoff, gbase, voff) do { _Pragma("unroll") for (int _i = 0; _i < 2; ++_i) \
;         __builtin_amdgcn_global_load_lds((const unsigned*)((const char*)(gbase) + (voff)[_i]), (PG8_LAS unsigned*)(lds + (bufoff) + ldsw + _i * 8192), 16, 0, 0); } while (0)
; #define PG8_LDA(dst, b, h) do { _Pragma("unroll") for (int m = 0; m < 4; ++m) _Pragma("unroll") for (int k = 0; k < 2; ++k) dst[m][k] = *(const PG8_LAS bf16x8*)(lds + PG8_SA(b, h) + aoff + m * 2048 + k * 1024); } while (0)
; #define PG8_LDB(dst, b, h) do { _Pragma("unroll") for (int n = 0; n < 2; ++n) _Pragma("unroll") for (int k = 0; k < 2; ++k) dst[n][k] = *(const PG8_LAS bf16x8*)(lds + PG8_SB(b, h) + boff + n * 2048 + k * 1024); } while (0)
; #define PG8_MMA(ai, bj, At, Bt) do { __builtin_amdgcn_s_setprio(1); _Pragma("unroll") for (int m = 0; m < 4; ++m) _Pragma("unroll") for (int n = 0; n < 2; ++n) _Pragma("unroll") for (int k = 0; k < 2; ++k) \
;         acc[ai][bj][m][n] = __builtin_amdgcn_mfma_f32_16x16x32_bf16(Bt[n][k], At[m][k], acc[ai][bj][m][n], 0, 0, 0); __builtin_amdgcn_s_setprio(0); } while (0)
; #define PG8_WAIT_V(n) asm volatile("s_waitcnt vmcnt(" #n ")" ::: "memory")
; #define PG8_WAIT_L(n) asm volatile("s_waitcnt lgkmcnt(" #n ")" ::: "memory")
; #define PG8_BAR __builtin_amdgcn_s_barrier()
; #define PG8_SCHED __builtin_amdgcn_sched_barrier(0)
; template <class Epi, class Sched, bool ALIGN_EPI = false, bool SP2 = false>
; __device__ __forceinline__ void gemm_phase(PG8_LAS unsigned char* lds, const Gemm g, const Sched& S, const Epi& E) {
;     ...
;             PG8_WAIT_V(8); PG8_WAIT_L(0); PG8_BAR; PG8_MMA(1, 0, At, B0); PG8_MMA(1, 1, At, B1); PG8_BAR; PG8_SCHED;
;             PG8_LDB(B0, 1, 0); PG8_LDB(B1, 1, 1); PG8_SCHED; PG8_LDA(At, 1, 0); PG8_STAGE(PG8_SA(0, 1), a2 + hstep, voffA);
;             PG8_WAIT_V(8); PG8_WAIT_L(0); PG8_BAR; PG8_MMA(0, 0, At, B0); PG8_MMA(0, 1, At, B1); PG8_BAR; PG8_SCHED;
	s_waitcnt lgkmcnt(0)
	v_mfma_f32_16x16x32_bf16 v[60:63], v[162:165], v[198:201], 0
	v_mfma_f32_16x16x32_bf16 v[56:59], v[170:173], v[198:201], 0
	v_mfma_f32_16x16x32_bf16 v[44:47], v[162:165], v[206:209], 0
	v_mfma_f32_16x16x32_bf16 v[40:43], v[170:173], v[206:209], 0
	v_mfma_f32_16x16x32_bf16 v[28:31], v[162:165], v[218:221], 0
	v_mfma_f32_16x16x32_bf16 v[24:27], v[170:173], v[218:221], 0
	v_mfma_f32_16x16x32_bf16 v[12:15], v[162:165], v[226:229], 0
	v_mfma_f32_16x16x32_bf16 v[8:11], v[170:173], v[226:229], 0
	v_mfma_f32_16x16x32_bf16 v[60:63], v[166:169], v[202:205], v[60:63]
	v_mfma_f32_16x16x32_bf16 v[56:59], v[174:177], v[202:205], v[56:59]
	v_mfma_f32_16x16x32_bf16 v[44:47], v[166:169], v[214:217], v[44:47]
	v_mfma_f32_16x16x32_bf16 v[40:43], v[174:177], v[214:217], v[40:43]
	v_mfma_f32_16x16x32_bf16 v[28:31], v[166:169], v[222:225], v[28:31]
	v_mfma_f32_16x16x32_bf16 v[24:27], v[174:177], v[222:225], v[24:27]
	v_mfma_f32_16x16x32_bf16 v[12:15], v[166:169], v[230:233], v[12:15]
	v_mfma_f32_16x16x32_bf16 v[8:11], v[174:177], v[230:233], v[8:11]
	s_setprio 0
	s_setprio 1
	v_mfma_f32_16x16x32_bf16 v[52:55], v[178:181], v[198:201], 0
	v_mfma_f32_16x16x32_bf16 v[48:51], v[190:193], v[198:201], 0
	v_mfma_f32_16x16x32_bf16 v[36:39], v[178:181], v[206:209], 0
	v_mfma_f32_16x16x32_bf16 v[32:35], v[190:193], v[206:209], 0
	v_mfma_f32_16x16x32_bf16 v[20:23], v[178:181], v[218:221], 0
	v_mfma_f32_16x16x32_bf16 v[16:19], v[190:193], v[218:221], 0
	v_mfma_f32_16x16x32_bf16 v[4:7], v[178:181], v[226:229], 0
	v_mfma_f32_16x16x32_bf16 v[0:3], v[190:193], v[226:229], 0
	v_mfma_f32_16x16x32_bf16 v[52:55], v[182:185], v[202:205], v[52:55]
	v_mfma_f32_16x16x32_bf16 v[48:51], v[194:197], v[202:205], v[48:51]
	v_mfma_f32_16x16x32_bf16 v[36:39], v[182:185], v[214:217], v[36:39]
	v_mfma_f32_16x16x32_bf16 v[32:35], v[194:197], v[214:217], v[32:35]
	v_mfma_f32_16x16x32_bf16 v[20:23], v[182:185], v[222:225], v[20:23]
	v_mfma_f32_16x16x32_bf16 v[16:19], v[194:197], v[222:225], v[16:19]
	v_mfma_f32_16x16x32_bf16 v[4:7], v[182:185], v[230:233], v[4:7]
	v_mfma_f32_16x16x32_bf16 v[0:3], v[194:197], v[230:233], v[0:3]
	s_setprio 0
	s_barrier
	v_add_u32_e32 v162, s75, v157
	v_add_u32_e32 v163, s84, v157
	ds_read_b128 v[164:167], v162
	ds_read_b128 v[168:171], v162 offset:1024
	ds_read_b128 v[172:175], v162 offset:2048
	ds_read_b128 v[176:179], v162 offset:3072
	ds_read_b128 v[180:183], v163
	ds_read_b128 v[184:187], v163 offset:1024
	ds_read_b128 v[190:193], v163 offset:2048
	ds_read_b128 v[194:197], v163 offset:3072
	s_mov_b32 m0, s30
	v_lshl_add_u64 v[240:241], v[210:211], 0, s[36:37]
	ds_read_b128 v[198:201], v161 offset:32768
	ds_read_b128 v[202:205], v161 offset:33792
	ds_read_b128 v[206:209], v161 offset:34816
	ds_read_b128 v[214:217], v161 offset:35840
	ds_read_b128 v[218:221], v161 offset:36864
	ds_read_b128 v[222:225], v161 offset:37888
	ds_read_b128 v[226:229], v161 offset:38912
	ds_read_b128 v[230:233], v161 offset:39936
	global_load_lds_dwordx4 v[240:241], off
	v_lshl_add_u64 v[240:241], v[234:235], 0, s[36:37]
	s_mov_b32 m0, s33
	s_nop 0
	global_load_lds_dwordx4 v[240:241], off
	s_waitcnt vmcnt(8)
	s_waitcnt lgkmcnt(0)
	s_setprio 1
	s_barrier
	s_waitcnt lgkmcnt(0)
	v_mfma_f32_16x16x32_bf16 v[124:127], v[164:167], v[198:201], v[124:127]
	v_mfma_f32_16x16x32_bf16 v[120:123], v[172:175], v[198:201], v[120:123]
	v_mfma_f32_16x16x32_bf16 v[116:119], v[164:167], v[206:209], v[116:119]
	v_mfma_f32_16x16x32_bf16 v[112:115], v[172:175], v[206:209], v[112:115]
	v_mfma_f32_16x16x32_bf16 v[108:111], v[164:167], v[218:221], v[108:111]
	v_mfma_f32_16x16x32_bf16 v[104:107], v[172:175], v[218:221], v[104:107]
	v_mfma_f32_16x16x32_bf16 v[100:103], v[164:167], v[226:229], v[100:103]
	v_mfma_f32_16x16x32_bf16 v[96:99], v[172:175], v[226:229], v[96:99]
	v_mfma_f32_16x16x32_bf16 v[124:127], v[168:171], v[202:205], v[124:127]
	v_mfma_f32_16x16x32_bf16 v[120:123], v[176:179], v[202:205], v[120:123]
	v_mfma_f32_16x16x32_bf16 v[116:119], v[168:171], v[214:217], v[116:119]
	v_mfma_f32_16x16x32_bf16 v[112:115], v[176:179], v[214:217], v[112:115]
	v_mfma_f32_16x16x32_bf16 v[108:111], v[168:171], v[222:225], v[108:111]
	v_mfma_f32_16x16x32_bf16 v[104:107], v[176:179], v[222:225], v[104:107]
	v_mfma_f32_16x16x32_bf16 v[100:103], v[168:171], v[230:233], v[100:103]
	v_mfma_f32_16x16x32_bf16 v[96:99], v[176:179], v[230:233], v[96:99]
	s_setprio 0
	s_setprio 1
	v_mfma_f32_16x16x32_bf16 v[88:91], v[180:183], v[198:201], v[88:91]
	v_mfma_f32_16x16x32_bf16 v[92:95], v[190:193], v[198:201], v[92:95]
	v_mfma_f32_16x16x32_bf16 v[80:83], v[180:183], v[206:209], v[80:83]
	v_mfma_f32_16x16x32_bf16 v[84:87], v[190:193], v[206:209], v[84:87]
	v_mfma_f32_16x16x32_bf16 v[72:75], v[180:183], v[218:221], v[72:75]
	v_mfma_f32_16x16x32_bf16 v[76:79], v[190:193], v[218:221], v[76:79]
	v_mfma_f32_16x16x32_bf16 v[64:67], v[180:183], v[226:229], v[64:67]
	v_mfma_f32_16x16x32_bf16 v[68:71], v[190:193], v[226:229], v[68:71]
	v_mfma_f32_16x16x32_bf16 v[88:91], v[184:187], v[202:205], v[88:91]
	v_mfma_f32_16x16x32_bf16 v[92:95], v[194:197], v[202:205], v[92:95]
	v_mfma_f32_16x16x32_bf16 v[80:83], v[184:187], v[214:217], v[80:83]
	v_mfma_f32_16x16x32_bf16 v[84:87], v[194:197], v[214:217], v[84:87]
	v_mfma_f32_16x16x32_bf16 v[72:75], v[184:187], v[222:225], v[72:75]
	v_mfma_f32_16x16x32_bf16 v[76:79], v[194:197], v[222:225], v[76:79]
	v_mfma_f32_16x16x32_bf16 v[64:67], v[184:187], v[230:233], v[64:67]
	v_mfma_f32_16x16x32_bf16 v[68:71], v[194:197], v[230:233], v[68:71]
	s_setprio 0
	s_barrier
; #define PG8_STAGE(bufoff, gbase, voff) do { _Pragma("unroll") for (int _i = 0; _i < 2; ++_i) \
;         __builtin_amdgcn_global_load_lds((const unsigned*)((const char*)(gbase) + (voff)[_i]), (PG8_LAS unsigned*)(lds + (bufoff) + ldsw + _i * 8192), 16, 0, 0); } while (0)
; #define PG8_LDA(dst, b, h) do { _Pragma("unroll") for (int m = 0; m < 4; ++m) _Pragma("unroll") for (int k = 0; k < 2; ++k) dst[m][k] = *(const PG8_LAS bf16x8*)(lds + PG8_SA(b, h) + aoff + m * 2048 + k * 1024); } while (0)
; #define PG8_LDB(dst, b, h) do { _Pragma("unroll") for (int n = 0; n < 2; ++n) _Pragma("unroll") for (int k = 0; k < 2; ++k) dst[n][k] = *(const PG8_LAS bf16x8*)(lds + PG8_SB(b, h) + boff + n * 2048 + k * 1024); } while (0)
; #define PG8_MMA(ai, bj, At, Bt) do { __builtin_amdgcn_s_setprio(1); _Pragma("unroll") for (int m = 0; m < 4; ++m) _Pragma("unroll") for (int n = 0; n < 2; ++n) _Pragma("unroll") for (int k = 0; k < 2; ++k) \
;         acc[ai][bj][m][n] = __builtin_amdgcn_mfma_f32_16x16x32_bf16(Bt[n][k], At[m][k], acc[ai][bj][m][n], 0, 0, 0); __builtin_amdgcn_s_setprio(0); } while (0)
; #define PG8_WAIT_V(n) asm volatile("s_waitcnt vmcnt(" #n ")" ::: "memory")
; #define PG8_WAIT_L(n) asm volatile("s_waitcnt lgkmcnt(" #n ")" ::: "memory")
; template <class Epi, class Sched, bool ALIGN_EPI = false, bool SP2 = false>
; __device__ __forceinline__ void gemm_phase(PG8_LAS unsigned char* lds, const Gemm g, const Sched& S, const Epi& E) {
;     ...
;             const bool last = (t == nt - 2);
;             const char* a1 = cA + (size_t)(t + 1) * kstep;
;             const char* a2 = last ? nA : cA + (size_t)(t + 2) * kstep; const char* b2 = last ? nB : cB + (size_t)(t + 2) * kstep;
;             const char* a3 = a2 + kstep; const char* b3 = b2 + kstep;
;             if (last && has_next) S.a_ready(nxt);
;             if constexpr (SP2) {
;             PG8_LDB(B0, 0, 0); PG8_LDB(B1, 0, 1); PG8_SCHED; PG8_LDA(At, 0, 0); PG8_STAGE(PG8_SA(1, 1), a1 + hstep, voffA);
;             PG8_WAIT_V(8); PG8_WAIT_L(0); PG8_BAR; PG8_MMA(0, 0, At, B0); PG8_MMA(0, 1, At, B1); PG8_BAR; PG8_SCHED;
;     ...
;             PG8_LDA(At, 1, 1); PG8_STAGE(PG8_SB(1, 0), b3, voffB); PG8_STAGE(PG8_SB(1, 1), b3 + hstep, voffB); PG8_STAGE(PG8_SA(1, 0), a3, voffA);
;             PG8_WAIT_V(8); PG8_WAIT_L(0); PG8_BAR; PG8_MMA(1, 0, At, B0); PG8_MMA(1, 1, At, B1); PG8_BAR; PG8_SCHED;
	s_add_i32 s82, s75, s23
	v_lshl_add_u64 v[240:241], v[236:237], 0, s[40:41]
	s_mov_b32 m0, s82
	s_add_i32 s83, s82, 0x2000
	ds_read_b128 v[198:201], v161 offset:49152
	ds_read_b128 v[202:205], v161 offset:50176
	ds_read_b128 v[206:209], v161 offset:51200
	ds_read_b128 v[214:217], v161 offset:52224
	ds_read_b128 v[218:221], v161 offset:53248
	ds_read_b128 v[222:225], v161 offset:54272
	ds_read_b128 v[226:229], v161 offset:55296
	ds_read_b128 v[230:233], v161 offset:56320
	global_load_lds_dwordx4 v[240:241], off
	v_lshl_add_u64 v[240:241], v[238:239], 0, s[40:41]
	s_mov_b32 m0, s83
	s_add_i32 s85, s84, s23
	global_load_lds_dwordx4 v[240:241], off
	v_lshl_add_u64 v[236:237], v[236:237], 0, s[46:47]
	s_mov_b32 m0, s85
	s_add_i32 s86, s85, 0x2000
	global_load_lds_dwordx4 v[236:237], off
	v_lshl_add_u64 v[236:237], v[238:239], 0, s[46:47]
	s_mov_b32 m0, s86
	v_lshl_add_u64 v[210:211], v[210:211], 0, s[40:41]
	global_load_lds_dwordx4 v[236:237], off
	s_mov_b32 m0, s71
	s_nop 0
	global_load_lds_dwordx4 v[210:211], off
	v_lshl_add_u64 v[210:211], v[234:235], 0, s[40:41]
	s_mov_b32 m0, s76
	s_nop 0
	global_load_lds_dwordx4 v[210:211], off
	s_waitcnt vmcnt(8)
	s_waitcnt lgkmcnt(0)
	s_setprio 1
	s_barrier
	s_waitcnt lgkmcnt(0)
	v_mfma_f32_16x16x32_bf16 v[60:63], v[164:167], v[198:201], v[60:63]
	v_mfma_f32_16x16x32_bf16 v[56:59], v[172:175], v[198:201], v[56:59]
	v_mfma_f32_16x16x32_bf16 v[44:47], v[164:167], v[206:209], v[44:47]
	v_mfma_f32_16x16x32_bf16 v[40:43], v[172:175], v[206:209], v[40:43]
	v_mfma_f32_16x16x32_bf16 v[28:31], v[164:167], v[218:221], v[28:31]
	v_mfma_f32_16x16x32_bf16 v[24:27], v[172:175], v[218:221], v[24:27]
	v_mfma_f32_16x16x32_bf16 v[12:15], v[164:167], v[226:229], v[12:15]
	v_mfma_f32_16x16x32_bf16 v[8:11], v[172:175], v[226:229], v[8:11]
	v_mfma_f32_16x16x32_bf16 v[60:63], v[168:171], v[202:205], v[60:63]
	v_mfma_f32_16x16x32_bf16 v[56:59], v[176:179], v[202:205], v[56:59]
	v_mfma_f32_16x16x32_bf16 v[44:47], v[168:171], v[214:217], v[44:47]
	v_mfma_f32_16x16x32_bf16 v[40:43], v[176:179], v[214:217], v[40:43]
	v_mfma_f32_16x16x32_bf16 v[28:31], v[168:171], v[222:225], v[28:31]
	v_mfma_f32_16x16x32_bf16 v[24:27], v[176:179], v[222:225], v[24:27]
	v_mfma_f32_16x16x32_bf16 v[12:15], v[168:171], v[230:233], v[12:15]
	v_mfma_f32_16x16x32_bf16 v[8:11], v[176:179], v[230:233], v[8:11]
	s_setprio 0
	s_setprio 1
	v_mfma_f32_16x16x32_bf16 v[52:55], v[180:183], v[198:201], v[52:55]
	v_mfma_f32_16x16x32_bf16 v[48:51], v[190:193], v[198:201], v[48:51]
	v_mfma_f32_16x16x32_bf16 v[36:39], v[180:183], v[206:209], v[36:39]
	v_mfma_f32_16x16x32_bf16 v[32:35], v[190:193], v[206:209], v[32:35]
	v_mfma_f32_16x16x32_bf16 v[20:23], v[180:183], v[218:221], v[20:23]
	v_mfma_f32_16x16x32_bf16 v[16:19], v[190:193], v[218:221], v[16:19]
	v_mfma_f32_16x16x32_bf16 v[4:7], v[180:183], v[226:229], v[4:7]
	v_mfma_f32_16x16x32_bf16 v[0:3], v[190:193], v[226:229], v[0:3]
	v_mfma_f32_16x16x32_bf16 v[52:55], v[184:187], v[202:205], v[52:55]
	v_mfma_f32_16x16x32_bf16 v[48:51], v[194:197], v[202:205], v[48:51]
	v_mfma_f32_16x16x32_bf16 v[36:39], v[184:187], v[214:217], v[36:39]
	v_mfma_f32_16x16x32_bf16 v[32:35], v[194:197], v[214:217], v[32:35]
	v_mfma_f32_16x16x32_bf16 v[20:23], v[184:187], v[222:225], v[20:23]
	v_mfma_f32_16x16x32_bf16 v[16:19], v[194:197], v[222:225], v[16:19]
	v_mfma_f32_16x16x32_bf16 v[4:7], v[184:187], v[230:233], v[4:7]
	v_mfma_f32_16x16x32_bf16 v[0:3], v[194:197], v[230:233], v[0:3]
	s_setprio 0
	s_barrier
	s_add_i32 s59, s59, 2
	s_add_u32 s64, s64, 0x100
	s_addc_u32 s65, s65, 0
	s_cmp_gt_u32 s59, 13
.LBB0_703:
	ds_read_b128 v[162:165], v159
	ds_read_b128 v[166:169], v159 offset:1024
	ds_read_b128 v[170:173], v159 offset:2048
	ds_read_b128 v[174:177], v159 offset:3072
	ds_read_b128 v[178:181], v160
	ds_read_b128 v[182:185], v160 offset:1024
	ds_read_b128 v[190:193], v160 offset:2048
	ds_read_b128 v[194:197], v160 offset:3072
	v_lshl_add_u64 v[210:211], v[148:149], 0, s[64:65]
	s_mov_b32 m0, s77
	v_lshl_add_u64 v[186:187], v[210:211], 0, s[10:11]
	v_lshl_add_u64 v[234:235], v[150:151], 0, s[64:65]
	ds_read_b128 v[198:201], v161
	ds_read_b128 v[202:205], v161 offset:1024
	ds_read_b128 v[206:209], v161 offset:2048
	ds_read_b128 v[214:217], v161 offset:3072
	ds_read_b128 v[218:221], v161 offset:4096
	ds_read_b128 v[222:225], v161 offset:5120
	ds_read_b128 v[226:229], v161 offset:6144
	ds_read_b128 v[230:233], v161 offset:7168
	global_load_lds_dwordx4 v[186:187], off
	v_lshl_add_u64 v[186:187], v[234:235], 0, s[10:11]
	s_mov_b32 m0, s78
	s_nop 0
	global_load_lds_dwordx4 v[186:187], off
	s_waitcnt vmcnt(8)
	s_waitcnt lgkmcnt(0)
	s_setprio 1
	s_barrier
; #define PG8_STAGE(bufoff, gbase, voff) do { _Pragma("unroll") for (int _i = 0; _i < 2; ++_i) \
;         __builtin_amdgcn_global_load_lds((const unsigned*)((const char*)(gbase) + (voff)[_i]), (PG8_LAS unsigned*)(lds + (bufoff) + ldsw + _i * 8192), 16, 0, 0); } while (0)
; #define PG8_LDA(dst, b, h) do { _Pragma("unroll") for (int m = 0; m < 4; ++m) _Pragma("unroll") for (int k = 0; k < 2; ++k) dst[m][k] = *(const PG8_LAS bf16x8*)(lds + PG8_SA(b, h) + aoff + m * 2048 + k * 1024); } while (0)
; #define PG8_LDB(dst, b, h) do { _Pragma("unroll") for (int n = 0; n < 2; ++n) _Pragma("unroll") for (int k = 0; k < 2; ++k) dst[n][k] = *(const PG8_LAS bf16x8*)(lds + PG8_SB(b, h) + boff + n * 2048 + k * 1024); } while (0)
; #define PG8_MMA(ai, bj, At, Bt) do { __builtin_amdgcn_s_setprio(1); _Pragma("unroll") for (int m = 0; m < 4; ++m) _Pragma("unroll") for (int n = 0; n < 2; ++n) _Pragma("unroll") for (int k = 0; k < 2; ++k) \
;         acc[ai][bj][m][n] = __builtin_amdgcn_mfma_f32_16x16x32_bf16(Bt[n][k], At[m][k], acc[ai][bj][m][n], 0, 0, 0); __builtin_amdgcn_s_setprio(0); } while (0)
; #define PG8_WAIT_V(n) asm volatile("s_waitcnt vmcnt(" #n ")" ::: "memory")
; #define PG8_WAIT_L(n) asm volatile("s_waitcnt lgkmcnt(" #n ")" ::: "memory")
; #define PG8_BAR __builtin_amdgcn_s_barrier()
; #define PG8_SCHED __builtin_amdgcn_sched_barrier(0)
; template <class Epi, class Sched, bool ALIGN_EPI = false, bool SP2 = false>
; __device__ __forceinline__ void gemm_phase(PG8_LAS unsigned char* lds, const Gemm g, const Sched& S, const Epi& E) {
;     ...
;             PG8_LDB(B0, 0, 0); PG8_LDB(B1, 0, 1); PG8_SCHED; PG8_LDA(At, 0, 0); PG8_STAGE(PG8_SA(1, 1), a1 + hstep, voffA);
;             PG8_WAIT_V(8); PG8_WAIT_L(0); PG8_BAR; PG8_MMA(0, 0, At, B0); PG8_MMA(0, 1, At, B1); PG8_BAR; PG8_SCHED;
;             PG8_LDA(At, 0, 1); PG8_STAGE(PG8_SB(0, 0), b2, voffB); PG8_STAGE(PG8_SB(0, 1), b2 + hstep, voffB); PG8_STAGE(PG8_SA(0, 0), a2, voffA);
;             PG8_WAIT_V(8); PG8_WAIT_L(0); PG8_BAR; PG8_MMA(1, 0, At, B0); PG8_MMA(1, 1, At, B1); PG8_BAR; PG8_SCHED;
;             PG8_LDB(B0, 1, 0); PG8_LDB(B1, 1, 1); PG8_SCHED; PG8_LDA(At, 1, 0); PG8_STAGE(PG8_SA(0, 1), a2 + hstep, voffA);
;             PG8_WAIT_V(8); PG8_WAIT_L(0); PG8_BAR; PG8_MMA(0, 0, At, B0); PG8_MMA(0, 1, At, B1); PG8_BAR; PG8_SCHED;
	s_waitcnt lgkmcnt(0)
	v_mfma_f32_16x16x32_bf16 v[124:127], v[162:165], v[198:201], v[124:127]
	v_mfma_f32_16x16x32_bf16 v[120:123], v[170:173], v[198:201], v[120:123]
	v_mfma_f32_16x16x32_bf16 v[116:119], v[162:165], v[206:209], v[116:119]
	v_mfma_f32_16x16x32_bf16 v[112:115], v[170:173], v[206:209], v[112:115]
	v_mfma_f32_16x16x32_bf16 v[108:111], v[162:165], v[218:221], v[108:111]
	v_mfma_f32_16x16x32_bf16 v[104:107], v[170:173], v[218:221], v[104:107]
	v_mfma_f32_16x16x32_bf16 v[100:103], v[162:165], v[226:229], v[100:103]
	v_mfma_f32_16x16x32_bf16 v[96:99], v[170:173], v[226:229], v[96:99]
	v_mfma_f32_16x16x32_bf16 v[124:127], v[166:169], v[202:205], v[124:127]
	v_mfma_f32_16x16x32_bf16 v[120:123], v[174:177], v[202:205], v[120:123]
	v_mfma_f32_16x16x32_bf16 v[116:119], v[166:169], v[214:217], v[116:119]
	v_mfma_f32_16x16x32_bf16 v[112:115], v[174:177], v[214:217], v[112:115]
	v_mfma_f32_16x16x32_bf16 v[108:111], v[166:169], v[222:225], v[108:111]
	v_mfma_f32_16x16x32_bf16 v[104:107], v[174:177], v[222:225], v[104:107]
	v_mfma_f32_16x16x32_bf16 v[100:103], v[166:169], v[230:233], v[100:103]
	v_mfma_f32_16x16x32_bf16 v[96:99], v[174:177], v[230:233], v[96:99]
	s_setprio 0
	s_setprio 1
	v_mfma_f32_16x16x32_bf16 v[88:91], v[178:181], v[198:201], v[88:91]
	v_mfma_f32_16x16x32_bf16 v[92:95], v[190:193], v[198:201], v[92:95]
	v_mfma_f32_16x16x32_bf16 v[80:83], v[178:181], v[206:209], v[80:83]
	v_mfma_f32_16x16x32_bf16 v[84:87], v[190:193], v[206:209], v[84:87]
	v_mfma_f32_16x16x32_bf16 v[72:75], v[178:181], v[218:221], v[72:75]
	v_mfma_f32_16x16x32_bf16 v[76:79], v[190:193], v[218:221], v[76:79]
	v_mfma_f32_16x16x32_bf16 v[64:67], v[178:181], v[226:229], v[64:67]
	v_mfma_f32_16x16x32_bf16 v[68:71], v[190:193], v[226:229], v[68:71]
	v_mfma_f32_16x16x32_bf16 v[88:91], v[182:185], v[202:205], v[88:91]
	v_mfma_f32_16x16x32_bf16 v[92:95], v[194:197], v[202:205], v[92:95]
	v_mfma_f32_16x16x32_bf16 v[80:83], v[182:185], v[214:217], v[80:83]
	v_mfma_f32_16x16x32_bf16 v[84:87], v[194:197], v[214:217], v[84:87]
	v_mfma_f32_16x16x32_bf16 v[72:75], v[182:185], v[222:225], v[72:75]
	v_mfma_f32_16x16x32_bf16 v[76:79], v[194:197], v[222:225], v[76:79]
	v_mfma_f32_16x16x32_bf16 v[64:67], v[182:185], v[230:233], v[64:67]
	v_mfma_f32_16x16x32_bf16 v[68:71], v[194:197], v[230:233], v[68:71]
	s_setprio 0
	s_barrier
	v_lshl_add_u64 v[236:237], v[152:153], 0, s[64:65]
	s_mov_b32 m0, s79
	v_lshl_add_u64 v[186:187], v[236:237], 0, s[14:15]
	v_lshl_add_u64 v[238:239], v[154:155], 0, s[64:65]
	ds_read_b128 v[198:201], v161 offset:16384
	ds_read_b128 v[202:205], v161 offset:17408
	ds_read_b128 v[206:209], v161 offset:18432
	ds_read_b128 v[214:217], v161 offset:19456
	ds_read_b128 v[218:221], v161 offset:20480
	ds_read_b128 v[222:225], v161 offset:21504
	ds_read_b128 v[226:229], v161 offset:22528
	ds_read_b128 v[230:233], v161 offset:23552
	global_load_lds_dwordx4 v[186:187], off
	v_lshl_add_u64 v[186:187], v[238:239], 0, s[14:15]
	s_mov_b32 m0, s80
	s_add_i32 s0, s74, s23
	global_load_lds_dwordx4 v[186:187], off
	v_lshl_add_u64 v[186:187], v[236:237], 0, s[36:37]
	s_mov_b32 m0, s0
	s_add_i32 s1, s0, 0x2000
	global_load_lds_dwordx4 v[186:187], off
	v_lshl_add_u64 v[186:187], v[238:239], 0, s[36:37]
	s_mov_b32 m0, s1
	s_nop 0
	global_load_lds_dwordx4 v[186:187], off
	v_lshl_add_u64 v[186:187], v[210:211], 0, s[14:15]
	s_mov_b32 m0, s28
	s_nop 0
	global_load_lds_dwordx4 v[186:187], off
	v_lshl_add_u64 v[186:187], v[234:235], 0, s[14:15]
	s_mov_b32 m0, s29
	s_nop 0
	global_load_lds_dwordx4 v[186:187], off
	s_waitcnt vmcnt(8)
	s_waitcnt lgkmcnt(0)
	s_setprio 1
	s_barrier
	s_waitcnt lgkmcnt(0)
	v_mfma_f32_16x16x32_bf16 v[60:63], v[162:165], v[198:201], v[60:63]
	v_mfma_f32_16x16x32_bf16 v[56:59], v[170:173], v[198:201], v[56:59]
	v_mfma_f32_16x16x32_bf16 v[44:47], v[162:165], v[206:209], v[44:47]
	v_mfma_f32_16x16x32_bf16 v[40:43], v[170:173], v[206:209], v[40:43]
	v_mfma_f32_16x16x32_bf16 v[28:31], v[162:165], v[218:221], v[28:31]
	v_mfma_f32_16x16x32_bf16 v[24:27], v[170:173], v[218:221], v[24:27]
	v_mfma_f32_16x16x32_bf16 v[12:15], v[162:165], v[226:229], v[12:15]
	v_mfma_f32_16x16x32_bf16 v[8:11], v[170:173], v[226:229], v[8:11]
	v_mfma_f32_16x16x32_bf16 v[60:63], v[166:169], v[202:205], v[60:63]
	v_mfma_f32_16x16x32_bf16 v[56:59], v[174:177], v[202:205], v[56:59]
	v_mfma_f32_16x16x32_bf16 v[44:47], v[166:169], v[214:217], v[44:47]
	v_mfma_f32_16x16x32_bf16 v[40:43], v[174:177], v[214:217], v[40:43]
	v_mfma_f32_16x16x32_bf16 v[28:31], v[166:169], v[222:225], v[28:31]
	v_mfma_f32_16x16x32_bf16 v[24:27], v[174:177], v[222:225], v[24:27]
	v_mfma_f32_16x16x32_bf16 v[12:15], v[166:169], v[230:233], v[12:15]
	v_mfma_f32_16x16x32_bf16 v[8:11], v[174:177], v[230:233], v[8:11]
	s_setprio 0
	s_setprio 1
	v_mfma_f32_16x16x32_bf16 v[52:55], v[178:181], v[198:201], v[52:55]
	v_mfma_f32_16x16x32_bf16 v[48:51], v[190:193], v[198:201], v[48:51]
	v_mfma_f32_16x16x32_bf16 v[36:39], v[178:181], v[206:209], v[36:39]
	v_mfma_f32_16x16x32_bf16 v[32:35], v[190:193], v[206:209], v[32:35]
	v_mfma_f32_16x16x32_bf16 v[20:23], v[178:181], v[218:221], v[20:23]
	v_mfma_f32_16x16x32_bf16 v[16:19], v[190:193], v[218:221], v[16:19]
	v_mfma_f32_16x16x32_bf16 v[4:7], v[178:181], v[226:229], v[4:7]
	v_mfma_f32_16x16x32_bf16 v[0:3], v[190:193], v[226:229], v[0:3]
	v_mfma_f32_16x16x32_bf16 v[52:55], v[182:185], v[202:205], v[52:55]
	v_mfma_f32_16x16x32_bf16 v[48:51], v[194:197], v[202:205], v[48:51]
	v_mfma_f32_16x16x32_bf16 v[36:39], v[182:185], v[214:217], v[36:39]
	v_mfma_f32_16x16x32_bf16 v[32:35], v[194:197], v[214:217], v[32:35]
	v_mfma_f32_16x16x32_bf16 v[20:23], v[182:185], v[222:225], v[20:23]
	v_mfma_f32_16x16x32_bf16 v[16:19], v[194:197], v[222:225], v[16:19]
	v_mfma_f32_16x16x32_bf16 v[4:7], v[182:185], v[230:233], v[4:7]
	v_mfma_f32_16x16x32_bf16 v[0:3], v[194:197], v[230:233], v[0:3]
	s_setprio 0
	s_barrier
; #define PG8_STAGE(bufoff, gbase, voff) do { _Pragma("unroll") for (int _i = 0; _i < 2; ++_i) \
;         __builtin_amdgcn_global_load_lds((const unsigned*)((const char*)(gbase) + (voff)[_i]), (PG8_LAS unsigned*)(lds + (bufoff) + ldsw + _i * 8192), 16, 0, 0); } while (0)
; #define PG8_LDA(dst, b, h) do { _Pragma("unroll") for (int m = 0; m < 4; ++m) _Pragma("unroll") for (int k = 0; k < 2; ++k) dst[m][k] = *(const PG8_LAS bf16x8*)(lds + PG8_SA(b, h) + aoff + m * 2048 + k * 1024); } while (0)
; #define PG8_LDB(dst, b, h) do { _Pragma("unroll") for (int n = 0; n < 2; ++n) _Pragma("unroll") for (int k = 0; k < 2; ++k) dst[n][k] = *(const PG8_LAS bf16x8*)(lds + PG8_SB(b, h) + boff + n * 2048 + k * 1024); } while (0)
; #define PG8_MMA(ai, bj, At, Bt) do { __builtin_amdgcn_s_setprio(1); _Pragma("unroll") for (int m = 0; m < 4; ++m) _Pragma("unroll") for (int n = 0; n < 2; ++n) _Pragma("unroll") for (int k = 0; k < 2; ++k) \
;         acc[ai][bj][m][n] = __builtin_amdgcn_mfma_f32_16x16x32_bf16(Bt[n][k], At[m][k], acc[ai][bj][m][n], 0, 0, 0); __builtin_amdgcn_s_setprio(0); } while (0)
; #define PG8_WAIT_V(n) asm volatile("s_waitcnt vmcnt(" #n ")" ::: "memory")
; #define PG8_WAIT_L(n) asm volatile("s_waitcnt lgkmcnt(" #n ")" ::: "memory")
; #define PG8_BAR __builtin_amdgcn_s_barrier()
; #define PG8_SCHED __builtin_amdgcn_sched_barrier(0)
; template <class Epi, class Sched, bool ALIGN_EPI = false, bool SP2 = false>
; __device__ __forceinline__ void gemm_phase(PG8_LAS unsigned char* lds, const Gemm g, const Sched& S, const Epi& E) {
;     ...
;             PG8_LDB(B0, 1, 0); PG8_LDB(B1, 1, 1); PG8_SCHED; PG8_LDA(At, 1, 0); PG8_STAGE(PG8_SA(0, 1), a2 + hstep, voffA);
;             PG8_WAIT_V(8); PG8_WAIT_L(0); PG8_BAR; PG8_MMA(0, 0, At, B0); PG8_MMA(0, 1, At, B1); PG8_BAR; PG8_SCHED;
;             PG8_LDA(At, 1, 1); PG8_STAGE(PG8_SB(1, 0), b3, voffB); PG8_STAGE(PG8_SB(1, 1), b3 + hstep, voffB); PG8_STAGE(PG8_SA(1, 0), a3, voffA);
;             PG8_WAIT_V(8); PG8_WAIT_L(0); PG8_BAR; PG8_MMA(1, 0, At, B0); PG8_MMA(1, 1, At, B1); PG8_BAR; PG8_SCHED;
	v_add_u32_e32 v162, s75, v157
	v_add_u32_e32 v163, s84, v157
	ds_read_b128 v[164:167], v162
	ds_read_b128 v[168:171], v162 offset:1024
	ds_read_b128 v[172:175], v162 offset:2048
	ds_read_b128 v[176:179], v162 offset:3072
	ds_read_b128 v[180:183], v163
	ds_read_b128 v[184:187], v163 offset:1024
	ds_read_b128 v[190:193], v163 offset:2048
	ds_read_b128 v[194:197], v163 offset:3072
	s_mov_b32 m0, s30
	v_lshl_add_u64 v[240:241], v[210:211], 0, s[36:37]
	ds_read_b128 v[198:201], v161 offset:32768
	ds_read_b128 v[202:205], v161 offset:33792
	ds_read_b128 v[206:209], v161 offset:34816
	ds_read_b128 v[214:217], v161 offset:35840
	ds_read_b128 v[218:221], v161 offset:36864
	ds_read_b128 v[222:225], v161 offset:37888
	ds_read_b128 v[226:229], v161 offset:38912
	ds_read_b128 v[230:233], v161 offset:39936
	global_load_lds_dwordx4 v[240:241], off
	v_lshl_add_u64 v[240:241], v[234:235], 0, s[36:37]
	s_mov_b32 m0, s33
	s_nop 0
	global_load_lds_dwordx4 v[240:241], off
	s_waitcnt vmcnt(8)
	s_waitcnt lgkmcnt(0)
	s_setprio 1
	s_barrier
	s_waitcnt lgkmcnt(0)
	v_mfma_f32_16x16x32_bf16 v[124:127], v[164:167], v[198:201], v[124:127]
	v_mfma_f32_16x16x32_bf16 v[120:123], v[172:175], v[198:201], v[120:123]
	v_mfma_f32_16x16x32_bf16 v[116:119], v[164:167], v[206:209], v[116:119]
	v_mfma_f32_16x16x32_bf16 v[112:115], v[172:175], v[206:209], v[112:115]
	v_mfma_f32_16x16x32_bf16 v[108:111], v[164:167], v[218:221], v[108:111]
	v_mfma_f32_16x16x32_bf16 v[104:107], v[172:175], v[218:221], v[104:107]
	v_mfma_f32_16x16x32_bf16 v[100:103], v[164:167], v[226:229], v[100:103]
	v_mfma_f32_16x16x32_bf16 v[96:99], v[172:175], v[226:229], v[96:99]
	v_mfma_f32_16x16x32_bf16 v[124:127], v[168:171], v[202:205], v[124:127]
	v_mfma_f32_16x16x32_bf16 v[120:123], v[176:179], v[202:205], v[120:123]
	v_mfma_f32_16x16x32_bf16 v[116:119], v[168:171], v[214:217], v[116:119]
	v_mfma_f32_16x16x32_bf16 v[112:115], v[176:179], v[214:217], v[112:115]
	v_mfma_f32_16x16x32_bf16 v[108:111], v[168:171], v[222:225], v[108:111]
	v_mfma_f32_16x16x32_bf16 v[104:107], v[176:179], v[222:225], v[104:107]
	v_mfma_f32_16x16x32_bf16 v[100:103], v[168:171], v[230:233], v[100:103]
	v_mfma_f32_16x16x32_bf16 v[96:99], v[176:179], v[230:233], v[96:99]
	s_setprio 0
	s_setprio 1
	v_mfma_f32_16x16x32_bf16 v[88:91], v[180:183], v[198:201], v[88:91]
	v_mfma_f32_16x16x32_bf16 v[92:95], v[190:193], v[198:201], v[92:95]
	v_mfma_f32_16x16x32_bf16 v[80:83], v[180:183], v[206:209], v[80:83]
	v_mfma_f32_16x16x32_bf16 v[84:87], v[190:193], v[206:209], v[84:87]
	v_mfma_f32_16x16x32_bf16 v[72:75], v[180:183], v[218:221], v[72:75]
	v_mfma_f32_16x16x32_bf16 v[76:79], v[190:193], v[218:221], v[76:79]
	v_mfma_f32_16x16x32_bf16 v[64:67], v[180:183], v[226:229], v[64:67]
	v_mfma_f32_16x16x32_bf16 v[68:71], v[190:193], v[226:229], v[68:71]
	v_mfma_f32_16x16x32_bf16 v[88:91], v[184:187], v[202:205], v[88:91]
	v_mfma_f32_16x16x32_bf16 v[92:95], v[194:197], v[202:205], v[92:95]
	v_mfma_f32_16x16x32_bf16 v[80:83], v[184:187], v[214:217], v[80:83]
	v_mfma_f32_16x16x32_bf16 v[84:87], v[194:197], v[214:217], v[84:87]
	v_mfma_f32_16x16x32_bf16 v[72:75], v[184:187], v[222:225], v[72:75]
	v_mfma_f32_16x16x32_bf16 v[76:79], v[194:197], v[222:225], v[76:79]
	v_mfma_f32_16x16x32_bf16 v[64:67], v[184:187], v[230:233], v[64:67]
	v_mfma_f32_16x16x32_bf16 v[68:71], v[194:197], v[230:233], v[68:71]
	s_setprio 0
	s_barrier
	s_add_i32 s82, s75, s23
	v_lshl_add_u64 v[240:241], v[236:237], 0, s[40:41]
	s_mov_b32 m0, s82
	s_add_i32 s83, s82, 0x2000
	ds_read_b128 v[198:201], v161 offset:49152
	ds_read_b128 v[202:205], v161 offset:50176
	ds_read_b128 v[206:209], v161 offset:51200
	ds_read_b128 v[214:217], v161 offset:52224
	ds_read_b128 v[218:221], v161 offset:53248
	ds_read_b128 v[222:225], v161 offset:54272
	ds_read_b128 v[226:229], v161 offset:55296
	ds_read_b128 v[230:233], v161 offset:56320
	global_load_lds_dwordx4 v[240:241], off
	v_lshl_add_u64 v[240:241], v[238:239], 0, s[40:41]
	s_mov_b32 m0, s83
	s_add_i32 s85, s84, s23
	global_load_lds_dwordx4 v[240:241], off
	v_lshl_add_u64 v[236:237], v[236:237], 0, s[46:47]
	s_mov_b32 m0, s85
	s_add_i32 s86, s85, 0x2000
	global_load_lds_dwordx4 v[236:237], off
	v_lshl_add_u64 v[236:237], v[238:239], 0, s[46:47]
	s_mov_b32 m0, s86
	v_lshl_add_u64 v[210:211], v[210:211], 0, s[40:41]
	global_load_lds_dwordx4 v[236:237], off
	s_mov_b32 m0, s71
	s_nop 0
	global_load_lds_dwordx4 v[210:211], off
	v_lshl_add_u64 v[210:211], v[234:235], 0, s[40:41]
	s_mov_b32 m0, s76
	s_nop 0
	global_load_lds_dwordx4 v[210:211], off
	s_waitcnt vmcnt(8)
	s_waitcnt lgkmcnt(0)
	s_setprio 1
	s_barrier
; __device__ __forceinline__ float bflo(unsigned w) { return __uint_as_float(w << 16); }
; __device__ __forceinline__ float bfhi(unsigned w) { return __uint_as_float(w & 0xffff0000u); }
; #define PG8_STAGE(bufoff, gbase, voff) do { _Pragma("unroll") for (int _i = 0; _i < 2; ++_i) \
;         __builtin_amdgcn_global_load_lds((const unsigned*)((const char*)(gbase) + (voff)[_i]), (PG8_LAS unsigned*)(lds + (bufoff) + ldsw + _i * 8192), 16, 0, 0); } while (0)
; #define PG8_LDA(dst, b, h) do { _Pragma("unroll") for (int m = 0; m < 4; ++m) _Pragma("unroll") for (int k = 0; k < 2; ++k) dst[m][k] = *(const PG8_LAS bf16x8*)(lds + PG8_SA(b, h) + aoff + m * 2048 + k * 1024); } while (0)
; #define PG8_WAIT_V(n) asm volatile("s_waitcnt vmcnt(" #n ")" ::: "memory")
;     __device__ __forceinline__ void mid(f32x4 (&acc)[2][2][4][2], const Unit& u, int wr, int wc, int fr, int fq) const {
;         int row0 = u.pm * BM + wr * 64 + fr, col0 = u.pn * BM + wc * 32 + 8 * fq;
;         asm volatile("" : "+v"(row0), "+v"(col0) :: "memory");
; #pragma unroll
;         for (int ai = 0; ai < 2; ++ai)
; #pragma unroll
;             for (int m = 0; m < 4; ++m) {
;                 int roff = row0 + ai * HALF + m * 16; asm volatile("" : "+v"(roff) :: "memory"); const bf16_t* gp = gates + (size_t)roff * 4096 + col0;
; #pragma unroll
;                 for (int bj = 0; bj < 2; ++bj) { const u32x4 a = __builtin_nontemporal_load((const u32x4*)(gp + bj * HALF));
;                     f32x4 r0, r1;
;                     r0[0] = bflo(a[0]); r0[1] = bfhi(a[0]); r0[2] = bflo(a[1]); r0[3] = bfhi(a[1]); r1[0] = bflo(a[2]); r1[1] = bfhi(a[2]); r1[2] = bflo(a[3]); r1[3] = bfhi(a[3]);
;                     acc[ai][bj][m][0] = acc[ai][bj][m][0] * r0; acc[ai][bj][m][1] = acc[ai][bj][m][1] * r1; }
; template <class Epi, class Sched, bool ALIGN_EPI = false, bool SP2 = false>
; __device__ __forceinline__ void gemm_phase(PG8_LAS unsigned char* lds, const Gemm g, const Sched& S, const Epi& E) {
;     ...
;             PG8_WAIT_V(8); PG8_WAIT_L(0); PG8_BAR; PG8_MMA(0, 0, At, B0); PG8_MMA(0, 1, At, B1); PG8_BAR; PG8_SCHED;
;             PG8_LDA(At, 1, 1); PG8_STAGE(PG8_SB(1, 0), b3, voffB); PG8_STAGE(PG8_SB(1, 1), b3 + hstep, voffB); PG8_STAGE(PG8_SA(1, 0), a3, voffA);
;             PG8_WAIT_V(8); PG8_WAIT_L(0); PG8_BAR; PG8_MMA(1, 0, At, B0); PG8_MMA(1, 1, At, B1); PG8_BAR; PG8_SCHED;
	s_waitcnt lgkmcnt(0)
	v_mfma_f32_16x16x32_bf16 v[60:63], v[164:167], v[198:201], v[60:63]
	v_mfma_f32_16x16x32_bf16 v[56:59], v[172:175], v[198:201], v[56:59]
	v_mfma_f32_16x16x32_bf16 v[44:47], v[164:167], v[206:209], v[44:47]
	v_mfma_f32_16x16x32_bf16 v[40:43], v[172:175], v[206:209], v[40:43]
	v_mfma_f32_16x16x32_bf16 v[28:31], v[164:167], v[218:221], v[28:31]
	v_mfma_f32_16x16x32_bf16 v[24:27], v[172:175], v[218:221], v[24:27]
	v_mfma_f32_16x16x32_bf16 v[12:15], v[164:167], v[226:229], v[12:15]
	v_mfma_f32_16x16x32_bf16 v[8:11], v[172:175], v[226:229], v[8:11]
	v_mfma_f32_16x16x32_bf16 v[60:63], v[168:171], v[202:205], v[60:63]
	v_mfma_f32_16x16x32_bf16 v[56:59], v[176:179], v[202:205], v[56:59]
	v_mfma_f32_16x16x32_bf16 v[44:47], v[168:171], v[214:217], v[44:47]
	v_mfma_f32_16x16x32_bf16 v[40:43], v[176:179], v[214:217], v[40:43]
	v_mfma_f32_16x16x32_bf16 v[28:31], v[168:171], v[222:225], v[28:31]
	v_mfma_f32_16x16x32_bf16 v[24:27], v[176:179], v[222:225], v[24:27]
	v_mfma_f32_16x16x32_bf16 v[12:15], v[168:171], v[230:233], v[12:15]
	v_mfma_f32_16x16x32_bf16 v[8:11], v[176:179], v[230:233], v[8:11]
	s_setprio 0
	s_setprio 1
	v_mfma_f32_16x16x32_bf16 v[52:55], v[180:183], v[198:201], v[52:55]
	v_mfma_f32_16x16x32_bf16 v[48:51], v[190:193], v[198:201], v[48:51]
	v_mfma_f32_16x16x32_bf16 v[36:39], v[180:183], v[206:209], v[36:39]
	v_mfma_f32_16x16x32_bf16 v[32:35], v[190:193], v[206:209], v[32:35]
	v_mfma_f32_16x16x32_bf16 v[20:23], v[180:183], v[218:221], v[20:23]
	v_mfma_f32_16x16x32_bf16 v[16:19], v[190:193], v[218:221], v[16:19]
	v_mfma_f32_16x16x32_bf16 v[4:7], v[180:183], v[226:229], v[4:7]
	v_mfma_f32_16x16x32_bf16 v[0:3], v[190:193], v[226:229], v[0:3]
	v_mfma_f32_16x16x32_bf16 v[52:55], v[184:187], v[202:205], v[52:55]
	v_mfma_f32_16x16x32_bf16 v[48:51], v[194:197], v[202:205], v[48:51]
	v_mfma_f32_16x16x32_bf16 v[36:39], v[184:187], v[214:217], v[36:39]
	v_mfma_f32_16x16x32_bf16 v[32:35], v[194:197], v[214:217], v[32:35]
	v_mfma_f32_16x16x32_bf16 v[20:23], v[184:187], v[222:225], v[20:23]
	v_mfma_f32_16x16x32_bf16 v[16:19], v[194:197], v[222:225], v[16:19]
	v_mfma_f32_16x16x32_bf16 v[4:7], v[184:187], v[230:233], v[4:7]
	v_mfma_f32_16x16x32_bf16 v[0:3], v[194:197], v[230:233], v[0:3]
	s_setprio 0
	s_barrier
	s_add_i32 s59, s59, 2
	s_add_u32 s64, s64, 0x100
	s_addc_u32 s65, s65, 0
	s_cmp_gt_u32 s59, 13
	s_cbranch_scc0 .LBB0_703
	v_lshl_add_u32 v148, s68, 8, v156
	v_lshl_or_b32 v150, s57, 8, v158
	v_ashrrev_i32_e32 v153, 31, v148
	v_mov_b32_e32 v152, v148
	v_ashrrev_i32_e32 v155, 31, v150
	v_mov_b32_e32 v154, v150
	v_lshlrev_b64 v[152:153], 13, v[152:153]
	v_lshlrev_b64 v[154:155], 1, v[154:155]
	v_lshl_add_u64 v[152:153], s[18:19], 0, v[152:153]
	v_lshl_add_u64 v[152:153], v[152:153], 0, v[154:155]
	s_mov_b64 s[64:65], 0x20000
	s_mov_b64 s[66:67], 0xa0000
	global_load_dwordx4 v[164:167], v[152:153], off nt
	global_load_dwordx4 v[168:171], v[152:153], off offset:256 nt
	v_lshl_add_u64 v[152:153], v[152:153], 0, s[64:65]
	global_load_dwordx4 v[172:175], v[152:153], off nt
	global_load_dwordx4 v[176:179], v[152:153], off offset:256 nt
	v_lshl_add_u64 v[152:153], v[152:153], 0, s[64:65]
	global_load_dwordx4 v[180:183], v[152:153], off nt
	global_load_dwordx4 v[184:187], v[152:153], off offset:256 nt
	v_lshl_add_u64 v[152:153], v[152:153], 0, s[64:65]
	global_load_dwordx4 v[190:193], v[152:153], off nt
	global_load_dwordx4 v[194:197], v[152:153], off offset:256 nt
	v_lshl_add_u64 v[152:153], v[152:153], 0, s[66:67]
	global_load_dwordx4 v[198:201], v[152:153], off nt
	global_load_dwordx4 v[202:205], v[152:153], off offset:256 nt
	v_lshl_add_u64 v[152:153], v[152:153], 0, s[64:65]
	global_load_dwordx4 v[206:209], v[152:153], off nt
	global_load_dwordx4 v[214:217], v[152:153], off offset:256 nt
	v_lshl_add_u64 v[152:153], v[152:153], 0, s[64:65]
	global_load_dwordx4 v[218:221], v[152:153], off nt
	global_load_dwordx4 v[222:225], v[152:153], off offset:256 nt
	v_lshl_add_u64 v[152:153], v[152:153], 0, s[64:65]
	global_load_dwordx4 v[226:229], v[152:153], off nt
	global_load_dwordx4 v[230:233], v[152:153], off offset:256 nt
	s_ashr_i32 s59, s58, 31
	s_lshl_b64 s[64:65], s[58:59], 20
	s_add_u32 s64, s72, s64
	s_addc_u32 s65, s73, s65
	s_ashr_i32 s57, s56, 31
	s_lshl_b64 s[66:67], s[56:57], 20
	s_add_u32 s66, s88, s66
	s_addc_u32 s67, s89, s67
	s_and_b64 s[68:69], s[2:3], exec
	s_cselect_b32 s57, s65, s63
	s_cselect_b32 s59, s64, s62
	s_cselect_b32 s87, s67, s61
	s_cselect_b32 s90, s66, s60
	s_waitcnt vmcnt(15)
	v_lshlrev_b32_e32 v234, 16, v164
	v_and_b32_e32 v235, 0xffff0000, v164
	v_lshlrev_b32_e32 v164, 16, v165
	v_and_b32_e32 v165, 0xffff0000, v165
	v_lshlrev_b32_e32 v236, 16, v166
	v_and_b32_e32 v237, 0xffff0000, v166
	v_lshlrev_b32_e32 v166, 16, v167
	v_and_b32_e32 v167, 0xffff0000, v167
	v_pk_mul_f32 v[124:125], v[124:125], v[234:235]
	v_pk_mul_f32 v[126:127], v[126:127], v[164:165]
	v_pk_mul_f32 v[120:121], v[120:121], v[236:237]
	v_pk_mul_f32 v[122:123], v[122:123], v[166:167]
	s_waitcnt vmcnt(14)
	v_lshlrev_b32_e32 v238, 16, v168
	v_and_b32_e32 v239, 0xffff0000, v168
	v_lshlrev_b32_e32 v168, 16, v169
	v_and_b32_e32 v169, 0xffff0000, v169
	v_lshlrev_b32_e32 v240, 16, v170
	v_and_b32_e32 v241, 0xffff0000, v170
	v_lshlrev_b32_e32 v170, 16, v171
	v_and_b32_e32 v171, 0xffff0000, v171
	v_pk_mul_f32 v[88:89], v[88:89], v[238:239]
	v_pk_mul_f32 v[90:91], v[90:91], v[168:169]
	v_pk_mul_f32 v[92:93], v[92:93], v[240:241]
	v_pk_mul_f32 v[94:95], v[94:95], v[170:171]
	s_waitcnt vmcnt(13)
; __device__ __forceinline__ float bflo(unsigned w) { return __uint_as_float(w << 16); }
; __device__ __forceinline__ float bfhi(unsigned w) { return __uint_as_float(w & 0xffff0000u); }
;     __device__ __forceinline__ void mid(f32x4 (&acc)[2][2][4][2], const Unit& u, int wr, int wc, int fr, int fq) const {
;     ...
;                 int roff = row0 + ai * HALF + m * 16; asm volatile("" : "+v"(roff) :: "memory"); const bf16_t* gp = gates + (size_t)roff * 4096 + col0;
; #pragma unroll
;                 for (int bj = 0; bj < 2; ++bj) { const u32x4 a = __builtin_nontemporal_load((const u32x4*)(gp + bj * HALF));
;                     f32x4 r0, r1;
;                     r0[0] = bflo(a[0]); r0[1] = bfhi(a[0]); r0[2] = bflo(a[1]); r0[3] = bfhi(a[1]); r1[0] = bflo(a[2]); r1[1] = bfhi(a[2]); r1[2] = bflo(a[3]); r1[3] = bfhi(a[3]);
;                     acc[ai][bj][m][0] = acc[ai][bj][m][0] * r0; acc[ai][bj][m][1] = acc[ai][bj][m][1] * r1; }
	v_lshlrev_b32_e32 v234, 16, v172
	v_and_b32_e32 v235, 0xffff0000, v172
	v_lshlrev_b32_e32 v172, 16, v173
	v_and_b32_e32 v173, 0xffff0000, v173
	v_lshlrev_b32_e32 v236, 16, v174
	v_and_b32_e32 v237, 0xffff0000, v174
	v_lshlrev_b32_e32 v174, 16, v175
	v_and_b32_e32 v175, 0xffff0000, v175
	v_pk_mul_f32 v[116:117], v[116:117], v[234:235]
	v_pk_mul_f32 v[118:119], v[118:119], v[172:173]
	v_pk_mul_f32 v[112:113], v[112:113], v[236:237]
	v_pk_mul_f32 v[114:115], v[114:115], v[174:175]
	s_waitcnt vmcnt(12)
	v_lshlrev_b32_e32 v238, 16, v176
	v_and_b32_e32 v239, 0xffff0000, v176
	v_lshlrev_b32_e32 v176, 16, v177
	v_and_b32_e32 v177, 0xffff0000, v177
	v_lshlrev_b32_e32 v240, 16, v178
	v_and_b32_e32 v241, 0xffff0000, v178
	v_lshlrev_b32_e32 v178, 16, v179
	v_and_b32_e32 v179, 0xffff0000, v179
	v_pk_mul_f32 v[80:81], v[80:81], v[238:239]
	v_pk_mul_f32 v[82:83], v[82:83], v[176:177]
	v_pk_mul_f32 v[84:85], v[84:85], v[240:241]
	v_pk_mul_f32 v[86:87], v[86:87], v[178:179]
	s_waitcnt vmcnt(11)
	v_lshlrev_b32_e32 v234, 16, v180
	v_and_b32_e32 v235, 0xffff0000, v180
	v_lshlrev_b32_e32 v180, 16, v181
	v_and_b32_e32 v181, 0xffff0000, v181
	v_lshlrev_b32_e32 v236, 16, v182
	v_and_b32_e32 v237, 0xffff0000, v182
	v_lshlrev_b32_e32 v182, 16, v183
	v_and_b32_e32 v183, 0xffff0000, v183
	v_pk_mul_f32 v[108:109], v[108:109], v[234:235]
	v_pk_mul_f32 v[110:111], v[110:111], v[180:181]
	v_pk_mul_f32 v[104:105], v[104:105], v[236:237]
	v_pk_mul_f32 v[106:107], v[106:107], v[182:183]
	s_waitcnt vmcnt(10)
	v_lshlrev_b32_e32 v238, 16, v184
	v_and_b32_e32 v239, 0xffff0000, v184
	v_lshlrev_b32_e32 v184, 16, v185
	v_and_b32_e32 v185, 0xffff0000, v185
	v_lshlrev_b32_e32 v240, 16, v186
	v_and_b32_e32 v241, 0xffff0000, v186
	v_lshlrev_b32_e32 v186, 16, v187
	v_and_b32_e32 v187, 0xffff0000, v187
	v_pk_mul_f32 v[72:73], v[72:73], v[238:239]
	v_pk_mul_f32 v[74:75], v[74:75], v[184:185]
	v_pk_mul_f32 v[76:77], v[76:77], v[240:241]
	v_pk_mul_f32 v[78:79], v[78:79], v[186:187]
	s_waitcnt vmcnt(9)
	v_lshlrev_b32_e32 v234, 16, v190
	v_and_b32_e32 v235, 0xffff0000, v190
	v_lshlrev_b32_e32 v190, 16, v191
	v_and_b32_e32 v191, 0xffff0000, v191
	v_lshlrev_b32_e32 v236, 16, v192
	v_and_b32_e32 v237, 0xffff0000, v192
	v_lshlrev_b32_e32 v192, 16, v193
	v_and_b32_e32 v193, 0xffff0000, v193
	v_pk_mul_f32 v[100:101], v[100:101], v[234:235]
	v_pk_mul_f32 v[102:103], v[102:103], v[190:191]
	v_pk_mul_f32 v[96:97], v[96:97], v[236:237]
	v_pk_mul_f32 v[98:99], v[98:99], v[192:193]
	s_waitcnt vmcnt(8)
	v_lshlrev_b32_e32 v238, 16, v194
	v_and_b32_e32 v239, 0xffff0000, v194
	v_lshlrev_b32_e32 v194, 16, v195
	v_and_b32_e32 v195, 0xffff0000, v195
	v_lshlrev_b32_e32 v240, 16, v196
	v_and_b32_e32 v241, 0xffff0000, v196
	v_lshlrev_b32_e32 v196, 16, v197
	v_and_b32_e32 v197, 0xffff0000, v197
	v_pk_mul_f32 v[64:65], v[64:65], v[238:239]
	v_pk_mul_f32 v[66:67], v[66:67], v[194:195]
	v_pk_mul_f32 v[68:69], v[68:69], v[240:241]
	v_pk_mul_f32 v[70:71], v[70:71], v[196:197]
	s_waitcnt vmcnt(7)
	v_lshlrev_b32_e32 v234, 16, v198
	v_and_b32_e32 v235, 0xffff0000, v198
	v_lshlrev_b32_e32 v198, 16, v199
	v_and_b32_e32 v199, 0xffff0000, v199
	v_lshlrev_b32_e32 v236, 16, v200
	v_and_b32_e32 v237, 0xffff0000, v200
	v_lshlrev_b32_e32 v200, 16, v201
	v_and_b32_e32 v201, 0xffff0000, v201
	v_pk_mul_f32 v[60:61], v[60:61], v[234:235]
	v_pk_mul_f32 v[62:63], v[62:63], v[198:199]
	v_pk_mul_f32 v[56:57], v[56:57], v[236:237]
	v_pk_mul_f32 v[58:59], v[58:59], v[200:201]
	s_waitcnt vmcnt(6)
	v_lshlrev_b32_e32 v238, 16, v202
	v_and_b32_e32 v239, 0xffff0000, v202
	v_lshlrev_b32_e32 v202, 16, v203
	v_and_b32_e32 v203, 0xffff0000, v203
	v_lshlrev_b32_e32 v240, 16, v204
	v_and_b32_e32 v241, 0xffff0000, v204
	v_lshlrev_b32_e32 v204, 16, v205
	v_and_b32_e32 v205, 0xffff0000, v205
	v_pk_mul_f32 v[52:53], v[52:53], v[238:239]
	v_pk_mul_f32 v[54:55], v[54:55], v[202:203]
	v_pk_mul_f32 v[48:49], v[48:49], v[240:241]
	v_pk_mul_f32 v[50:51], v[50:51], v[204:205]
	s_waitcnt vmcnt(5)
	v_lshlrev_b32_e32 v234, 16, v206
	v_and_b32_e32 v235, 0xffff0000, v206
	v_lshlrev_b32_e32 v206, 16, v207
	v_and_b32_e32 v207, 0xffff0000, v207
	v_lshlrev_b32_e32 v236, 16, v208
	v_and_b32_e32 v237, 0xffff0000, v208
	v_lshlrev_b32_e32 v208, 16, v209
	v_and_b32_e32 v209, 0xffff0000, v209
	v_pk_mul_f32 v[44:45], v[44:45], v[234:235]
	v_pk_mul_f32 v[46:47], v[46:47], v[206:207]
	v_pk_mul_f32 v[40:41], v[40:41], v[236:237]
	v_pk_mul_f32 v[42:43], v[42:43], v[208:209]
	s_waitcnt vmcnt(4)
	v_lshlrev_b32_e32 v238, 16, v214
	v_and_b32_e32 v239, 0xffff0000, v214
	v_lshlrev_b32_e32 v214, 16, v215
	v_and_b32_e32 v215, 0xffff0000, v215
	v_lshlrev_b32_e32 v240, 16, v216
	v_and_b32_e32 v241, 0xffff0000, v216
	v_lshlrev_b32_e32 v216, 16, v217
	v_and_b32_e32 v217, 0xffff0000, v217
	v_pk_mul_f32 v[36:37], v[36:37], v[238:239]
	v_pk_mul_f32 v[38:39], v[38:39], v[214:215]
	v_pk_mul_f32 v[32:33], v[32:33], v[240:241]
	v_pk_mul_f32 v[34:35], v[34:35], v[216:217]
	s_waitcnt vmcnt(3)
	v_lshlrev_b32_e32 v234, 16, v218
	v_and_b32_e32 v235, 0xffff0000, v218
	v_lshlrev_b32_e32 v218, 16, v219
	v_and_b32_e32 v219, 0xffff0000, v219
	v_lshlrev_b32_e32 v236, 16, v220
	v_and_b32_e32 v237, 0xffff0000, v220
	v_lshlrev_b32_e32 v220, 16, v221
	v_and_b32_e32 v221, 0xffff0000, v221
	v_pk_mul_f32 v[28:29], v[28:29], v[234:235]
	v_pk_mul_f32 v[30:31], v[30:31], v[218:219]
	v_pk_mul_f32 v[24:25], v[24:25], v[236:237]
	v_pk_mul_f32 v[26:27], v[26:27], v[220:221]
	s_waitcnt vmcnt(2)
	v_lshlrev_b32_e32 v238, 16, v222
	v_and_b32_e32 v239, 0xffff0000, v222
	v_lshlrev_b32_e32 v222, 16, v223
	v_and_b32_e32 v223, 0xffff0000, v223
	v_lshlrev_b32_e32 v240, 16, v224
	v_and_b32_e32 v241, 0xffff0000, v224
	v_lshlrev_b32_e32 v224, 16, v225
	v_and_b32_e32 v225, 0xffff0000, v225
	v_pk_mul_f32 v[20:21], v[20:21], v[238:239]
	v_pk_mul_f32 v[22:23], v[22:23], v[222:223]
	v_pk_mul_f32 v[16:17], v[16:17], v[240:241]
	v_pk_mul_f32 v[18:19], v[18:19], v[224:225]
	s_waitcnt vmcnt(1)
	v_lshlrev_b32_e32 v234, 16, v226
	v_and_b32_e32 v235, 0xffff0000, v226
	v_lshlrev_b32_e32 v226, 16, v227
	v_and_b32_e32 v227, 0xffff0000, v227
	v_lshlrev_b32_e32 v236, 16, v228
	v_and_b32_e32 v237, 0xffff0000, v228
	v_lshlrev_b32_e32 v228, 16, v229
	v_and_b32_e32 v229, 0xffff0000, v229
	v_pk_mul_f32 v[12:13], v[12:13], v[234:235]
	v_pk_mul_f32 v[14:15], v[14:15], v[226:227]
	v_pk_mul_f32 v[8:9], v[8:9], v[236:237]
	v_pk_mul_f32 v[10:11], v[10:11], v[228:229]
	s_waitcnt vmcnt(0)
	v_lshlrev_b32_e32 v238, 16, v230
	v_and_b32_e32 v239, 0xffff0000, v230
	v_lshlrev_b32_e32 v230, 16, v231
	v_and_b32_e32 v231, 0xffff0000, v231
	v_lshlrev_b32_e32 v240, 16, v232
	v_and_b32_e32 v241, 0xffff0000, v232
	v_lshlrev_b32_e32 v232, 16, v233
	v_and_b32_e32 v233, 0xffff0000, v233
	v_pk_mul_f32 v[4:5], v[4:5], v[238:239]
	v_pk_mul_f32 v[6:7], v[6:7], v[230:231]
	v_pk_mul_f32 v[0:1], v[0:1], v[240:241]
	v_pk_mul_f32 v[2:3], v[2:3], v[232:233]
	s_add_u32 s62, s62, 0x80880
	s_addc_u32 s63, s63, 0
	s_add_u32 s91, s60, 0x900
	s_addc_u32 s92, s61, 0
	s_mov_b32 s93, 14
; #define PG8_STAGE(bufoff, gbase, voff) do { _Pragma("unroll") for (int _i = 0; _i < 2; ++_i) \
;         __builtin_amdgcn_global_load_lds((const unsigned*)((const char*)(gbase) + (voff)[_i]), (PG8_LAS unsigned*)(lds + (bufoff) + ldsw + _i * 8192), 16, 0, 0); } while (0)
; #define PG8_LDA(dst, b, h) do { _Pragma("unroll") for (int m = 0; m < 4; ++m) _Pragma("unroll") for (int k = 0; k < 2; ++k) dst[m][k] = *(const PG8_LAS bf16x8*)(lds + PG8_SA(b, h) + aoff + m * 2048 + k * 1024); } while (0)
; #define PG8_LDB(dst, b, h) do { _Pragma("unroll") for (int n = 0; n < 2; ++n) _Pragma("unroll") for (int k = 0; k < 2; ++k) dst[n][k] = *(const PG8_LAS bf16x8*)(lds + PG8_SB(b, h) + boff + n * 2048 + k * 1024); } while (0)
; #define PG8_MMA(ai, bj, At, Bt) do { __builtin_amdgcn_s_setprio(1); _Pragma("unroll") for (int m = 0; m < 4; ++m) _Pragma("unroll") for (int n = 0; n < 2; ++n) _Pragma("unroll") for (int k = 0; k < 2; ++k) \
;         acc[ai][bj][m][n] = __builtin_amdgcn_mfma_f32_16x16x32_bf16(Bt[n][k], At[m][k], acc[ai][bj][m][n], 0, 0, 0); __builtin_amdgcn_s_setprio(0); } while (0)
; #define PG8_WAIT_V(n) asm volatile("s_waitcnt vmcnt(" #n ")" ::: "memory")
; #define PG8_WAIT_L(n) asm volatile("s_waitcnt lgkmcnt(" #n ")" ::: "memory")
; #define PG8_BAR __builtin_amdgcn_s_barrier()
; #define PG8_SCHED __builtin_amdgcn_sched_barrier(0)
; template <class Epi, class Sched, bool ALIGN_EPI = false, bool SP2 = false>
; __device__ __forceinline__ void gemm_phase(PG8_LAS unsigned char* lds, const Gemm g, const Sched& S, const Epi& E) {
;     ...
;             PG8_LDB(B0, 0, 0); PG8_LDB(B1, 0, 1); PG8_SCHED; PG8_LDA(At, 0, 0); PG8_STAGE(PG8_SA(1, 1), a1 + hstep, voffA);
;             PG8_WAIT_V(8); PG8_WAIT_L(0); PG8_BAR; PG8_MMA(0, 0, At, B0); PG8_MMA(0, 1, At, B1); PG8_BAR; PG8_SCHED;
;             PG8_LDA(At, 0, 1); PG8_STAGE(PG8_SB(0, 0), b2, voffB); PG8_STAGE(PG8_SB(0, 1), b2 + hstep, voffB); PG8_STAGE(PG8_SA(0, 0), a2, voffA);
;             PG8_WAIT_V(8); PG8_WAIT_L(0); PG8_BAR; PG8_MMA(1, 0, At, B0); PG8_MMA(1, 1, At, B1); PG8_BAR; PG8_SCHED;
.LBB0_705:
	ds_read_b128 v[152:155], v159
	ds_read_b128 v[164:167], v159 offset:1024
	ds_read_b128 v[168:171], v159 offset:2048
	ds_read_b128 v[172:175], v159 offset:3072
	ds_read_b128 v[176:179], v160
	ds_read_b128 v[180:183], v160 offset:1024
	ds_read_b128 v[184:187], v160 offset:2048
	ds_read_b128 v[190:193], v160 offset:3072
	s_add_u32 s60, s62, 0xfff80080
	s_addc_u32 s61, s63, -1
	s_cmp_eq_u32 s93, 28
	s_cselect_b32 s69, s57, s61
	s_cselect_b32 s68, s59, s60
	s_cselect_b32 s61, s87, s92
	s_cselect_b32 s60, s90, s91
	s_mov_b32 m0, s77
	v_lshl_add_u64 v[210:211], s[62:63], 0, v[136:137]
	ds_read_b128 v[194:197], v161
	ds_read_b128 v[198:201], v161 offset:1024
	ds_read_b128 v[202:205], v161 offset:2048
	ds_read_b128 v[206:209], v161 offset:3072
	ds_read_b128 v[214:217], v161 offset:4096
	ds_read_b128 v[218:221], v161 offset:5120
	ds_read_b128 v[222:225], v161 offset:6144
	ds_read_b128 v[226:229], v161 offset:7168
	global_load_lds_dwordx4 v[210:211], off
	v_lshl_add_u64 v[210:211], s[62:63], 0, v[132:133]
	s_mov_b32 m0, s78
	s_nop 0
	global_load_lds_dwordx4 v[210:211], off
	s_waitcnt vmcnt(8)
	s_waitcnt lgkmcnt(0)
	s_setprio 1
	s_barrier
	s_waitcnt lgkmcnt(0)
	v_mfma_f32_16x16x32_bf16 v[124:127], v[152:155], v[194:197], v[124:127]
	v_mfma_f32_16x16x32_bf16 v[120:123], v[168:171], v[194:197], v[120:123]
	v_mfma_f32_16x16x32_bf16 v[116:119], v[152:155], v[202:205], v[116:119]
	v_mfma_f32_16x16x32_bf16 v[112:115], v[168:171], v[202:205], v[112:115]
	v_mfma_f32_16x16x32_bf16 v[108:111], v[152:155], v[214:217], v[108:111]
	v_mfma_f32_16x16x32_bf16 v[104:107], v[168:171], v[214:217], v[104:107]
	v_mfma_f32_16x16x32_bf16 v[100:103], v[152:155], v[222:225], v[100:103]
	v_mfma_f32_16x16x32_bf16 v[96:99], v[168:171], v[222:225], v[96:99]
	v_mfma_f32_16x16x32_bf16 v[124:127], v[164:167], v[198:201], v[124:127]
	v_mfma_f32_16x16x32_bf16 v[120:123], v[172:175], v[198:201], v[120:123]
	v_mfma_f32_16x16x32_bf16 v[116:119], v[164:167], v[206:209], v[116:119]
	v_mfma_f32_16x16x32_bf16 v[112:115], v[172:175], v[206:209], v[112:115]
	v_mfma_f32_16x16x32_bf16 v[108:111], v[164:167], v[218:221], v[108:111]
	v_mfma_f32_16x16x32_bf16 v[104:107], v[172:175], v[218:221], v[104:107]
	v_mfma_f32_16x16x32_bf16 v[100:103], v[164:167], v[226:229], v[100:103]
	v_mfma_f32_16x16x32_bf16 v[96:99], v[172:175], v[226:229], v[96:99]
	s_setprio 0
	s_setprio 1
	v_mfma_f32_16x16x32_bf16 v[88:91], v[176:179], v[194:197], v[88:91]
	v_mfma_f32_16x16x32_bf16 v[92:95], v[184:187], v[194:197], v[92:95]
	v_mfma_f32_16x16x32_bf16 v[80:83], v[176:179], v[202:205], v[80:83]
	v_mfma_f32_16x16x32_bf16 v[84:87], v[184:187], v[202:205], v[84:87]
	v_mfma_f32_16x16x32_bf16 v[72:75], v[176:179], v[214:217], v[72:75]
	v_mfma_f32_16x16x32_bf16 v[76:79], v[184:187], v[214:217], v[76:79]
	v_mfma_f32_16x16x32_bf16 v[64:67], v[176:179], v[222:225], v[64:67]
	v_mfma_f32_16x16x32_bf16 v[68:71], v[184:187], v[222:225], v[68:71]
	v_mfma_f32_16x16x32_bf16 v[88:91], v[180:183], v[198:201], v[88:91]
	v_mfma_f32_16x16x32_bf16 v[92:95], v[190:193], v[198:201], v[92:95]
	v_mfma_f32_16x16x32_bf16 v[80:83], v[180:183], v[206:209], v[80:83]
	v_mfma_f32_16x16x32_bf16 v[84:87], v[190:193], v[206:209], v[84:87]
	v_mfma_f32_16x16x32_bf16 v[72:75], v[180:183], v[218:221], v[72:75]
	v_mfma_f32_16x16x32_bf16 v[76:79], v[190:193], v[218:221], v[76:79]
	v_mfma_f32_16x16x32_bf16 v[64:67], v[180:183], v[226:229], v[64:67]
	v_mfma_f32_16x16x32_bf16 v[68:71], v[190:193], v[226:229], v[68:71]
	s_setprio 0
	s_barrier
	s_mov_b32 m0, s79
	v_lshl_add_u64 v[210:211], s[60:61], 0, v[130:131]
	s_add_u32 s94, s60, 0x80000
	ds_read_b128 v[194:197], v161 offset:16384
	ds_read_b128 v[198:201], v161 offset:17408
	ds_read_b128 v[202:205], v161 offset:18432
	ds_read_b128 v[206:209], v161 offset:19456
	ds_read_b128 v[214:217], v161 offset:20480
	ds_read_b128 v[218:221], v161 offset:21504
	ds_read_b128 v[222:225], v161 offset:22528
	ds_read_b128 v[226:229], v161 offset:23552
	global_load_lds_dwordx4 v[210:211], off
	v_lshl_add_u64 v[230:231], s[60:61], 0, v[134:135]
	s_mov_b32 m0, s80
	s_addc_u32 s95, s61, 0
	global_load_lds_dwordx4 v[230:231], off
	v_lshl_add_u64 v[232:233], s[94:95], 0, v[130:131]
	s_mov_b32 m0, s0
	v_lshl_add_u64 v[234:235], s[68:69], 0, v[132:133]
	global_load_lds_dwordx4 v[232:233], off
	v_lshl_add_u64 v[232:233], s[94:95], 0, v[134:135]
	s_mov_b32 m0, s1
	s_nop 0
	global_load_lds_dwordx4 v[232:233], off
	v_lshl_add_u64 v[232:233], s[68:69], 0, v[128:129]
	s_mov_b32 m0, s28
	s_nop 0
	global_load_lds_dwordx4 v[232:233], off
	s_mov_b32 m0, s29
	s_nop 0
	global_load_lds_dwordx4 v[234:235], off
	s_waitcnt vmcnt(8)
	s_waitcnt lgkmcnt(0)
	s_setprio 1
	s_barrier
; #define PG8_STAGE(bufoff, gbase, voff) do { _Pragma("unroll") for (int _i = 0; _i < 2; ++_i) \
;         __builtin_amdgcn_global_load_lds((const unsigned*)((const char*)(gbase) + (voff)[_i]), (PG8_LAS unsigned*)(lds + (bufoff) + ldsw + _i * 8192), 16, 0, 0); } while (0)
; #define PG8_LDA(dst, b, h) do { _Pragma("unroll") for (int m = 0; m < 4; ++m) _Pragma("unroll") for (int k = 0; k < 2; ++k) dst[m][k] = *(const PG8_LAS bf16x8*)(lds + PG8_SA(b, h) + aoff + m * 2048 + k * 1024); } while (0)
; #define PG8_LDB(dst, b, h) do { _Pragma("unroll") for (int n = 0; n < 2; ++n) _Pragma("unroll") for (int k = 0; k < 2; ++k) dst[n][k] = *(const PG8_LAS bf16x8*)(lds + PG8_SB(b, h) + boff + n * 2048 + k * 1024); } while (0)
; #define PG8_MMA(ai, bj, At, Bt) do { __builtin_amdgcn_s_setprio(1); _Pragma("unroll") for (int m = 0; m < 4; ++m) _Pragma("unroll") for (int n = 0; n < 2; ++n) _Pragma("unroll") for (int k = 0; k < 2; ++k) \
;         acc[ai][bj][m][n] = __builtin_amdgcn_mfma_f32_16x16x32_bf16(Bt[n][k], At[m][k], acc[ai][bj][m][n], 0, 0, 0); __builtin_amdgcn_s_setprio(0); } while (0)
; #define PG8_WAIT_V(n) asm volatile("s_waitcnt vmcnt(" #n ")" ::: "memory")
; #define PG8_WAIT_L(n) asm volatile("s_waitcnt lgkmcnt(" #n ")" ::: "memory")
; #define PG8_BAR __builtin_amdgcn_s_barrier()
; #define PG8_SCHED __builtin_amdgcn_sched_barrier(0)
; template <class Epi, class Sched, bool ALIGN_EPI = false, bool SP2 = false>
; __device__ __forceinline__ void gemm_phase(PG8_LAS unsigned char* lds, const Gemm g, const Sched& S, const Epi& E) {
;     ...
;             PG8_WAIT_V(8); PG8_WAIT_L(0); PG8_BAR; PG8_MMA(1, 0, At, B0); PG8_MMA(1, 1, At, B1); PG8_BAR; PG8_SCHED;
;             PG8_LDB(B0, 1, 0); PG8_LDB(B1, 1, 1); PG8_SCHED; PG8_LDA(At, 1, 0); PG8_STAGE(PG8_SA(0, 1), a2 + hstep, voffA);
;             PG8_WAIT_V(8); PG8_WAIT_L(0); PG8_BAR; PG8_MMA(0, 0, At, B0); PG8_MMA(0, 1, At, B1); PG8_BAR; PG8_SCHED;
	s_waitcnt lgkmcnt(0)
	v_mfma_f32_16x16x32_bf16 v[60:63], v[152:155], v[194:197], v[60:63]
	v_mfma_f32_16x16x32_bf16 v[56:59], v[168:171], v[194:197], v[56:59]
	v_mfma_f32_16x16x32_bf16 v[44:47], v[152:155], v[202:205], v[44:47]
	v_mfma_f32_16x16x32_bf16 v[40:43], v[168:171], v[202:205], v[40:43]
	v_mfma_f32_16x16x32_bf16 v[28:31], v[152:155], v[214:217], v[28:31]
	v_mfma_f32_16x16x32_bf16 v[24:27], v[168:171], v[214:217], v[24:27]
	v_mfma_f32_16x16x32_bf16 v[12:15], v[152:155], v[222:225], v[12:15]
	v_mfma_f32_16x16x32_bf16 v[8:11], v[168:171], v[222:225], v[8:11]
	v_mfma_f32_16x16x32_bf16 v[60:63], v[164:167], v[198:201], v[60:63]
	v_mfma_f32_16x16x32_bf16 v[56:59], v[172:175], v[198:201], v[56:59]
	v_mfma_f32_16x16x32_bf16 v[44:47], v[164:167], v[206:209], v[44:47]
	v_mfma_f32_16x16x32_bf16 v[40:43], v[172:175], v[206:209], v[40:43]
	v_mfma_f32_16x16x32_bf16 v[28:31], v[164:167], v[218:221], v[28:31]
	v_mfma_f32_16x16x32_bf16 v[24:27], v[172:175], v[218:221], v[24:27]
	v_mfma_f32_16x16x32_bf16 v[12:15], v[164:167], v[226:229], v[12:15]
	v_mfma_f32_16x16x32_bf16 v[8:11], v[172:175], v[226:229], v[8:11]
	s_setprio 0
	s_setprio 1
	v_mfma_f32_16x16x32_bf16 v[52:55], v[176:179], v[194:197], v[52:55]
	v_mfma_f32_16x16x32_bf16 v[48:51], v[184:187], v[194:197], v[48:51]
	v_mfma_f32_16x16x32_bf16 v[36:39], v[176:179], v[202:205], v[36:39]
	v_mfma_f32_16x16x32_bf16 v[32:35], v[184:187], v[202:205], v[32:35]
	v_mfma_f32_16x16x32_bf16 v[20:23], v[176:179], v[214:217], v[20:23]
	v_mfma_f32_16x16x32_bf16 v[16:19], v[184:187], v[214:217], v[16:19]
	v_mfma_f32_16x16x32_bf16 v[4:7], v[176:179], v[222:225], v[4:7]
	v_mfma_f32_16x16x32_bf16 v[0:3], v[184:187], v[222:225], v[0:3]
	v_mfma_f32_16x16x32_bf16 v[52:55], v[180:183], v[198:201], v[52:55]
	v_mfma_f32_16x16x32_bf16 v[48:51], v[190:193], v[198:201], v[48:51]
	v_mfma_f32_16x16x32_bf16 v[36:39], v[180:183], v[206:209], v[36:39]
	v_mfma_f32_16x16x32_bf16 v[32:35], v[190:193], v[206:209], v[32:35]
	v_mfma_f32_16x16x32_bf16 v[20:23], v[180:183], v[218:221], v[20:23]
	v_mfma_f32_16x16x32_bf16 v[16:19], v[190:193], v[218:221], v[16:19]
	v_mfma_f32_16x16x32_bf16 v[4:7], v[180:183], v[226:229], v[4:7]
	v_mfma_f32_16x16x32_bf16 v[0:3], v[190:193], v[226:229], v[0:3]
	s_setprio 0
	s_barrier
	ds_read_b128 v[152:155], v162
	ds_read_b128 v[164:167], v162 offset:1024
	ds_read_b128 v[168:171], v162 offset:2048
	ds_read_b128 v[172:175], v162 offset:3072
	ds_read_b128 v[176:179], v163
	ds_read_b128 v[180:183], v163 offset:1024
	ds_read_b128 v[184:187], v163 offset:2048
	ds_read_b128 v[190:193], v163 offset:3072
	s_add_u32 s68, s68, 0x80000
	s_addc_u32 s69, s69, 0
	s_mov_b32 m0, s30
	v_lshl_add_u64 v[236:237], s[68:69], 0, v[128:129]
	ds_read_b128 v[194:197], v161 offset:32768
	ds_read_b128 v[198:201], v161 offset:33792
	ds_read_b128 v[202:205], v161 offset:34816
	ds_read_b128 v[206:209], v161 offset:35840
	ds_read_b128 v[214:217], v161 offset:36864
	ds_read_b128 v[218:221], v161 offset:37888
	ds_read_b128 v[222:225], v161 offset:38912
	ds_read_b128 v[226:229], v161 offset:39936
	global_load_lds_dwordx4 v[236:237], off
	v_lshl_add_u64 v[236:237], s[68:69], 0, v[132:133]
	s_mov_b32 m0, s33
	s_nop 0
	global_load_lds_dwordx4 v[236:237], off
	s_waitcnt vmcnt(8)
	s_waitcnt lgkmcnt(0)
	s_setprio 1
	s_barrier
	s_waitcnt lgkmcnt(0)
	v_mfma_f32_16x16x32_bf16 v[124:127], v[152:155], v[194:197], v[124:127]
	v_mfma_f32_16x16x32_bf16 v[120:123], v[168:171], v[194:197], v[120:123]
	v_mfma_f32_16x16x32_bf16 v[116:119], v[152:155], v[202:205], v[116:119]
	v_mfma_f32_16x16x32_bf16 v[112:115], v[168:171], v[202:205], v[112:115]
	v_mfma_f32_16x16x32_bf16 v[108:111], v[152:155], v[214:217], v[108:111]
	v_mfma_f32_16x16x32_bf16 v[104:107], v[168:171], v[214:217], v[104:107]
	v_mfma_f32_16x16x32_bf16 v[100:103], v[152:155], v[222:225], v[100:103]
	v_mfma_f32_16x16x32_bf16 v[96:99], v[168:171], v[222:225], v[96:99]
	v_mfma_f32_16x16x32_bf16 v[124:127], v[164:167], v[198:201], v[124:127]
	v_mfma_f32_16x16x32_bf16 v[120:123], v[172:175], v[198:201], v[120:123]
	v_mfma_f32_16x16x32_bf16 v[116:119], v[164:167], v[206:209], v[116:119]
	v_mfma_f32_16x16x32_bf16 v[112:115], v[172:175], v[206:209], v[112:115]
	v_mfma_f32_16x16x32_bf16 v[108:111], v[164:167], v[218:221], v[108:111]
	v_mfma_f32_16x16x32_bf16 v[104:107], v[172:175], v[218:221], v[104:107]
	v_mfma_f32_16x16x32_bf16 v[100:103], v[164:167], v[226:229], v[100:103]
	v_mfma_f32_16x16x32_bf16 v[96:99], v[172:175], v[226:229], v[96:99]
	s_setprio 0
	s_setprio 1
	v_mfma_f32_16x16x32_bf16 v[88:91], v[176:179], v[194:197], v[88:91]
	v_mfma_f32_16x16x32_bf16 v[92:95], v[184:187], v[194:197], v[92:95]
	v_mfma_f32_16x16x32_bf16 v[80:83], v[176:179], v[202:205], v[80:83]
	v_mfma_f32_16x16x32_bf16 v[84:87], v[184:187], v[202:205], v[84:87]
	v_mfma_f32_16x16x32_bf16 v[72:75], v[176:179], v[214:217], v[72:75]
	v_mfma_f32_16x16x32_bf16 v[76:79], v[184:187], v[214:217], v[76:79]
	v_mfma_f32_16x16x32_bf16 v[64:67], v[176:179], v[222:225], v[64:67]
	v_mfma_f32_16x16x32_bf16 v[68:71], v[184:187], v[222:225], v[68:71]
	v_mfma_f32_16x16x32_bf16 v[88:91], v[180:183], v[198:201], v[88:91]
	v_mfma_f32_16x16x32_bf16 v[92:95], v[190:193], v[198:201], v[92:95]
	v_mfma_f32_16x16x32_bf16 v[80:83], v[180:183], v[206:209], v[80:83]
	v_mfma_f32_16x16x32_bf16 v[84:87], v[190:193], v[206:209], v[84:87]
	v_mfma_f32_16x16x32_bf16 v[72:75], v[180:183], v[218:221], v[72:75]
	v_mfma_f32_16x16x32_bf16 v[76:79], v[190:193], v[218:221], v[76:79]
	v_mfma_f32_16x16x32_bf16 v[64:67], v[180:183], v[226:229], v[64:67]
	v_mfma_f32_16x16x32_bf16 v[68:71], v[190:193], v[226:229], v[68:71]
	s_setprio 0
	s_barrier
; #define PG8_STAGE(bufoff, gbase, voff) do { _Pragma("unroll") for (int _i = 0; _i < 2; ++_i) \
;         __builtin_amdgcn_global_load_lds((const unsigned*)((const char*)(gbase) + (voff)[_i]), (PG8_LAS unsigned*)(lds + (bufoff) + ldsw + _i * 8192), 16, 0, 0); } while (0)
; #define PG8_LDA(dst, b, h) do { _Pragma("unroll") for (int m = 0; m < 4; ++m) _Pragma("unroll") for (int k = 0; k < 2; ++k) dst[m][k] = *(const PG8_LAS bf16x8*)(lds + PG8_SA(b, h) + aoff + m * 2048 + k * 1024); } while (0)
; #define PG8_MMA(ai, bj, At, Bt) do { __builtin_amdgcn_s_setprio(1); _Pragma("unroll") for (int m = 0; m < 4; ++m) _Pragma("unroll") for (int n = 0; n < 2; ++n) _Pragma("unroll") for (int k = 0; k < 2; ++k) \
;         acc[ai][bj][m][n] = __builtin_amdgcn_mfma_f32_16x16x32_bf16(Bt[n][k], At[m][k], acc[ai][bj][m][n], 0, 0, 0); __builtin_amdgcn_s_setprio(0); } while (0)
; #define PG8_WAIT_V(n) asm volatile("s_waitcnt vmcnt(" #n ")" ::: "memory")
; #define PG8_WAIT_L(n) asm volatile("s_waitcnt lgkmcnt(" #n ")" ::: "memory")
; #define PG8_BAR __builtin_amdgcn_s_barrier()
; #define PG8_SCHED __builtin_amdgcn_sched_barrier(0)
; template <class Epi, class Sched, bool ALIGN_EPI = false, bool SP2 = false>
; __device__ __forceinline__ void gemm_phase(PG8_LAS unsigned char* lds, const Gemm g, const Sched& S, const Epi& E) {
;     ...
;         for (int t = seg * tseg; t < (seg + 1) * tseg; t += 2) {
;     ...
;             PG8_LDA(At, 1, 1); PG8_STAGE(PG8_SB(1, 0), b3, voffB); PG8_STAGE(PG8_SB(1, 1), b3 + hstep, voffB); PG8_STAGE(PG8_SA(1, 0), a3, voffA);
;             PG8_WAIT_V(8); PG8_WAIT_L(0); PG8_BAR; PG8_MMA(1, 0, At, B0); PG8_MMA(1, 1, At, B1); PG8_BAR; PG8_SCHED;
;     ...
;         if constexpr (ALIGN_EPI) { if (wr == 0) PG8_BAR; }
	s_mov_b32 m0, s82
	v_lshl_add_u64 v[210:211], v[210:211], 0, s[8:9]
	s_add_u32 s60, s60, 0x80080
	ds_read_b128 v[194:197], v161 offset:49152
	ds_read_b128 v[198:201], v161 offset:50176
	ds_read_b128 v[202:205], v161 offset:51200
	ds_read_b128 v[206:209], v161 offset:52224
	ds_read_b128 v[214:217], v161 offset:53248
	ds_read_b128 v[218:221], v161 offset:54272
	ds_read_b128 v[222:225], v161 offset:55296
	ds_read_b128 v[226:229], v161 offset:56320
	global_load_lds_dwordx4 v[210:211], off
	v_lshl_add_u64 v[210:211], v[230:231], 0, s[8:9]
	s_mov_b32 m0, s83
	s_addc_u32 s61, s61, 0
	global_load_lds_dwordx4 v[210:211], off
	v_lshl_add_u64 v[210:211], s[60:61], 0, v[130:131]
	s_mov_b32 m0, s85
	s_nop 0
	global_load_lds_dwordx4 v[210:211], off
	v_lshl_add_u64 v[210:211], s[60:61], 0, v[134:135]
	s_mov_b32 m0, s86
	s_nop 0
	global_load_lds_dwordx4 v[210:211], off
	v_lshl_add_u64 v[210:211], v[232:233], 0, s[8:9]
	s_mov_b32 m0, s71
	s_nop 0
	global_load_lds_dwordx4 v[210:211], off
	v_lshl_add_u64 v[210:211], v[234:235], 0, s[8:9]
	s_mov_b32 m0, s76
	s_nop 0
	global_load_lds_dwordx4 v[210:211], off
	s_waitcnt vmcnt(8)
	s_waitcnt lgkmcnt(0)
	s_setprio 1
	s_barrier
	s_waitcnt lgkmcnt(0)
	v_mfma_f32_16x16x32_bf16 v[60:63], v[152:155], v[194:197], v[60:63]
	v_mfma_f32_16x16x32_bf16 v[56:59], v[168:171], v[194:197], v[56:59]
	v_mfma_f32_16x16x32_bf16 v[44:47], v[152:155], v[202:205], v[44:47]
	v_mfma_f32_16x16x32_bf16 v[40:43], v[168:171], v[202:205], v[40:43]
	v_mfma_f32_16x16x32_bf16 v[28:31], v[152:155], v[214:217], v[28:31]
	v_mfma_f32_16x16x32_bf16 v[24:27], v[168:171], v[214:217], v[24:27]
	v_mfma_f32_16x16x32_bf16 v[12:15], v[152:155], v[222:225], v[12:15]
	v_mfma_f32_16x16x32_bf16 v[8:11], v[168:171], v[222:225], v[8:11]
	v_mfma_f32_16x16x32_bf16 v[60:63], v[164:167], v[198:201], v[60:63]
	v_mfma_f32_16x16x32_bf16 v[56:59], v[172:175], v[198:201], v[56:59]
	v_mfma_f32_16x16x32_bf16 v[44:47], v[164:167], v[206:209], v[44:47]
	v_mfma_f32_16x16x32_bf16 v[40:43], v[172:175], v[206:209], v[40:43]
	v_mfma_f32_16x16x32_bf16 v[28:31], v[164:167], v[218:221], v[28:31]
	v_mfma_f32_16x16x32_bf16 v[24:27], v[172:175], v[218:221], v[24:27]
	v_mfma_f32_16x16x32_bf16 v[12:15], v[164:167], v[226:229], v[12:15]
	v_mfma_f32_16x16x32_bf16 v[8:11], v[172:175], v[226:229], v[8:11]
	s_setprio 0
	s_setprio 1
	v_mfma_f32_16x16x32_bf16 v[52:55], v[176:179], v[194:197], v[52:55]
	v_mfma_f32_16x16x32_bf16 v[48:51], v[184:187], v[194:197], v[48:51]
	v_mfma_f32_16x16x32_bf16 v[36:39], v[176:179], v[202:205], v[36:39]
	v_mfma_f32_16x16x32_bf16 v[32:35], v[184:187], v[202:205], v[32:35]
	v_mfma_f32_16x16x32_bf16 v[20:23], v[176:179], v[214:217], v[20:23]
	v_mfma_f32_16x16x32_bf16 v[16:19], v[184:187], v[214:217], v[16:19]
	v_mfma_f32_16x16x32_bf16 v[4:7], v[176:179], v[222:225], v[4:7]
	v_mfma_f32_16x16x32_bf16 v[0:3], v[184:187], v[222:225], v[0:3]
	v_mfma_f32_16x16x32_bf16 v[52:55], v[180:183], v[198:201], v[52:55]
	v_mfma_f32_16x16x32_bf16 v[48:51], v[190:193], v[198:201], v[48:51]
	v_mfma_f32_16x16x32_bf16 v[36:39], v[180:183], v[206:209], v[36:39]
	v_mfma_f32_16x16x32_bf16 v[32:35], v[190:193], v[206:209], v[32:35]
	v_mfma_f32_16x16x32_bf16 v[20:23], v[180:183], v[218:221], v[20:23]
	v_mfma_f32_16x16x32_bf16 v[16:19], v[190:193], v[218:221], v[16:19]
	v_mfma_f32_16x16x32_bf16 v[4:7], v[180:183], v[226:229], v[4:7]
	v_mfma_f32_16x16x32_bf16 v[0:3], v[190:193], v[226:229], v[0:3]
	s_setprio 0
	s_barrier
	s_add_i32 s93, s93, 2
	s_add_u32 s62, s62, 0x100
	s_addc_u32 s63, s63, 0
	s_add_u32 s91, s91, 0x100
	s_addc_u32 s92, s92, 0
	s_cmp_lt_u32 s93, 30
	s_cbranch_scc1 .LBB0_705
	s_and_b64 vcc, exec, s[12:13]
	s_cbranch_vccz .LBB0_708
	s_barrier

;     __device__ bool next(int i, Unit& u) const { if (i >= n) return false; const int q = first + i; u.pm = rowbase + q % rows; u.pn = q / rows; return true; }
; #define PG8_STAGE(bufoff, gbase, voff) do { _Pragma("unroll") for (int _i = 0; _i < 2; ++_i) \
;         __builtin_amdgcn_global_load_lds((const unsigned*)((const char*)(gbase) + (voff)[_i]), (PG8_LAS unsigned*)(lds + (bufoff) + ldsw + _i * 8192), 16, 0, 0); } while (0)
; #define PG8_LDA(dst, b, h) do { _Pragma("unroll") for (int m = 0; m < 4; ++m) _Pragma("unroll") for (int k = 0; k < 2; ++k) dst[m][k] = *(const PG8_LAS bf16x8*)(lds + PG8_SA(b, h) + aoff + m * 2048 + k * 1024); } while (0)
; #define PG8_WAIT_V(n) asm volatile("s_waitcnt vmcnt(" #n ")" ::: "memory")
; template <class Epi, class Sched, bool ALIGN_EPI = false, bool SP2 = false>
; __device__ __forceinline__ void gemm_phase(PG8_LAS unsigned char* lds, const Gemm g, const Sched& S, const Epi& E) {
;     ...
;         const bool has_next = S.next(ui + 1, nxt);
;         const char* nA = has_next ? (const char*)g.A + (size_t)nxt.pm * tstep : cA; const char* nB = has_next ? (const char*)g.Bt + (size_t)nxt.pn * tstep : cB;
;         constexpr int NSEG = Epi::HAS_MID ? 2 : 1; const int tseg = nt / NSEG;
; #pragma unroll
;         for (int seg = 0; seg < NSEG; ++seg) {
;         if constexpr (Epi::HAS_MID) { if (seg == 1) E.mid(acc, cur, wr, wc, fr, fq); }
;         for (int t = seg * tseg; t < (seg + 1) * tseg; t += 2) {
;             const bool last = (t == nt - 2);
;             const char* a1 = cA + (size_t)(t + 1) * kstep;
;             const char* a2 = last ? nA : cA + (size_t)(t + 2) * kstep; const char* b2 = last ? nB : cB + (size_t)(t + 2) * kstep;
;             const char* a3 = a2 + kstep; const char* b3 = b2 + kstep;
;             if (last && has_next) S.a_ready(nxt);
;             if constexpr (SP2) {
;             PG8_LDB(B0, 0, 0); PG8_LDB(B1, 0, 1); PG8_SCHED; PG8_LDA(At, 0, 0); PG8_STAGE(PG8_SA(1, 1), a1 + hstep, voffA);
;             PG8_WAIT_V(8); PG8_WAIT_L(0); PG8_BAR; PG8_MMA(0, 0, At, B0); PG8_MMA(0, 1, At, B1); PG8_BAR; PG8_SCHED;
;             PG8_LDA(At, 0, 1); PG8_STAGE(PG8_SB(0, 0), b2, voffB); PG8_STAGE(PG8_SB(0, 1), b2 + hstep, voffB); PG8_STAGE(PG8_SA(0, 0), a2, voffA);
;             PG8_WAIT_V(8); PG8_WAIT_L(0); PG8_BAR; PG8_MMA(1, 0, At, B0); PG8_MMA(1, 1, At, B1); PG8_BAR; PG8_SCHED;
.LBB0_780:
	s_ashr_i32 s47, s46, 31
	s_lshl_b64 s[0:1], s[46:47], 20
	s_add_u32 s56, s54, s0
	s_addc_u32 s57, s55, s1
	s_and_b64 s[0:1], s[4:5], exec
	s_cselect_b32 s0, s57, s63
	s_cselect_b32 s1, s56, s62
	s_ashr_i32 s41, s40, 31
	s_lshl_b64 s[58:59], s[40:41], 20
	s_add_u32 s58, s20, s58
	s_addc_u32 s59, s21, s59
	s_and_b64 s[66:67], s[4:5], exec
	s_cselect_b32 s41, s59, s65
	s_cselect_b32 s47, s58, s64
	s_add_u32 s62, s62, 0x80080
	s_addc_u32 s63, s63, 0
	s_add_u32 s71, s64, 0x100
	s_addc_u32 s76, s65, 0
	s_mov_b32 s77, -2
	ds_read_b128 v[128:131], v169
	ds_read_b128 v[132:135], v169 offset:1024
	ds_read_b128 v[136:139], v169 offset:2048
	ds_read_b128 v[140:143], v169 offset:3072
	ds_read_b128 v[160:163], v170
	ds_read_b128 v[172:175], v170 offset:1024
	ds_read_b128 v[176:179], v170 offset:2048
	ds_read_b128 v[180:183], v170 offset:3072
	s_add_u32 s64, s62, 0xfff80080
	s_addc_u32 s65, s63, -1
	s_cmp_eq_u32 s77, 28
	s_cselect_b32 s67, s0, s65
	s_cselect_b32 s66, s1, s64
	s_cselect_b32 s65, s41, s76
	s_cselect_b32 s64, s47, s71
	v_lshl_add_u64 v[164:165], s[62:63], 0, v[152:153]
	s_add_i32 m0, s3, 0xc000
	ds_read_b128 v[184:187], v171
	ds_read_b128 v[190:193], v171 offset:1024
	ds_read_b128 v[194:197], v171 offset:2048
	ds_read_b128 v[198:201], v171 offset:3072
	ds_read_b128 v[202:205], v171 offset:4096
	ds_read_b128 v[206:209], v171 offset:5120
	ds_read_b128 v[214:217], v171 offset:6144
	ds_read_b128 v[218:221], v171 offset:7168
	global_load_lds_dwordx4 v[164:165], off
	v_lshl_add_u64 v[164:165], s[62:63], 0, v[154:155]
	s_add_i32 m0, s3, 0xe000
	s_nop 0
	global_load_lds_dwordx4 v[164:165], off
	s_waitcnt vmcnt(8)
	s_waitcnt lgkmcnt(0)
	s_setprio 1
	s_barrier
	s_waitcnt lgkmcnt(0)
	v_mfma_f32_16x16x32_bf16 v[124:127], v[128:131], v[184:187], 0
	v_mfma_f32_16x16x32_bf16 v[120:123], v[136:139], v[184:187], 0
	v_mfma_f32_16x16x32_bf16 v[108:111], v[128:131], v[194:197], 0
	v_mfma_f32_16x16x32_bf16 v[104:107], v[136:139], v[194:197], 0
	v_mfma_f32_16x16x32_bf16 v[92:95], v[128:131], v[202:205], 0
	v_mfma_f32_16x16x32_bf16 v[88:91], v[136:139], v[202:205], 0
	v_mfma_f32_16x16x32_bf16 v[76:79], v[128:131], v[214:217], 0
	v_mfma_f32_16x16x32_bf16 v[72:75], v[136:139], v[214:217], 0
	v_mfma_f32_16x16x32_bf16 v[124:127], v[132:135], v[190:193], v[124:127]
	v_mfma_f32_16x16x32_bf16 v[120:123], v[140:143], v[190:193], v[120:123]
	v_mfma_f32_16x16x32_bf16 v[108:111], v[132:135], v[198:201], v[108:111]
	v_mfma_f32_16x16x32_bf16 v[104:107], v[140:143], v[198:201], v[104:107]
	v_mfma_f32_16x16x32_bf16 v[92:95], v[132:135], v[206:209], v[92:95]
	v_mfma_f32_16x16x32_bf16 v[88:91], v[140:143], v[206:209], v[88:91]
	v_mfma_f32_16x16x32_bf16 v[76:79], v[132:135], v[218:221], v[76:79]
	v_mfma_f32_16x16x32_bf16 v[72:75], v[140:143], v[218:221], v[72:75]
	s_setprio 0
	s_setprio 1
	v_mfma_f32_16x16x32_bf16 v[116:119], v[160:163], v[184:187], 0
	v_mfma_f32_16x16x32_bf16 v[112:115], v[176:179], v[184:187], 0
	v_mfma_f32_16x16x32_bf16 v[100:103], v[160:163], v[194:197], 0
	v_mfma_f32_16x16x32_bf16 v[96:99], v[176:179], v[194:197], 0
	v_mfma_f32_16x16x32_bf16 v[84:87], v[160:163], v[202:205], 0
	v_mfma_f32_16x16x32_bf16 v[80:83], v[176:179], v[202:205], 0
	v_mfma_f32_16x16x32_bf16 v[68:71], v[160:163], v[214:217], 0
	v_mfma_f32_16x16x32_bf16 v[64:67], v[176:179], v[214:217], 0
	v_mfma_f32_16x16x32_bf16 v[116:119], v[172:175], v[190:193], v[116:119]
	v_mfma_f32_16x16x32_bf16 v[112:115], v[180:183], v[190:193], v[112:115]
	v_mfma_f32_16x16x32_bf16 v[100:103], v[172:175], v[198:201], v[100:103]
	v_mfma_f32_16x16x32_bf16 v[96:99], v[180:183], v[198:201], v[96:99]
	v_mfma_f32_16x16x32_bf16 v[84:87], v[172:175], v[206:209], v[84:87]
	v_mfma_f32_16x16x32_bf16 v[80:83], v[180:183], v[206:209], v[80:83]
	v_mfma_f32_16x16x32_bf16 v[68:71], v[172:175], v[218:221], v[68:71]
	v_mfma_f32_16x16x32_bf16 v[64:67], v[180:183], v[218:221], v[64:67]
	s_setprio 0
	s_barrier
	s_add_i32 s78, s31, s2
	v_lshl_add_u64 v[164:165], s[64:65], 0, v[146:147]
	s_mov_b32 m0, s78
	ds_read_b128 v[184:187], v171 offset:16384
	ds_read_b128 v[190:193], v171 offset:17408
	ds_read_b128 v[194:197], v171 offset:18432
	ds_read_b128 v[198:201], v171 offset:19456
	ds_read_b128 v[202:205], v171 offset:20480
	ds_read_b128 v[206:209], v171 offset:21504
	ds_read_b128 v[214:217], v171 offset:22528
	ds_read_b128 v[218:221], v171 offset:23552
	global_load_lds_dwordx4 v[164:165], off
	s_add_i32 m0, s78, 0x2000
	s_add_u32 s78, s64, 0x80000
	v_lshl_add_u64 v[210:211], s[64:65], 0, v[150:151]
	s_addc_u32 s79, s65, 0
	s_add_i32 s80, s74, s2
	global_load_lds_dwordx4 v[210:211], off
	v_lshl_add_u64 v[222:223], s[78:79], 0, v[146:147]
	s_mov_b32 m0, s80
	v_lshl_add_u64 v[224:225], s[66:67], 0, v[148:149]
	global_load_lds_dwordx4 v[222:223], off
	v_lshl_add_u64 v[222:223], s[78:79], 0, v[150:151]
	s_add_i32 m0, s80, 0x2000
	s_nop 0
	global_load_lds_dwordx4 v[222:223], off
	v_lshl_add_u64 v[222:223], s[66:67], 0, v[144:145]
	s_mov_b32 m0, s3
	s_nop 0
	global_load_lds_dwordx4 v[222:223], off
	s_mov_b32 m0, s23
	s_nop 0
	global_load_lds_dwordx4 v[224:225], off
	s_waitcnt vmcnt(8)
	s_waitcnt lgkmcnt(0)
	s_setprio 1
	s_barrier
; #define PG8_STAGE(bufoff, gbase, voff) do { _Pragma("unroll") for (int _i = 0; _i < 2; ++_i) \
;         __builtin_amdgcn_global_load_lds((const unsigned*)((const char*)(gbase) + (voff)[_i]), (PG8_LAS unsigned*)(lds + (bufoff) + ldsw + _i * 8192), 16, 0, 0); } while (0)
; #define PG8_LDA(dst, b, h) do { _Pragma("unroll") for (int m = 0; m < 4; ++m) _Pragma("unroll") for (int k = 0; k < 2; ++k) dst[m][k] = *(const PG8_LAS bf16x8*)(lds + PG8_SA(b, h) + aoff + m * 2048 + k * 1024); } while (0)
; #define PG8_LDB(dst, b, h) do { _Pragma("unroll") for (int n = 0; n < 2; ++n) _Pragma("unroll") for (int k = 0; k < 2; ++k) dst[n][k] = *(const PG8_LAS bf16x8*)(lds + PG8_SB(b, h) + boff + n * 2048 + k * 1024); } while (0)
; #define PG8_MMA(ai, bj, At, Bt) do { __builtin_amdgcn_s_setprio(1); _Pragma("unroll") for (int m = 0; m < 4; ++m) _Pragma("unroll") for (int n = 0; n < 2; ++n) _Pragma("unroll") for (int k = 0; k < 2; ++k) \
;         acc[ai][bj][m][n] = __builtin_amdgcn_mfma_f32_16x16x32_bf16(Bt[n][k], At[m][k], acc[ai][bj][m][n], 0, 0, 0); __builtin_amdgcn_s_setprio(0); } while (0)
; #define PG8_WAIT_V(n) asm volatile("s_waitcnt vmcnt(" #n ")" ::: "memory")
; #define PG8_WAIT_L(n) asm volatile("s_waitcnt lgkmcnt(" #n ")" ::: "memory")
; #define PG8_BAR __builtin_amdgcn_s_barrier()
; #define PG8_SCHED __builtin_amdgcn_sched_barrier(0)
; template <class Epi, class Sched, bool ALIGN_EPI = false, bool SP2 = false>
; __device__ __forceinline__ void gemm_phase(PG8_LAS unsigned char* lds, const Gemm g, const Sched& S, const Epi& E) {
;     ...
;             PG8_WAIT_V(8); PG8_WAIT_L(0); PG8_BAR; PG8_MMA(1, 0, At, B0); PG8_MMA(1, 1, At, B1); PG8_BAR; PG8_SCHED;
;             PG8_LDB(B0, 1, 0); PG8_LDB(B1, 1, 1); PG8_SCHED; PG8_LDA(At, 1, 0); PG8_STAGE(PG8_SA(0, 1), a2 + hstep, voffA);
;             PG8_WAIT_V(8); PG8_WAIT_L(0); PG8_BAR; PG8_MMA(0, 0, At, B0); PG8_MMA(0, 1, At, B1); PG8_BAR; PG8_SCHED;
	s_waitcnt lgkmcnt(0)
	v_mfma_f32_16x16x32_bf16 v[60:63], v[128:131], v[184:187], 0
	v_mfma_f32_16x16x32_bf16 v[56:59], v[136:139], v[184:187], 0
	v_mfma_f32_16x16x32_bf16 v[44:47], v[128:131], v[194:197], 0
	v_mfma_f32_16x16x32_bf16 v[40:43], v[136:139], v[194:197], 0
	v_mfma_f32_16x16x32_bf16 v[28:31], v[128:131], v[202:205], 0
	v_mfma_f32_16x16x32_bf16 v[24:27], v[136:139], v[202:205], 0
	v_mfma_f32_16x16x32_bf16 v[12:15], v[128:131], v[214:217], 0
	v_mfma_f32_16x16x32_bf16 v[8:11], v[136:139], v[214:217], 0
	v_mfma_f32_16x16x32_bf16 v[60:63], v[132:135], v[190:193], v[60:63]
	v_mfma_f32_16x16x32_bf16 v[56:59], v[140:143], v[190:193], v[56:59]
	v_mfma_f32_16x16x32_bf16 v[44:47], v[132:135], v[198:201], v[44:47]
	v_mfma_f32_16x16x32_bf16 v[40:43], v[140:143], v[198:201], v[40:43]
	v_mfma_f32_16x16x32_bf16 v[28:31], v[132:135], v[206:209], v[28:31]
	v_mfma_f32_16x16x32_bf16 v[24:27], v[140:143], v[206:209], v[24:27]
	v_mfma_f32_16x16x32_bf16 v[12:15], v[132:135], v[218:221], v[12:15]
	v_mfma_f32_16x16x32_bf16 v[8:11], v[140:143], v[218:221], v[8:11]
	s_setprio 0
	s_setprio 1
	v_mfma_f32_16x16x32_bf16 v[52:55], v[160:163], v[184:187], 0
	v_mfma_f32_16x16x32_bf16 v[48:51], v[176:179], v[184:187], 0
	v_mfma_f32_16x16x32_bf16 v[36:39], v[160:163], v[194:197], 0
	v_mfma_f32_16x16x32_bf16 v[32:35], v[176:179], v[194:197], 0
	v_mfma_f32_16x16x32_bf16 v[20:23], v[160:163], v[202:205], 0
	v_mfma_f32_16x16x32_bf16 v[16:19], v[176:179], v[202:205], 0
	v_mfma_f32_16x16x32_bf16 v[4:7], v[160:163], v[214:217], 0
	v_mfma_f32_16x16x32_bf16 v[0:3], v[176:179], v[214:217], 0
	v_mfma_f32_16x16x32_bf16 v[52:55], v[172:175], v[190:193], v[52:55]
	v_mfma_f32_16x16x32_bf16 v[48:51], v[180:183], v[190:193], v[48:51]
	v_mfma_f32_16x16x32_bf16 v[36:39], v[172:175], v[198:201], v[36:39]
	v_mfma_f32_16x16x32_bf16 v[32:35], v[180:183], v[198:201], v[32:35]
	v_mfma_f32_16x16x32_bf16 v[20:23], v[172:175], v[206:209], v[20:23]
	v_mfma_f32_16x16x32_bf16 v[16:19], v[180:183], v[206:209], v[16:19]
	v_mfma_f32_16x16x32_bf16 v[4:7], v[172:175], v[218:221], v[4:7]
	v_mfma_f32_16x16x32_bf16 v[0:3], v[180:183], v[218:221], v[0:3]
	s_setprio 0
	s_barrier
	v_add_u32_e32 v140, s75, v167
	v_add_u32_e32 v180, s84, v167
	ds_read_b128 v[128:131], v140
	ds_read_b128 v[132:135], v140 offset:1024
	ds_read_b128 v[136:139], v140 offset:2048
	ds_read_b128 v[140:143], v140 offset:3072
	ds_read_b128 v[160:163], v180
	ds_read_b128 v[172:175], v180 offset:1024
	ds_read_b128 v[176:179], v180 offset:2048
	ds_read_b128 v[180:183], v180 offset:3072
	s_add_u32 s66, s66, 0x80000
	s_addc_u32 s67, s67, 0
	s_mov_b32 m0, s28
	v_lshl_add_u64 v[226:227], s[66:67], 0, v[144:145]
	ds_read_b128 v[184:187], v171 offset:32768
	ds_read_b128 v[190:193], v171 offset:33792
	ds_read_b128 v[194:197], v171 offset:34816
	ds_read_b128 v[198:201], v171 offset:35840
	ds_read_b128 v[202:205], v171 offset:36864
	ds_read_b128 v[206:209], v171 offset:37888
	ds_read_b128 v[214:217], v171 offset:38912
	ds_read_b128 v[218:221], v171 offset:39936
	global_load_lds_dwordx4 v[226:227], off
	v_lshl_add_u64 v[226:227], s[66:67], 0, v[148:149]
	s_mov_b32 m0, s29
	s_nop 0
	global_load_lds_dwordx4 v[226:227], off
	s_waitcnt vmcnt(8)
	s_waitcnt lgkmcnt(0)
	s_setprio 1
	s_barrier
	s_waitcnt lgkmcnt(0)
	v_mfma_f32_16x16x32_bf16 v[124:127], v[128:131], v[184:187], v[124:127]
	v_mfma_f32_16x16x32_bf16 v[120:123], v[136:139], v[184:187], v[120:123]
	v_mfma_f32_16x16x32_bf16 v[108:111], v[128:131], v[194:197], v[108:111]
	v_mfma_f32_16x16x32_bf16 v[104:107], v[136:139], v[194:197], v[104:107]
	v_mfma_f32_16x16x32_bf16 v[92:95], v[128:131], v[202:205], v[92:95]
	v_mfma_f32_16x16x32_bf16 v[88:91], v[136:139], v[202:205], v[88:91]
	v_mfma_f32_16x16x32_bf16 v[76:79], v[128:131], v[214:217], v[76:79]
	v_mfma_f32_16x16x32_bf16 v[72:75], v[136:139], v[214:217], v[72:75]
	v_mfma_f32_16x16x32_bf16 v[124:127], v[132:135], v[190:193], v[124:127]
	v_mfma_f32_16x16x32_bf16 v[120:123], v[140:143], v[190:193], v[120:123]
	v_mfma_f32_16x16x32_bf16 v[108:111], v[132:135], v[198:201], v[108:111]
	v_mfma_f32_16x16x32_bf16 v[104:107], v[140:143], v[198:201], v[104:107]
	v_mfma_f32_16x16x32_bf16 v[92:95], v[132:135], v[206:209], v[92:95]
	v_mfma_f32_16x16x32_bf16 v[88:91], v[140:143], v[206:209], v[88:91]
	v_mfma_f32_16x16x32_bf16 v[76:79], v[132:135], v[218:221], v[76:79]
	v_mfma_f32_16x16x32_bf16 v[72:75], v[140:143], v[218:221], v[72:75]
	s_setprio 0
	s_setprio 1
	v_mfma_f32_16x16x32_bf16 v[116:119], v[160:163], v[184:187], v[116:119]
	v_mfma_f32_16x16x32_bf16 v[112:115], v[176:179], v[184:187], v[112:115]
	v_mfma_f32_16x16x32_bf16 v[100:103], v[160:163], v[194:197], v[100:103]
	v_mfma_f32_16x16x32_bf16 v[96:99], v[176:179], v[194:197], v[96:99]
	v_mfma_f32_16x16x32_bf16 v[84:87], v[160:163], v[202:205], v[84:87]
	v_mfma_f32_16x16x32_bf16 v[80:83], v[176:179], v[202:205], v[80:83]
	v_mfma_f32_16x16x32_bf16 v[68:71], v[160:163], v[214:217], v[68:71]
	v_mfma_f32_16x16x32_bf16 v[64:67], v[176:179], v[214:217], v[64:67]
	v_mfma_f32_16x16x32_bf16 v[116:119], v[172:175], v[190:193], v[116:119]
	v_mfma_f32_16x16x32_bf16 v[112:115], v[180:183], v[190:193], v[112:115]
	v_mfma_f32_16x16x32_bf16 v[100:103], v[172:175], v[198:201], v[100:103]
	v_mfma_f32_16x16x32_bf16 v[96:99], v[180:183], v[198:201], v[96:99]
	v_mfma_f32_16x16x32_bf16 v[84:87], v[172:175], v[206:209], v[84:87]
	v_mfma_f32_16x16x32_bf16 v[80:83], v[180:183], v[206:209], v[80:83]
	v_mfma_f32_16x16x32_bf16 v[68:71], v[172:175], v[218:221], v[68:71]
	v_mfma_f32_16x16x32_bf16 v[64:67], v[180:183], v[218:221], v[64:67]
	s_setprio 0
	s_barrier
; #define PG8_STAGE(bufoff, gbase, voff) do { _Pragma("unroll") for (int _i = 0; _i < 2; ++_i) \
;         __builtin_amdgcn_global_load_lds((const unsigned*)((const char*)(gbase) + (voff)[_i]), (PG8_LAS unsigned*)(lds + (bufoff) + ldsw + _i * 8192), 16, 0, 0); } while (0)
; #define PG8_LDA(dst, b, h) do { _Pragma("unroll") for (int m = 0; m < 4; ++m) _Pragma("unroll") for (int k = 0; k < 2; ++k) dst[m][k] = *(const PG8_LAS bf16x8*)(lds + PG8_SA(b, h) + aoff + m * 2048 + k * 1024); } while (0)
; #define PG8_WAIT_V(n) asm volatile("s_waitcnt vmcnt(" #n ")" ::: "memory")
; #define PG8_WAIT_L(n) asm volatile("s_waitcnt lgkmcnt(" #n ")" ::: "memory")
; #define PG8_BAR __builtin_amdgcn_s_barrier()
; template <class Epi, class Sched, bool ALIGN_EPI = false, bool SP2 = false>
; __device__ __forceinline__ void gemm_phase(PG8_LAS unsigned char* lds, const Gemm g, const Sched& S, const Epi& E) {
;     ...
;         for (int t = seg * tseg; t < (seg + 1) * tseg; t += 2) {
;             const bool last = (t == nt - 2);
;             const char* a1 = cA + (size_t)(t + 1) * kstep;
;             const char* a2 = last ? nA : cA + (size_t)(t + 2) * kstep; const char* b2 = last ? nB : cB + (size_t)(t + 2) * kstep;
;             const char* a3 = a2 + kstep; const char* b3 = b2 + kstep;
;             if (last && has_next) S.a_ready(nxt);
;             if constexpr (SP2) {
;             PG8_LDB(B0, 0, 0); PG8_LDB(B1, 0, 1); PG8_SCHED; PG8_LDA(At, 0, 0); PG8_STAGE(PG8_SA(1, 1), a1 + hstep, voffA);
;             PG8_WAIT_V(8); PG8_WAIT_L(0); PG8_BAR; PG8_MMA(0, 0, At, B0); PG8_MMA(0, 1, At, B1); PG8_BAR; PG8_SCHED;
;             PG8_LDA(At, 0, 1); PG8_STAGE(PG8_SB(0, 0), b2, voffB); PG8_STAGE(PG8_SB(0, 1), b2 + hstep, voffB); PG8_STAGE(PG8_SA(0, 0), a2, voffA);
;             PG8_WAIT_V(8); PG8_WAIT_L(0); PG8_BAR; PG8_MMA(1, 0, At, B0); PG8_MMA(1, 1, At, B1); PG8_BAR; PG8_SCHED;
;             PG8_LDB(B0, 1, 0); PG8_LDB(B1, 1, 1); PG8_SCHED; PG8_LDA(At, 1, 0); PG8_STAGE(PG8_SA(0, 1), a2 + hstep, voffA);
;             PG8_WAIT_V(8); PG8_WAIT_L(0); PG8_BAR; PG8_MMA(0, 0, At, B0); PG8_MMA(0, 1, At, B1); PG8_BAR; PG8_SCHED;
;             PG8_LDA(At, 1, 1); PG8_STAGE(PG8_SB(1, 0), b3, voffB); PG8_STAGE(PG8_SB(1, 1), b3 + hstep, voffB); PG8_STAGE(PG8_SA(1, 0), a3, voffA);
;             PG8_WAIT_V(8); PG8_WAIT_L(0); PG8_BAR; PG8_MMA(1, 0, At, B0); PG8_MMA(1, 1, At, B1); PG8_BAR; PG8_SCHED;
	s_add_i32 s66, s75, s2
	v_lshl_add_u64 v[164:165], v[164:165], 0, s[8:9]
	s_mov_b32 m0, s66
	ds_read_b128 v[184:187], v171 offset:49152
	ds_read_b128 v[190:193], v171 offset:50176
	ds_read_b128 v[194:197], v171 offset:51200
	ds_read_b128 v[198:201], v171 offset:52224
	ds_read_b128 v[202:205], v171 offset:53248
	ds_read_b128 v[206:209], v171 offset:54272
	ds_read_b128 v[214:217], v171 offset:55296
	ds_read_b128 v[218:221], v171 offset:56320
	global_load_lds_dwordx4 v[164:165], off
	s_add_i32 m0, s66, 0x2000
	s_add_u32 s64, s64, 0x80080
	v_lshl_add_u64 v[164:165], v[210:211], 0, s[8:9]
	s_addc_u32 s65, s65, 0
	s_add_i32 s66, s84, s2
	global_load_lds_dwordx4 v[164:165], off
	v_lshl_add_u64 v[164:165], s[64:65], 0, v[146:147]
	s_mov_b32 m0, s66
	s_nop 0
	global_load_lds_dwordx4 v[164:165], off
	v_lshl_add_u64 v[164:165], s[64:65], 0, v[150:151]
	s_add_i32 m0, s66, 0x2000
	s_nop 0
	global_load_lds_dwordx4 v[164:165], off
	v_lshl_add_u64 v[164:165], v[222:223], 0, s[8:9]
	s_mov_b32 m0, s68
	s_nop 0
	global_load_lds_dwordx4 v[164:165], off
	v_lshl_add_u64 v[164:165], v[224:225], 0, s[8:9]
	s_mov_b32 m0, s69
	s_nop 0
	global_load_lds_dwordx4 v[164:165], off
	s_waitcnt vmcnt(8)
	s_waitcnt lgkmcnt(0)
	s_setprio 1
	s_barrier
	s_waitcnt lgkmcnt(0)
	v_mfma_f32_16x16x32_bf16 v[60:63], v[128:131], v[184:187], v[60:63]
	v_mfma_f32_16x16x32_bf16 v[56:59], v[136:139], v[184:187], v[56:59]
	v_mfma_f32_16x16x32_bf16 v[44:47], v[128:131], v[194:197], v[44:47]
	v_mfma_f32_16x16x32_bf16 v[40:43], v[136:139], v[194:197], v[40:43]
	v_mfma_f32_16x16x32_bf16 v[28:31], v[128:131], v[202:205], v[28:31]
	v_mfma_f32_16x16x32_bf16 v[24:27], v[136:139], v[202:205], v[24:27]
	v_mfma_f32_16x16x32_bf16 v[12:15], v[128:131], v[214:217], v[12:15]
	v_mfma_f32_16x16x32_bf16 v[8:11], v[136:139], v[214:217], v[8:11]
	v_mfma_f32_16x16x32_bf16 v[60:63], v[132:135], v[190:193], v[60:63]
	v_mfma_f32_16x16x32_bf16 v[56:59], v[140:143], v[190:193], v[56:59]
	v_mfma_f32_16x16x32_bf16 v[44:47], v[132:135], v[198:201], v[44:47]
	v_mfma_f32_16x16x32_bf16 v[40:43], v[140:143], v[198:201], v[40:43]
	v_mfma_f32_16x16x32_bf16 v[28:31], v[132:135], v[206:209], v[28:31]
	v_mfma_f32_16x16x32_bf16 v[24:27], v[140:143], v[206:209], v[24:27]
	v_mfma_f32_16x16x32_bf16 v[12:15], v[132:135], v[218:221], v[12:15]
	v_mfma_f32_16x16x32_bf16 v[8:11], v[140:143], v[218:221], v[8:11]
	s_setprio 0
	s_setprio 1
	v_mfma_f32_16x16x32_bf16 v[52:55], v[160:163], v[184:187], v[52:55]
	v_mfma_f32_16x16x32_bf16 v[48:51], v[176:179], v[184:187], v[48:51]
	v_mfma_f32_16x16x32_bf16 v[36:39], v[160:163], v[194:197], v[36:39]
	v_mfma_f32_16x16x32_bf16 v[32:35], v[176:179], v[194:197], v[32:35]
	v_mfma_f32_16x16x32_bf16 v[20:23], v[160:163], v[202:205], v[20:23]
	v_mfma_f32_16x16x32_bf16 v[16:19], v[176:179], v[202:205], v[16:19]
	v_mfma_f32_16x16x32_bf16 v[4:7], v[160:163], v[214:217], v[4:7]
	v_mfma_f32_16x16x32_bf16 v[0:3], v[176:179], v[214:217], v[0:3]
	v_mfma_f32_16x16x32_bf16 v[52:55], v[172:175], v[190:193], v[52:55]
	v_mfma_f32_16x16x32_bf16 v[48:51], v[180:183], v[190:193], v[48:51]
	v_mfma_f32_16x16x32_bf16 v[36:39], v[172:175], v[198:201], v[36:39]
	v_mfma_f32_16x16x32_bf16 v[32:35], v[180:183], v[198:201], v[32:35]
	v_mfma_f32_16x16x32_bf16 v[20:23], v[172:175], v[206:209], v[20:23]
	v_mfma_f32_16x16x32_bf16 v[16:19], v[180:183], v[206:209], v[16:19]
	v_mfma_f32_16x16x32_bf16 v[4:7], v[172:175], v[218:221], v[4:7]
	v_mfma_f32_16x16x32_bf16 v[0:3], v[180:183], v[218:221], v[0:3]
	s_setprio 0
	s_barrier
	s_add_i32 s77, s77, 2
	s_add_u32 s62, s62, 0x100
	s_addc_u32 s63, s63, 0
	s_add_u32 s71, s71, 0x100
	s_addc_u32 s76, s76, 0
	s_cmp_gt_u32 s77, 29
.LBB0_781:
	ds_read_b128 v[128:131], v169
	ds_read_b128 v[132:135], v169 offset:1024
	ds_read_b128 v[136:139], v169 offset:2048
	ds_read_b128 v[140:143], v169 offset:3072
	ds_read_b128 v[160:163], v170
	ds_read_b128 v[172:175], v170 offset:1024
	ds_read_b128 v[176:179], v170 offset:2048
	ds_read_b128 v[180:183], v170 offset:3072
	s_add_u32 s64, s62, 0xfff80080
	s_addc_u32 s65, s63, -1
	s_cmp_eq_u32 s77, 28
	s_cselect_b32 s67, s0, s65
	s_cselect_b32 s66, s1, s64
	s_cselect_b32 s65, s41, s76
	s_cselect_b32 s64, s47, s71
	v_lshl_add_u64 v[164:165], s[62:63], 0, v[152:153]
	s_add_i32 m0, s3, 0xc000
	ds_read_b128 v[184:187], v171
	ds_read_b128 v[190:193], v171 offset:1024
	ds_read_b128 v[194:197], v171 offset:2048
	ds_read_b128 v[198:201], v171 offset:3072
	ds_read_b128 v[202:205], v171 offset:4096
	ds_read_b128 v[206:209], v171 offset:5120
	ds_read_b128 v[214:217], v171 offset:6144
	ds_read_b128 v[218:221], v171 offset:7168
	global_load_lds_dwordx4 v[164:165], off
	v_lshl_add_u64 v[164:165], s[62:63], 0, v[154:155]
	s_add_i32 m0, s3, 0xe000
	s_nop 0
	global_load_lds_dwordx4 v[164:165], off
	s_waitcnt vmcnt(8)
	s_waitcnt lgkmcnt(0)
	s_setprio 1
	s_barrier
; #define PG8_STAGE(bufoff, gbase, voff) do { _Pragma("unroll") for (int _i = 0; _i < 2; ++_i) \
;         __builtin_amdgcn_global_load_lds((const unsigned*)((const char*)(gbase) + (voff)[_i]), (PG8_LAS unsigned*)(lds + (bufoff) + ldsw + _i * 8192), 16, 0, 0); } while (0)
; #define PG8_LDA(dst, b, h) do { _Pragma("unroll") for (int m = 0; m < 4; ++m) _Pragma("unroll") for (int k = 0; k < 2; ++k) dst[m][k] = *(const PG8_LAS bf16x8*)(lds + PG8_SA(b, h) + aoff + m * 2048 + k * 1024); } while (0)
; #define PG8_LDB(dst, b, h) do { _Pragma("unroll") for (int n = 0; n < 2; ++n) _Pragma("unroll") for (int k = 0; k < 2; ++k) dst[n][k] = *(const PG8_LAS bf16x8*)(lds + PG8_SB(b, h) + boff + n * 2048 + k * 1024); } while (0)
; #define PG8_MMA(ai, bj, At, Bt) do { __builtin_amdgcn_s_setprio(1); _Pragma("unroll") for (int m = 0; m < 4; ++m) _Pragma("unroll") for (int n = 0; n < 2; ++n) _Pragma("unroll") for (int k = 0; k < 2; ++k) \
;         acc[ai][bj][m][n] = __builtin_amdgcn_mfma_f32_16x16x32_bf16(Bt[n][k], At[m][k], acc[ai][bj][m][n], 0, 0, 0); __builtin_amdgcn_s_setprio(0); } while (0)
; #define PG8_BAR __builtin_amdgcn_s_barrier()
; template <class Epi, class Sched, bool ALIGN_EPI = false, bool SP2 = false>
; __device__ __forceinline__ void gemm_phase(PG8_LAS unsigned char* lds, const Gemm g, const Sched& S, const Epi& E) {
;     ...
;             if constexpr (SP2) {
;             PG8_LDB(B0, 0, 0); PG8_LDB(B1, 0, 1); PG8_SCHED; PG8_LDA(At, 0, 0); PG8_STAGE(PG8_SA(1, 1), a1 + hstep, voffA);
;             PG8_WAIT_V(8); PG8_WAIT_L(0); PG8_BAR; PG8_MMA(0, 0, At, B0); PG8_MMA(0, 1, At, B1); PG8_BAR; PG8_SCHED;
;             PG8_LDA(At, 0, 1); PG8_STAGE(PG8_SB(0, 0), b2, voffB); PG8_STAGE(PG8_SB(0, 1), b2 + hstep, voffB); PG8_STAGE(PG8_SA(0, 0), a2, voffA);
;             PG8_WAIT_V(8); PG8_WAIT_L(0); PG8_BAR; PG8_MMA(1, 0, At, B0); PG8_MMA(1, 1, At, B1); PG8_BAR; PG8_SCHED;
;             PG8_LDB(B0, 1, 0); PG8_LDB(B1, 1, 1); PG8_SCHED; PG8_LDA(At, 1, 0); PG8_STAGE(PG8_SA(0, 1), a2 + hstep, voffA);
;             PG8_WAIT_V(8); PG8_WAIT_L(0); PG8_BAR; PG8_MMA(0, 0, At, B0); PG8_MMA(0, 1, At, B1); PG8_BAR; PG8_SCHED;
;             PG8_LDA(At, 1, 1); PG8_STAGE(PG8_SB(1, 0), b3, voffB); PG8_STAGE(PG8_SB(1, 1), b3 + hstep, voffB); PG8_STAGE(PG8_SA(1, 0), a3, voffA);
;             PG8_WAIT_V(8); PG8_WAIT_L(0); PG8_BAR; PG8_MMA(1, 0, At, B0); PG8_MMA(1, 1, At, B1); PG8_BAR; PG8_SCHED;
	s_waitcnt lgkmcnt(0)
	v_mfma_f32_16x16x32_bf16 v[124:127], v[128:131], v[184:187], v[124:127]
	v_mfma_f32_16x16x32_bf16 v[120:123], v[136:139], v[184:187], v[120:123]
	v_mfma_f32_16x16x32_bf16 v[108:111], v[128:131], v[194:197], v[108:111]
	v_mfma_f32_16x16x32_bf16 v[104:107], v[136:139], v[194:197], v[104:107]
	v_mfma_f32_16x16x32_bf16 v[92:95], v[128:131], v[202:205], v[92:95]
	v_mfma_f32_16x16x32_bf16 v[88:91], v[136:139], v[202:205], v[88:91]
	v_mfma_f32_16x16x32_bf16 v[76:79], v[128:131], v[214:217], v[76:79]
	v_mfma_f32_16x16x32_bf16 v[72:75], v[136:139], v[214:217], v[72:75]
	v_mfma_f32_16x16x32_bf16 v[124:127], v[132:135], v[190:193], v[124:127]
	v_mfma_f32_16x16x32_bf16 v[120:123], v[140:143], v[190:193], v[120:123]
	v_mfma_f32_16x16x32_bf16 v[108:111], v[132:135], v[198:201], v[108:111]
	v_mfma_f32_16x16x32_bf16 v[104:107], v[140:143], v[198:201], v[104:107]
	v_mfma_f32_16x16x32_bf16 v[92:95], v[132:135], v[206:209], v[92:95]
	v_mfma_f32_16x16x32_bf16 v[88:91], v[140:143], v[206:209], v[88:91]
	v_mfma_f32_16x16x32_bf16 v[76:79], v[132:135], v[218:221], v[76:79]
	v_mfma_f32_16x16x32_bf16 v[72:75], v[140:143], v[218:221], v[72:75]
	s_setprio 0
	s_setprio 1
	v_mfma_f32_16x16x32_bf16 v[116:119], v[160:163], v[184:187], v[116:119]
	v_mfma_f32_16x16x32_bf16 v[112:115], v[176:179], v[184:187], v[112:115]
	v_mfma_f32_16x16x32_bf16 v[100:103], v[160:163], v[194:197], v[100:103]
	v_mfma_f32_16x16x32_bf16 v[96:99], v[176:179], v[194:197], v[96:99]
	v_mfma_f32_16x16x32_bf16 v[84:87], v[160:163], v[202:205], v[84:87]
	v_mfma_f32_16x16x32_bf16 v[80:83], v[176:179], v[202:205], v[80:83]
	v_mfma_f32_16x16x32_bf16 v[68:71], v[160:163], v[214:217], v[68:71]
	v_mfma_f32_16x16x32_bf16 v[64:67], v[176:179], v[214:217], v[64:67]
	v_mfma_f32_16x16x32_bf16 v[116:119], v[172:175], v[190:193], v[116:119]
	v_mfma_f32_16x16x32_bf16 v[112:115], v[180:183], v[190:193], v[112:115]
	v_mfma_f32_16x16x32_bf16 v[100:103], v[172:175], v[198:201], v[100:103]
	v_mfma_f32_16x16x32_bf16 v[96:99], v[180:183], v[198:201], v[96:99]
	v_mfma_f32_16x16x32_bf16 v[84:87], v[172:175], v[206:209], v[84:87]
	v_mfma_f32_16x16x32_bf16 v[80:83], v[180:183], v[206:209], v[80:83]
	v_mfma_f32_16x16x32_bf16 v[68:71], v[172:175], v[218:221], v[68:71]
	v_mfma_f32_16x16x32_bf16 v[64:67], v[180:183], v[218:221], v[64:67]
	s_setprio 0
	s_barrier
	s_add_i32 s78, s31, s2
	v_lshl_add_u64 v[164:165], s[64:65], 0, v[146:147]
	s_mov_b32 m0, s78
	ds_read_b128 v[184:187], v171 offset:16384
	ds_read_b128 v[190:193], v171 offset:17408
	ds_read_b128 v[194:197], v171 offset:18432
	ds_read_b128 v[198:201], v171 offset:19456
	ds_read_b128 v[202:205], v171 offset:20480
	ds_read_b128 v[206:209], v171 offset:21504
	ds_read_b128 v[214:217], v171 offset:22528
	ds_read_b128 v[218:221], v171 offset:23552
	global_load_lds_dwordx4 v[164:165], off
	s_add_i32 m0, s78, 0x2000
	s_add_u32 s78, s64, 0x80000
	v_lshl_add_u64 v[210:211], s[64:65], 0, v[150:151]
	s_addc_u32 s79, s65, 0
	s_add_i32 s80, s74, s2
	global_load_lds_dwordx4 v[210:211], off
	v_lshl_add_u64 v[222:223], s[78:79], 0, v[146:147]
	s_mov_b32 m0, s80
	v_lshl_add_u64 v[224:225], s[66:67], 0, v[148:149]
	global_load_lds_dwordx4 v[222:223], off
	v_lshl_add_u64 v[222:223], s[78:79], 0, v[150:151]
	s_add_i32 m0, s80, 0x2000
	s_nop 0
	global_load_lds_dwordx4 v[222:223], off
	v_lshl_add_u64 v[222:223], s[66:67], 0, v[144:145]
	s_mov_b32 m0, s3
	s_nop 0
	global_load_lds_dwordx4 v[222:223], off
	s_mov_b32 m0, s23
	s_nop 0
	global_load_lds_dwordx4 v[224:225], off
	s_waitcnt vmcnt(8)
	s_waitcnt lgkmcnt(0)
	s_setprio 1
	s_barrier
	s_waitcnt lgkmcnt(0)
	v_mfma_f32_16x16x32_bf16 v[60:63], v[128:131], v[184:187], v[60:63]
	v_mfma_f32_16x16x32_bf16 v[56:59], v[136:139], v[184:187], v[56:59]
	v_mfma_f32_16x16x32_bf16 v[44:47], v[128:131], v[194:197], v[44:47]
	v_mfma_f32_16x16x32_bf16 v[40:43], v[136:139], v[194:197], v[40:43]
	v_mfma_f32_16x16x32_bf16 v[28:31], v[128:131], v[202:205], v[28:31]
	v_mfma_f32_16x16x32_bf16 v[24:27], v[136:139], v[202:205], v[24:27]
	v_mfma_f32_16x16x32_bf16 v[12:15], v[128:131], v[214:217], v[12:15]
	v_mfma_f32_16x16x32_bf16 v[8:11], v[136:139], v[214:217], v[8:11]
	v_mfma_f32_16x16x32_bf16 v[60:63], v[132:135], v[190:193], v[60:63]
	v_mfma_f32_16x16x32_bf16 v[56:59], v[140:143], v[190:193], v[56:59]
	v_mfma_f32_16x16x32_bf16 v[44:47], v[132:135], v[198:201], v[44:47]
	v_mfma_f32_16x16x32_bf16 v[40:43], v[140:143], v[198:201], v[40:43]
	v_mfma_f32_16x16x32_bf16 v[28:31], v[132:135], v[206:209], v[28:31]
	v_mfma_f32_16x16x32_bf16 v[24:27], v[140:143], v[206:209], v[24:27]
	v_mfma_f32_16x16x32_bf16 v[12:15], v[132:135], v[218:221], v[12:15]
	v_mfma_f32_16x16x32_bf16 v[8:11], v[140:143], v[218:221], v[8:11]
	s_setprio 0
	s_setprio 1
	v_mfma_f32_16x16x32_bf16 v[52:55], v[160:163], v[184:187], v[52:55]
	v_mfma_f32_16x16x32_bf16 v[48:51], v[176:179], v[184:187], v[48:51]
	v_mfma_f32_16x16x32_bf16 v[36:39], v[160:163], v[194:197], v[36:39]
	v_mfma_f32_16x16x32_bf16 v[32:35], v[176:179], v[194:197], v[32:35]
	v_mfma_f32_16x16x32_bf16 v[20:23], v[160:163], v[202:205], v[20:23]
	v_mfma_f32_16x16x32_bf16 v[16:19], v[176:179], v[202:205], v[16:19]
	v_mfma_f32_16x16x32_bf16 v[4:7], v[160:163], v[214:217], v[4:7]
	v_mfma_f32_16x16x32_bf16 v[0:3], v[176:179], v[214:217], v[0:3]
	v_mfma_f32_16x16x32_bf16 v[52:55], v[172:175], v[190:193], v[52:55]
	v_mfma_f32_16x16x32_bf16 v[48:51], v[180:183], v[190:193], v[48:51]
	v_mfma_f32_16x16x32_bf16 v[36:39], v[172:175], v[198:201], v[36:39]
	v_mfma_f32_16x16x32_bf16 v[32:35], v[180:183], v[198:201], v[32:35]
	v_mfma_f32_16x16x32_bf16 v[20:23], v[172:175], v[206:209], v[20:23]
	v_mfma_f32_16x16x32_bf16 v[16:19], v[180:183], v[206:209], v[16:19]
	v_mfma_f32_16x16x32_bf16 v[4:7], v[172:175], v[218:221], v[4:7]
	v_mfma_f32_16x16x32_bf16 v[0:3], v[180:183], v[218:221], v[0:3]
	s_setprio 0
	s_barrier
; #define PG8_STAGE(bufoff, gbase, voff) do { _Pragma("unroll") for (int _i = 0; _i < 2; ++_i) \
;         __builtin_amdgcn_global_load_lds((const unsigned*)((const char*)(gbase) + (voff)[_i]), (PG8_LAS unsigned*)(lds + (bufoff) + ldsw + _i * 8192), 16, 0, 0); } while (0)
; #define PG8_LDA(dst, b, h) do { _Pragma("unroll") for (int m = 0; m < 4; ++m) _Pragma("unroll") for (int k = 0; k < 2; ++k) dst[m][k] = *(const PG8_LAS bf16x8*)(lds + PG8_SA(b, h) + aoff + m * 2048 + k * 1024); } while (0)
; #define PG8_LDB(dst, b, h) do { _Pragma("unroll") for (int n = 0; n < 2; ++n) _Pragma("unroll") for (int k = 0; k < 2; ++k) dst[n][k] = *(const PG8_LAS bf16x8*)(lds + PG8_SB(b, h) + boff + n * 2048 + k * 1024); } while (0)
; #define PG8_MMA(ai, bj, At, Bt) do { __builtin_amdgcn_s_setprio(1); _Pragma("unroll") for (int m = 0; m < 4; ++m) _Pragma("unroll") for (int n = 0; n < 2; ++n) _Pragma("unroll") for (int k = 0; k < 2; ++k) \
;         acc[ai][bj][m][n] = __builtin_amdgcn_mfma_f32_16x16x32_bf16(Bt[n][k], At[m][k], acc[ai][bj][m][n], 0, 0, 0); __builtin_amdgcn_s_setprio(0); } while (0)
; #define PG8_BAR __builtin_amdgcn_s_barrier()
; template <class Epi, class Sched, bool ALIGN_EPI = false, bool SP2 = false>
; __device__ __forceinline__ void gemm_phase(PG8_LAS unsigned char* lds, const Gemm g, const Sched& S, const Epi& E) {
;     ...
;             if constexpr (SP2) {
;             PG8_LDB(B0, 0, 0); PG8_LDB(B1, 0, 1); PG8_SCHED; PG8_LDA(At, 0, 0); PG8_STAGE(PG8_SA(1, 1), a1 + hstep, voffA);
;             PG8_WAIT_V(8); PG8_WAIT_L(0); PG8_BAR; PG8_MMA(0, 0, At, B0); PG8_MMA(0, 1, At, B1); PG8_BAR; PG8_SCHED;
;             PG8_LDA(At, 0, 1); PG8_STAGE(PG8_SB(0, 0), b2, voffB); PG8_STAGE(PG8_SB(0, 1), b2 + hstep, voffB); PG8_STAGE(PG8_SA(0, 0), a2, voffA);
;             PG8_WAIT_V(8); PG8_WAIT_L(0); PG8_BAR; PG8_MMA(1, 0, At, B0); PG8_MMA(1, 1, At, B1); PG8_BAR; PG8_SCHED;
;             PG8_LDB(B0, 1, 0); PG8_LDB(B1, 1, 1); PG8_SCHED; PG8_LDA(At, 1, 0); PG8_STAGE(PG8_SA(0, 1), a2 + hstep, voffA);
;             PG8_WAIT_V(8); PG8_WAIT_L(0); PG8_BAR; PG8_MMA(0, 0, At, B0); PG8_MMA(0, 1, At, B1); PG8_BAR; PG8_SCHED;
;             PG8_LDA(At, 1, 1); PG8_STAGE(PG8_SB(1, 0), b3, voffB); PG8_STAGE(PG8_SB(1, 1), b3 + hstep, voffB); PG8_STAGE(PG8_SA(1, 0), a3, voffA);
;             PG8_WAIT_V(8); PG8_WAIT_L(0); PG8_BAR; PG8_MMA(1, 0, At, B0); PG8_MMA(1, 1, At, B1); PG8_BAR; PG8_SCHED;
	v_add_u32_e32 v140, s75, v167
	v_add_u32_e32 v180, s84, v167
	ds_read_b128 v[128:131], v140
	ds_read_b128 v[132:135], v140 offset:1024
	ds_read_b128 v[136:139], v140 offset:2048
	ds_read_b128 v[140:143], v140 offset:3072
	ds_read_b128 v[160:163], v180
	ds_read_b128 v[172:175], v180 offset:1024
	ds_read_b128 v[176:179], v180 offset:2048
	ds_read_b128 v[180:183], v180 offset:3072
	s_add_u32 s66, s66, 0x80000
	s_addc_u32 s67, s67, 0
	s_mov_b32 m0, s28
	v_lshl_add_u64 v[226:227], s[66:67], 0, v[144:145]
	ds_read_b128 v[184:187], v171 offset:32768
	ds_read_b128 v[190:193], v171 offset:33792
	ds_read_b128 v[194:197], v171 offset:34816
	ds_read_b128 v[198:201], v171 offset:35840
	ds_read_b128 v[202:205], v171 offset:36864
	ds_read_b128 v[206:209], v171 offset:37888
	ds_read_b128 v[214:217], v171 offset:38912
	ds_read_b128 v[218:221], v171 offset:39936
	global_load_lds_dwordx4 v[226:227], off
	v_lshl_add_u64 v[226:227], s[66:67], 0, v[148:149]
	s_mov_b32 m0, s29
	s_nop 0
	global_load_lds_dwordx4 v[226:227], off
	s_waitcnt vmcnt(8)
	s_waitcnt lgkmcnt(0)
	s_setprio 1
	s_barrier
	s_waitcnt lgkmcnt(0)
	v_mfma_f32_16x16x32_bf16 v[124:127], v[128:131], v[184:187], v[124:127]
	v_mfma_f32_16x16x32_bf16 v[120:123], v[136:139], v[184:187], v[120:123]
	v_mfma_f32_16x16x32_bf16 v[108:111], v[128:131], v[194:197], v[108:111]
	v_mfma_f32_16x16x32_bf16 v[104:107], v[136:139], v[194:197], v[104:107]
	v_mfma_f32_16x16x32_bf16 v[92:95], v[128:131], v[202:205], v[92:95]
	v_mfma_f32_16x16x32_bf16 v[88:91], v[136:139], v[202:205], v[88:91]
	v_mfma_f32_16x16x32_bf16 v[76:79], v[128:131], v[214:217], v[76:79]
	v_mfma_f32_16x16x32_bf16 v[72:75], v[136:139], v[214:217], v[72:75]
	v_mfma_f32_16x16x32_bf16 v[124:127], v[132:135], v[190:193], v[124:127]
	v_mfma_f32_16x16x32_bf16 v[120:123], v[140:143], v[190:193], v[120:123]
	v_mfma_f32_16x16x32_bf16 v[108:111], v[132:135], v[198:201], v[108:111]
	v_mfma_f32_16x16x32_bf16 v[104:107], v[140:143], v[198:201], v[104:107]
	v_mfma_f32_16x16x32_bf16 v[92:95], v[132:135], v[206:209], v[92:95]
	v_mfma_f32_16x16x32_bf16 v[88:91], v[140:143], v[206:209], v[88:91]
	v_mfma_f32_16x16x32_bf16 v[76:79], v[132:135], v[218:221], v[76:79]
	v_mfma_f32_16x16x32_bf16 v[72:75], v[140:143], v[218:221], v[72:75]
	s_setprio 0
	s_setprio 1
	v_mfma_f32_16x16x32_bf16 v[116:119], v[160:163], v[184:187], v[116:119]
	v_mfma_f32_16x16x32_bf16 v[112:115], v[176:179], v[184:187], v[112:115]
	v_mfma_f32_16x16x32_bf16 v[100:103], v[160:163], v[194:197], v[100:103]
	v_mfma_f32_16x16x32_bf16 v[96:99], v[176:179], v[194:197], v[96:99]
	v_mfma_f32_16x16x32_bf16 v[84:87], v[160:163], v[202:205], v[84:87]
	v_mfma_f32_16x16x32_bf16 v[80:83], v[176:179], v[202:205], v[80:83]
	v_mfma_f32_16x16x32_bf16 v[68:71], v[160:163], v[214:217], v[68:71]
	v_mfma_f32_16x16x32_bf16 v[64:67], v[176:179], v[214:217], v[64:67]
	v_mfma_f32_16x16x32_bf16 v[116:119], v[172:175], v[190:193], v[116:119]
	v_mfma_f32_16x16x32_bf16 v[112:115], v[180:183], v[190:193], v[112:115]
	v_mfma_f32_16x16x32_bf16 v[100:103], v[172:175], v[198:201], v[100:103]
	v_mfma_f32_16x16x32_bf16 v[96:99], v[180:183], v[198:201], v[96:99]
	v_mfma_f32_16x16x32_bf16 v[84:87], v[172:175], v[206:209], v[84:87]
	v_mfma_f32_16x16x32_bf16 v[80:83], v[180:183], v[206:209], v[80:83]
	v_mfma_f32_16x16x32_bf16 v[68:71], v[172:175], v[218:221], v[68:71]
	v_mfma_f32_16x16x32_bf16 v[64:67], v[180:183], v[218:221], v[64:67]
	s_setprio 0
	s_barrier
; #define PG8_STAGE(bufoff, gbase, voff) do { _Pragma("unroll") for (int _i = 0; _i < 2; ++_i) \
;         __builtin_amdgcn_global_load_lds((const unsigned*)((const char*)(gbase) + (voff)[_i]), (PG8_LAS unsigned*)(lds + (bufoff) + ldsw + _i * 8192), 16, 0, 0); } while (0)
; #define PG8_LDA(dst, b, h) do { _Pragma("unroll") for (int m = 0; m < 4; ++m) _Pragma("unroll") for (int k = 0; k < 2; ++k) dst[m][k] = *(const PG8_LAS bf16x8*)(lds + PG8_SA(b, h) + aoff + m * 2048 + k * 1024); } while (0)
; #define PG8_LDB(dst, b, h) do { _Pragma("unroll") for (int n = 0; n < 2; ++n) _Pragma("unroll") for (int k = 0; k < 2; ++k) dst[n][k] = *(const PG8_LAS bf16x8*)(lds + PG8_SB(b, h) + boff + n * 2048 + k * 1024); } while (0)
; #define PG8_WAIT_V(n) asm volatile("s_waitcnt vmcnt(" #n ")" ::: "memory")
; #define PG8_WAIT_L(n) asm volatile("s_waitcnt lgkmcnt(" #n ")" ::: "memory")
; #define PG8_BAR __builtin_amdgcn_s_barrier()
; #define PG8_SCHED __builtin_amdgcn_sched_barrier(0)
; template <class Epi, class Sched, bool ALIGN_EPI = false, bool SP2 = false>
; __device__ __forceinline__ void gemm_phase(PG8_LAS unsigned char* lds, const Gemm g, const Sched& S, const Epi& E) {
;     ...
;             if constexpr (SP2) {
;             PG8_LDB(B0, 0, 0); PG8_LDB(B1, 0, 1); PG8_SCHED; PG8_LDA(At, 0, 0); PG8_STAGE(PG8_SA(1, 1), a1 + hstep, voffA);
;             PG8_WAIT_V(8); PG8_WAIT_L(0); PG8_BAR; PG8_MMA(0, 0, At, B0); PG8_MMA(0, 1, At, B1); PG8_BAR; PG8_SCHED;
;             PG8_LDA(At, 0, 1); PG8_STAGE(PG8_SB(0, 0), b2, voffB); PG8_STAGE(PG8_SB(0, 1), b2 + hstep, voffB); PG8_STAGE(PG8_SA(0, 0), a2, voffA);
;             PG8_WAIT_V(8); PG8_WAIT_L(0); PG8_BAR; PG8_MMA(1, 0, At, B0); PG8_MMA(1, 1, At, B1); PG8_BAR; PG8_SCHED;
;             PG8_LDB(B0, 1, 0); PG8_LDB(B1, 1, 1); PG8_SCHED; PG8_LDA(At, 1, 0); PG8_STAGE(PG8_SA(0, 1), a2 + hstep, voffA);
;             PG8_WAIT_V(8); PG8_WAIT_L(0); PG8_BAR; PG8_MMA(0, 0, At, B0); PG8_MMA(0, 1, At, B1); PG8_BAR; PG8_SCHED;
;             PG8_LDA(At, 1, 1); PG8_STAGE(PG8_SB(1, 0), b3, voffB); PG8_STAGE(PG8_SB(1, 1), b3 + hstep, voffB); PG8_STAGE(PG8_SA(1, 0), a3, voffA);
;             PG8_WAIT_V(8); PG8_WAIT_L(0); PG8_BAR; PG8_MMA(1, 0, At, B0); PG8_MMA(1, 1, At, B1); PG8_BAR; PG8_SCHED;
;     ...
;         if constexpr (ALIGN_EPI) { if (wr == 0) PG8_BAR; }
	s_add_i32 s66, s75, s2
	v_lshl_add_u64 v[164:165], v[164:165], 0, s[8:9]
	s_mov_b32 m0, s66
	ds_read_b128 v[184:187], v171 offset:49152
	ds_read_b128 v[190:193], v171 offset:50176
	ds_read_b128 v[194:197], v171 offset:51200
	ds_read_b128 v[198:201], v171 offset:52224
	ds_read_b128 v[202:205], v171 offset:53248
	ds_read_b128 v[206:209], v171 offset:54272
	ds_read_b128 v[214:217], v171 offset:55296
	ds_read_b128 v[218:221], v171 offset:56320
	global_load_lds_dwordx4 v[164:165], off
	s_add_i32 m0, s66, 0x2000
	s_add_u32 s64, s64, 0x80080
	v_lshl_add_u64 v[164:165], v[210:211], 0, s[8:9]
	s_addc_u32 s65, s65, 0
	s_add_i32 s66, s84, s2
	global_load_lds_dwordx4 v[164:165], off
	v_lshl_add_u64 v[164:165], s[64:65], 0, v[146:147]
	s_mov_b32 m0, s66
	s_nop 0
	global_load_lds_dwordx4 v[164:165], off
	v_lshl_add_u64 v[164:165], s[64:65], 0, v[150:151]
	s_add_i32 m0, s66, 0x2000
	s_nop 0
	global_load_lds_dwordx4 v[164:165], off
	v_lshl_add_u64 v[164:165], v[222:223], 0, s[8:9]
	s_mov_b32 m0, s68
	s_nop 0
	global_load_lds_dwordx4 v[164:165], off
	v_lshl_add_u64 v[164:165], v[224:225], 0, s[8:9]
	s_mov_b32 m0, s69
	s_nop 0
	global_load_lds_dwordx4 v[164:165], off
	s_waitcnt vmcnt(8)
	s_waitcnt lgkmcnt(0)
	s_setprio 1
	s_barrier
	s_waitcnt lgkmcnt(0)
	v_mfma_f32_16x16x32_bf16 v[60:63], v[128:131], v[184:187], v[60:63]
	v_mfma_f32_16x16x32_bf16 v[56:59], v[136:139], v[184:187], v[56:59]
	v_mfma_f32_16x16x32_bf16 v[44:47], v[128:131], v[194:197], v[44:47]
	v_mfma_f32_16x16x32_bf16 v[40:43], v[136:139], v[194:197], v[40:43]
	v_mfma_f32_16x16x32_bf16 v[28:31], v[128:131], v[202:205], v[28:31]
	v_mfma_f32_16x16x32_bf16 v[24:27], v[136:139], v[202:205], v[24:27]
	v_mfma_f32_16x16x32_bf16 v[12:15], v[128:131], v[214:217], v[12:15]
	v_mfma_f32_16x16x32_bf16 v[8:11], v[136:139], v[214:217], v[8:11]
	v_mfma_f32_16x16x32_bf16 v[60:63], v[132:135], v[190:193], v[60:63]
	v_mfma_f32_16x16x32_bf16 v[56:59], v[140:143], v[190:193], v[56:59]
	v_mfma_f32_16x16x32_bf16 v[44:47], v[132:135], v[198:201], v[44:47]
	v_mfma_f32_16x16x32_bf16 v[40:43], v[140:143], v[198:201], v[40:43]
	v_mfma_f32_16x16x32_bf16 v[28:31], v[132:135], v[206:209], v[28:31]
	v_mfma_f32_16x16x32_bf16 v[24:27], v[140:143], v[206:209], v[24:27]
	v_mfma_f32_16x16x32_bf16 v[12:15], v[132:135], v[218:221], v[12:15]
	v_mfma_f32_16x16x32_bf16 v[8:11], v[140:143], v[218:221], v[8:11]
	s_setprio 0
	s_setprio 1
	v_mfma_f32_16x16x32_bf16 v[52:55], v[160:163], v[184:187], v[52:55]
	v_mfma_f32_16x16x32_bf16 v[48:51], v[176:179], v[184:187], v[48:51]
	v_mfma_f32_16x16x32_bf16 v[36:39], v[160:163], v[194:197], v[36:39]
	v_mfma_f32_16x16x32_bf16 v[32:35], v[176:179], v[194:197], v[32:35]
	v_mfma_f32_16x16x32_bf16 v[20:23], v[160:163], v[202:205], v[20:23]
	v_mfma_f32_16x16x32_bf16 v[16:19], v[176:179], v[202:205], v[16:19]
	v_mfma_f32_16x16x32_bf16 v[4:7], v[160:163], v[214:217], v[4:7]
	v_mfma_f32_16x16x32_bf16 v[0:3], v[176:179], v[214:217], v[0:3]
	v_mfma_f32_16x16x32_bf16 v[52:55], v[172:175], v[190:193], v[52:55]
	v_mfma_f32_16x16x32_bf16 v[48:51], v[180:183], v[190:193], v[48:51]
	v_mfma_f32_16x16x32_bf16 v[36:39], v[172:175], v[198:201], v[36:39]
	v_mfma_f32_16x16x32_bf16 v[32:35], v[180:183], v[198:201], v[32:35]
	v_mfma_f32_16x16x32_bf16 v[20:23], v[172:175], v[206:209], v[20:23]
	v_mfma_f32_16x16x32_bf16 v[16:19], v[180:183], v[206:209], v[16:19]
	v_mfma_f32_16x16x32_bf16 v[4:7], v[172:175], v[218:221], v[4:7]
	v_mfma_f32_16x16x32_bf16 v[0:3], v[180:183], v[218:221], v[0:3]
	s_setprio 0
	s_barrier
	s_add_i32 s77, s77, 2
	s_add_u32 s62, s62, 0x100
	s_addc_u32 s63, s63, 0
	s_add_u32 s71, s71, 0x100
	s_addc_u32 s76, s76, 0
	s_cmp_gt_u32 s77, 29
	s_cbranch_scc0 .LBB0_781
	s_and_b64 vcc, exec, s[10:11]
	s_cbranch_vccz .LBB0_784
	s_barrier

;     __device__ bool next(int i, Unit& u) const { if (i >= n) return false; const int q = first + i; u.pm = rowbase + q % rows; u.pn = q / rows; return true; }
; #define PG8_STAGE(bufoff, gbase, voff) do { _Pragma("unroll") for (int _i = 0; _i < 2; ++_i) \
;         __builtin_amdgcn_global_load_lds((const unsigned*)((const char*)(gbase) + (voff)[_i]), (PG8_LAS unsigned*)(lds + (bufoff) + ldsw + _i * 8192), 16, 0, 0); } while (0)
; #define PG8_LDA(dst, b, h) do { _Pragma("unroll") for (int m = 0; m < 4; ++m) _Pragma("unroll") for (int k = 0; k < 2; ++k) dst[m][k] = *(const PG8_LAS bf16x8*)(lds + PG8_SA(b, h) + aoff + m * 2048 + k * 1024); } while (0)
; #define PG8_WAIT_V(n) asm volatile("s_waitcnt vmcnt(" #n ")" ::: "memory")
; template <class Epi, class Sched, bool ALIGN_EPI = false, bool SP2 = false>
; __device__ __forceinline__ void gemm_phase(PG8_LAS unsigned char* lds, const Gemm g, const Sched& S, const Epi& E) {
;     ...
;         const bool has_next = S.next(ui + 1, nxt);
;         const char* nA = has_next ? (const char*)g.A + (size_t)nxt.pm * tstep : cA; const char* nB = has_next ? (const char*)g.Bt + (size_t)nxt.pn * tstep : cB;
;         constexpr int NSEG = Epi::HAS_MID ? 2 : 1; const int tseg = nt / NSEG;
; #pragma unroll
;         for (int seg = 0; seg < NSEG; ++seg) {
;         if constexpr (Epi::HAS_MID) { if (seg == 1) E.mid(acc, cur, wr, wc, fr, fq); }
;         for (int t = seg * tseg; t < (seg + 1) * tseg; t += 2) {
;             const bool last = (t == nt - 2);
;             const char* a1 = cA + (size_t)(t + 1) * kstep;
;             const char* a2 = last ? nA : cA + (size_t)(t + 2) * kstep; const char* b2 = last ? nB : cB + (size_t)(t + 2) * kstep;
;             const char* a3 = a2 + kstep; const char* b3 = b2 + kstep;
;             if (last && has_next) S.a_ready(nxt);
;             if constexpr (SP2) {
;             PG8_LDB(B0, 0, 0); PG8_LDB(B1, 0, 1); PG8_SCHED; PG8_LDA(At, 0, 0); PG8_STAGE(PG8_SA(1, 1), a1 + hstep, voffA);
;             PG8_WAIT_V(8); PG8_WAIT_L(0); PG8_BAR; PG8_MMA(0, 0, At, B0); PG8_MMA(0, 1, At, B1); PG8_BAR; PG8_SCHED;
;             PG8_LDA(At, 0, 1); PG8_STAGE(PG8_SB(0, 0), b2, voffB); PG8_STAGE(PG8_SB(0, 1), b2 + hstep, voffB); PG8_STAGE(PG8_SA(0, 0), a2, voffA);
;             PG8_WAIT_V(8); PG8_WAIT_L(0); PG8_BAR; PG8_MMA(1, 0, At, B0); PG8_MMA(1, 1, At, B1); PG8_BAR; PG8_SCHED;
.LBB0_927:
	s_ashr_i32 s89, s88, 31
	s_lshl_b64 s[0:1], s[88:89], 20
	s_add_u32 s90, s54, s0
	s_addc_u32 s91, s55, s1
	s_and_b64 s[0:1], s[12:13], exec
	s_cselect_b32 s0, s91, s17
	s_cselect_b32 s1, s90, s16
	s_ashr_i32 s87, s86, 31
	s_lshl_b64 s[20:21], s[86:87], 20
	v_readlane_b32 s56, v242, 24
	v_readlane_b32 s57, v242, 25
	s_add_u32 s92, s56, s20
	s_addc_u32 s93, s57, s21
	s_and_b64 s[20:21], s[12:13], exec
	s_cselect_b32 s15, s93, s19
	s_cselect_b32 s87, s92, s18
	s_add_u32 s16, s16, 0x80080
	s_addc_u32 s17, s17, 0
	s_add_u32 s89, s18, 0x100
	s_addc_u32 s96, s19, 0
	s_mov_b32 s97, -2
	ds_read_b128 v[118:121], v225
	ds_read_b128 v[122:125], v225 offset:1024
	ds_read_b128 v[126:129], v225 offset:2048
	ds_read_b128 v[130:133], v225 offset:3072
	ds_read_b128 v[134:137], v226
	ds_read_b128 v[138:141], v226 offset:1024
	ds_read_b128 v[142:145], v226 offset:2048
	ds_read_b128 v[146:149], v226 offset:3072
	s_add_u32 s18, s16, 0xfff80080
	s_addc_u32 s19, s17, -1
	s_cmp_eq_u32 s97, 28
	s_cselect_b32 s21, s0, s19
	s_cselect_b32 s20, s1, s18
	s_cselect_b32 s19, s15, s96
	s_cselect_b32 s18, s87, s89
	v_lshl_add_u64 v[112:113], s[16:17], 0, v[190:191]
	s_add_i32 m0, s29, 0xc000
	ds_read_b128 v[162:165], v227
	ds_read_b128 v[166:169], v227 offset:1024
	ds_read_b128 v[170:173], v227 offset:2048
	ds_read_b128 v[174:177], v227 offset:3072
	ds_read_b128 v[198:201], v227 offset:4096
	ds_read_b128 v[202:205], v227 offset:5120
	ds_read_b128 v[206:209], v227 offset:6144
	ds_read_b128 v[228:231], v227 offset:7168
	global_load_lds_dwordx4 v[112:113], off
	v_lshl_add_u64 v[112:113], s[16:17], 0, v[192:193]
	s_add_i32 m0, s29, 0xe000
	s_nop 0
	global_load_lds_dwordx4 v[112:113], off
	s_waitcnt vmcnt(8)
	s_waitcnt lgkmcnt(0)
	s_setprio 1
	s_barrier
	s_waitcnt lgkmcnt(0)
	v_mfma_f32_16x16x32_bf16 v[158:161], v[118:121], v[162:165], 0
	v_mfma_f32_16x16x32_bf16 v[60:63], v[126:129], v[162:165], 0
	v_mfma_f32_16x16x32_bf16 v[154:157], v[118:121], v[170:173], 0
	v_mfma_f32_16x16x32_bf16 v[52:55], v[126:129], v[170:173], 0
	v_mfma_f32_16x16x32_bf16 v[112:115], v[118:121], v[198:201], 0
	v_mfma_f32_16x16x32_bf16 v[44:47], v[126:129], v[198:201], 0
	v_mfma_f32_16x16x32_bf16 v[100:103], v[118:121], v[206:209], 0
	v_mfma_f32_16x16x32_bf16 v[36:39], v[126:129], v[206:209], 0
	v_mfma_f32_16x16x32_bf16 v[158:161], v[122:125], v[166:169], v[158:161]
	v_mfma_f32_16x16x32_bf16 v[60:63], v[130:133], v[166:169], v[60:63]
	v_mfma_f32_16x16x32_bf16 v[154:157], v[122:125], v[174:177], v[154:157]
	v_mfma_f32_16x16x32_bf16 v[52:55], v[130:133], v[174:177], v[52:55]
	v_mfma_f32_16x16x32_bf16 v[112:115], v[122:125], v[202:205], v[112:115]
	v_mfma_f32_16x16x32_bf16 v[44:47], v[130:133], v[202:205], v[44:47]
	v_mfma_f32_16x16x32_bf16 v[100:103], v[122:125], v[228:231], v[100:103]
	v_mfma_f32_16x16x32_bf16 v[36:39], v[130:133], v[228:231], v[36:39]
	s_setprio 0
	s_setprio 1
	v_mfma_f32_16x16x32_bf16 v[108:111], v[134:137], v[162:165], 0
	v_mfma_f32_16x16x32_bf16 v[56:59], v[142:145], v[162:165], 0
	v_mfma_f32_16x16x32_bf16 v[150:153], v[134:137], v[170:173], 0
	v_mfma_f32_16x16x32_bf16 v[48:51], v[142:145], v[170:173], 0
	v_mfma_f32_16x16x32_bf16 v[104:107], v[134:137], v[198:201], 0
	v_mfma_f32_16x16x32_bf16 v[40:43], v[142:145], v[198:201], 0
	v_mfma_f32_16x16x32_bf16 v[96:99], v[134:137], v[206:209], 0
	v_mfma_f32_16x16x32_bf16 v[32:35], v[142:145], v[206:209], 0
	v_mfma_f32_16x16x32_bf16 v[108:111], v[138:141], v[166:169], v[108:111]
	v_mfma_f32_16x16x32_bf16 v[56:59], v[146:149], v[166:169], v[56:59]
	v_mfma_f32_16x16x32_bf16 v[150:153], v[138:141], v[174:177], v[150:153]
	v_mfma_f32_16x16x32_bf16 v[48:51], v[146:149], v[174:177], v[48:51]
	v_mfma_f32_16x16x32_bf16 v[104:107], v[138:141], v[202:205], v[104:107]
	v_mfma_f32_16x16x32_bf16 v[40:43], v[146:149], v[202:205], v[40:43]
	v_mfma_f32_16x16x32_bf16 v[96:99], v[138:141], v[228:231], v[96:99]
	v_mfma_f32_16x16x32_bf16 v[32:35], v[146:149], v[228:231], v[32:35]
	s_setprio 0
	s_barrier
	s_add_i32 vcc_lo, s31, s28
	v_lshl_add_u64 v[210:211], s[18:19], 0, v[180:181]
	s_mov_b32 m0, vcc_lo
	ds_read_b128 v[162:165], v227 offset:16384
	ds_read_b128 v[166:169], v227 offset:17408
	ds_read_b128 v[170:173], v227 offset:18432
	ds_read_b128 v[174:177], v227 offset:19456
	ds_read_b128 v[198:201], v227 offset:20480
	ds_read_b128 v[202:205], v227 offset:21504
	ds_read_b128 v[206:209], v227 offset:22528
	ds_read_b128 v[228:231], v227 offset:23552
	global_load_lds_dwordx4 v[210:211], off
	s_add_i32 m0, vcc_lo, 0x2000
	s_add_u32 vcc_lo, s18, 0x80000
	v_lshl_add_u64 v[232:233], s[18:19], 0, v[184:185]
	s_addc_u32 vcc_hi, s19, 0
	s_add_i32 s22, s74, s28
	global_load_lds_dwordx4 v[232:233], off
	v_lshl_add_u64 v[116:117], vcc, 0, v[180:181]
	s_mov_b32 m0, s22
	v_lshl_add_u64 v[234:235], s[20:21], 0, v[178:179]
	global_load_lds_dwordx4 v[116:117], off
	v_lshl_add_u64 v[116:117], vcc, 0, v[184:185]
	s_add_i32 m0, s22, 0x2000
	v_lshl_add_u64 v[236:237], s[20:21], 0, v[182:183]
	global_load_lds_dwordx4 v[116:117], off
	s_mov_b32 m0, s29
	s_nop 0
	global_load_lds_dwordx4 v[234:235], off
	s_mov_b32 m0, s85
	s_nop 0
	global_load_lds_dwordx4 v[236:237], off
	s_waitcnt vmcnt(8)
	s_waitcnt lgkmcnt(0)
	s_setprio 1
	s_barrier
; #define PG8_STAGE(bufoff, gbase, voff) do { _Pragma("unroll") for (int _i = 0; _i < 2; ++_i) \
;         __builtin_amdgcn_global_load_lds((const unsigned*)((const char*)(gbase) + (voff)[_i]), (PG8_LAS unsigned*)(lds + (bufoff) + ldsw + _i * 8192), 16, 0, 0); } while (0)
; #define PG8_LDA(dst, b, h) do { _Pragma("unroll") for (int m = 0; m < 4; ++m) _Pragma("unroll") for (int k = 0; k < 2; ++k) dst[m][k] = *(const PG8_LAS bf16x8*)(lds + PG8_SA(b, h) + aoff + m * 2048 + k * 1024); } while (0)
; #define PG8_LDB(dst, b, h) do { _Pragma("unroll") for (int n = 0; n < 2; ++n) _Pragma("unroll") for (int k = 0; k < 2; ++k) dst[n][k] = *(const PG8_LAS bf16x8*)(lds + PG8_SB(b, h) + boff + n * 2048 + k * 1024); } while (0)
; #define PG8_MMA(ai, bj, At, Bt) do { __builtin_amdgcn_s_setprio(1); _Pragma("unroll") for (int m = 0; m < 4; ++m) _Pragma("unroll") for (int n = 0; n < 2; ++n) _Pragma("unroll") for (int k = 0; k < 2; ++k) \
;         acc[ai][bj][m][n] = __builtin_amdgcn_mfma_f32_16x16x32_bf16(Bt[n][k], At[m][k], acc[ai][bj][m][n], 0, 0, 0); __builtin_amdgcn_s_setprio(0); } while (0)
; #define PG8_BAR __builtin_amdgcn_s_barrier()
; template <class Epi, class Sched, bool ALIGN_EPI = false, bool SP2 = false>
; __device__ __forceinline__ void gemm_phase(PG8_LAS unsigned char* lds, const Gemm g, const Sched& S, const Epi& E) {
;     ...
;             if constexpr (SP2) {
;             PG8_LDB(B0, 0, 0); PG8_LDB(B1, 0, 1); PG8_SCHED; PG8_LDA(At, 0, 0); PG8_STAGE(PG8_SA(1, 1), a1 + hstep, voffA);
;             PG8_WAIT_V(8); PG8_WAIT_L(0); PG8_BAR; PG8_MMA(0, 0, At, B0); PG8_MMA(0, 1, At, B1); PG8_BAR; PG8_SCHED;
;             PG8_LDA(At, 0, 1); PG8_STAGE(PG8_SB(0, 0), b2, voffB); PG8_STAGE(PG8_SB(0, 1), b2 + hstep, voffB); PG8_STAGE(PG8_SA(0, 0), a2, voffA);
;             PG8_WAIT_V(8); PG8_WAIT_L(0); PG8_BAR; PG8_MMA(1, 0, At, B0); PG8_MMA(1, 1, At, B1); PG8_BAR; PG8_SCHED;
;             PG8_LDB(B0, 1, 0); PG8_LDB(B1, 1, 1); PG8_SCHED; PG8_LDA(At, 1, 0); PG8_STAGE(PG8_SA(0, 1), a2 + hstep, voffA);
;             PG8_WAIT_V(8); PG8_WAIT_L(0); PG8_BAR; PG8_MMA(0, 0, At, B0); PG8_MMA(0, 1, At, B1); PG8_BAR; PG8_SCHED;
;             PG8_LDA(At, 1, 1); PG8_STAGE(PG8_SB(1, 0), b3, voffB); PG8_STAGE(PG8_SB(1, 1), b3 + hstep, voffB); PG8_STAGE(PG8_SA(1, 0), a3, voffA);
;             PG8_WAIT_V(8); PG8_WAIT_L(0); PG8_BAR; PG8_MMA(1, 0, At, B0); PG8_MMA(1, 1, At, B1); PG8_BAR; PG8_SCHED;
	s_waitcnt lgkmcnt(0)
	v_mfma_f32_16x16x32_bf16 v[92:95], v[118:121], v[162:165], 0
	v_mfma_f32_16x16x32_bf16 v[28:31], v[126:129], v[162:165], 0
	v_mfma_f32_16x16x32_bf16 v[84:87], v[118:121], v[170:173], 0
	v_mfma_f32_16x16x32_bf16 v[20:23], v[126:129], v[170:173], 0
	v_mfma_f32_16x16x32_bf16 v[76:79], v[118:121], v[198:201], 0
	v_mfma_f32_16x16x32_bf16 v[12:15], v[126:129], v[198:201], 0
	v_mfma_f32_16x16x32_bf16 v[68:71], v[118:121], v[206:209], 0
	v_mfma_f32_16x16x32_bf16 v[4:7], v[126:129], v[206:209], 0
	v_mfma_f32_16x16x32_bf16 v[92:95], v[122:125], v[166:169], v[92:95]
	v_mfma_f32_16x16x32_bf16 v[28:31], v[130:133], v[166:169], v[28:31]
	v_mfma_f32_16x16x32_bf16 v[84:87], v[122:125], v[174:177], v[84:87]
	v_mfma_f32_16x16x32_bf16 v[20:23], v[130:133], v[174:177], v[20:23]
	v_mfma_f32_16x16x32_bf16 v[76:79], v[122:125], v[202:205], v[76:79]
	v_mfma_f32_16x16x32_bf16 v[12:15], v[130:133], v[202:205], v[12:15]
	v_mfma_f32_16x16x32_bf16 v[68:71], v[122:125], v[228:231], v[68:71]
	v_mfma_f32_16x16x32_bf16 v[4:7], v[130:133], v[228:231], v[4:7]
	s_setprio 0
	s_setprio 1
	v_mfma_f32_16x16x32_bf16 v[88:91], v[134:137], v[162:165], 0
	v_mfma_f32_16x16x32_bf16 v[24:27], v[142:145], v[162:165], 0
	v_mfma_f32_16x16x32_bf16 v[80:83], v[134:137], v[170:173], 0
	v_mfma_f32_16x16x32_bf16 v[16:19], v[142:145], v[170:173], 0
	v_mfma_f32_16x16x32_bf16 v[72:75], v[134:137], v[198:201], 0
	v_mfma_f32_16x16x32_bf16 v[8:11], v[142:145], v[198:201], 0
	v_mfma_f32_16x16x32_bf16 v[64:67], v[134:137], v[206:209], 0
	v_mfma_f32_16x16x32_bf16 v[0:3], v[142:145], v[206:209], 0
	v_mfma_f32_16x16x32_bf16 v[88:91], v[138:141], v[166:169], v[88:91]
	v_mfma_f32_16x16x32_bf16 v[24:27], v[146:149], v[166:169], v[24:27]
	v_mfma_f32_16x16x32_bf16 v[80:83], v[138:141], v[174:177], v[80:83]
	v_mfma_f32_16x16x32_bf16 v[16:19], v[146:149], v[174:177], v[16:19]
	v_mfma_f32_16x16x32_bf16 v[72:75], v[138:141], v[202:205], v[72:75]
	v_mfma_f32_16x16x32_bf16 v[8:11], v[146:149], v[202:205], v[8:11]
	v_mfma_f32_16x16x32_bf16 v[64:67], v[138:141], v[228:231], v[64:67]
	v_mfma_f32_16x16x32_bf16 v[0:3], v[146:149], v[228:231], v[0:3]
	s_setprio 0
	s_barrier
	v_add_u32_e32 v116, s75, v214
	ds_read_b128 v[118:121], v116
	ds_read_b128 v[122:125], v116 offset:1024
	ds_read_b128 v[126:129], v116 offset:2048
	ds_read_b128 v[130:133], v116 offset:3072
	v_add_u32_e32 v116, s84, v214
	ds_read_b128 v[134:137], v116
	ds_read_b128 v[138:141], v116 offset:1024
	ds_read_b128 v[142:145], v116 offset:2048
	ds_read_b128 v[146:149], v116 offset:3072
	s_add_u32 s20, s20, 0x80000
	s_addc_u32 s21, s21, 0
	s_mov_b32 m0, s95
	v_lshl_add_u64 v[116:117], s[20:21], 0, v[178:179]
	ds_read_b128 v[162:165], v227 offset:32768
	ds_read_b128 v[166:169], v227 offset:33792
	ds_read_b128 v[170:173], v227 offset:34816
	ds_read_b128 v[174:177], v227 offset:35840
	ds_read_b128 v[198:201], v227 offset:36864
	ds_read_b128 v[202:205], v227 offset:37888
	ds_read_b128 v[206:209], v227 offset:38912
	ds_read_b128 v[228:231], v227 offset:39936
	global_load_lds_dwordx4 v[116:117], off
	v_lshl_add_u64 v[116:117], s[20:21], 0, v[182:183]
	s_mov_b32 m0, s2
	s_nop 0
	global_load_lds_dwordx4 v[116:117], off
	s_waitcnt vmcnt(8)
	s_waitcnt lgkmcnt(0)
	s_setprio 1
	s_barrier
	s_waitcnt lgkmcnt(0)
	v_mfma_f32_16x16x32_bf16 v[158:161], v[118:121], v[162:165], v[158:161]
	v_mfma_f32_16x16x32_bf16 v[60:63], v[126:129], v[162:165], v[60:63]
	v_mfma_f32_16x16x32_bf16 v[154:157], v[118:121], v[170:173], v[154:157]
	v_mfma_f32_16x16x32_bf16 v[52:55], v[126:129], v[170:173], v[52:55]
	v_mfma_f32_16x16x32_bf16 v[112:115], v[118:121], v[198:201], v[112:115]
	v_mfma_f32_16x16x32_bf16 v[44:47], v[126:129], v[198:201], v[44:47]
	v_mfma_f32_16x16x32_bf16 v[100:103], v[118:121], v[206:209], v[100:103]
	v_mfma_f32_16x16x32_bf16 v[36:39], v[126:129], v[206:209], v[36:39]
	v_mfma_f32_16x16x32_bf16 v[158:161], v[122:125], v[166:169], v[158:161]
	v_mfma_f32_16x16x32_bf16 v[60:63], v[130:133], v[166:169], v[60:63]
	v_mfma_f32_16x16x32_bf16 v[154:157], v[122:125], v[174:177], v[154:157]
	v_mfma_f32_16x16x32_bf16 v[52:55], v[130:133], v[174:177], v[52:55]
	v_mfma_f32_16x16x32_bf16 v[114:117], v[122:125], v[202:205], v[112:115]
	v_mfma_f32_16x16x32_bf16 v[44:47], v[130:133], v[202:205], v[44:47]
	v_mfma_f32_16x16x32_bf16 v[100:103], v[122:125], v[228:231], v[100:103]
	v_mfma_f32_16x16x32_bf16 v[36:39], v[130:133], v[228:231], v[36:39]
	s_setprio 0
	s_setprio 1
	v_mfma_f32_16x16x32_bf16 v[108:111], v[134:137], v[162:165], v[108:111]
	v_mfma_f32_16x16x32_bf16 v[56:59], v[142:145], v[162:165], v[56:59]
	v_mfma_f32_16x16x32_bf16 v[150:153], v[134:137], v[170:173], v[150:153]
	v_mfma_f32_16x16x32_bf16 v[48:51], v[142:145], v[170:173], v[48:51]
	v_mfma_f32_16x16x32_bf16 v[104:107], v[134:137], v[198:201], v[104:107]
	v_mfma_f32_16x16x32_bf16 v[40:43], v[142:145], v[198:201], v[40:43]
	v_mfma_f32_16x16x32_bf16 v[96:99], v[134:137], v[206:209], v[96:99]
	v_mfma_f32_16x16x32_bf16 v[32:35], v[142:145], v[206:209], v[32:35]
	v_mfma_f32_16x16x32_bf16 v[108:111], v[138:141], v[166:169], v[108:111]
	v_mfma_f32_16x16x32_bf16 v[56:59], v[146:149], v[166:169], v[56:59]
	v_mfma_f32_16x16x32_bf16 v[150:153], v[138:141], v[174:177], v[150:153]
	v_mfma_f32_16x16x32_bf16 v[48:51], v[146:149], v[174:177], v[48:51]
	v_mfma_f32_16x16x32_bf16 v[104:107], v[138:141], v[202:205], v[104:107]
	v_mfma_f32_16x16x32_bf16 v[40:43], v[146:149], v[202:205], v[40:43]
	v_mfma_f32_16x16x32_bf16 v[96:99], v[138:141], v[228:231], v[96:99]
	v_mfma_f32_16x16x32_bf16 v[32:35], v[146:149], v[228:231], v[32:35]
	s_setprio 0
	s_barrier
; #define PG8_STAGE(bufoff, gbase, voff) do { _Pragma("unroll") for (int _i = 0; _i < 2; ++_i) \
;         __builtin_amdgcn_global_load_lds((const unsigned*)((const char*)(gbase) + (voff)[_i]), (PG8_LAS unsigned*)(lds + (bufoff) + ldsw + _i * 8192), 16, 0, 0); } while (0)
; #define PG8_LDA(dst, b, h) do { _Pragma("unroll") for (int m = 0; m < 4; ++m) _Pragma("unroll") for (int k = 0; k < 2; ++k) dst[m][k] = *(const PG8_LAS bf16x8*)(lds + PG8_SA(b, h) + aoff + m * 2048 + k * 1024); } while (0)
; #define PG8_WAIT_V(n) asm volatile("s_waitcnt vmcnt(" #n ")" ::: "memory")
; #define PG8_WAIT_L(n) asm volatile("s_waitcnt lgkmcnt(" #n ")" ::: "memory")
; #define PG8_BAR __builtin_amdgcn_s_barrier()
; template <class Epi, class Sched, bool ALIGN_EPI = false, bool SP2 = false>
; __device__ __forceinline__ void gemm_phase(PG8_LAS unsigned char* lds, const Gemm g, const Sched& S, const Epi& E) {
;     ...
;         for (int t = seg * tseg; t < (seg + 1) * tseg; t += 2) {
;             const bool last = (t == nt - 2);
;             const char* a1 = cA + (size_t)(t + 1) * kstep;
;             const char* a2 = last ? nA : cA + (size_t)(t + 2) * kstep; const char* b2 = last ? nB : cB + (size_t)(t + 2) * kstep;
;             const char* a3 = a2 + kstep; const char* b3 = b2 + kstep;
;             if (last && has_next) S.a_ready(nxt);
;             if constexpr (SP2) {
;             PG8_LDB(B0, 0, 0); PG8_LDB(B1, 0, 1); PG8_SCHED; PG8_LDA(At, 0, 0); PG8_STAGE(PG8_SA(1, 1), a1 + hstep, voffA);
;             PG8_WAIT_V(8); PG8_WAIT_L(0); PG8_BAR; PG8_MMA(0, 0, At, B0); PG8_MMA(0, 1, At, B1); PG8_BAR; PG8_SCHED;
;             PG8_LDA(At, 0, 1); PG8_STAGE(PG8_SB(0, 0), b2, voffB); PG8_STAGE(PG8_SB(0, 1), b2 + hstep, voffB); PG8_STAGE(PG8_SA(0, 0), a2, voffA);
;             PG8_WAIT_V(8); PG8_WAIT_L(0); PG8_BAR; PG8_MMA(1, 0, At, B0); PG8_MMA(1, 1, At, B1); PG8_BAR; PG8_SCHED;
;             PG8_LDB(B0, 1, 0); PG8_LDB(B1, 1, 1); PG8_SCHED; PG8_LDA(At, 1, 0); PG8_STAGE(PG8_SA(0, 1), a2 + hstep, voffA);
;             PG8_WAIT_V(8); PG8_WAIT_L(0); PG8_BAR; PG8_MMA(0, 0, At, B0); PG8_MMA(0, 1, At, B1); PG8_BAR; PG8_SCHED;
;             PG8_LDA(At, 1, 1); PG8_STAGE(PG8_SB(1, 0), b3, voffB); PG8_STAGE(PG8_SB(1, 1), b3 + hstep, voffB); PG8_STAGE(PG8_SA(1, 0), a3, voffA);
;             PG8_WAIT_V(8); PG8_WAIT_L(0); PG8_BAR; PG8_MMA(1, 0, At, B0); PG8_MMA(1, 1, At, B1); PG8_BAR; PG8_SCHED;
	s_add_i32 s20, s75, s28
	v_lshl_add_u64 v[112:113], v[210:211], 0, s[46:47]
	s_mov_b32 m0, s20
	ds_read_b128 v[162:165], v227 offset:49152
	ds_read_b128 v[166:169], v227 offset:50176
	ds_read_b128 v[170:173], v227 offset:51200
	ds_read_b128 v[174:177], v227 offset:52224
	ds_read_b128 v[198:201], v227 offset:53248
	ds_read_b128 v[202:205], v227 offset:54272
	ds_read_b128 v[206:209], v227 offset:55296
	ds_read_b128 v[228:231], v227 offset:56320
	global_load_lds_dwordx4 v[112:113], off
	s_add_i32 m0, s20, 0x2000
	s_add_u32 s18, s18, 0x80080
	v_lshl_add_u64 v[112:113], v[232:233], 0, s[46:47]
	s_addc_u32 s19, s19, 0
	s_add_i32 s20, s84, s28
	global_load_lds_dwordx4 v[112:113], off
	v_lshl_add_u64 v[112:113], s[18:19], 0, v[180:181]
	s_mov_b32 m0, s20
	s_nop 0
	global_load_lds_dwordx4 v[112:113], off
	v_lshl_add_u64 v[112:113], s[18:19], 0, v[184:185]
	s_add_i32 m0, s20, 0x2000
	s_nop 0
	global_load_lds_dwordx4 v[112:113], off
	v_lshl_add_u64 v[112:113], v[234:235], 0, s[46:47]
	s_mov_b32 m0, s30
	s_nop 0
	global_load_lds_dwordx4 v[112:113], off
	v_lshl_add_u64 v[112:113], v[236:237], 0, s[46:47]
	s_mov_b32 m0, s23
	s_nop 0
	global_load_lds_dwordx4 v[112:113], off
	s_waitcnt vmcnt(8)
	s_waitcnt lgkmcnt(0)
	s_setprio 1
	s_barrier
	s_waitcnt lgkmcnt(0)
	v_mfma_f32_16x16x32_bf16 v[92:95], v[118:121], v[162:165], v[92:95]
	v_mfma_f32_16x16x32_bf16 v[28:31], v[126:129], v[162:165], v[28:31]
	v_mfma_f32_16x16x32_bf16 v[84:87], v[118:121], v[170:173], v[84:87]
	v_mfma_f32_16x16x32_bf16 v[20:23], v[126:129], v[170:173], v[20:23]
	v_mfma_f32_16x16x32_bf16 v[76:79], v[118:121], v[198:201], v[76:79]
	v_mfma_f32_16x16x32_bf16 v[12:15], v[126:129], v[198:201], v[12:15]
	v_mfma_f32_16x16x32_bf16 v[68:71], v[118:121], v[206:209], v[68:71]
	v_mfma_f32_16x16x32_bf16 v[4:7], v[126:129], v[206:209], v[4:7]
	v_mfma_f32_16x16x32_bf16 v[92:95], v[122:125], v[166:169], v[92:95]
	v_mfma_f32_16x16x32_bf16 v[28:31], v[130:133], v[166:169], v[28:31]
	v_mfma_f32_16x16x32_bf16 v[84:87], v[122:125], v[174:177], v[84:87]
	v_mfma_f32_16x16x32_bf16 v[20:23], v[130:133], v[174:177], v[20:23]
	v_mfma_f32_16x16x32_bf16 v[76:79], v[122:125], v[202:205], v[76:79]
	v_mfma_f32_16x16x32_bf16 v[12:15], v[130:133], v[202:205], v[12:15]
	v_mfma_f32_16x16x32_bf16 v[68:71], v[122:125], v[228:231], v[68:71]
	v_mfma_f32_16x16x32_bf16 v[4:7], v[130:133], v[228:231], v[4:7]
	s_setprio 0
	s_setprio 1
	v_mfma_f32_16x16x32_bf16 v[88:91], v[134:137], v[162:165], v[88:91]
	v_mfma_f32_16x16x32_bf16 v[24:27], v[142:145], v[162:165], v[24:27]
	v_mfma_f32_16x16x32_bf16 v[80:83], v[134:137], v[170:173], v[80:83]
	v_mfma_f32_16x16x32_bf16 v[16:19], v[142:145], v[170:173], v[16:19]
	v_mfma_f32_16x16x32_bf16 v[72:75], v[134:137], v[198:201], v[72:75]
	v_mfma_f32_16x16x32_bf16 v[8:11], v[142:145], v[198:201], v[8:11]
	v_mfma_f32_16x16x32_bf16 v[64:67], v[134:137], v[206:209], v[64:67]
	v_mfma_f32_16x16x32_bf16 v[0:3], v[142:145], v[206:209], v[0:3]
	v_mfma_f32_16x16x32_bf16 v[88:91], v[138:141], v[166:169], v[88:91]
	v_mfma_f32_16x16x32_bf16 v[24:27], v[146:149], v[166:169], v[24:27]
	v_mfma_f32_16x16x32_bf16 v[80:83], v[138:141], v[174:177], v[80:83]
	v_mfma_f32_16x16x32_bf16 v[16:19], v[146:149], v[174:177], v[16:19]
	v_mfma_f32_16x16x32_bf16 v[72:75], v[138:141], v[202:205], v[72:75]
	v_mfma_f32_16x16x32_bf16 v[8:11], v[146:149], v[202:205], v[8:11]
	v_mfma_f32_16x16x32_bf16 v[64:67], v[138:141], v[228:231], v[64:67]
	v_mfma_f32_16x16x32_bf16 v[0:3], v[146:149], v[228:231], v[0:3]
	s_setprio 0
	s_barrier
	s_add_i32 s97, s97, 2
	s_add_u32 s16, s16, 0x100
	s_addc_u32 s17, s17, 0
	s_add_u32 s89, s89, 0x100
	s_addc_u32 s96, s96, 0
	s_cmp_gt_u32 s97, 29
.LBB0_928:
	ds_read_b128 v[118:121], v225
	ds_read_b128 v[122:125], v225 offset:1024
	ds_read_b128 v[126:129], v225 offset:2048
	ds_read_b128 v[130:133], v225 offset:3072
	ds_read_b128 v[134:137], v226
	ds_read_b128 v[138:141], v226 offset:1024
	ds_read_b128 v[142:145], v226 offset:2048
	ds_read_b128 v[146:149], v226 offset:3072
	s_add_u32 s18, s16, 0xfff80080
	s_addc_u32 s19, s17, -1
	s_cmp_eq_u32 s97, 28
	s_cselect_b32 s21, s0, s19
	s_cselect_b32 s20, s1, s18
	s_cselect_b32 s19, s15, s96
	s_cselect_b32 s18, s87, s89
	v_lshl_add_u64 v[112:113], s[16:17], 0, v[190:191]
	s_add_i32 m0, s29, 0xc000
	ds_read_b128 v[162:165], v227
	ds_read_b128 v[166:169], v227 offset:1024
	ds_read_b128 v[170:173], v227 offset:2048
	ds_read_b128 v[174:177], v227 offset:3072
	ds_read_b128 v[198:201], v227 offset:4096
	ds_read_b128 v[202:205], v227 offset:5120
	ds_read_b128 v[206:209], v227 offset:6144
	ds_read_b128 v[228:231], v227 offset:7168
	global_load_lds_dwordx4 v[112:113], off
	v_lshl_add_u64 v[112:113], s[16:17], 0, v[192:193]
	s_add_i32 m0, s29, 0xe000
	s_nop 0
	global_load_lds_dwordx4 v[112:113], off
	s_waitcnt vmcnt(8)
	s_waitcnt lgkmcnt(0)
	s_setprio 1
	s_barrier
; #define PG8_STAGE(bufoff, gbase, voff) do { _Pragma("unroll") for (int _i = 0; _i < 2; ++_i) \
;         __builtin_amdgcn_global_load_lds((const unsigned*)((const char*)(gbase) + (voff)[_i]), (PG8_LAS unsigned*)(lds + (bufoff) + ldsw + _i * 8192), 16, 0, 0); } while (0)
; #define PG8_LDA(dst, b, h) do { _Pragma("unroll") for (int m = 0; m < 4; ++m) _Pragma("unroll") for (int k = 0; k < 2; ++k) dst[m][k] = *(const PG8_LAS bf16x8*)(lds + PG8_SA(b, h) + aoff + m * 2048 + k * 1024); } while (0)
; #define PG8_LDB(dst, b, h) do { _Pragma("unroll") for (int n = 0; n < 2; ++n) _Pragma("unroll") for (int k = 0; k < 2; ++k) dst[n][k] = *(const PG8_LAS bf16x8*)(lds + PG8_SB(b, h) + boff + n * 2048 + k * 1024); } while (0)
; #define PG8_MMA(ai, bj, At, Bt) do { __builtin_amdgcn_s_setprio(1); _Pragma("unroll") for (int m = 0; m < 4; ++m) _Pragma("unroll") for (int n = 0; n < 2; ++n) _Pragma("unroll") for (int k = 0; k < 2; ++k) \
;         acc[ai][bj][m][n] = __builtin_amdgcn_mfma_f32_16x16x32_bf16(Bt[n][k], At[m][k], acc[ai][bj][m][n], 0, 0, 0); __builtin_amdgcn_s_setprio(0); } while (0)
; #define PG8_BAR __builtin_amdgcn_s_barrier()
; template <class Epi, class Sched, bool ALIGN_EPI = false, bool SP2 = false>
; __device__ __forceinline__ void gemm_phase(PG8_LAS unsigned char* lds, const Gemm g, const Sched& S, const Epi& E) {
;     ...
;             if constexpr (SP2) {
;             PG8_LDB(B0, 0, 0); PG8_LDB(B1, 0, 1); PG8_SCHED; PG8_LDA(At, 0, 0); PG8_STAGE(PG8_SA(1, 1), a1 + hstep, voffA);
;             PG8_WAIT_V(8); PG8_WAIT_L(0); PG8_BAR; PG8_MMA(0, 0, At, B0); PG8_MMA(0, 1, At, B1); PG8_BAR; PG8_SCHED;
;             PG8_LDA(At, 0, 1); PG8_STAGE(PG8_SB(0, 0), b2, voffB); PG8_STAGE(PG8_SB(0, 1), b2 + hstep, voffB); PG8_STAGE(PG8_SA(0, 0), a2, voffA);
;             PG8_WAIT_V(8); PG8_WAIT_L(0); PG8_BAR; PG8_MMA(1, 0, At, B0); PG8_MMA(1, 1, At, B1); PG8_BAR; PG8_SCHED;
;             PG8_LDB(B0, 1, 0); PG8_LDB(B1, 1, 1); PG8_SCHED; PG8_LDA(At, 1, 0); PG8_STAGE(PG8_SA(0, 1), a2 + hstep, voffA);
;             PG8_WAIT_V(8); PG8_WAIT_L(0); PG8_BAR; PG8_MMA(0, 0, At, B0); PG8_MMA(0, 1, At, B1); PG8_BAR; PG8_SCHED;
;             PG8_LDA(At, 1, 1); PG8_STAGE(PG8_SB(1, 0), b3, voffB); PG8_STAGE(PG8_SB(1, 1), b3 + hstep, voffB); PG8_STAGE(PG8_SA(1, 0), a3, voffA);
;             PG8_WAIT_V(8); PG8_WAIT_L(0); PG8_BAR; PG8_MMA(1, 0, At, B0); PG8_MMA(1, 1, At, B1); PG8_BAR; PG8_SCHED;
	s_waitcnt lgkmcnt(0)
	v_mfma_f32_16x16x32_bf16 v[158:161], v[118:121], v[162:165], v[158:161]
	v_mfma_f32_16x16x32_bf16 v[60:63], v[126:129], v[162:165], v[60:63]
	v_mfma_f32_16x16x32_bf16 v[154:157], v[118:121], v[170:173], v[154:157]
	v_mfma_f32_16x16x32_bf16 v[52:55], v[126:129], v[170:173], v[52:55]
	v_mfma_f32_16x16x32_bf16 v[112:115], v[118:121], v[198:201], v[114:117]
	v_mfma_f32_16x16x32_bf16 v[44:47], v[126:129], v[198:201], v[44:47]
	v_mfma_f32_16x16x32_bf16 v[100:103], v[118:121], v[206:209], v[100:103]
	v_mfma_f32_16x16x32_bf16 v[36:39], v[126:129], v[206:209], v[36:39]
	v_mfma_f32_16x16x32_bf16 v[158:161], v[122:125], v[166:169], v[158:161]
	v_mfma_f32_16x16x32_bf16 v[60:63], v[130:133], v[166:169], v[60:63]
	v_mfma_f32_16x16x32_bf16 v[154:157], v[122:125], v[174:177], v[154:157]
	v_mfma_f32_16x16x32_bf16 v[52:55], v[130:133], v[174:177], v[52:55]
	v_mfma_f32_16x16x32_bf16 v[112:115], v[122:125], v[202:205], v[112:115]
	v_mfma_f32_16x16x32_bf16 v[44:47], v[130:133], v[202:205], v[44:47]
	v_mfma_f32_16x16x32_bf16 v[100:103], v[122:125], v[228:231], v[100:103]
	v_mfma_f32_16x16x32_bf16 v[36:39], v[130:133], v[228:231], v[36:39]
	s_setprio 0
	s_setprio 1
	v_mfma_f32_16x16x32_bf16 v[108:111], v[134:137], v[162:165], v[108:111]
	v_mfma_f32_16x16x32_bf16 v[56:59], v[142:145], v[162:165], v[56:59]
	v_mfma_f32_16x16x32_bf16 v[150:153], v[134:137], v[170:173], v[150:153]
	v_mfma_f32_16x16x32_bf16 v[48:51], v[142:145], v[170:173], v[48:51]
	v_mfma_f32_16x16x32_bf16 v[104:107], v[134:137], v[198:201], v[104:107]
	v_mfma_f32_16x16x32_bf16 v[40:43], v[142:145], v[198:201], v[40:43]
	v_mfma_f32_16x16x32_bf16 v[96:99], v[134:137], v[206:209], v[96:99]
	v_mfma_f32_16x16x32_bf16 v[32:35], v[142:145], v[206:209], v[32:35]
	v_mfma_f32_16x16x32_bf16 v[108:111], v[138:141], v[166:169], v[108:111]
	v_mfma_f32_16x16x32_bf16 v[56:59], v[146:149], v[166:169], v[56:59]
	v_mfma_f32_16x16x32_bf16 v[150:153], v[138:141], v[174:177], v[150:153]
	v_mfma_f32_16x16x32_bf16 v[48:51], v[146:149], v[174:177], v[48:51]
	v_mfma_f32_16x16x32_bf16 v[104:107], v[138:141], v[202:205], v[104:107]
	v_mfma_f32_16x16x32_bf16 v[40:43], v[146:149], v[202:205], v[40:43]
	v_mfma_f32_16x16x32_bf16 v[96:99], v[138:141], v[228:231], v[96:99]
	v_mfma_f32_16x16x32_bf16 v[32:35], v[146:149], v[228:231], v[32:35]
	s_setprio 0
	s_barrier
	s_add_i32 vcc_lo, s31, s28
	v_lshl_add_u64 v[210:211], s[18:19], 0, v[180:181]
	s_mov_b32 m0, vcc_lo
	ds_read_b128 v[162:165], v227 offset:16384
	ds_read_b128 v[166:169], v227 offset:17408
	ds_read_b128 v[170:173], v227 offset:18432
	ds_read_b128 v[174:177], v227 offset:19456
	ds_read_b128 v[198:201], v227 offset:20480
	ds_read_b128 v[202:205], v227 offset:21504
	ds_read_b128 v[206:209], v227 offset:22528
	ds_read_b128 v[228:231], v227 offset:23552
	global_load_lds_dwordx4 v[210:211], off
	s_add_i32 m0, vcc_lo, 0x2000
	s_add_u32 vcc_lo, s18, 0x80000
	v_lshl_add_u64 v[232:233], s[18:19], 0, v[184:185]
	s_addc_u32 vcc_hi, s19, 0
	s_add_i32 s22, s74, s28
	global_load_lds_dwordx4 v[232:233], off
	v_lshl_add_u64 v[116:117], vcc, 0, v[180:181]
	s_mov_b32 m0, s22
	v_lshl_add_u64 v[234:235], s[20:21], 0, v[178:179]
	global_load_lds_dwordx4 v[116:117], off
	v_lshl_add_u64 v[116:117], vcc, 0, v[184:185]
	s_add_i32 m0, s22, 0x2000
	v_lshl_add_u64 v[236:237], s[20:21], 0, v[182:183]
	global_load_lds_dwordx4 v[116:117], off
	s_mov_b32 m0, s29
	s_nop 0
	global_load_lds_dwordx4 v[234:235], off
	s_mov_b32 m0, s85
	s_nop 0
	global_load_lds_dwordx4 v[236:237], off
	s_waitcnt vmcnt(8)
	s_waitcnt lgkmcnt(0)
	s_setprio 1
	s_barrier
	s_waitcnt lgkmcnt(0)
	v_mfma_f32_16x16x32_bf16 v[92:95], v[118:121], v[162:165], v[92:95]
	v_mfma_f32_16x16x32_bf16 v[28:31], v[126:129], v[162:165], v[28:31]
	v_mfma_f32_16x16x32_bf16 v[84:87], v[118:121], v[170:173], v[84:87]
	v_mfma_f32_16x16x32_bf16 v[20:23], v[126:129], v[170:173], v[20:23]
	v_mfma_f32_16x16x32_bf16 v[76:79], v[118:121], v[198:201], v[76:79]
	v_mfma_f32_16x16x32_bf16 v[12:15], v[126:129], v[198:201], v[12:15]
	v_mfma_f32_16x16x32_bf16 v[68:71], v[118:121], v[206:209], v[68:71]
	v_mfma_f32_16x16x32_bf16 v[4:7], v[126:129], v[206:209], v[4:7]
	v_mfma_f32_16x16x32_bf16 v[92:95], v[122:125], v[166:169], v[92:95]
	v_mfma_f32_16x16x32_bf16 v[28:31], v[130:133], v[166:169], v[28:31]
	v_mfma_f32_16x16x32_bf16 v[84:87], v[122:125], v[174:177], v[84:87]
	v_mfma_f32_16x16x32_bf16 v[20:23], v[130:133], v[174:177], v[20:23]
	v_mfma_f32_16x16x32_bf16 v[76:79], v[122:125], v[202:205], v[76:79]
	v_mfma_f32_16x16x32_bf16 v[12:15], v[130:133], v[202:205], v[12:15]
	v_mfma_f32_16x16x32_bf16 v[68:71], v[122:125], v[228:231], v[68:71]
	v_mfma_f32_16x16x32_bf16 v[4:7], v[130:133], v[228:231], v[4:7]
	s_setprio 0
	s_setprio 1
	v_mfma_f32_16x16x32_bf16 v[88:91], v[134:137], v[162:165], v[88:91]
	v_mfma_f32_16x16x32_bf16 v[24:27], v[142:145], v[162:165], v[24:27]
	v_mfma_f32_16x16x32_bf16 v[80:83], v[134:137], v[170:173], v[80:83]
	v_mfma_f32_16x16x32_bf16 v[16:19], v[142:145], v[170:173], v[16:19]
	v_mfma_f32_16x16x32_bf16 v[72:75], v[134:137], v[198:201], v[72:75]
	v_mfma_f32_16x16x32_bf16 v[8:11], v[142:145], v[198:201], v[8:11]
	v_mfma_f32_16x16x32_bf16 v[64:67], v[134:137], v[206:209], v[64:67]
	v_mfma_f32_16x16x32_bf16 v[0:3], v[142:145], v[206:209], v[0:3]
	v_mfma_f32_16x16x32_bf16 v[88:91], v[138:141], v[166:169], v[88:91]
	v_mfma_f32_16x16x32_bf16 v[24:27], v[146:149], v[166:169], v[24:27]
	v_mfma_f32_16x16x32_bf16 v[80:83], v[138:141], v[174:177], v[80:83]
	v_mfma_f32_16x16x32_bf16 v[16:19], v[146:149], v[174:177], v[16:19]
	v_mfma_f32_16x16x32_bf16 v[72:75], v[138:141], v[202:205], v[72:75]
	v_mfma_f32_16x16x32_bf16 v[8:11], v[146:149], v[202:205], v[8:11]
	v_mfma_f32_16x16x32_bf16 v[64:67], v[138:141], v[228:231], v[64:67]
	v_mfma_f32_16x16x32_bf16 v[0:3], v[146:149], v[228:231], v[0:3]
	s_setprio 0
	s_barrier
; #define PG8_STAGE(bufoff, gbase, voff) do { _Pragma("unroll") for (int _i = 0; _i < 2; ++_i) \
;         __builtin_amdgcn_global_load_lds((const unsigned*)((const char*)(gbase) + (voff)[_i]), (PG8_LAS unsigned*)(lds + (bufoff) + ldsw + _i * 8192), 16, 0, 0); } while (0)
; #define PG8_LDA(dst, b, h) do { _Pragma("unroll") for (int m = 0; m < 4; ++m) _Pragma("unroll") for (int k = 0; k < 2; ++k) dst[m][k] = *(const PG8_LAS bf16x8*)(lds + PG8_SA(b, h) + aoff + m * 2048 + k * 1024); } while (0)
; #define PG8_LDB(dst, b, h) do { _Pragma("unroll") for (int n = 0; n < 2; ++n) _Pragma("unroll") for (int k = 0; k < 2; ++k) dst[n][k] = *(const PG8_LAS bf16x8*)(lds + PG8_SB(b, h) + boff + n * 2048 + k * 1024); } while (0)
; #define PG8_MMA(ai, bj, At, Bt) do { __builtin_amdgcn_s_setprio(1); _Pragma("unroll") for (int m = 0; m < 4; ++m) _Pragma("unroll") for (int n = 0; n < 2; ++n) _Pragma("unroll") for (int k = 0; k < 2; ++k) \
;         acc[ai][bj][m][n] = __builtin_amdgcn_mfma_f32_16x16x32_bf16(Bt[n][k], At[m][k], acc[ai][bj][m][n], 0, 0, 0); __builtin_amdgcn_s_setprio(0); } while (0)
; #define PG8_BAR __builtin_amdgcn_s_barrier()
; template <class Epi, class Sched, bool ALIGN_EPI = false, bool SP2 = false>
; __device__ __forceinline__ void gemm_phase(PG8_LAS unsigned char* lds, const Gemm g, const Sched& S, const Epi& E) {
;     ...
;             if constexpr (SP2) {
;             PG8_LDB(B0, 0, 0); PG8_LDB(B1, 0, 1); PG8_SCHED; PG8_LDA(At, 0, 0); PG8_STAGE(PG8_SA(1, 1), a1 + hstep, voffA);
;             PG8_WAIT_V(8); PG8_WAIT_L(0); PG8_BAR; PG8_MMA(0, 0, At, B0); PG8_MMA(0, 1, At, B1); PG8_BAR; PG8_SCHED;
;             PG8_LDA(At, 0, 1); PG8_STAGE(PG8_SB(0, 0), b2, voffB); PG8_STAGE(PG8_SB(0, 1), b2 + hstep, voffB); PG8_STAGE(PG8_SA(0, 0), a2, voffA);
;             PG8_WAIT_V(8); PG8_WAIT_L(0); PG8_BAR; PG8_MMA(1, 0, At, B0); PG8_MMA(1, 1, At, B1); PG8_BAR; PG8_SCHED;
;             PG8_LDB(B0, 1, 0); PG8_LDB(B1, 1, 1); PG8_SCHED; PG8_LDA(At, 1, 0); PG8_STAGE(PG8_SA(0, 1), a2 + hstep, voffA);
;             PG8_WAIT_V(8); PG8_WAIT_L(0); PG8_BAR; PG8_MMA(0, 0, At, B0); PG8_MMA(0, 1, At, B1); PG8_BAR; PG8_SCHED;
;             PG8_LDA(At, 1, 1); PG8_STAGE(PG8_SB(1, 0), b3, voffB); PG8_STAGE(PG8_SB(1, 1), b3 + hstep, voffB); PG8_STAGE(PG8_SA(1, 0), a3, voffA);
;             PG8_WAIT_V(8); PG8_WAIT_L(0); PG8_BAR; PG8_MMA(1, 0, At, B0); PG8_MMA(1, 1, At, B1); PG8_BAR; PG8_SCHED;
	v_add_u32_e32 v116, s75, v214
	ds_read_b128 v[118:121], v116
	ds_read_b128 v[122:125], v116 offset:1024
	ds_read_b128 v[126:129], v116 offset:2048
	ds_read_b128 v[130:133], v116 offset:3072
	v_add_u32_e32 v116, s84, v214
	ds_read_b128 v[134:137], v116
	ds_read_b128 v[138:141], v116 offset:1024
	ds_read_b128 v[142:145], v116 offset:2048
	ds_read_b128 v[146:149], v116 offset:3072
	s_add_u32 s20, s20, 0x80000
	s_addc_u32 s21, s21, 0
	s_mov_b32 m0, s95
	v_lshl_add_u64 v[116:117], s[20:21], 0, v[178:179]
	ds_read_b128 v[162:165], v227 offset:32768
	ds_read_b128 v[166:169], v227 offset:33792
	ds_read_b128 v[170:173], v227 offset:34816
	ds_read_b128 v[174:177], v227 offset:35840
	ds_read_b128 v[198:201], v227 offset:36864
	ds_read_b128 v[202:205], v227 offset:37888
	ds_read_b128 v[206:209], v227 offset:38912
	ds_read_b128 v[228:231], v227 offset:39936
	global_load_lds_dwordx4 v[116:117], off
	v_lshl_add_u64 v[116:117], s[20:21], 0, v[182:183]
	s_mov_b32 m0, s2
	s_nop 0
	global_load_lds_dwordx4 v[116:117], off
	s_waitcnt vmcnt(8)
	s_waitcnt lgkmcnt(0)
	s_setprio 1
	s_barrier
	s_waitcnt lgkmcnt(0)
	v_mfma_f32_16x16x32_bf16 v[158:161], v[118:121], v[162:165], v[158:161]
	v_mfma_f32_16x16x32_bf16 v[60:63], v[126:129], v[162:165], v[60:63]
	v_mfma_f32_16x16x32_bf16 v[154:157], v[118:121], v[170:173], v[154:157]
	v_mfma_f32_16x16x32_bf16 v[52:55], v[126:129], v[170:173], v[52:55]
	v_mfma_f32_16x16x32_bf16 v[112:115], v[118:121], v[198:201], v[112:115]
	v_mfma_f32_16x16x32_bf16 v[44:47], v[126:129], v[198:201], v[44:47]
	v_mfma_f32_16x16x32_bf16 v[100:103], v[118:121], v[206:209], v[100:103]
	v_mfma_f32_16x16x32_bf16 v[36:39], v[126:129], v[206:209], v[36:39]
	v_mfma_f32_16x16x32_bf16 v[158:161], v[122:125], v[166:169], v[158:161]
	v_mfma_f32_16x16x32_bf16 v[60:63], v[130:133], v[166:169], v[60:63]
	v_mfma_f32_16x16x32_bf16 v[154:157], v[122:125], v[174:177], v[154:157]
	v_mfma_f32_16x16x32_bf16 v[52:55], v[130:133], v[174:177], v[52:55]
	v_mfma_f32_16x16x32_bf16 v[114:117], v[122:125], v[202:205], v[112:115]
	v_mfma_f32_16x16x32_bf16 v[44:47], v[130:133], v[202:205], v[44:47]
	v_mfma_f32_16x16x32_bf16 v[100:103], v[122:125], v[228:231], v[100:103]
	v_mfma_f32_16x16x32_bf16 v[36:39], v[130:133], v[228:231], v[36:39]
	s_setprio 0
	s_setprio 1
	v_mfma_f32_16x16x32_bf16 v[108:111], v[134:137], v[162:165], v[108:111]
	v_mfma_f32_16x16x32_bf16 v[56:59], v[142:145], v[162:165], v[56:59]
	v_mfma_f32_16x16x32_bf16 v[150:153], v[134:137], v[170:173], v[150:153]
	v_mfma_f32_16x16x32_bf16 v[48:51], v[142:145], v[170:173], v[48:51]
	v_mfma_f32_16x16x32_bf16 v[104:107], v[134:137], v[198:201], v[104:107]
	v_mfma_f32_16x16x32_bf16 v[40:43], v[142:145], v[198:201], v[40:43]
	v_mfma_f32_16x16x32_bf16 v[96:99], v[134:137], v[206:209], v[96:99]
	v_mfma_f32_16x16x32_bf16 v[32:35], v[142:145], v[206:209], v[32:35]
	v_mfma_f32_16x16x32_bf16 v[108:111], v[138:141], v[166:169], v[108:111]
	v_mfma_f32_16x16x32_bf16 v[56:59], v[146:149], v[166:169], v[56:59]
	v_mfma_f32_16x16x32_bf16 v[150:153], v[138:141], v[174:177], v[150:153]
	v_mfma_f32_16x16x32_bf16 v[48:51], v[146:149], v[174:177], v[48:51]
	v_mfma_f32_16x16x32_bf16 v[104:107], v[138:141], v[202:205], v[104:107]
	v_mfma_f32_16x16x32_bf16 v[40:43], v[146:149], v[202:205], v[40:43]
	v_mfma_f32_16x16x32_bf16 v[96:99], v[138:141], v[228:231], v[96:99]
	v_mfma_f32_16x16x32_bf16 v[32:35], v[146:149], v[228:231], v[32:35]
	s_setprio 0
	s_barrier
; #define PG8_STAGE(bufoff, gbase, voff) do { _Pragma("unroll") for (int _i = 0; _i < 2; ++_i) \
;         __builtin_amdgcn_global_load_lds((const unsigned*)((const char*)(gbase) + (voff)[_i]), (PG8_LAS unsigned*)(lds + (bufoff) + ldsw + _i * 8192), 16, 0, 0); } while (0)
; #define PG8_LDA(dst, b, h) do { _Pragma("unroll") for (int m = 0; m < 4; ++m) _Pragma("unroll") for (int k = 0; k < 2; ++k) dst[m][k] = *(const PG8_LAS bf16x8*)(lds + PG8_SA(b, h) + aoff + m * 2048 + k * 1024); } while (0)
; #define PG8_LDB(dst, b, h) do { _Pragma("unroll") for (int n = 0; n < 2; ++n) _Pragma("unroll") for (int k = 0; k < 2; ++k) dst[n][k] = *(const PG8_LAS bf16x8*)(lds + PG8_SB(b, h) + boff + n * 2048 + k * 1024); } while (0)
; #define PG8_WAIT_V(n) asm volatile("s_waitcnt vmcnt(" #n ")" ::: "memory")
; #define PG8_WAIT_L(n) asm volatile("s_waitcnt lgkmcnt(" #n ")" ::: "memory")
; #define PG8_BAR __builtin_amdgcn_s_barrier()
; #define PG8_SCHED __builtin_amdgcn_sched_barrier(0)
; template <class Epi, class Sched, bool ALIGN_EPI = false, bool SP2 = false>
; __device__ __forceinline__ void gemm_phase(PG8_LAS unsigned char* lds, const Gemm g, const Sched& S, const Epi& E) {
;     ...
;             if constexpr (SP2) {
;             PG8_LDB(B0, 0, 0); PG8_LDB(B1, 0, 1); PG8_SCHED; PG8_LDA(At, 0, 0); PG8_STAGE(PG8_SA(1, 1), a1 + hstep, voffA);
;             PG8_WAIT_V(8); PG8_WAIT_L(0); PG8_BAR; PG8_MMA(0, 0, At, B0); PG8_MMA(0, 1, At, B1); PG8_BAR; PG8_SCHED;
;             PG8_LDA(At, 0, 1); PG8_STAGE(PG8_SB(0, 0), b2, voffB); PG8_STAGE(PG8_SB(0, 1), b2 + hstep, voffB); PG8_STAGE(PG8_SA(0, 0), a2, voffA);
;             PG8_WAIT_V(8); PG8_WAIT_L(0); PG8_BAR; PG8_MMA(1, 0, At, B0); PG8_MMA(1, 1, At, B1); PG8_BAR; PG8_SCHED;
;             PG8_LDB(B0, 1, 0); PG8_LDB(B1, 1, 1); PG8_SCHED; PG8_LDA(At, 1, 0); PG8_STAGE(PG8_SA(0, 1), a2 + hstep, voffA);
;             PG8_WAIT_V(8); PG8_WAIT_L(0); PG8_BAR; PG8_MMA(0, 0, At, B0); PG8_MMA(0, 1, At, B1); PG8_BAR; PG8_SCHED;
;             PG8_LDA(At, 1, 1); PG8_STAGE(PG8_SB(1, 0), b3, voffB); PG8_STAGE(PG8_SB(1, 1), b3 + hstep, voffB); PG8_STAGE(PG8_SA(1, 0), a3, voffA);
;             PG8_WAIT_V(8); PG8_WAIT_L(0); PG8_BAR; PG8_MMA(1, 0, At, B0); PG8_MMA(1, 1, At, B1); PG8_BAR; PG8_SCHED;
;     ...
;         if constexpr (ALIGN_EPI) { if (wr == 0) PG8_BAR; }
	s_add_i32 s20, s75, s28
	v_lshl_add_u64 v[112:113], v[210:211], 0, s[46:47]
	s_mov_b32 m0, s20
	ds_read_b128 v[162:165], v227 offset:49152
	ds_read_b128 v[166:169], v227 offset:50176
	ds_read_b128 v[170:173], v227 offset:51200
	ds_read_b128 v[174:177], v227 offset:52224
	ds_read_b128 v[198:201], v227 offset:53248
	ds_read_b128 v[202:205], v227 offset:54272
	ds_read_b128 v[206:209], v227 offset:55296
	ds_read_b128 v[228:231], v227 offset:56320
	global_load_lds_dwordx4 v[112:113], off
	s_add_i32 m0, s20, 0x2000
	s_add_u32 s18, s18, 0x80080
	v_lshl_add_u64 v[112:113], v[232:233], 0, s[46:47]
	s_addc_u32 s19, s19, 0
	s_add_i32 s20, s84, s28
	global_load_lds_dwordx4 v[112:113], off
	v_lshl_add_u64 v[112:113], s[18:19], 0, v[180:181]
	s_mov_b32 m0, s20
	s_nop 0
	global_load_lds_dwordx4 v[112:113], off
	v_lshl_add_u64 v[112:113], s[18:19], 0, v[184:185]
	s_add_i32 m0, s20, 0x2000
	s_nop 0
	global_load_lds_dwordx4 v[112:113], off
	v_lshl_add_u64 v[112:113], v[234:235], 0, s[46:47]
	s_mov_b32 m0, s30
	s_nop 0
	global_load_lds_dwordx4 v[112:113], off
	v_lshl_add_u64 v[112:113], v[236:237], 0, s[46:47]
	s_mov_b32 m0, s23
	s_nop 0
	global_load_lds_dwordx4 v[112:113], off
	s_waitcnt vmcnt(8)
	s_waitcnt lgkmcnt(0)
	s_setprio 1
	s_barrier
	s_waitcnt lgkmcnt(0)
	v_mfma_f32_16x16x32_bf16 v[92:95], v[118:121], v[162:165], v[92:95]
	v_mfma_f32_16x16x32_bf16 v[28:31], v[126:129], v[162:165], v[28:31]
	v_mfma_f32_16x16x32_bf16 v[84:87], v[118:121], v[170:173], v[84:87]
	v_mfma_f32_16x16x32_bf16 v[20:23], v[126:129], v[170:173], v[20:23]
	v_mfma_f32_16x16x32_bf16 v[76:79], v[118:121], v[198:201], v[76:79]
	v_mfma_f32_16x16x32_bf16 v[12:15], v[126:129], v[198:201], v[12:15]
	v_mfma_f32_16x16x32_bf16 v[68:71], v[118:121], v[206:209], v[68:71]
	v_mfma_f32_16x16x32_bf16 v[4:7], v[126:129], v[206:209], v[4:7]
	v_mfma_f32_16x16x32_bf16 v[92:95], v[122:125], v[166:169], v[92:95]
	v_mfma_f32_16x16x32_bf16 v[28:31], v[130:133], v[166:169], v[28:31]
	v_mfma_f32_16x16x32_bf16 v[84:87], v[122:125], v[174:177], v[84:87]
	v_mfma_f32_16x16x32_bf16 v[20:23], v[130:133], v[174:177], v[20:23]
	v_mfma_f32_16x16x32_bf16 v[76:79], v[122:125], v[202:205], v[76:79]
	v_mfma_f32_16x16x32_bf16 v[12:15], v[130:133], v[202:205], v[12:15]
	v_mfma_f32_16x16x32_bf16 v[68:71], v[122:125], v[228:231], v[68:71]
	v_mfma_f32_16x16x32_bf16 v[4:7], v[130:133], v[228:231], v[4:7]
	s_setprio 0
	s_setprio 1
	v_mfma_f32_16x16x32_bf16 v[88:91], v[134:137], v[162:165], v[88:91]
	v_mfma_f32_16x16x32_bf16 v[24:27], v[142:145], v[162:165], v[24:27]
	v_mfma_f32_16x16x32_bf16 v[80:83], v[134:137], v[170:173], v[80:83]
	v_mfma_f32_16x16x32_bf16 v[16:19], v[142:145], v[170:173], v[16:19]
	v_mfma_f32_16x16x32_bf16 v[72:75], v[134:137], v[198:201], v[72:75]
	v_mfma_f32_16x16x32_bf16 v[8:11], v[142:145], v[198:201], v[8:11]
	v_mfma_f32_16x16x32_bf16 v[64:67], v[134:137], v[206:209], v[64:67]
	v_mfma_f32_16x16x32_bf16 v[0:3], v[142:145], v[206:209], v[0:3]
	v_mfma_f32_16x16x32_bf16 v[88:91], v[138:141], v[166:169], v[88:91]
	v_mfma_f32_16x16x32_bf16 v[24:27], v[146:149], v[166:169], v[24:27]
	v_mfma_f32_16x16x32_bf16 v[80:83], v[138:141], v[174:177], v[80:83]
	v_mfma_f32_16x16x32_bf16 v[16:19], v[146:149], v[174:177], v[16:19]
	v_mfma_f32_16x16x32_bf16 v[72:75], v[138:141], v[202:205], v[72:75]
	v_mfma_f32_16x16x32_bf16 v[8:11], v[146:149], v[202:205], v[8:11]
	v_mfma_f32_16x16x32_bf16 v[64:67], v[138:141], v[228:231], v[64:67]
	v_mfma_f32_16x16x32_bf16 v[0:3], v[146:149], v[228:231], v[0:3]
	s_setprio 0
	s_barrier
	s_add_i32 s97, s97, 2
	s_add_u32 s16, s16, 0x100
	s_addc_u32 s17, s17, 0
	s_add_u32 s89, s89, 0x100
	s_addc_u32 s96, s96, 0
	s_cmp_gt_u32 s97, 29
	s_cbranch_scc0 .LBB0_928
	v_readlane_b32 s0, v242, 20
	v_readlane_b32 s1, v242, 21
	s_and_b64 vcc, exec, s[0:1]
	s_cbranch_vccz .LBB0_931
	s_barrier

; #define PG8_STAGE(bufoff, gbase, voff) do { _Pragma("unroll") for (int _i = 0; _i < 2; ++_i) \
;         __builtin_amdgcn_global_load_lds((const unsigned*)((const char*)(gbase) + (voff)[_i]), (PG8_LAS unsigned*)(lds + (bufoff) + ldsw + _i * 8192), 16, 0, 0); } while (0)
; #define PG8_LDA(dst, b, h) do { _Pragma("unroll") for (int m = 0; m < 4; ++m) _Pragma("unroll") for (int k = 0; k < 2; ++k) dst[m][k] = *(const PG8_LAS bf16x8*)(lds + PG8_SA(b, h) + aoff + m * 2048 + k * 1024); } while (0)
; #define PG8_LDB(dst, b, h) do { _Pragma("unroll") for (int n = 0; n < 2; ++n) _Pragma("unroll") for (int k = 0; k < 2; ++k) dst[n][k] = *(const PG8_LAS bf16x8*)(lds + PG8_SB(b, h) + boff + n * 2048 + k * 1024); } while (0)
; #define PG8_MMA(ai, bj, At, Bt) do { __builtin_amdgcn_s_setprio(1); _Pragma("unroll") for (int m = 0; m < 4; ++m) _Pragma("unroll") for (int n = 0; n < 2; ++n) _Pragma("unroll") for (int k = 0; k < 2; ++k) \
;         acc[ai][bj][m][n] = __builtin_amdgcn_mfma_f32_16x16x32_bf16(Bt[n][k], At[m][k], acc[ai][bj][m][n], 0, 0, 0); __builtin_amdgcn_s_setprio(0); } while (0)
; #define PG8_WAIT_V(n) asm volatile("s_waitcnt vmcnt(" #n ")" ::: "memory")
; #define PG8_BAR __builtin_amdgcn_s_barrier()
; template <class Epi, class Sched, bool ALIGN_EPI = false, bool SP2 = false>
; __device__ __forceinline__ void gemm_phase(PG8_LAS unsigned char* lds, const Gemm g, const Sched& S, const Epi& E) {
;     ...
;         for (int t = seg * tseg; t < (seg + 1) * tseg; t += 2) {
;             const bool last = (t == nt - 2);
;             const char* a1 = cA + (size_t)(t + 1) * kstep;
;             const char* a2 = last ? nA : cA + (size_t)(t + 2) * kstep; const char* b2 = last ? nB : cB + (size_t)(t + 2) * kstep;
;             const char* a3 = a2 + kstep; const char* b3 = b2 + kstep;
;             if (last && has_next) S.a_ready(nxt);
;             if constexpr (SP2) {
;             PG8_LDB(B0, 0, 0); PG8_LDB(B1, 0, 1); PG8_SCHED; PG8_LDA(At, 0, 0); PG8_STAGE(PG8_SA(1, 1), a1 + hstep, voffA);
;             PG8_WAIT_V(8); PG8_WAIT_L(0); PG8_BAR; PG8_MMA(0, 0, At, B0); PG8_MMA(0, 1, At, B1); PG8_BAR; PG8_SCHED;
;             PG8_LDA(At, 0, 1); PG8_STAGE(PG8_SB(0, 0), b2, voffB); PG8_STAGE(PG8_SB(0, 1), b2 + hstep, voffB); PG8_STAGE(PG8_SA(0, 0), a2, voffA);
;             PG8_WAIT_V(8); PG8_WAIT_L(0); PG8_BAR; PG8_MMA(1, 0, At, B0); PG8_MMA(1, 1, At, B1); PG8_BAR; PG8_SCHED;
.LBB0_1100:
	s_add_u32 s0, s38, 0x100
	s_addc_u32 s1, s39, 0
	s_mov_b32 s59, -2
	ds_read_b128 v[120:123], v169
	ds_read_b128 v[124:127], v169 offset:1024
	ds_read_b128 v[128:131], v169 offset:2048
	ds_read_b128 v[132:135], v169 offset:3072
	ds_read_b128 v[160:163], v170
	ds_read_b128 v[172:175], v170 offset:1024
	ds_read_b128 v[176:179], v170 offset:2048
	ds_read_b128 v[180:183], v170 offset:3072
	s_add_u32 s38, s34, 0x100
	s_addc_u32 s39, s35, 0
	s_cmpk_eq_i32 s59, 0x54
	s_cselect_b32 s43, s5, s39
	s_cselect_b32 s42, s4, s38
	s_cselect_b32 s41, s21, s1
	s_cselect_b32 s40, s20, s0
	v_lshl_add_u64 v[164:165], s[34:35], 0, v[152:153]
	s_add_i32 m0, s28, 0xc000
	ds_read_b128 v[184:187], v171
	ds_read_b128 v[190:193], v171 offset:1024
	ds_read_b128 v[194:197], v171 offset:2048
	ds_read_b128 v[198:201], v171 offset:3072
	ds_read_b128 v[202:205], v171 offset:4096
	ds_read_b128 v[206:209], v171 offset:5120
	ds_read_b128 v[214:217], v171 offset:6144
	ds_read_b128 v[218:221], v171 offset:7168
	global_load_lds_dwordx4 v[164:165], off
	v_lshl_add_u64 v[164:165], s[34:35], 0, v[154:155]
	s_add_i32 m0, s28, 0xe000
	s_nop 0
	global_load_lds_dwordx4 v[164:165], off
	s_waitcnt vmcnt(8)
	s_waitcnt lgkmcnt(0)
	s_setprio 1
	s_barrier
	s_waitcnt lgkmcnt(0)
	v_mfma_f32_16x16x32_bf16 v[140:143], v[120:123], v[184:187], 0
	v_mfma_f32_16x16x32_bf16 v[136:139], v[128:131], v[184:187], 0
	v_mfma_f32_16x16x32_bf16 v[116:119], v[120:123], v[194:197], 0
	v_mfma_f32_16x16x32_bf16 v[104:107], v[128:131], v[194:197], 0
	v_mfma_f32_16x16x32_bf16 v[100:103], v[120:123], v[202:205], 0
	v_mfma_f32_16x16x32_bf16 v[88:91], v[128:131], v[202:205], 0
	v_mfma_f32_16x16x32_bf16 v[84:87], v[120:123], v[214:217], 0
	v_mfma_f32_16x16x32_bf16 v[72:75], v[128:131], v[214:217], 0
	v_mfma_f32_16x16x32_bf16 v[140:143], v[124:127], v[190:193], v[140:143]
	v_mfma_f32_16x16x32_bf16 v[136:139], v[132:135], v[190:193], v[136:139]
	v_mfma_f32_16x16x32_bf16 v[116:119], v[124:127], v[198:201], v[116:119]
	v_mfma_f32_16x16x32_bf16 v[104:107], v[132:135], v[198:201], v[104:107]
	v_mfma_f32_16x16x32_bf16 v[100:103], v[124:127], v[206:209], v[100:103]
	v_mfma_f32_16x16x32_bf16 v[88:91], v[132:135], v[206:209], v[88:91]
	v_mfma_f32_16x16x32_bf16 v[84:87], v[124:127], v[218:221], v[84:87]
	v_mfma_f32_16x16x32_bf16 v[72:75], v[132:135], v[218:221], v[72:75]
	s_setprio 0
	s_setprio 1
	v_mfma_f32_16x16x32_bf16 v[112:115], v[160:163], v[184:187], 0
	v_mfma_f32_16x16x32_bf16 v[108:111], v[176:179], v[184:187], 0
	v_mfma_f32_16x16x32_bf16 v[96:99], v[160:163], v[194:197], 0
	v_mfma_f32_16x16x32_bf16 v[92:95], v[176:179], v[194:197], 0
	v_mfma_f32_16x16x32_bf16 v[80:83], v[160:163], v[202:205], 0
	v_mfma_f32_16x16x32_bf16 v[76:79], v[176:179], v[202:205], 0
	v_mfma_f32_16x16x32_bf16 v[68:71], v[160:163], v[214:217], 0
	v_mfma_f32_16x16x32_bf16 v[64:67], v[176:179], v[214:217], 0
	v_mfma_f32_16x16x32_bf16 v[112:115], v[172:175], v[190:193], v[112:115]
	v_mfma_f32_16x16x32_bf16 v[108:111], v[180:183], v[190:193], v[108:111]
	v_mfma_f32_16x16x32_bf16 v[96:99], v[172:175], v[198:201], v[96:99]
	v_mfma_f32_16x16x32_bf16 v[92:95], v[180:183], v[198:201], v[92:95]
	v_mfma_f32_16x16x32_bf16 v[80:83], v[172:175], v[206:209], v[80:83]
	v_mfma_f32_16x16x32_bf16 v[76:79], v[180:183], v[206:209], v[76:79]
	v_mfma_f32_16x16x32_bf16 v[68:71], v[172:175], v[218:221], v[68:71]
	v_mfma_f32_16x16x32_bf16 v[64:67], v[180:183], v[218:221], v[64:67]
	s_setprio 0
	s_barrier
	s_add_i32 s22, s31, s23
	v_lshl_add_u64 v[164:165], s[40:41], 0, v[146:147]
	s_mov_b32 m0, s22
	ds_read_b128 v[184:187], v171 offset:16384
	ds_read_b128 v[190:193], v171 offset:17408
	ds_read_b128 v[194:197], v171 offset:18432
	ds_read_b128 v[198:201], v171 offset:19456
	ds_read_b128 v[202:205], v171 offset:20480
	ds_read_b128 v[206:209], v171 offset:21504
	ds_read_b128 v[214:217], v171 offset:22528
	ds_read_b128 v[218:221], v171 offset:23552
	global_load_lds_dwordx4 v[164:165], off
	s_add_i32 m0, s22, 0x2000
	s_add_u32 s34, s40, 0x160000
	v_lshl_add_u64 v[210:211], s[40:41], 0, v[150:151]
	s_addc_u32 s35, s41, 0
	s_add_i32 s22, s74, s23
	global_load_lds_dwordx4 v[210:211], off
	v_lshl_add_u64 v[222:223], s[34:35], 0, v[146:147]
	s_mov_b32 m0, s22
	v_lshl_add_u64 v[224:225], s[42:43], 0, v[148:149]
	global_load_lds_dwordx4 v[222:223], off
	v_lshl_add_u64 v[222:223], s[34:35], 0, v[150:151]
	s_add_i32 m0, s22, 0x2000
	s_nop 0
	global_load_lds_dwordx4 v[222:223], off
	v_lshl_add_u64 v[222:223], s[42:43], 0, v[144:145]
	s_mov_b32 m0, s28
	s_nop 0
	global_load_lds_dwordx4 v[222:223], off
	s_mov_b32 m0, s29
	s_nop 0
	global_load_lds_dwordx4 v[224:225], off
	s_waitcnt vmcnt(8)
	s_waitcnt lgkmcnt(0)
	s_setprio 1
	s_barrier
; #define PG8_STAGE(bufoff, gbase, voff) do { _Pragma("unroll") for (int _i = 0; _i < 2; ++_i) \
;         __builtin_amdgcn_global_load_lds((const unsigned*)((const char*)(gbase) + (voff)[_i]), (PG8_LAS unsigned*)(lds + (bufoff) + ldsw + _i * 8192), 16, 0, 0); } while (0)
; #define PG8_LDA(dst, b, h) do { _Pragma("unroll") for (int m = 0; m < 4; ++m) _Pragma("unroll") for (int k = 0; k < 2; ++k) dst[m][k] = *(const PG8_LAS bf16x8*)(lds + PG8_SA(b, h) + aoff + m * 2048 + k * 1024); } while (0)
; #define PG8_LDB(dst, b, h) do { _Pragma("unroll") for (int n = 0; n < 2; ++n) _Pragma("unroll") for (int k = 0; k < 2; ++k) dst[n][k] = *(const PG8_LAS bf16x8*)(lds + PG8_SB(b, h) + boff + n * 2048 + k * 1024); } while (0)
; #define PG8_MMA(ai, bj, At, Bt) do { __builtin_amdgcn_s_setprio(1); _Pragma("unroll") for (int m = 0; m < 4; ++m) _Pragma("unroll") for (int n = 0; n < 2; ++n) _Pragma("unroll") for (int k = 0; k < 2; ++k) \
;         acc[ai][bj][m][n] = __builtin_amdgcn_mfma_f32_16x16x32_bf16(Bt[n][k], At[m][k], acc[ai][bj][m][n], 0, 0, 0); __builtin_amdgcn_s_setprio(0); } while (0)
; #define PG8_BAR __builtin_amdgcn_s_barrier()
; template <class Epi, class Sched, bool ALIGN_EPI = false, bool SP2 = false>
; __device__ __forceinline__ void gemm_phase(PG8_LAS unsigned char* lds, const Gemm g, const Sched& S, const Epi& E) {
;     ...
;             if constexpr (SP2) {
;             PG8_LDB(B0, 0, 0); PG8_LDB(B1, 0, 1); PG8_SCHED; PG8_LDA(At, 0, 0); PG8_STAGE(PG8_SA(1, 1), a1 + hstep, voffA);
;             PG8_WAIT_V(8); PG8_WAIT_L(0); PG8_BAR; PG8_MMA(0, 0, At, B0); PG8_MMA(0, 1, At, B1); PG8_BAR; PG8_SCHED;
;             PG8_LDA(At, 0, 1); PG8_STAGE(PG8_SB(0, 0), b2, voffB); PG8_STAGE(PG8_SB(0, 1), b2 + hstep, voffB); PG8_STAGE(PG8_SA(0, 0), a2, voffA);
;             PG8_WAIT_V(8); PG8_WAIT_L(0); PG8_BAR; PG8_MMA(1, 0, At, B0); PG8_MMA(1, 1, At, B1); PG8_BAR; PG8_SCHED;
;             PG8_LDB(B0, 1, 0); PG8_LDB(B1, 1, 1); PG8_SCHED; PG8_LDA(At, 1, 0); PG8_STAGE(PG8_SA(0, 1), a2 + hstep, voffA);
;             PG8_WAIT_V(8); PG8_WAIT_L(0); PG8_BAR; PG8_MMA(0, 0, At, B0); PG8_MMA(0, 1, At, B1); PG8_BAR; PG8_SCHED;
;             PG8_LDA(At, 1, 1); PG8_STAGE(PG8_SB(1, 0), b3, voffB); PG8_STAGE(PG8_SB(1, 1), b3 + hstep, voffB); PG8_STAGE(PG8_SA(1, 0), a3, voffA);
;             PG8_WAIT_V(8); PG8_WAIT_L(0); PG8_BAR; PG8_MMA(1, 0, At, B0); PG8_MMA(1, 1, At, B1); PG8_BAR; PG8_SCHED;
	s_waitcnt lgkmcnt(0)
	v_mfma_f32_16x16x32_bf16 v[60:63], v[120:123], v[184:187], 0
	v_mfma_f32_16x16x32_bf16 v[56:59], v[128:131], v[184:187], 0
	v_mfma_f32_16x16x32_bf16 v[52:55], v[120:123], v[194:197], 0
	v_mfma_f32_16x16x32_bf16 v[40:43], v[128:131], v[194:197], 0
	v_mfma_f32_16x16x32_bf16 v[36:39], v[120:123], v[202:205], 0
	v_mfma_f32_16x16x32_bf16 v[24:27], v[128:131], v[202:205], 0
	v_mfma_f32_16x16x32_bf16 v[20:23], v[120:123], v[214:217], 0
	v_mfma_f32_16x16x32_bf16 v[8:11], v[128:131], v[214:217], 0
	v_mfma_f32_16x16x32_bf16 v[60:63], v[124:127], v[190:193], v[60:63]
	v_mfma_f32_16x16x32_bf16 v[56:59], v[132:135], v[190:193], v[56:59]
	v_mfma_f32_16x16x32_bf16 v[52:55], v[124:127], v[198:201], v[52:55]
	v_mfma_f32_16x16x32_bf16 v[40:43], v[132:135], v[198:201], v[40:43]
	v_mfma_f32_16x16x32_bf16 v[36:39], v[124:127], v[206:209], v[36:39]
	v_mfma_f32_16x16x32_bf16 v[24:27], v[132:135], v[206:209], v[24:27]
	v_mfma_f32_16x16x32_bf16 v[20:23], v[124:127], v[218:221], v[20:23]
	v_mfma_f32_16x16x32_bf16 v[8:11], v[132:135], v[218:221], v[8:11]
	s_setprio 0
	s_setprio 1
	v_mfma_f32_16x16x32_bf16 v[48:51], v[160:163], v[184:187], 0
	v_mfma_f32_16x16x32_bf16 v[44:47], v[176:179], v[184:187], 0
	v_mfma_f32_16x16x32_bf16 v[32:35], v[160:163], v[194:197], 0
	v_mfma_f32_16x16x32_bf16 v[28:31], v[176:179], v[194:197], 0
	v_mfma_f32_16x16x32_bf16 v[16:19], v[160:163], v[202:205], 0
	v_mfma_f32_16x16x32_bf16 v[12:15], v[176:179], v[202:205], 0
	v_mfma_f32_16x16x32_bf16 v[4:7], v[160:163], v[214:217], 0
	v_mfma_f32_16x16x32_bf16 v[0:3], v[176:179], v[214:217], 0
	v_mfma_f32_16x16x32_bf16 v[48:51], v[172:175], v[190:193], v[48:51]
	v_mfma_f32_16x16x32_bf16 v[44:47], v[180:183], v[190:193], v[44:47]
	v_mfma_f32_16x16x32_bf16 v[32:35], v[172:175], v[198:201], v[32:35]
	v_mfma_f32_16x16x32_bf16 v[28:31], v[180:183], v[198:201], v[28:31]
	v_mfma_f32_16x16x32_bf16 v[16:19], v[172:175], v[206:209], v[16:19]
	v_mfma_f32_16x16x32_bf16 v[12:15], v[180:183], v[206:209], v[12:15]
	v_mfma_f32_16x16x32_bf16 v[4:7], v[172:175], v[218:221], v[4:7]
	v_mfma_f32_16x16x32_bf16 v[0:3], v[180:183], v[218:221], v[0:3]
	s_setprio 0
	s_barrier
	v_add_u32_e32 v132, s75, v167
	v_add_u32_e32 v180, s84, v167
	ds_read_b128 v[120:123], v132
	ds_read_b128 v[124:127], v132 offset:1024
	ds_read_b128 v[128:131], v132 offset:2048
	ds_read_b128 v[132:135], v132 offset:3072
	ds_read_b128 v[160:163], v180
	ds_read_b128 v[172:175], v180 offset:1024
	ds_read_b128 v[176:179], v180 offset:2048
	ds_read_b128 v[180:183], v180 offset:3072
	s_add_u32 s34, s42, 0x160000
	s_addc_u32 s35, s43, 0
	s_mov_b32 m0, s30
	v_lshl_add_u64 v[226:227], s[34:35], 0, v[144:145]
	ds_read_b128 v[184:187], v171 offset:32768
	ds_read_b128 v[190:193], v171 offset:33792
	ds_read_b128 v[194:197], v171 offset:34816
	ds_read_b128 v[198:201], v171 offset:35840
	ds_read_b128 v[202:205], v171 offset:36864
	ds_read_b128 v[206:209], v171 offset:37888
	ds_read_b128 v[214:217], v171 offset:38912
	ds_read_b128 v[218:221], v171 offset:39936
	global_load_lds_dwordx4 v[226:227], off
	v_lshl_add_u64 v[226:227], s[34:35], 0, v[148:149]
	s_mov_b32 m0, s33
	s_nop 0
	global_load_lds_dwordx4 v[226:227], off
	s_waitcnt vmcnt(8)
	s_waitcnt lgkmcnt(0)
	s_setprio 1
	s_barrier
	s_waitcnt lgkmcnt(0)
	v_mfma_f32_16x16x32_bf16 v[140:143], v[120:123], v[184:187], v[140:143]
	v_mfma_f32_16x16x32_bf16 v[136:139], v[128:131], v[184:187], v[136:139]
	v_mfma_f32_16x16x32_bf16 v[116:119], v[120:123], v[194:197], v[116:119]
	v_mfma_f32_16x16x32_bf16 v[104:107], v[128:131], v[194:197], v[104:107]
	v_mfma_f32_16x16x32_bf16 v[100:103], v[120:123], v[202:205], v[100:103]
	v_mfma_f32_16x16x32_bf16 v[88:91], v[128:131], v[202:205], v[88:91]
	v_mfma_f32_16x16x32_bf16 v[84:87], v[120:123], v[214:217], v[84:87]
	v_mfma_f32_16x16x32_bf16 v[72:75], v[128:131], v[214:217], v[72:75]
	v_mfma_f32_16x16x32_bf16 v[140:143], v[124:127], v[190:193], v[140:143]
	v_mfma_f32_16x16x32_bf16 v[136:139], v[132:135], v[190:193], v[136:139]
	v_mfma_f32_16x16x32_bf16 v[116:119], v[124:127], v[198:201], v[116:119]
	v_mfma_f32_16x16x32_bf16 v[104:107], v[132:135], v[198:201], v[104:107]
	v_mfma_f32_16x16x32_bf16 v[100:103], v[124:127], v[206:209], v[100:103]
	v_mfma_f32_16x16x32_bf16 v[88:91], v[132:135], v[206:209], v[88:91]
	v_mfma_f32_16x16x32_bf16 v[84:87], v[124:127], v[218:221], v[84:87]
	v_mfma_f32_16x16x32_bf16 v[72:75], v[132:135], v[218:221], v[72:75]
	s_setprio 0
	s_setprio 1
	v_mfma_f32_16x16x32_bf16 v[112:115], v[160:163], v[184:187], v[112:115]
	v_mfma_f32_16x16x32_bf16 v[108:111], v[176:179], v[184:187], v[108:111]
	v_mfma_f32_16x16x32_bf16 v[96:99], v[160:163], v[194:197], v[96:99]
	v_mfma_f32_16x16x32_bf16 v[92:95], v[176:179], v[194:197], v[92:95]
	v_mfma_f32_16x16x32_bf16 v[80:83], v[160:163], v[202:205], v[80:83]
	v_mfma_f32_16x16x32_bf16 v[76:79], v[176:179], v[202:205], v[76:79]
	v_mfma_f32_16x16x32_bf16 v[68:71], v[160:163], v[214:217], v[68:71]
	v_mfma_f32_16x16x32_bf16 v[64:67], v[176:179], v[214:217], v[64:67]
	v_mfma_f32_16x16x32_bf16 v[112:115], v[172:175], v[190:193], v[112:115]
	v_mfma_f32_16x16x32_bf16 v[108:111], v[180:183], v[190:193], v[108:111]
	v_mfma_f32_16x16x32_bf16 v[96:99], v[172:175], v[198:201], v[96:99]
	v_mfma_f32_16x16x32_bf16 v[92:95], v[180:183], v[198:201], v[92:95]
	v_mfma_f32_16x16x32_bf16 v[80:83], v[172:175], v[206:209], v[80:83]
	v_mfma_f32_16x16x32_bf16 v[76:79], v[180:183], v[206:209], v[76:79]
	v_mfma_f32_16x16x32_bf16 v[68:71], v[172:175], v[218:221], v[68:71]
	v_mfma_f32_16x16x32_bf16 v[64:67], v[180:183], v[218:221], v[64:67]
	s_setprio 0
	s_barrier
; #define PG8_STAGE(bufoff, gbase, voff) do { _Pragma("unroll") for (int _i = 0; _i < 2; ++_i) \
;         __builtin_amdgcn_global_load_lds((const unsigned*)((const char*)(gbase) + (voff)[_i]), (PG8_LAS unsigned*)(lds + (bufoff) + ldsw + _i * 8192), 16, 0, 0); } while (0)
; #define PG8_LDA(dst, b, h) do { _Pragma("unroll") for (int m = 0; m < 4; ++m) _Pragma("unroll") for (int k = 0; k < 2; ++k) dst[m][k] = *(const PG8_LAS bf16x8*)(lds + PG8_SA(b, h) + aoff + m * 2048 + k * 1024); } while (0)
; #define PG8_WAIT_V(n) asm volatile("s_waitcnt vmcnt(" #n ")" ::: "memory")
; #define PG8_WAIT_L(n) asm volatile("s_waitcnt lgkmcnt(" #n ")" ::: "memory")
; #define PG8_BAR __builtin_amdgcn_s_barrier()
; template <class Epi, class Sched, bool ALIGN_EPI = false, bool SP2 = false>
; __device__ __forceinline__ void gemm_phase(PG8_LAS unsigned char* lds, const Gemm g, const Sched& S, const Epi& E) {
;     ...
;         for (int t = seg * tseg; t < (seg + 1) * tseg; t += 2) {
;             const bool last = (t == nt - 2);
;             const char* a1 = cA + (size_t)(t + 1) * kstep;
;             const char* a2 = last ? nA : cA + (size_t)(t + 2) * kstep; const char* b2 = last ? nB : cB + (size_t)(t + 2) * kstep;
;             const char* a3 = a2 + kstep; const char* b3 = b2 + kstep;
;             if (last && has_next) S.a_ready(nxt);
;             if constexpr (SP2) {
;             PG8_LDB(B0, 0, 0); PG8_LDB(B1, 0, 1); PG8_SCHED; PG8_LDA(At, 0, 0); PG8_STAGE(PG8_SA(1, 1), a1 + hstep, voffA);
;             PG8_WAIT_V(8); PG8_WAIT_L(0); PG8_BAR; PG8_MMA(0, 0, At, B0); PG8_MMA(0, 1, At, B1); PG8_BAR; PG8_SCHED;
;             PG8_LDA(At, 0, 1); PG8_STAGE(PG8_SB(0, 0), b2, voffB); PG8_STAGE(PG8_SB(0, 1), b2 + hstep, voffB); PG8_STAGE(PG8_SA(0, 0), a2, voffA);
;             PG8_WAIT_V(8); PG8_WAIT_L(0); PG8_BAR; PG8_MMA(1, 0, At, B0); PG8_MMA(1, 1, At, B1); PG8_BAR; PG8_SCHED;
;             PG8_LDB(B0, 1, 0); PG8_LDB(B1, 1, 1); PG8_SCHED; PG8_LDA(At, 1, 0); PG8_STAGE(PG8_SA(0, 1), a2 + hstep, voffA);
;             PG8_WAIT_V(8); PG8_WAIT_L(0); PG8_BAR; PG8_MMA(0, 0, At, B0); PG8_MMA(0, 1, At, B1); PG8_BAR; PG8_SCHED;
;             PG8_LDA(At, 1, 1); PG8_STAGE(PG8_SB(1, 0), b3, voffB); PG8_STAGE(PG8_SB(1, 1), b3 + hstep, voffB); PG8_STAGE(PG8_SA(1, 0), a3, voffA);
;             PG8_WAIT_V(8); PG8_WAIT_L(0); PG8_BAR; PG8_MMA(1, 0, At, B0); PG8_MMA(1, 1, At, B1); PG8_BAR; PG8_SCHED;
	s_add_i32 s22, s75, s23
	v_lshl_add_u64 v[164:165], v[164:165], 0, s[8:9]
	s_mov_b32 m0, s22
	ds_read_b128 v[184:187], v171 offset:49152
	ds_read_b128 v[190:193], v171 offset:50176
	ds_read_b128 v[194:197], v171 offset:51200
	ds_read_b128 v[198:201], v171 offset:52224
	ds_read_b128 v[202:205], v171 offset:53248
	ds_read_b128 v[206:209], v171 offset:54272
	ds_read_b128 v[214:217], v171 offset:55296
	ds_read_b128 v[218:221], v171 offset:56320
	global_load_lds_dwordx4 v[164:165], off
	s_add_i32 m0, s22, 0x2000
	s_add_u32 s34, s40, 0x160080
	v_lshl_add_u64 v[164:165], v[210:211], 0, s[8:9]
	s_addc_u32 s35, s41, 0
	s_add_i32 s22, s84, s23
	global_load_lds_dwordx4 v[164:165], off
	v_lshl_add_u64 v[164:165], s[34:35], 0, v[146:147]
	s_mov_b32 m0, s22
	s_nop 0
	global_load_lds_dwordx4 v[164:165], off
	v_lshl_add_u64 v[164:165], s[34:35], 0, v[150:151]
	s_add_i32 m0, s22, 0x2000
	s_nop 0
	global_load_lds_dwordx4 v[164:165], off
	v_lshl_add_u64 v[164:165], v[222:223], 0, s[8:9]
	s_mov_b32 m0, s47
	s_nop 0
	global_load_lds_dwordx4 v[164:165], off
	v_lshl_add_u64 v[164:165], v[224:225], 0, s[8:9]
	s_mov_b32 m0, s52
	s_nop 0
	global_load_lds_dwordx4 v[164:165], off
	s_waitcnt vmcnt(8)
	s_waitcnt lgkmcnt(0)
	s_setprio 1
	s_barrier
	s_waitcnt lgkmcnt(0)
	v_mfma_f32_16x16x32_bf16 v[60:63], v[120:123], v[184:187], v[60:63]
	v_mfma_f32_16x16x32_bf16 v[56:59], v[128:131], v[184:187], v[56:59]
	v_mfma_f32_16x16x32_bf16 v[52:55], v[120:123], v[194:197], v[52:55]
	v_mfma_f32_16x16x32_bf16 v[40:43], v[128:131], v[194:197], v[40:43]
	v_mfma_f32_16x16x32_bf16 v[36:39], v[120:123], v[202:205], v[36:39]
	v_mfma_f32_16x16x32_bf16 v[24:27], v[128:131], v[202:205], v[24:27]
	v_mfma_f32_16x16x32_bf16 v[20:23], v[120:123], v[214:217], v[20:23]
	v_mfma_f32_16x16x32_bf16 v[8:11], v[128:131], v[214:217], v[8:11]
	v_mfma_f32_16x16x32_bf16 v[60:63], v[124:127], v[190:193], v[60:63]
	v_mfma_f32_16x16x32_bf16 v[56:59], v[132:135], v[190:193], v[56:59]
	v_mfma_f32_16x16x32_bf16 v[52:55], v[124:127], v[198:201], v[52:55]
	v_mfma_f32_16x16x32_bf16 v[40:43], v[132:135], v[198:201], v[40:43]
	v_mfma_f32_16x16x32_bf16 v[36:39], v[124:127], v[206:209], v[36:39]
	v_mfma_f32_16x16x32_bf16 v[24:27], v[132:135], v[206:209], v[24:27]
	v_mfma_f32_16x16x32_bf16 v[20:23], v[124:127], v[218:221], v[20:23]
	v_mfma_f32_16x16x32_bf16 v[8:11], v[132:135], v[218:221], v[8:11]
	s_setprio 0
	s_setprio 1
	v_mfma_f32_16x16x32_bf16 v[48:51], v[160:163], v[184:187], v[48:51]
	v_mfma_f32_16x16x32_bf16 v[44:47], v[176:179], v[184:187], v[44:47]
	v_mfma_f32_16x16x32_bf16 v[32:35], v[160:163], v[194:197], v[32:35]
	v_mfma_f32_16x16x32_bf16 v[28:31], v[176:179], v[194:197], v[28:31]
	v_mfma_f32_16x16x32_bf16 v[16:19], v[160:163], v[202:205], v[16:19]
	v_mfma_f32_16x16x32_bf16 v[12:15], v[176:179], v[202:205], v[12:15]
	v_mfma_f32_16x16x32_bf16 v[4:7], v[160:163], v[214:217], v[4:7]
	v_mfma_f32_16x16x32_bf16 v[0:3], v[176:179], v[214:217], v[0:3]
	v_mfma_f32_16x16x32_bf16 v[48:51], v[172:175], v[190:193], v[48:51]
	v_mfma_f32_16x16x32_bf16 v[44:47], v[180:183], v[190:193], v[44:47]
	v_mfma_f32_16x16x32_bf16 v[32:35], v[172:175], v[198:201], v[32:35]
	v_mfma_f32_16x16x32_bf16 v[28:31], v[180:183], v[198:201], v[28:31]
	v_mfma_f32_16x16x32_bf16 v[16:19], v[172:175], v[206:209], v[16:19]
	v_mfma_f32_16x16x32_bf16 v[12:15], v[180:183], v[206:209], v[12:15]
	v_mfma_f32_16x16x32_bf16 v[4:7], v[172:175], v[218:221], v[4:7]
	v_mfma_f32_16x16x32_bf16 v[0:3], v[180:183], v[218:221], v[0:3]
	s_setprio 0
	s_barrier
	s_add_i32 s59, s59, 2
	s_add_u32 s0, s0, 0x100
	s_addc_u32 s1, s1, 0
	s_cmpk_gt_u32 s59, 0x55
	s_mov_b64 s[34:35], s[38:39]
.LBB0_1101:
	ds_read_b128 v[120:123], v169
	ds_read_b128 v[124:127], v169 offset:1024
	ds_read_b128 v[128:131], v169 offset:2048
	ds_read_b128 v[132:135], v169 offset:3072
	ds_read_b128 v[160:163], v170
	ds_read_b128 v[172:175], v170 offset:1024
	ds_read_b128 v[176:179], v170 offset:2048
	ds_read_b128 v[180:183], v170 offset:3072
	s_add_u32 s38, s34, 0x100
	s_addc_u32 s39, s35, 0
	s_cmpk_eq_i32 s59, 0x54
	s_cselect_b32 s43, s5, s39
	s_cselect_b32 s42, s4, s38
	s_cselect_b32 s41, s21, s1
	s_cselect_b32 s40, s20, s0
	v_lshl_add_u64 v[164:165], s[34:35], 0, v[152:153]
	s_add_i32 m0, s28, 0xc000
	ds_read_b128 v[184:187], v171
	ds_read_b128 v[190:193], v171 offset:1024
	ds_read_b128 v[194:197], v171 offset:2048
	ds_read_b128 v[198:201], v171 offset:3072
	ds_read_b128 v[202:205], v171 offset:4096
	ds_read_b128 v[206:209], v171 offset:5120
	ds_read_b128 v[214:217], v171 offset:6144
	ds_read_b128 v[218:221], v171 offset:7168
	global_load_lds_dwordx4 v[164:165], off
	v_lshl_add_u64 v[164:165], s[34:35], 0, v[154:155]
	s_add_i32 m0, s28, 0xe000
	s_nop 0
	global_load_lds_dwordx4 v[164:165], off
	s_waitcnt vmcnt(8)
	s_waitcnt lgkmcnt(0)
	s_setprio 1
	s_barrier
; #define PG8_STAGE(bufoff, gbase, voff) do { _Pragma("unroll") for (int _i = 0; _i < 2; ++_i) \
;         __builtin_amdgcn_global_load_lds((const unsigned*)((const char*)(gbase) + (voff)[_i]), (PG8_LAS unsigned*)(lds + (bufoff) + ldsw + _i * 8192), 16, 0, 0); } while (0)
; #define PG8_LDA(dst, b, h) do { _Pragma("unroll") for (int m = 0; m < 4; ++m) _Pragma("unroll") for (int k = 0; k < 2; ++k) dst[m][k] = *(const PG8_LAS bf16x8*)(lds + PG8_SA(b, h) + aoff + m * 2048 + k * 1024); } while (0)
; #define PG8_LDB(dst, b, h) do { _Pragma("unroll") for (int n = 0; n < 2; ++n) _Pragma("unroll") for (int k = 0; k < 2; ++k) dst[n][k] = *(const PG8_LAS bf16x8*)(lds + PG8_SB(b, h) + boff + n * 2048 + k * 1024); } while (0)
; #define PG8_MMA(ai, bj, At, Bt) do { __builtin_amdgcn_s_setprio(1); _Pragma("unroll") for (int m = 0; m < 4; ++m) _Pragma("unroll") for (int n = 0; n < 2; ++n) _Pragma("unroll") for (int k = 0; k < 2; ++k) \
;         acc[ai][bj][m][n] = __builtin_amdgcn_mfma_f32_16x16x32_bf16(Bt[n][k], At[m][k], acc[ai][bj][m][n], 0, 0, 0); __builtin_amdgcn_s_setprio(0); } while (0)
; #define PG8_BAR __builtin_amdgcn_s_barrier()
; template <class Epi, class Sched, bool ALIGN_EPI = false, bool SP2 = false>
; __device__ __forceinline__ void gemm_phase(PG8_LAS unsigned char* lds, const Gemm g, const Sched& S, const Epi& E) {
;     ...
;             if constexpr (SP2) {
;             PG8_LDB(B0, 0, 0); PG8_LDB(B1, 0, 1); PG8_SCHED; PG8_LDA(At, 0, 0); PG8_STAGE(PG8_SA(1, 1), a1 + hstep, voffA);
;             PG8_WAIT_V(8); PG8_WAIT_L(0); PG8_BAR; PG8_MMA(0, 0, At, B0); PG8_MMA(0, 1, At, B1); PG8_BAR; PG8_SCHED;
;             PG8_LDA(At, 0, 1); PG8_STAGE(PG8_SB(0, 0), b2, voffB); PG8_STAGE(PG8_SB(0, 1), b2 + hstep, voffB); PG8_STAGE(PG8_SA(0, 0), a2, voffA);
;             PG8_WAIT_V(8); PG8_WAIT_L(0); PG8_BAR; PG8_MMA(1, 0, At, B0); PG8_MMA(1, 1, At, B1); PG8_BAR; PG8_SCHED;
;             PG8_LDB(B0, 1, 0); PG8_LDB(B1, 1, 1); PG8_SCHED; PG8_LDA(At, 1, 0); PG8_STAGE(PG8_SA(0, 1), a2 + hstep, voffA);
;             PG8_WAIT_V(8); PG8_WAIT_L(0); PG8_BAR; PG8_MMA(0, 0, At, B0); PG8_MMA(0, 1, At, B1); PG8_BAR; PG8_SCHED;
;             PG8_LDA(At, 1, 1); PG8_STAGE(PG8_SB(1, 0), b3, voffB); PG8_STAGE(PG8_SB(1, 1), b3 + hstep, voffB); PG8_STAGE(PG8_SA(1, 0), a3, voffA);
;             PG8_WAIT_V(8); PG8_WAIT_L(0); PG8_BAR; PG8_MMA(1, 0, At, B0); PG8_MMA(1, 1, At, B1); PG8_BAR; PG8_SCHED;
	s_waitcnt lgkmcnt(0)
	v_mfma_f32_16x16x32_bf16 v[140:143], v[120:123], v[184:187], v[140:143]
	v_mfma_f32_16x16x32_bf16 v[136:139], v[128:131], v[184:187], v[136:139]
	v_mfma_f32_16x16x32_bf16 v[116:119], v[120:123], v[194:197], v[116:119]
	v_mfma_f32_16x16x32_bf16 v[104:107], v[128:131], v[194:197], v[104:107]
	v_mfma_f32_16x16x32_bf16 v[100:103], v[120:123], v[202:205], v[100:103]
	v_mfma_f32_16x16x32_bf16 v[88:91], v[128:131], v[202:205], v[88:91]
	v_mfma_f32_16x16x32_bf16 v[84:87], v[120:123], v[214:217], v[84:87]
	v_mfma_f32_16x16x32_bf16 v[72:75], v[128:131], v[214:217], v[72:75]
	v_mfma_f32_16x16x32_bf16 v[140:143], v[124:127], v[190:193], v[140:143]
	v_mfma_f32_16x16x32_bf16 v[136:139], v[132:135], v[190:193], v[136:139]
	v_mfma_f32_16x16x32_bf16 v[116:119], v[124:127], v[198:201], v[116:119]
	v_mfma_f32_16x16x32_bf16 v[104:107], v[132:135], v[198:201], v[104:107]
	v_mfma_f32_16x16x32_bf16 v[100:103], v[124:127], v[206:209], v[100:103]
	v_mfma_f32_16x16x32_bf16 v[88:91], v[132:135], v[206:209], v[88:91]
	v_mfma_f32_16x16x32_bf16 v[84:87], v[124:127], v[218:221], v[84:87]
	v_mfma_f32_16x16x32_bf16 v[72:75], v[132:135], v[218:221], v[72:75]
	s_setprio 0
	s_setprio 1
	v_mfma_f32_16x16x32_bf16 v[112:115], v[160:163], v[184:187], v[112:115]
	v_mfma_f32_16x16x32_bf16 v[108:111], v[176:179], v[184:187], v[108:111]
	v_mfma_f32_16x16x32_bf16 v[96:99], v[160:163], v[194:197], v[96:99]
	v_mfma_f32_16x16x32_bf16 v[92:95], v[176:179], v[194:197], v[92:95]
	v_mfma_f32_16x16x32_bf16 v[80:83], v[160:163], v[202:205], v[80:83]
	v_mfma_f32_16x16x32_bf16 v[76:79], v[176:179], v[202:205], v[76:79]
	v_mfma_f32_16x16x32_bf16 v[68:71], v[160:163], v[214:217], v[68:71]
	v_mfma_f32_16x16x32_bf16 v[64:67], v[176:179], v[214:217], v[64:67]
	v_mfma_f32_16x16x32_bf16 v[112:115], v[172:175], v[190:193], v[112:115]
	v_mfma_f32_16x16x32_bf16 v[108:111], v[180:183], v[190:193], v[108:111]
	v_mfma_f32_16x16x32_bf16 v[96:99], v[172:175], v[198:201], v[96:99]
	v_mfma_f32_16x16x32_bf16 v[92:95], v[180:183], v[198:201], v[92:95]
	v_mfma_f32_16x16x32_bf16 v[80:83], v[172:175], v[206:209], v[80:83]
	v_mfma_f32_16x16x32_bf16 v[76:79], v[180:183], v[206:209], v[76:79]
	v_mfma_f32_16x16x32_bf16 v[68:71], v[172:175], v[218:221], v[68:71]
	v_mfma_f32_16x16x32_bf16 v[64:67], v[180:183], v[218:221], v[64:67]
	s_setprio 0
	s_barrier
	s_add_i32 s22, s31, s23
	v_lshl_add_u64 v[164:165], s[40:41], 0, v[146:147]
	s_mov_b32 m0, s22
	ds_read_b128 v[184:187], v171 offset:16384
	ds_read_b128 v[190:193], v171 offset:17408
	ds_read_b128 v[194:197], v171 offset:18432
	ds_read_b128 v[198:201], v171 offset:19456
	ds_read_b128 v[202:205], v171 offset:20480
	ds_read_b128 v[206:209], v171 offset:21504
	ds_read_b128 v[214:217], v171 offset:22528
	ds_read_b128 v[218:221], v171 offset:23552
	global_load_lds_dwordx4 v[164:165], off
	s_add_i32 m0, s22, 0x2000
	s_add_u32 s34, s40, 0x160000
	v_lshl_add_u64 v[210:211], s[40:41], 0, v[150:151]
	s_addc_u32 s35, s41, 0
	s_add_i32 s22, s74, s23
	global_load_lds_dwordx4 v[210:211], off
	v_lshl_add_u64 v[222:223], s[34:35], 0, v[146:147]
	s_mov_b32 m0, s22
	v_lshl_add_u64 v[224:225], s[42:43], 0, v[148:149]
	global_load_lds_dwordx4 v[222:223], off
	v_lshl_add_u64 v[222:223], s[34:35], 0, v[150:151]
	s_add_i32 m0, s22, 0x2000
	s_nop 0
	global_load_lds_dwordx4 v[222:223], off
	v_lshl_add_u64 v[222:223], s[42:43], 0, v[144:145]
	s_mov_b32 m0, s28
	s_nop 0
	global_load_lds_dwordx4 v[222:223], off
	s_mov_b32 m0, s29
	s_nop 0
	global_load_lds_dwordx4 v[224:225], off
	s_waitcnt vmcnt(8)
	s_waitcnt lgkmcnt(0)
	s_setprio 1
	s_barrier
	s_waitcnt lgkmcnt(0)
	v_mfma_f32_16x16x32_bf16 v[60:63], v[120:123], v[184:187], v[60:63]
	v_mfma_f32_16x16x32_bf16 v[56:59], v[128:131], v[184:187], v[56:59]
	v_mfma_f32_16x16x32_bf16 v[52:55], v[120:123], v[194:197], v[52:55]
	v_mfma_f32_16x16x32_bf16 v[40:43], v[128:131], v[194:197], v[40:43]
	v_mfma_f32_16x16x32_bf16 v[36:39], v[120:123], v[202:205], v[36:39]
	v_mfma_f32_16x16x32_bf16 v[24:27], v[128:131], v[202:205], v[24:27]
	v_mfma_f32_16x16x32_bf16 v[20:23], v[120:123], v[214:217], v[20:23]
	v_mfma_f32_16x16x32_bf16 v[8:11], v[128:131], v[214:217], v[8:11]
	v_mfma_f32_16x16x32_bf16 v[60:63], v[124:127], v[190:193], v[60:63]
	v_mfma_f32_16x16x32_bf16 v[56:59], v[132:135], v[190:193], v[56:59]
	v_mfma_f32_16x16x32_bf16 v[52:55], v[124:127], v[198:201], v[52:55]
	v_mfma_f32_16x16x32_bf16 v[40:43], v[132:135], v[198:201], v[40:43]
	v_mfma_f32_16x16x32_bf16 v[36:39], v[124:127], v[206:209], v[36:39]
	v_mfma_f32_16x16x32_bf16 v[24:27], v[132:135], v[206:209], v[24:27]
	v_mfma_f32_16x16x32_bf16 v[20:23], v[124:127], v[218:221], v[20:23]
	v_mfma_f32_16x16x32_bf16 v[8:11], v[132:135], v[218:221], v[8:11]
	s_setprio 0
	s_setprio 1
	v_mfma_f32_16x16x32_bf16 v[48:51], v[160:163], v[184:187], v[48:51]
	v_mfma_f32_16x16x32_bf16 v[44:47], v[176:179], v[184:187], v[44:47]
	v_mfma_f32_16x16x32_bf16 v[32:35], v[160:163], v[194:197], v[32:35]
	v_mfma_f32_16x16x32_bf16 v[28:31], v[176:179], v[194:197], v[28:31]
	v_mfma_f32_16x16x32_bf16 v[16:19], v[160:163], v[202:205], v[16:19]
	v_mfma_f32_16x16x32_bf16 v[12:15], v[176:179], v[202:205], v[12:15]
	v_mfma_f32_16x16x32_bf16 v[4:7], v[160:163], v[214:217], v[4:7]
	v_mfma_f32_16x16x32_bf16 v[0:3], v[176:179], v[214:217], v[0:3]
	v_mfma_f32_16x16x32_bf16 v[48:51], v[172:175], v[190:193], v[48:51]
	v_mfma_f32_16x16x32_bf16 v[44:47], v[180:183], v[190:193], v[44:47]
	v_mfma_f32_16x16x32_bf16 v[32:35], v[172:175], v[198:201], v[32:35]
	v_mfma_f32_16x16x32_bf16 v[28:31], v[180:183], v[198:201], v[28:31]
	v_mfma_f32_16x16x32_bf16 v[16:19], v[172:175], v[206:209], v[16:19]
	v_mfma_f32_16x16x32_bf16 v[12:15], v[180:183], v[206:209], v[12:15]
	v_mfma_f32_16x16x32_bf16 v[4:7], v[172:175], v[218:221], v[4:7]
	v_mfma_f32_16x16x32_bf16 v[0:3], v[180:183], v[218:221], v[0:3]
	s_setprio 0
	s_barrier
; #define PG8_STAGE(bufoff, gbase, voff) do { _Pragma("unroll") for (int _i = 0; _i < 2; ++_i) \
;         __builtin_amdgcn_global_load_lds((const unsigned*)((const char*)(gbase) + (voff)[_i]), (PG8_LAS unsigned*)(lds + (bufoff) + ldsw + _i * 8192), 16, 0, 0); } while (0)
; #define PG8_LDA(dst, b, h) do { _Pragma("unroll") for (int m = 0; m < 4; ++m) _Pragma("unroll") for (int k = 0; k < 2; ++k) dst[m][k] = *(const PG8_LAS bf16x8*)(lds + PG8_SA(b, h) + aoff + m * 2048 + k * 1024); } while (0)
; #define PG8_LDB(dst, b, h) do { _Pragma("unroll") for (int n = 0; n < 2; ++n) _Pragma("unroll") for (int k = 0; k < 2; ++k) dst[n][k] = *(const PG8_LAS bf16x8*)(lds + PG8_SB(b, h) + boff + n * 2048 + k * 1024); } while (0)
; #define PG8_MMA(ai, bj, At, Bt) do { __builtin_amdgcn_s_setprio(1); _Pragma("unroll") for (int m = 0; m < 4; ++m) _Pragma("unroll") for (int n = 0; n < 2; ++n) _Pragma("unroll") for (int k = 0; k < 2; ++k) \
;         acc[ai][bj][m][n] = __builtin_amdgcn_mfma_f32_16x16x32_bf16(Bt[n][k], At[m][k], acc[ai][bj][m][n], 0, 0, 0); __builtin_amdgcn_s_setprio(0); } while (0)
; #define PG8_BAR __builtin_amdgcn_s_barrier()
; template <class Epi, class Sched, bool ALIGN_EPI = false, bool SP2 = false>
; __device__ __forceinline__ void gemm_phase(PG8_LAS unsigned char* lds, const Gemm g, const Sched& S, const Epi& E) {
;     ...
;             if constexpr (SP2) {
;             PG8_LDB(B0, 0, 0); PG8_LDB(B1, 0, 1); PG8_SCHED; PG8_LDA(At, 0, 0); PG8_STAGE(PG8_SA(1, 1), a1 + hstep, voffA);
;             PG8_WAIT_V(8); PG8_WAIT_L(0); PG8_BAR; PG8_MMA(0, 0, At, B0); PG8_MMA(0, 1, At, B1); PG8_BAR; PG8_SCHED;
;             PG8_LDA(At, 0, 1); PG8_STAGE(PG8_SB(0, 0), b2, voffB); PG8_STAGE(PG8_SB(0, 1), b2 + hstep, voffB); PG8_STAGE(PG8_SA(0, 0), a2, voffA);
;             PG8_WAIT_V(8); PG8_WAIT_L(0); PG8_BAR; PG8_MMA(1, 0, At, B0); PG8_MMA(1, 1, At, B1); PG8_BAR; PG8_SCHED;
;             PG8_LDB(B0, 1, 0); PG8_LDB(B1, 1, 1); PG8_SCHED; PG8_LDA(At, 1, 0); PG8_STAGE(PG8_SA(0, 1), a2 + hstep, voffA);
;             PG8_WAIT_V(8); PG8_WAIT_L(0); PG8_BAR; PG8_MMA(0, 0, At, B0); PG8_MMA(0, 1, At, B1); PG8_BAR; PG8_SCHED;
;             PG8_LDA(At, 1, 1); PG8_STAGE(PG8_SB(1, 0), b3, voffB); PG8_STAGE(PG8_SB(1, 1), b3 + hstep, voffB); PG8_STAGE(PG8_SA(1, 0), a3, voffA);
;             PG8_WAIT_V(8); PG8_WAIT_L(0); PG8_BAR; PG8_MMA(1, 0, At, B0); PG8_MMA(1, 1, At, B1); PG8_BAR; PG8_SCHED;
	v_add_u32_e32 v132, s75, v167
	v_add_u32_e32 v180, s84, v167
	ds_read_b128 v[120:123], v132
	ds_read_b128 v[124:127], v132 offset:1024
	ds_read_b128 v[128:131], v132 offset:2048
	ds_read_b128 v[132:135], v132 offset:3072
	ds_read_b128 v[160:163], v180
	ds_read_b128 v[172:175], v180 offset:1024
	ds_read_b128 v[176:179], v180 offset:2048
	ds_read_b128 v[180:183], v180 offset:3072
	s_add_u32 s34, s42, 0x160000
	s_addc_u32 s35, s43, 0
	s_mov_b32 m0, s30
	v_lshl_add_u64 v[226:227], s[34:35], 0, v[144:145]
	ds_read_b128 v[184:187], v171 offset:32768
	ds_read_b128 v[190:193], v171 offset:33792
	ds_read_b128 v[194:197], v171 offset:34816
	ds_read_b128 v[198:201], v171 offset:35840
	ds_read_b128 v[202:205], v171 offset:36864
	ds_read_b128 v[206:209], v171 offset:37888
	ds_read_b128 v[214:217], v171 offset:38912
	ds_read_b128 v[218:221], v171 offset:39936
	global_load_lds_dwordx4 v[226:227], off
	v_lshl_add_u64 v[226:227], s[34:35], 0, v[148:149]
	s_mov_b32 m0, s33
	s_nop 0
	global_load_lds_dwordx4 v[226:227], off
	s_waitcnt vmcnt(8)
	s_waitcnt lgkmcnt(0)
	s_setprio 1
	s_barrier
	s_waitcnt lgkmcnt(0)
	v_mfma_f32_16x16x32_bf16 v[140:143], v[120:123], v[184:187], v[140:143]
	v_mfma_f32_16x16x32_bf16 v[136:139], v[128:131], v[184:187], v[136:139]
	v_mfma_f32_16x16x32_bf16 v[116:119], v[120:123], v[194:197], v[116:119]
	v_mfma_f32_16x16x32_bf16 v[104:107], v[128:131], v[194:197], v[104:107]
	v_mfma_f32_16x16x32_bf16 v[100:103], v[120:123], v[202:205], v[100:103]
	v_mfma_f32_16x16x32_bf16 v[88:91], v[128:131], v[202:205], v[88:91]
	v_mfma_f32_16x16x32_bf16 v[84:87], v[120:123], v[214:217], v[84:87]
	v_mfma_f32_16x16x32_bf16 v[72:75], v[128:131], v[214:217], v[72:75]
	v_mfma_f32_16x16x32_bf16 v[140:143], v[124:127], v[190:193], v[140:143]
	v_mfma_f32_16x16x32_bf16 v[136:139], v[132:135], v[190:193], v[136:139]
	v_mfma_f32_16x16x32_bf16 v[116:119], v[124:127], v[198:201], v[116:119]
	v_mfma_f32_16x16x32_bf16 v[104:107], v[132:135], v[198:201], v[104:107]
	v_mfma_f32_16x16x32_bf16 v[100:103], v[124:127], v[206:209], v[100:103]
	v_mfma_f32_16x16x32_bf16 v[88:91], v[132:135], v[206:209], v[88:91]
	v_mfma_f32_16x16x32_bf16 v[84:87], v[124:127], v[218:221], v[84:87]
	v_mfma_f32_16x16x32_bf16 v[72:75], v[132:135], v[218:221], v[72:75]
	s_setprio 0
	s_setprio 1
	v_mfma_f32_16x16x32_bf16 v[112:115], v[160:163], v[184:187], v[112:115]
	v_mfma_f32_16x16x32_bf16 v[108:111], v[176:179], v[184:187], v[108:111]
	v_mfma_f32_16x16x32_bf16 v[96:99], v[160:163], v[194:197], v[96:99]
	v_mfma_f32_16x16x32_bf16 v[92:95], v[176:179], v[194:197], v[92:95]
	v_mfma_f32_16x16x32_bf16 v[80:83], v[160:163], v[202:205], v[80:83]
	v_mfma_f32_16x16x32_bf16 v[76:79], v[176:179], v[202:205], v[76:79]
	v_mfma_f32_16x16x32_bf16 v[68:71], v[160:163], v[214:217], v[68:71]
	v_mfma_f32_16x16x32_bf16 v[64:67], v[176:179], v[214:217], v[64:67]
	v_mfma_f32_16x16x32_bf16 v[112:115], v[172:175], v[190:193], v[112:115]
	v_mfma_f32_16x16x32_bf16 v[108:111], v[180:183], v[190:193], v[108:111]
	v_mfma_f32_16x16x32_bf16 v[96:99], v[172:175], v[198:201], v[96:99]
	v_mfma_f32_16x16x32_bf16 v[92:95], v[180:183], v[198:201], v[92:95]
	v_mfma_f32_16x16x32_bf16 v[80:83], v[172:175], v[206:209], v[80:83]
	v_mfma_f32_16x16x32_bf16 v[76:79], v[180:183], v[206:209], v[76:79]
	v_mfma_f32_16x16x32_bf16 v[68:71], v[172:175], v[218:221], v[68:71]
	v_mfma_f32_16x16x32_bf16 v[64:67], v[180:183], v[218:221], v[64:67]
	s_setprio 0
	s_barrier
; #define PG8_STAGE(bufoff, gbase, voff) do { _Pragma("unroll") for (int _i = 0; _i < 2; ++_i) \
;         __builtin_amdgcn_global_load_lds((const unsigned*)((const char*)(gbase) + (voff)[_i]), (PG8_LAS unsigned*)(lds + (bufoff) + ldsw + _i * 8192), 16, 0, 0); } while (0)
; #define PG8_LDA(dst, b, h) do { _Pragma("unroll") for (int m = 0; m < 4; ++m) _Pragma("unroll") for (int k = 0; k < 2; ++k) dst[m][k] = *(const PG8_LAS bf16x8*)(lds + PG8_SA(b, h) + aoff + m * 2048 + k * 1024); } while (0)
; #define PG8_LDB(dst, b, h) do { _Pragma("unroll") for (int n = 0; n < 2; ++n) _Pragma("unroll") for (int k = 0; k < 2; ++k) dst[n][k] = *(const PG8_LAS bf16x8*)(lds + PG8_SB(b, h) + boff + n * 2048 + k * 1024); } while (0)
; #define PG8_WAIT_V(n) asm volatile("s_waitcnt vmcnt(" #n ")" ::: "memory")
; #define PG8_WAIT_L(n) asm volatile("s_waitcnt lgkmcnt(" #n ")" ::: "memory")
; #define PG8_BAR __builtin_amdgcn_s_barrier()
; #define PG8_SCHED __builtin_amdgcn_sched_barrier(0)
; template <class Epi, class Sched, bool ALIGN_EPI = false, bool SP2 = false>
; __device__ __forceinline__ void gemm_phase(PG8_LAS unsigned char* lds, const Gemm g, const Sched& S, const Epi& E) {
;     ...
;             if constexpr (SP2) {
;             PG8_LDB(B0, 0, 0); PG8_LDB(B1, 0, 1); PG8_SCHED; PG8_LDA(At, 0, 0); PG8_STAGE(PG8_SA(1, 1), a1 + hstep, voffA);
;             PG8_WAIT_V(8); PG8_WAIT_L(0); PG8_BAR; PG8_MMA(0, 0, At, B0); PG8_MMA(0, 1, At, B1); PG8_BAR; PG8_SCHED;
;             PG8_LDA(At, 0, 1); PG8_STAGE(PG8_SB(0, 0), b2, voffB); PG8_STAGE(PG8_SB(0, 1), b2 + hstep, voffB); PG8_STAGE(PG8_SA(0, 0), a2, voffA);
;             PG8_WAIT_V(8); PG8_WAIT_L(0); PG8_BAR; PG8_MMA(1, 0, At, B0); PG8_MMA(1, 1, At, B1); PG8_BAR; PG8_SCHED;
;             PG8_LDB(B0, 1, 0); PG8_LDB(B1, 1, 1); PG8_SCHED; PG8_LDA(At, 1, 0); PG8_STAGE(PG8_SA(0, 1), a2 + hstep, voffA);
;             PG8_WAIT_V(8); PG8_WAIT_L(0); PG8_BAR; PG8_MMA(0, 0, At, B0); PG8_MMA(0, 1, At, B1); PG8_BAR; PG8_SCHED;
;             PG8_LDA(At, 1, 1); PG8_STAGE(PG8_SB(1, 0), b3, voffB); PG8_STAGE(PG8_SB(1, 1), b3 + hstep, voffB); PG8_STAGE(PG8_SA(1, 0), a3, voffA);
;             PG8_WAIT_V(8); PG8_WAIT_L(0); PG8_BAR; PG8_MMA(1, 0, At, B0); PG8_MMA(1, 1, At, B1); PG8_BAR; PG8_SCHED;
;     ...
;         if constexpr (ALIGN_EPI) { if (wr == 0) PG8_BAR; }
	s_add_i32 s22, s75, s23
	v_lshl_add_u64 v[164:165], v[164:165], 0, s[8:9]
	s_mov_b32 m0, s22
	ds_read_b128 v[184:187], v171 offset:49152
	ds_read_b128 v[190:193], v171 offset:50176
	ds_read_b128 v[194:197], v171 offset:51200
	ds_read_b128 v[198:201], v171 offset:52224
	ds_read_b128 v[202:205], v171 offset:53248
	ds_read_b128 v[206:209], v171 offset:54272
	ds_read_b128 v[214:217], v171 offset:55296
	ds_read_b128 v[218:221], v171 offset:56320
	global_load_lds_dwordx4 v[164:165], off
	s_add_i32 m0, s22, 0x2000
	s_add_u32 s34, s40, 0x160080
	v_lshl_add_u64 v[164:165], v[210:211], 0, s[8:9]
	s_addc_u32 s35, s41, 0
	s_add_i32 s22, s84, s23
	global_load_lds_dwordx4 v[164:165], off
	v_lshl_add_u64 v[164:165], s[34:35], 0, v[146:147]
	s_mov_b32 m0, s22
	s_nop 0
	global_load_lds_dwordx4 v[164:165], off
	v_lshl_add_u64 v[164:165], s[34:35], 0, v[150:151]
	s_add_i32 m0, s22, 0x2000
	s_nop 0
	global_load_lds_dwordx4 v[164:165], off
	v_lshl_add_u64 v[164:165], v[222:223], 0, s[8:9]
	s_mov_b32 m0, s47
	s_nop 0
	global_load_lds_dwordx4 v[164:165], off
	v_lshl_add_u64 v[164:165], v[224:225], 0, s[8:9]
	s_mov_b32 m0, s52
	s_nop 0
	global_load_lds_dwordx4 v[164:165], off
	s_waitcnt vmcnt(8)
	s_waitcnt lgkmcnt(0)
	s_setprio 1
	s_barrier
	s_waitcnt lgkmcnt(0)
	v_mfma_f32_16x16x32_bf16 v[60:63], v[120:123], v[184:187], v[60:63]
	v_mfma_f32_16x16x32_bf16 v[56:59], v[128:131], v[184:187], v[56:59]
	v_mfma_f32_16x16x32_bf16 v[52:55], v[120:123], v[194:197], v[52:55]
	v_mfma_f32_16x16x32_bf16 v[40:43], v[128:131], v[194:197], v[40:43]
	v_mfma_f32_16x16x32_bf16 v[36:39], v[120:123], v[202:205], v[36:39]
	v_mfma_f32_16x16x32_bf16 v[24:27], v[128:131], v[202:205], v[24:27]
	v_mfma_f32_16x16x32_bf16 v[20:23], v[120:123], v[214:217], v[20:23]
	v_mfma_f32_16x16x32_bf16 v[8:11], v[128:131], v[214:217], v[8:11]
	v_mfma_f32_16x16x32_bf16 v[60:63], v[124:127], v[190:193], v[60:63]
	v_mfma_f32_16x16x32_bf16 v[56:59], v[132:135], v[190:193], v[56:59]
	v_mfma_f32_16x16x32_bf16 v[52:55], v[124:127], v[198:201], v[52:55]
	v_mfma_f32_16x16x32_bf16 v[40:43], v[132:135], v[198:201], v[40:43]
	v_mfma_f32_16x16x32_bf16 v[36:39], v[124:127], v[206:209], v[36:39]
	v_mfma_f32_16x16x32_bf16 v[24:27], v[132:135], v[206:209], v[24:27]
	v_mfma_f32_16x16x32_bf16 v[20:23], v[124:127], v[218:221], v[20:23]
	v_mfma_f32_16x16x32_bf16 v[8:11], v[132:135], v[218:221], v[8:11]
	s_setprio 0
	s_setprio 1
	v_mfma_f32_16x16x32_bf16 v[48:51], v[160:163], v[184:187], v[48:51]
	v_mfma_f32_16x16x32_bf16 v[44:47], v[176:179], v[184:187], v[44:47]
	v_mfma_f32_16x16x32_bf16 v[32:35], v[160:163], v[194:197], v[32:35]
	v_mfma_f32_16x16x32_bf16 v[28:31], v[176:179], v[194:197], v[28:31]
	v_mfma_f32_16x16x32_bf16 v[16:19], v[160:163], v[202:205], v[16:19]
	v_mfma_f32_16x16x32_bf16 v[12:15], v[176:179], v[202:205], v[12:15]
	v_mfma_f32_16x16x32_bf16 v[4:7], v[160:163], v[214:217], v[4:7]
	v_mfma_f32_16x16x32_bf16 v[0:3], v[176:179], v[214:217], v[0:3]
	v_mfma_f32_16x16x32_bf16 v[48:51], v[172:175], v[190:193], v[48:51]
	v_mfma_f32_16x16x32_bf16 v[44:47], v[180:183], v[190:193], v[44:47]
	v_mfma_f32_16x16x32_bf16 v[32:35], v[172:175], v[198:201], v[32:35]
	v_mfma_f32_16x16x32_bf16 v[28:31], v[180:183], v[198:201], v[28:31]
	v_mfma_f32_16x16x32_bf16 v[16:19], v[172:175], v[206:209], v[16:19]
	v_mfma_f32_16x16x32_bf16 v[12:15], v[180:183], v[206:209], v[12:15]
	v_mfma_f32_16x16x32_bf16 v[4:7], v[172:175], v[218:221], v[4:7]
	v_mfma_f32_16x16x32_bf16 v[0:3], v[180:183], v[218:221], v[0:3]
	s_setprio 0
	s_barrier
	s_add_i32 s59, s59, 2
	s_add_u32 s0, s0, 0x100
	s_addc_u32 s1, s1, 0
	s_cmpk_gt_u32 s59, 0x55
	s_mov_b64 s[34:35], s[38:39]
	s_cbranch_scc0 .LBB0_1101
	s_and_b64 vcc, exec, s[10:11]
	s_cbranch_vccz .LBB0_1104
	s_barrier
